# K-loop: one wave-uniform test per half step selects a no-load copy of the MFMA group instead of a branch around every DMA load
# speedup vs baseline: 1.0711x; 1.0113x over previous
.LBB0_150:
	s_and_b32 s27, s37, 0x10000
	s_xor_b32 s38, s27, 0x10000
	s_add_i32 s27, s27, 0
	s_add_i32 s101, s100, s38
	s_cmpk_eq_i32 s4, 0
	s_cbranch_scc1 .Lg1n_150
	s_waitcnt lgkmcnt(3)
	v_mfma_f32_16x16x32_bf16 v[124:127], v[160:163], v[180:183], v[124:127]
	v_mfma_f32_16x16x32_bf16 v[108:111], v[168:171], v[180:183], v[108:111]
	v_mfma_f32_16x16x32_bf16 v[92:95], v[172:175], v[180:183], v[92:95]
	v_mfma_f32_16x16x32_bf16 v[76:79], v[176:179], v[180:183], v[76:79]
	ds_read_b128 v[240:243], v200
	ds_read_b128 v[244:247], v201
	s_add_i32 m0, s101, 0x4000
	v_lshl_add_u64 v[142:143], v[142:143], 0, s[98:99]
	global_load_lds_dwordx4 v[142:143], off
	s_waitcnt lgkmcnt(4)
	v_mfma_f32_16x16x32_bf16 v[120:123], v[160:163], v[184:187], v[120:123]
	v_mfma_f32_16x16x32_bf16 v[104:107], v[168:171], v[184:187], v[104:107]
	v_mfma_f32_16x16x32_bf16 v[88:91], v[172:175], v[184:187], v[88:91]
	v_mfma_f32_16x16x32_bf16 v[72:75], v[176:179], v[184:187], v[72:75]
	ds_read_b128 v[248:251], v202
	ds_read_b128 v[252:255], v203
	s_add_i32 m0, s101, 0xc000
	v_lshl_add_u64 v[130:131], v[130:131], 0, s[98:99]
	global_load_lds_dwordx4 v[130:131], off
	s_waitcnt lgkmcnt(5)
	v_mfma_f32_16x16x32_bf16 v[116:119], v[160:163], v[188:191], v[116:119]
	v_mfma_f32_16x16x32_bf16 v[100:103], v[168:171], v[188:191], v[100:103]
	v_mfma_f32_16x16x32_bf16 v[84:87], v[172:175], v[188:191], v[84:87]
	v_mfma_f32_16x16x32_bf16 v[68:71], v[176:179], v[188:191], v[68:71]
	s_add_i32 m0, s101, 0x6000
	v_lshl_add_u64 v[140:141], v[140:141], 0, s[98:99]
	global_load_lds_dwordx4 v[140:141], off
	s_waitcnt lgkmcnt(4)
	v_mfma_f32_16x16x32_bf16 v[112:115], v[160:163], v[192:195], v[112:115]
	v_mfma_f32_16x16x32_bf16 v[96:99], v[168:171], v[192:195], v[96:99]
	v_mfma_f32_16x16x32_bf16 v[80:83], v[172:175], v[192:195], v[80:83]
	v_mfma_f32_16x16x32_bf16 v[64:67], v[176:179], v[192:195], v[64:67]
	s_add_i32 m0, s101, 0xe000
	v_lshl_add_u64 v[128:129], v[128:129], 0, s[98:99]
	global_load_lds_dwordx4 v[128:129], off
.Lg2_150:
	ds_read_b128 v[160:163], v196 offset:1024
	ds_read_b128 v[168:171], v197 offset:1024
	ds_read_b128 v[172:175], v198 offset:1024
	ds_read_b128 v[176:179], v199 offset:1024
	s_waitcnt lgkmcnt(4)
	v_mfma_f32_16x16x32_bf16 v[60:63], v[240:243], v[180:183], v[60:63]
	v_mfma_f32_16x16x32_bf16 v[44:47], v[244:247], v[180:183], v[44:47]
	v_mfma_f32_16x16x32_bf16 v[16:19], v[248:251], v[180:183], v[16:19]
	v_mfma_f32_16x16x32_bf16 v[36:39], v[252:255], v[180:183], v[36:39]
	ds_read_b128 v[180:183], v134 offset:33792
	v_mfma_f32_16x16x32_bf16 v[56:59], v[240:243], v[184:187], v[56:59]
	v_mfma_f32_16x16x32_bf16 v[40:43], v[244:247], v[184:187], v[40:43]
	v_mfma_f32_16x16x32_bf16 v[12:15], v[248:251], v[184:187], v[12:15]
	v_mfma_f32_16x16x32_bf16 v[28:31], v[252:255], v[184:187], v[28:31]
	ds_read_b128 v[184:187], v134 offset:35840
	v_mfma_f32_16x16x32_bf16 v[52:55], v[240:243], v[188:191], v[52:55]
	v_mfma_f32_16x16x32_bf16 v[32:35], v[244:247], v[188:191], v[32:35]
	v_mfma_f32_16x16x32_bf16 v[4:7], v[248:251], v[188:191], v[4:7]
	v_mfma_f32_16x16x32_bf16 v[20:23], v[252:255], v[188:191], v[20:23]
	ds_read_b128 v[188:191], v134 offset:37888
	v_mfma_f32_16x16x32_bf16 v[48:51], v[240:243], v[192:195], v[48:51]
	v_mfma_f32_16x16x32_bf16 v[24:27], v[244:247], v[192:195], v[24:27]
	v_mfma_f32_16x16x32_bf16 v[0:3], v[248:251], v[192:195], v[0:3]
	v_mfma_f32_16x16x32_bf16 v[8:11], v[252:255], v[192:195], v[8:11]
	ds_read_b128 v[192:195], v134 offset:39936
	s_waitcnt lgkmcnt(3)
	v_mfma_f32_16x16x32_bf16 v[124:127], v[160:163], v[180:183], v[124:127]
	v_mfma_f32_16x16x32_bf16 v[108:111], v[168:171], v[180:183], v[108:111]
	v_mfma_f32_16x16x32_bf16 v[92:95], v[172:175], v[180:183], v[92:95]
	v_mfma_f32_16x16x32_bf16 v[76:79], v[176:179], v[180:183], v[76:79]
	ds_read_b128 v[240:243], v200 offset:1024
	ds_read_b128 v[244:247], v201 offset:1024
	s_waitcnt lgkmcnt(4)
	v_mfma_f32_16x16x32_bf16 v[120:123], v[160:163], v[184:187], v[120:123]
	v_mfma_f32_16x16x32_bf16 v[104:107], v[168:171], v[184:187], v[104:107]
	v_mfma_f32_16x16x32_bf16 v[88:91], v[172:175], v[184:187], v[88:91]
	v_mfma_f32_16x16x32_bf16 v[72:75], v[176:179], v[184:187], v[72:75]
	ds_read_b128 v[248:251], v202 offset:1024
	ds_read_b128 v[252:255], v203 offset:1024
	s_waitcnt lgkmcnt(5)
	v_mfma_f32_16x16x32_bf16 v[116:119], v[160:163], v[188:191], v[116:119]
	v_mfma_f32_16x16x32_bf16 v[100:103], v[168:171], v[188:191], v[100:103]
	v_mfma_f32_16x16x32_bf16 v[84:87], v[172:175], v[188:191], v[84:87]
	v_mfma_f32_16x16x32_bf16 v[68:71], v[176:179], v[188:191], v[68:71]
	s_waitcnt lgkmcnt(4)
	v_mfma_f32_16x16x32_bf16 v[112:115], v[160:163], v[192:195], v[112:115]
	v_mfma_f32_16x16x32_bf16 v[96:99], v[168:171], v[192:195], v[96:99]
	v_mfma_f32_16x16x32_bf16 v[80:83], v[172:175], v[192:195], v[80:83]
	v_mfma_f32_16x16x32_bf16 v[64:67], v[176:179], v[192:195], v[64:67]
	s_waitcnt vmcnt(0) lgkmcnt(0)
	s_barrier
	s_add_i32 s101, s100, s27
	s_cmpk_eq_i32 s4, 0x700
	s_cbranch_scc1 .Lg4n_150
	v_mfma_f32_16x16x32_bf16 v[60:63], v[240:243], v[180:183], v[60:63]
	v_mfma_f32_16x16x32_bf16 v[44:47], v[244:247], v[180:183], v[44:47]
	v_mfma_f32_16x16x32_bf16 v[16:19], v[248:251], v[180:183], v[16:19]
	v_mfma_f32_16x16x32_bf16 v[36:39], v[252:255], v[180:183], v[36:39]
	v_add3_u32 v134, s38, v149, v150
	ds_read_b128 v[180:183], v134 offset:32768
	v_add3_u32 v196, s38, v149, v151
	v_add3_u32 v197, s38, v153, v152
	v_add3_u32 v198, s38, v153, v154
	v_add3_u32 v199, s38, v153, v155
	ds_read_b128 v[160:163], v196
	ds_read_b128 v[168:171], v197
	ds_read_b128 v[172:175], v198
	ds_read_b128 v[176:179], v199
	s_mov_b32 m0, s101
	v_lshl_add_u64 v[146:147], v[146:147], 0, s[98:99]
	global_load_lds_dwordx4 v[146:147], off
	v_mfma_f32_16x16x32_bf16 v[56:59], v[240:243], v[184:187], v[56:59]
	v_mfma_f32_16x16x32_bf16 v[40:43], v[244:247], v[184:187], v[40:43]
	v_mfma_f32_16x16x32_bf16 v[12:15], v[248:251], v[184:187], v[12:15]
	v_mfma_f32_16x16x32_bf16 v[28:31], v[252:255], v[184:187], v[28:31]
	ds_read_b128 v[184:187], v134 offset:34816
	v_add3_u32 v200, s38, v153, v156
	v_add3_u32 v201, s38, v153, v157
	v_add3_u32 v202, s38, v153, v158
	v_add3_u32 v203, s38, v153, v159
	s_add_i32 m0, s101, 0x8000
	v_lshl_add_u64 v[138:139], v[138:139], 0, s[98:99]
	global_load_lds_dwordx4 v[138:139], off
	v_mfma_f32_16x16x32_bf16 v[52:55], v[240:243], v[188:191], v[52:55]
	v_mfma_f32_16x16x32_bf16 v[32:35], v[244:247], v[188:191], v[32:35]
	v_mfma_f32_16x16x32_bf16 v[4:7], v[248:251], v[188:191], v[4:7]
	v_mfma_f32_16x16x32_bf16 v[20:23], v[252:255], v[188:191], v[20:23]
	ds_read_b128 v[188:191], v134 offset:36864
	s_add_i32 m0, s101, 0x2000
	v_lshl_add_u64 v[144:145], v[144:145], 0, s[98:99]
	global_load_lds_dwordx4 v[144:145], off
	v_mfma_f32_16x16x32_bf16 v[48:51], v[240:243], v[192:195], v[48:51]
	v_mfma_f32_16x16x32_bf16 v[24:27], v[244:247], v[192:195], v[24:27]
	v_mfma_f32_16x16x32_bf16 v[0:3], v[248:251], v[192:195], v[0:3]
	v_mfma_f32_16x16x32_bf16 v[8:11], v[252:255], v[192:195], v[8:11]
	ds_read_b128 v[192:195], v134 offset:38912
	s_add_i32 m0, s101, 0xa000
	v_lshl_add_u64 v[136:137], v[136:137], 0, s[98:99]
	global_load_lds_dwordx4 v[136:137], off
.Ltl_150:
	s_add_i32 s37, s37, 0x10000
	s_add_u32 s4, s4, 0x80
	s_addc_u32 s5, s5, 0
	s_cmpk_lg_i32 s4, 0x780
	s_cbranch_scc1 .LBB0_150
	s_branch .Lex_150
.Lg1n_150:
	s_waitcnt lgkmcnt(3)
	v_mfma_f32_16x16x32_bf16 v[124:127], v[160:163], v[180:183], v[124:127]
	v_mfma_f32_16x16x32_bf16 v[108:111], v[168:171], v[180:183], v[108:111]
	v_mfma_f32_16x16x32_bf16 v[92:95], v[172:175], v[180:183], v[92:95]
	v_mfma_f32_16x16x32_bf16 v[76:79], v[176:179], v[180:183], v[76:79]
	ds_read_b128 v[240:243], v200
	ds_read_b128 v[244:247], v201
	s_waitcnt lgkmcnt(4)
	v_mfma_f32_16x16x32_bf16 v[120:123], v[160:163], v[184:187], v[120:123]
	v_mfma_f32_16x16x32_bf16 v[104:107], v[168:171], v[184:187], v[104:107]
	v_mfma_f32_16x16x32_bf16 v[88:91], v[172:175], v[184:187], v[88:91]
	v_mfma_f32_16x16x32_bf16 v[72:75], v[176:179], v[184:187], v[72:75]
	ds_read_b128 v[248:251], v202
	ds_read_b128 v[252:255], v203
	s_waitcnt lgkmcnt(5)
	v_mfma_f32_16x16x32_bf16 v[116:119], v[160:163], v[188:191], v[116:119]
	v_mfma_f32_16x16x32_bf16 v[100:103], v[168:171], v[188:191], v[100:103]
	v_mfma_f32_16x16x32_bf16 v[84:87], v[172:175], v[188:191], v[84:87]
	v_mfma_f32_16x16x32_bf16 v[68:71], v[176:179], v[188:191], v[68:71]
	s_waitcnt lgkmcnt(4)
	v_mfma_f32_16x16x32_bf16 v[112:115], v[160:163], v[192:195], v[112:115]
	v_mfma_f32_16x16x32_bf16 v[96:99], v[168:171], v[192:195], v[96:99]
	v_mfma_f32_16x16x32_bf16 v[80:83], v[172:175], v[192:195], v[80:83]
	v_mfma_f32_16x16x32_bf16 v[64:67], v[176:179], v[192:195], v[64:67]
	s_branch .Lg2_150
.Lg4n_150:
	v_mfma_f32_16x16x32_bf16 v[60:63], v[240:243], v[180:183], v[60:63]
	v_mfma_f32_16x16x32_bf16 v[44:47], v[244:247], v[180:183], v[44:47]
	v_mfma_f32_16x16x32_bf16 v[16:19], v[248:251], v[180:183], v[16:19]
	v_mfma_f32_16x16x32_bf16 v[36:39], v[252:255], v[180:183], v[36:39]
	v_add3_u32 v134, s38, v149, v150
	ds_read_b128 v[180:183], v134 offset:32768
	v_add3_u32 v196, s38, v149, v151
	v_add3_u32 v197, s38, v153, v152
	v_add3_u32 v198, s38, v153, v154
	v_add3_u32 v199, s38, v153, v155
	ds_read_b128 v[160:163], v196
	ds_read_b128 v[168:171], v197
	ds_read_b128 v[172:175], v198
	ds_read_b128 v[176:179], v199
	v_mfma_f32_16x16x32_bf16 v[56:59], v[240:243], v[184:187], v[56:59]
	v_mfma_f32_16x16x32_bf16 v[40:43], v[244:247], v[184:187], v[40:43]
	v_mfma_f32_16x16x32_bf16 v[12:15], v[248:251], v[184:187], v[12:15]
	v_mfma_f32_16x16x32_bf16 v[28:31], v[252:255], v[184:187], v[28:31]
	ds_read_b128 v[184:187], v134 offset:34816
	v_add3_u32 v200, s38, v153, v156
	v_add3_u32 v201, s38, v153, v157
	v_add3_u32 v202, s38, v153, v158
	v_add3_u32 v203, s38, v153, v159
	v_mfma_f32_16x16x32_bf16 v[52:55], v[240:243], v[188:191], v[52:55]
	v_mfma_f32_16x16x32_bf16 v[32:35], v[244:247], v[188:191], v[32:35]
	v_mfma_f32_16x16x32_bf16 v[4:7], v[248:251], v[188:191], v[4:7]
	v_mfma_f32_16x16x32_bf16 v[20:23], v[252:255], v[188:191], v[20:23]
	ds_read_b128 v[188:191], v134 offset:36864
	v_mfma_f32_16x16x32_bf16 v[48:51], v[240:243], v[192:195], v[48:51]
	v_mfma_f32_16x16x32_bf16 v[24:27], v[244:247], v[192:195], v[24:27]
	v_mfma_f32_16x16x32_bf16 v[0:3], v[248:251], v[192:195], v[0:3]
	v_mfma_f32_16x16x32_bf16 v[8:11], v[252:255], v[192:195], v[8:11]
	ds_read_b128 v[192:195], v134 offset:38912
	s_branch .Ltl_150
.Lex_150:
	s_waitcnt lgkmcnt(0)
	s_add_i32 s27, 0, 0x10000
	v_add3_u32 v134, s27, v153, v159
	ds_read_b128 v[128:131], v134
	v_add3_u32 v200, s27, v153, v158
	v_add3_u32 v201, s27, v153, v157
	v_add3_u32 v202, s27, v153, v156
	v_add3_u32 v203, s27, v153, v155
	v_add3_u32 v204, s27, v153, v154
	v_add3_u32 v205, s27, v153, v152
	v_add3_u32 v188, s27, v149, v151
	v_add3_u32 v196, s52, v149, v150
	ds_read_b128 v[136:139], v200
	ds_read_b128 v[140:143], v201
	ds_read_b128 v[144:147], v202
	ds_read_b128 v[156:159], v203
	ds_read_b128 v[160:163], v204
	ds_read_b128 v[152:155], v205
	ds_read_b128 v[168:171], v188
	ds_read_b128 v[148:151], v196
	s_waitcnt lgkmcnt(0)
	v_mfma_f32_16x16x32_bf16 v[172:175], v[128:131], v[148:151], v[36:39]
	s_nop 2
	ds_read_b128 v[36:39], v196 offset:2048
	s_waitcnt lgkmcnt(0)
	v_mfma_f32_16x16x32_bf16 v[176:179], v[128:131], v[36:39], v[28:31]
	s_nop 2
	ds_read_b128 v[28:31], v196 offset:4096
	s_waitcnt lgkmcnt(0)
	v_mfma_f32_16x16x32_bf16 v[4:7], v[136:139], v[28:31], v[4:7]
	v_mfma_f32_16x16x32_bf16 v[76:79], v[156:159], v[148:151], v[76:79]
	v_mfma_f32_16x16x32_bf16 v[104:107], v[152:155], v[36:39], v[104:107]
	v_mfma_f32_16x16x32_bf16 v[88:91], v[160:163], v[36:39], v[88:91]
	v_mfma_f32_16x16x32_bf16 v[72:75], v[156:159], v[36:39], v[72:75]
	v_mfma_f32_16x16x32_bf16 v[180:183], v[128:131], v[28:31], v[20:23]
	v_mfma_f32_16x16x32_bf16 v[184:187], v[160:163], v[28:31], v[84:87]
	v_mfma_f32_16x16x32_bf16 v[68:71], v[156:159], v[28:31], v[68:71]
	s_nop 0
	ds_read_b128 v[20:23], v196 offset:6144
	s_waitcnt lgkmcnt(0)
	v_mfma_f32_16x16x32_bf16 v[64:67], v[156:159], v[20:23], v[64:67]
	v_mfma_f32_16x16x32_bf16 v[84:87], v[168:171], v[36:39], v[120:123]
	v_mfma_f32_16x16x32_bf16 v[156:159], v[144:147], v[36:39], v[56:59]
	v_mfma_f32_16x16x32_bf16 v[40:43], v[140:143], v[36:39], v[40:43]
	v_mfma_f32_16x16x32_bf16 v[36:39], v[136:139], v[36:39], v[12:15]
	v_mfma_f32_16x16x32_bf16 v[108:111], v[152:155], v[148:151], v[108:111]
	v_mfma_f32_16x16x32_bf16 v[100:103], v[152:155], v[28:31], v[100:103]
	v_mfma_f32_16x16x32_bf16 v[128:131], v[128:131], v[20:23], v[8:11]
	v_mfma_f32_16x16x32_bf16 v[8:11], v[168:171], v[20:23], v[112:115]
	v_mfma_f32_16x16x32_bf16 v[96:99], v[152:155], v[20:23], v[96:99]
	v_mfma_f32_16x16x32_bf16 v[112:115], v[168:171], v[28:31], v[116:119]
	v_mfma_f32_16x16x32_bf16 v[116:119], v[168:171], v[148:151], v[124:127]
	v_mfma_f32_16x16x32_bf16 v[120:123], v[160:163], v[148:151], v[92:95]
	v_mfma_f32_16x16x32_bf16 v[152:155], v[144:147], v[148:151], v[60:63]
	v_mfma_f32_16x16x32_bf16 v[168:171], v[140:143], v[148:151], v[44:47]
	v_mfma_f32_16x16x32_bf16 v[148:151], v[136:139], v[148:151], v[16:19]
	v_mfma_f32_16x16x32_bf16 v[32:35], v[140:143], v[28:31], v[32:35]
	v_mfma_f32_16x16x32_bf16 v[140:143], v[140:143], v[20:23], v[24:27]
	v_mfma_f32_16x16x32_bf16 v[80:83], v[160:163], v[20:23], v[80:83]
	v_mfma_f32_16x16x32_bf16 v[0:3], v[136:139], v[20:23], v[0:3]
	v_mfma_f32_16x16x32_bf16 v[160:163], v[144:147], v[28:31], v[52:55]
	v_mfma_f32_16x16x32_bf16 v[144:147], v[144:147], v[20:23], v[48:51]
	ds_read_b128 v[12:15], v188 offset:1024
	ds_read_b128 v[16:19], v205 offset:1024
	ds_read_b128 v[24:27], v204 offset:1024
	ds_read_b128 v[44:47], v203 offset:1024
	ds_read_b128 v[136:139], v196 offset:1024
	ds_read_b128 v[188:191], v196 offset:3072
	ds_read_b128 v[192:195], v196 offset:5120
	ds_read_b128 v[196:199], v196 offset:7168
	s_waitcnt lgkmcnt(3)
	v_mfma_f32_16x16x32_bf16 v[116:119], v[12:15], v[136:139], v[116:119]
	s_waitcnt lgkmcnt(2)
	v_mfma_f32_16x16x32_bf16 v[84:87], v[12:15], v[188:191], v[84:87]
	s_waitcnt lgkmcnt(1)
	v_mfma_f32_16x16x32_bf16 v[52:55], v[12:15], v[192:195], v[112:115]
	s_waitcnt lgkmcnt(0)
	v_mfma_f32_16x16x32_bf16 v[20:23], v[12:15], v[196:199], v[8:11]
	s_nop 2
	ds_read_b128 v[8:11], v202 offset:1024
	v_mfma_f32_16x16x32_bf16 v[124:127], v[16:19], v[136:139], v[108:111]
	v_mfma_f32_16x16x32_bf16 v[92:95], v[16:19], v[188:191], v[104:107]
	v_mfma_f32_16x16x32_bf16 v[60:63], v[16:19], v[192:195], v[100:103]
	v_mfma_f32_16x16x32_bf16 v[28:31], v[16:19], v[196:199], v[96:99]
	s_nop 2
	ds_read_b128 v[96:99], v201 offset:1024
	v_mfma_f32_16x16x32_bf16 v[120:123], v[24:27], v[136:139], v[120:123]
	v_mfma_f32_16x16x32_bf16 v[88:91], v[24:27], v[188:191], v[88:91]
	v_mfma_f32_16x16x32_bf16 v[56:59], v[24:27], v[192:195], v[184:187]
	v_mfma_f32_16x16x32_bf16 v[24:27], v[24:27], v[196:199], v[80:83]
	s_nop 1
	ds_read_b128 v[184:187], v200 offset:1024
	v_mfma_f32_16x16x32_bf16 v[112:115], v[44:47], v[136:139], v[76:79]
	v_mfma_f32_16x16x32_bf16 v[80:83], v[44:47], v[188:191], v[72:75]
	v_mfma_f32_16x16x32_bf16 v[48:51], v[44:47], v[192:195], v[68:71]
	v_mfma_f32_16x16x32_bf16 v[16:19], v[44:47], v[196:199], v[64:67]
	ds_read_b128 v[200:203], v134 offset:1024
	s_waitcnt lgkmcnt(3)
	v_mfma_f32_16x16x32_bf16 v[108:111], v[8:11], v[136:139], v[152:155]
	v_mfma_f32_16x16x32_bf16 v[76:79], v[8:11], v[188:191], v[156:159]
	v_mfma_f32_16x16x32_bf16 v[44:47], v[8:11], v[192:195], v[160:163]
	v_mfma_f32_16x16x32_bf16 v[12:15], v[8:11], v[196:199], v[144:147]
	s_waitcnt lgkmcnt(2)
	v_mfma_f32_16x16x32_bf16 v[104:107], v[96:99], v[136:139], v[168:171]
	v_mfma_f32_16x16x32_bf16 v[72:75], v[96:99], v[188:191], v[40:43]
	v_mfma_f32_16x16x32_bf16 v[40:43], v[96:99], v[192:195], v[32:35]
	v_mfma_f32_16x16x32_bf16 v[8:11], v[96:99], v[196:199], v[140:143]
	s_waitcnt lgkmcnt(1)
	v_mfma_f32_16x16x32_bf16 v[100:103], v[184:187], v[136:139], v[148:151]
	v_mfma_f32_16x16x32_bf16 v[68:71], v[184:187], v[188:191], v[36:39]
	v_mfma_f32_16x16x32_bf16 v[36:39], v[184:187], v[192:195], v[4:7]
	v_mfma_f32_16x16x32_bf16 v[0:3], v[184:187], v[196:199], v[0:3]
	s_waitcnt lgkmcnt(0)
	v_mfma_f32_16x16x32_bf16 v[96:99], v[200:203], v[136:139], v[172:175]
	v_mfma_f32_16x16x32_bf16 v[64:67], v[200:203], v[188:191], v[176:179]
	v_mfma_f32_16x16x32_bf16 v[32:35], v[200:203], v[192:195], v[180:183]
	v_mfma_f32_16x16x32_bf16 v[4:7], v[200:203], v[196:199], v[128:131]
	v_mov_b32_e32 v172, v132
	s_waitcnt vmcnt(0)
	s_barrier
	s_and_b64 vcc, exec, s[34:35]
	v_ashrrev_i32_e32 v128, 1, v172
	v_and_b32_e32 v171, 0xffffff80, v128
	v_and_b32_e32 v170, 15, v172
	v_bfe_u32 v169, v172, 4, 2
	v_add_u32_e32 v168, s66, v171
	s_cbranch_vccz .LBB0_154
	v_lshlrev_b32_e32 v144, 2, v169
	v_and_b32_e32 v173, 64, v172
	v_or_b32_e32 v154, v168, v144
	v_lshrrev_b32_e32 v145, 6, v168
	v_cmp_eq_u32_e32 vcc, 0, v173
	v_or_b32_e32 v130, 1, v154
	s_add_u32 s4, s6, 0x22b6000
	v_cndmask_b32_e32 v128, v144, v145, vcc
	v_lshlrev_b32_e32 v128, 5, v128
	v_cndmask_b32_e32 v130, v130, v145, vcc
	v_and_or_b32 v128, v128, s53, v170
	v_lshlrev_b32_e32 v130, 5, v130
	s_addc_u32 s5, s36, 0
	v_lshlrev_b32_e32 v134, 3, v128
	v_and_or_b32 v130, v130, s54, v170
	v_lshl_add_u64 v[128:129], s[4:5], 0, v[134:135]
	v_lshlrev_b32_e32 v134, 3, v130
	v_lshl_add_u64 v[130:131], s[4:5], 0, v[134:135]
	flat_load_dwordx2 v[142:143], v[128:129]
	flat_load_dwordx2 v[146:147], v[130:131]
	s_nop 0
	flat_load_dwordx2 v[130:131], v[130:131] offset:128
	s_nop 0
	flat_load_dwordx2 v[136:137], v[128:129] offset:128
	v_or_b32_e32 v128, 2, v154
	v_cndmask_b32_e32 v128, v128, v145, vcc
	v_lshlrev_b32_e32 v128, 5, v128
	v_and_or_b32 v128, v128, s54, v170
	v_lshlrev_b32_e32 v134, 3, v128
	v_lshl_add_u64 v[128:129], s[4:5], 0, v[134:135]
	v_or_b32_e32 v134, 3, v154
	v_cndmask_b32_e32 v134, v134, v145, vcc
	v_lshlrev_b32_e32 v134, 5, v134
	v_and_or_b32 v134, v134, s54, v170
	v_lshlrev_b32_e32 v134, 3, v134
	flat_load_dwordx2 v[148:149], v[128:129]
	s_nop 0
	flat_load_dwordx2 v[128:129], v[128:129] offset:128
	v_lshl_add_u64 v[138:139], s[4:5], 0, v[134:135]
	flat_load_dwordx2 v[150:151], v[138:139]
	flat_load_dwordx2 v[152:153], v[138:139] offset:128
	v_or_b32_e32 v134, 16, v154
	v_or_b32_e32 v138, 17, v154
	v_cndmask_b32_e32 v134, v134, v145, vcc
	v_cndmask_b32_e32 v138, v138, v145, vcc
	v_lshlrev_b32_e32 v134, 5, v134
	v_lshlrev_b32_e32 v138, 5, v138
	v_and_or_b32 v134, v134, s54, v170
	v_and_or_b32 v138, v138, s54, v170
	v_lshlrev_b32_e32 v134, 3, v134
	v_lshl_add_u64 v[140:141], s[4:5], 0, v[134:135]
	v_lshlrev_b32_e32 v134, 3, v138
	v_lshl_add_u64 v[156:157], s[4:5], 0, v[134:135]
	flat_load_dwordx2 v[138:139], v[140:141]
	flat_load_dwordx2 v[158:159], v[156:157]
	v_or_b32_e32 v134, 18, v154
	v_or_b32_e32 v155, 19, v154
	v_cndmask_b32_e32 v134, v134, v145, vcc
	v_cndmask_b32_e32 v155, v155, v145, vcc
	v_lshlrev_b32_e32 v134, 5, v134
	v_lshlrev_b32_e32 v155, 5, v155
	v_and_or_b32 v134, v134, s54, v170
	flat_load_dwordx2 v[156:157], v[156:157] offset:128
	s_nop 0
	flat_load_dwordx2 v[140:141], v[140:141] offset:128
	v_and_or_b32 v155, v155, s54, v170
	v_lshlrev_b32_e32 v134, 3, v134
	v_lshl_add_u64 v[160:161], s[4:5], 0, v[134:135]
	v_lshlrev_b32_e32 v134, 3, v155
	v_lshl_add_u64 v[162:163], s[4:5], 0, v[134:135]
	flat_load_dwordx2 v[174:175], v[160:161]
	s_nop 0
	flat_load_dwordx2 v[160:161], v[160:161] offset:128
	s_nop 0
	flat_load_dwordx2 v[176:177], v[162:163]
	s_and_b32 s6, s66, 0xf00
	s_mov_b64 s[38:39], s[6:7]
	s_waitcnt vmcnt(0) lgkmcnt(0)
	v_mov_b32_e32 v178, v143
	v_mov_b32_e32 v179, v147
	v_mov_b32_e32 v143, v146
	v_mov_b32_e32 v146, v137
	v_mov_b32_e32 v147, v131
	v_mov_b32_e32 v137, v130
	v_pk_mul_f32 v[130:131], v[116:117], v[178:179]
	v_pk_mul_f32 v[178:179], v[52:53], v[178:179]
	v_pk_fma_f32 v[52:53], v[52:53], v[142:143], v[130:131]
	v_pk_fma_f32 v[116:117], v[116:117], v[142:143], v[178:179] neg_lo:[0,0,1] neg_hi:[0,0,1]
	v_pk_mul_f32 v[180:181], v[84:85], v[146:147]
	v_pk_mul_f32 v[146:147], v[20:21], v[146:147]
	v_pk_fma_f32 v[20:21], v[20:21], v[136:137], v[180:181]
	v_pk_fma_f32 v[84:85], v[84:85], v[136:137], v[146:147] neg_lo:[0,0,1] neg_hi:[0,0,1]
	v_mul_f32_e32 v182, v118, v148
	v_mul_f32_e32 v184, v54, v149
	v_mul_f32_e32 v186, v118, v149
	v_mul_f32_e32 v148, v54, v148
	v_mul_f32_e32 v188, v86, v128
	v_mul_f32_e32 v190, v22, v129
	v_mul_f32_e32 v192, v86, v129
	v_mul_f32_e32 v194, v22, v128
	v_mov_b32_e32 v54, v119
	v_mov_b32_e32 v118, v55
	v_mov_b32_e32 v22, v87
	v_mov_b32_e32 v86, v23
	v_pk_mul_f32 v[128:129], v[54:55], v[150:151]
	v_pk_mul_f32 v[54:55], v[118:119], v[150:151]
	v_pk_mul_f32 v[118:119], v[22:23], v[152:153]
	v_pk_mul_f32 v[22:23], v[86:87], v[152:153]
	v_mov_b32_e32 v189, v118
	v_mov_b32_e32 v195, v22
	v_or_b32_e32 v22, 32, v154
	v_cndmask_b32_e32 v22, v22, v145, vcc
	v_lshlrev_b32_e32 v22, 5, v22
	v_and_or_b32 v22, v22, s54, v170
	v_lshlrev_b32_e32 v134, 3, v22
	v_or_b32_e32 v22, 33, v154
	v_cndmask_b32_e32 v22, v22, v145, vcc
	v_lshlrev_b32_e32 v22, 5, v22
	v_and_or_b32 v22, v22, s54, v170
	v_mov_b32_e32 v191, v119
	v_lshl_add_u64 v[118:119], s[4:5], 0, v[134:135]
	v_lshlrev_b32_e32 v134, 3, v22
	v_lshl_add_u64 v[142:143], s[4:5], 0, v[134:135]
	v_or_b32_e32 v134, 34, v154
	v_cndmask_b32_e32 v134, v134, v145, vcc
	v_lshlrev_b32_e32 v134, 5, v134
	v_and_or_b32 v134, v134, s54, v170
	v_lshlrev_b32_e32 v134, 3, v134
	v_lshl_add_u64 v[136:137], s[4:5], 0, v[134:135]
	flat_load_dwordx2 v[86:87], v[162:163] offset:128
	flat_load_dwordx2 v[146:147], v[118:119]
	flat_load_dwordx2 v[150:151], v[142:143]
	s_nop 0
	flat_load_dwordx2 v[142:143], v[142:143] offset:128
	s_nop 0
	flat_load_dwordx2 v[152:153], v[118:119] offset:128
	v_mov_b32_e32 v118, v139
	v_mov_b32_e32 v119, v159
	v_mov_b32_e32 v139, v158
	flat_load_dwordx2 v[158:159], v[136:137]
	v_mov_b32_e32 v149, v54
	v_mov_b32_e32 v187, v55
	v_pk_add_f32 v[54:55], v[148:149], v[186:187]
	v_mov_b32_e32 v148, v141
	v_mov_b32_e32 v149, v157
	v_pk_mul_f32 v[178:179], v[92:93], v[148:149]
	v_mov_b32_e32 v141, v156
	flat_load_dwordx2 v[156:157], v[136:137] offset:128
	v_pk_mul_f32 v[180:181], v[28:29], v[148:149]
	v_mul_f32_e32 v136, v126, v174
	v_mul_f32_e32 v148, v62, v175
	v_mul_f32_e32 v174, v62, v174
	v_or_b32_e32 v62, 35, v154
	v_pk_add_f32 v[130:131], v[188:189], v[190:191] neg_lo:[0,1] neg_hi:[0,1]
	v_cndmask_b32_e32 v62, v62, v145, vcc
	v_mul_f32_e32 v188, v94, v160
	v_mul_f32_e32 v190, v30, v161
	v_mul_f32_e32 v160, v30, v160
	v_or_b32_e32 v30, 48, v154
	v_lshlrev_b32_e32 v62, 5, v62
	v_cndmask_b32_e32 v30, v30, v145, vcc
	v_and_or_b32 v62, v62, s54, v170
	v_lshlrev_b32_e32 v30, 5, v30
	v_mov_b32_e32 v183, v128
	v_mov_b32_e32 v185, v129
	v_lshlrev_b32_e32 v134, 3, v62
	v_and_or_b32 v30, v30, s54, v170
	v_pk_add_f32 v[128:129], v[182:183], v[184:185] neg_lo:[0,1] neg_hi:[0,1]
	v_lshl_add_u64 v[184:185], s[4:5], 0, v[134:135]
	v_lshlrev_b32_e32 v134, 3, v30
	v_or_b32_e32 v30, 49, v154
	v_cndmask_b32_e32 v30, v30, v145, vcc
	v_mov_b32_e32 v193, v23
	v_mov_b32_e32 v62, v127
	v_lshlrev_b32_e32 v30, 5, v30
	v_pk_add_f32 v[22:23], v[194:195], v[192:193]
	v_pk_mul_f32 v[194:195], v[62:63], v[176:177]
	v_and_or_b32 v30, v30, s54, v170
	v_mov_b32_e32 v137, v194
	v_mov_b32_e32 v149, v195
	v_lshl_add_u64 v[194:195], s[4:5], 0, v[134:135]
	v_lshlrev_b32_e32 v134, 3, v30
	v_pk_mul_f32 v[162:163], v[124:125], v[118:119]
	v_pk_mul_f32 v[118:119], v[60:61], v[118:119]
	v_lshl_add_u64 v[196:197], s[4:5], 0, v[134:135]
	flat_load_dwordx2 v[186:187], v[184:185]
	v_pk_fma_f32 v[124:125], v[124:125], v[138:139], v[118:119] neg_lo:[0,0,1] neg_hi:[0,0,1]
	flat_load_dwordx2 v[184:185], v[184:185] offset:128
	s_nop 0
	flat_load_dwordx2 v[118:119], v[194:195]
	flat_load_dwordx2 v[198:199], v[196:197]
	v_pk_add_f32 v[136:137], v[136:137], v[148:149] neg_lo:[0,1] neg_hi:[0,1]
	flat_load_dwordx2 v[196:197], v[196:197] offset:128
	s_nop 0
	flat_load_dwordx2 v[148:149], v[194:195] offset:128
	v_or_b32_e32 v134, 50, v154
	v_cndmask_b32_e32 v134, v134, v145, vcc
	v_lshlrev_b32_e32 v134, 5, v134
	v_mul_f32_e32 v182, v126, v175
	v_mov_b32_e32 v126, v63
	v_and_or_b32 v134, v134, s54, v170
	v_pk_mul_f32 v[62:63], v[126:127], v[176:177]
	v_lshlrev_b32_e32 v134, 3, v134
	v_mul_f32_e32 v192, v94, v161
	v_mov_b32_e32 v175, v62
	v_mov_b32_e32 v183, v63
	v_mov_b32_e32 v30, v95
	v_pk_fma_f32 v[92:93], v[92:93], v[140:141], v[180:181] neg_lo:[0,0,1] neg_hi:[0,0,1]
	v_mov_b32_e32 v94, v31
	v_pk_fma_f32 v[28:29], v[28:29], v[140:141], v[178:179]
	v_lshl_add_u64 v[140:141], s[4:5], 0, v[134:135]
	v_pk_fma_f32 v[60:61], v[60:61], v[138:139], v[162:163]
	v_pk_add_f32 v[62:63], v[174:175], v[182:183]
	flat_load_dwordx2 v[174:175], v[140:141] offset:128
	s_waitcnt vmcnt(0) lgkmcnt(0)
	v_pk_mul_f32 v[126:127], v[30:31], v[86:87]
	v_pk_mul_f32 v[30:31], v[94:95], v[86:87]
	v_mov_b32_e32 v86, v147
	v_mov_b32_e32 v87, v151
	v_mov_b32_e32 v147, v150
	flat_load_dwordx2 v[150:151], v[140:141]
	v_mul_f32_e32 v162, v122, v158
	v_mul_f32_e32 v140, v58, v159
	v_mul_f32_e32 v158, v58, v158
	v_or_b32_e32 v58, 51, v154
	v_cndmask_b32_e32 v58, v58, v145, vcc
	v_lshlrev_b32_e32 v58, 5, v58
	v_and_or_b32 v58, v58, s54, v170
	v_mov_b32_e32 v189, v126
	v_mov_b32_e32 v191, v127
	v_lshlrev_b32_e32 v134, 3, v58
	v_pk_add_f32 v[138:139], v[188:189], v[190:191] neg_lo:[0,1] neg_hi:[0,1]
	v_mov_b32_e32 v161, v30
	v_mov_b32_e32 v193, v31
	v_mov_b32_e32 v94, v153
	v_mov_b32_e32 v95, v143
	v_lshl_add_u64 v[188:189], s[4:5], 0, v[134:135]
	v_pk_add_f32 v[30:31], v[160:161], v[192:193]
	v_pk_mul_f32 v[160:161], v[88:89], v[94:95]
	v_mov_b32_e32 v153, v142
	v_pk_mul_f32 v[142:143], v[24:25], v[94:95]
	flat_load_dwordx2 v[94:95], v[188:189]
	v_pk_mul_f32 v[126:127], v[120:121], v[86:87]
	v_pk_mul_f32 v[86:87], v[56:57], v[86:87]
	v_mul_f32_e32 v178, v90, v156
	v_mul_f32_e32 v180, v26, v157
	v_mul_f32_e32 v182, v90, v157
	v_mul_f32_e32 v156, v26, v156
	v_mov_b32_e32 v26, v91
	v_mov_b32_e32 v90, v27
	v_pk_fma_f32 v[120:121], v[120:121], v[146:147], v[86:87] neg_lo:[0,0,1] neg_hi:[0,0,1]
	v_pk_fma_f32 v[56:57], v[56:57], v[146:147], v[126:127]
	v_mul_f32_e32 v176, v122, v159
	v_mov_b32_e32 v58, v123
	v_mov_b32_e32 v122, v59
	v_pk_fma_f32 v[88:89], v[88:89], v[152:153], v[142:143] neg_lo:[0,0,1] neg_hi:[0,0,1]
	v_pk_fma_f32 v[24:25], v[24:25], v[152:153], v[160:161]
	flat_load_dwordx2 v[152:153], v[188:189] offset:128
	v_pk_mul_f32 v[190:191], v[58:59], v[186:187]
	v_pk_mul_f32 v[58:59], v[122:123], v[186:187]
	v_pk_mul_f32 v[86:87], v[26:27], v[184:185]
	v_pk_mul_f32 v[26:27], v[90:91], v[184:185]
	v_mov_b32_e32 v91, v197
	v_mov_b32_e32 v90, v149
	v_pk_mul_f32 v[126:127], v[80:81], v[90:91]
	v_pk_mul_f32 v[146:147], v[16:17], v[90:91]
	v_or_b32_e32 v90, 1, v145
	v_cndmask_b32_e32 v90, v144, v90, vcc
	v_lshlrev_b32_e32 v90, 5, v90
	v_and_or_b32 v90, v90, s54, v170
	v_lshlrev_b32_e32 v134, 3, v90
	v_lshl_add_u64 v[90:91], s[4:5], 0, v[134:135]
	v_or_b32_e32 v134, 0x41, v154
	v_lshrrev_b32_e32 v144, 6, v134
	v_cndmask_b32_e32 v134, v134, v144, vcc
	v_lshlrev_b32_e32 v134, 5, v134
	v_and_or_b32 v134, v134, s54, v170
	v_mov_b32_e32 v163, v190
	v_mov_b32_e32 v141, v191
	v_mov_b32_e32 v159, v58
	v_mov_b32_e32 v177, v59
	v_mov_b32_e32 v157, v26
	v_mov_b32_e32 v183, v27
	v_lshlrev_b32_e32 v134, 3, v134
	v_pk_add_f32 v[140:141], v[162:163], v[140:141] neg_lo:[0,1] neg_hi:[0,1]
	v_pk_add_f32 v[58:59], v[158:159], v[176:177]
	v_pk_add_f32 v[26:27], v[156:157], v[182:183]
	v_lshl_add_u64 v[144:145], s[4:5], 0, v[134:135]
	flat_load_dwordx2 v[156:157], v[90:91]
	flat_load_dwordx2 v[158:159], v[144:145]
	flat_load_dwordx2 v[160:161], v[144:145] offset:128
	flat_load_dwordx2 v[162:163], v[90:91] offset:128
	v_or_b32_e32 v90, 0x42, v154
	v_lshrrev_b32_e32 v91, 6, v90
	v_cndmask_b32_e32 v90, v90, v91, vcc
	v_lshlrev_b32_e32 v90, 5, v90
	v_and_or_b32 v90, v90, s54, v170
	v_lshlrev_b32_e32 v134, 3, v90
	v_lshl_add_u64 v[90:91], s[4:5], 0, v[134:135]
	flat_load_dwordx2 v[182:183], v[90:91] offset:128
	flat_load_dwordx2 v[176:177], v[90:91]
	v_mov_b32_e32 v179, v86
	v_mov_b32_e32 v181, v87
	v_mul_f32_e32 v184, v82, v174
	v_mul_f32_e32 v186, v18, v175
	v_mul_f32_e32 v174, v18, v174
	v_or_b32_e32 v18, 0x43, v154
	v_pk_add_f32 v[142:143], v[178:179], v[180:181] neg_lo:[0,1] neg_hi:[0,1]
	s_waitcnt vmcnt(0) lgkmcnt(0)
	v_mul_f32_e32 v144, v114, v150
	v_mul_f32_e32 v178, v50, v151
	v_mul_f32_e32 v150, v50, v150
	v_lshrrev_b32_e32 v50, 6, v18
	v_cndmask_b32_e32 v18, v18, v50, vcc
	v_lshlrev_b32_e32 v18, 5, v18
	v_and_or_b32 v18, v18, s54, v170
	v_lshlrev_b32_e32 v134, 3, v18
	v_mov_b32_e32 v50, v115
	v_or_b32_e32 v18, 0x50, v154
	v_pk_mul_f32 v[192:193], v[50:51], v[94:95]
	v_lshrrev_b32_e32 v50, 6, v18
	v_cndmask_b32_e32 v18, v18, v50, vcc
	v_lshlrev_b32_e32 v18, 5, v18
	v_and_or_b32 v18, v18, s54, v170
	v_lshl_add_u64 v[90:91], s[4:5], 0, v[134:135]
	v_lshlrev_b32_e32 v134, 3, v18
	v_or_b32_e32 v18, 0x51, v154
	v_mul_f32_e32 v188, v82, v175
	v_lshrrev_b32_e32 v82, 6, v18
	v_cndmask_b32_e32 v18, v18, v82, vcc
	v_lshlrev_b32_e32 v18, 5, v18
	v_mov_b32_e32 v86, v119
	v_mov_b32_e32 v87, v199
	v_and_or_b32 v18, v18, s54, v170
	v_pk_mul_f32 v[122:123], v[112:113], v[86:87]
	v_mov_b32_e32 v119, v198
	v_pk_mul_f32 v[86:87], v[48:49], v[86:87]
	v_mul_f32_e32 v180, v114, v151
	v_mov_b32_e32 v114, v51
	v_lshl_add_u64 v[50:51], s[4:5], 0, v[134:135]
	v_lshlrev_b32_e32 v134, 3, v18
	v_mov_b32_e32 v145, v192
	v_mov_b32_e32 v179, v193
	v_pk_fma_f32 v[112:113], v[112:113], v[118:119], v[86:87] neg_lo:[0,0,1] neg_hi:[0,0,1]
	v_lshl_add_u64 v[86:87], s[4:5], 0, v[134:135]
	v_or_b32_e32 v18, 0x52, v154
	flat_load_dwordx2 v[190:191], v[90:91]
	v_pk_add_f32 v[144:145], v[144:145], v[178:179] neg_lo:[0,1] neg_hi:[0,1]
	flat_load_dwordx2 v[178:179], v[90:91] offset:128
	s_nop 0
	flat_load_dwordx2 v[90:91], v[50:51]
	flat_load_dwordx2 v[192:193], v[86:87]
	flat_load_dwordx2 v[194:195], v[86:87] offset:128
	s_nop 0
	flat_load_dwordx2 v[86:87], v[50:51] offset:128
	v_lshrrev_b32_e32 v50, 6, v18
	v_cndmask_b32_e32 v18, v18, v50, vcc
	v_lshlrev_b32_e32 v18, 5, v18
	v_and_or_b32 v18, v18, s54, v170
	v_lshlrev_b32_e32 v134, 3, v18
	v_lshl_add_u64 v[50:51], s[4:5], 0, v[134:135]
	v_pk_mul_f32 v[94:95], v[114:115], v[94:95]
	v_mov_b32_e32 v18, v83
	v_mov_b32_e32 v151, v94
	v_mov_b32_e32 v181, v95
	flat_load_dwordx2 v[94:95], v[50:51] offset:128
	v_mov_b32_e32 v82, v19
	v_pk_mul_f32 v[114:115], v[18:19], v[152:153]
	v_pk_mul_f32 v[18:19], v[82:83], v[152:153]
	v_mov_b32_e32 v149, v196
	v_mov_b32_e32 v175, v18
	v_mov_b32_e32 v189, v19
	flat_load_dwordx2 v[196:197], v[50:51]
	v_pk_add_f32 v[50:51], v[150:151], v[180:181]
	v_pk_add_f32 v[18:19], v[174:175], v[188:189]
	v_mov_b32_e32 v82, v157
	v_mov_b32_e32 v157, v158
	v_mov_b32_e32 v83, v159
	v_pk_fma_f32 v[48:49], v[48:49], v[118:119], v[122:123]
	v_mov_b32_e32 v185, v114
	v_mov_b32_e32 v187, v115
	v_pk_fma_f32 v[80:81], v[80:81], v[148:149], v[146:147] neg_lo:[0,0,1] neg_hi:[0,0,1]
	v_pk_fma_f32 v[16:17], v[16:17], v[148:149], v[126:127]
	v_pk_mul_f32 v[114:115], v[108:109], v[82:83]
	v_pk_mul_f32 v[118:119], v[44:45], v[82:83]
	v_mul_f32_e32 v174, v14, v183
	v_mul_f32_e32 v180, v14, v182
	v_or_b32_e32 v14, 0x53, v154
	v_mul_f32_e32 v150, v46, v177
	v_mul_f32_e32 v158, v46, v176
	v_lshrrev_b32_e32 v46, 6, v14
	v_cndmask_b32_e32 v14, v14, v46, vcc
	v_lshlrev_b32_e32 v14, 5, v14
	v_and_or_b32 v14, v14, s54, v170
	v_lshlrev_b32_e32 v134, 3, v14
	v_mov_b32_e32 v82, v163
	v_mov_b32_e32 v83, v161
	v_mov_b32_e32 v163, v160
	v_mul_f32_e32 v148, v110, v176
	v_mul_f32_e32 v160, v78, v182
	v_mul_f32_e32 v176, v78, v183
	v_lshl_add_u64 v[182:183], s[4:5], 0, v[134:135]
	v_pk_mul_f32 v[122:123], v[76:77], v[82:83]
	v_pk_mul_f32 v[126:127], v[12:13], v[82:83]
	flat_load_dwordx2 v[82:83], v[182:183]
	v_pk_fma_f32 v[12:13], v[12:13], v[162:163], v[122:123]
	flat_load_dwordx2 v[122:123], v[182:183] offset:128
	v_mul_f32_e32 v152, v110, v177
	v_mov_b32_e32 v46, v111
	v_mov_b32_e32 v110, v47
	v_mov_b32_e32 v14, v79
	v_pk_add_f32 v[146:147], v[184:185], v[186:187] neg_lo:[0,1] neg_hi:[0,1]
	v_pk_fma_f32 v[76:77], v[76:77], v[162:163], v[126:127] neg_lo:[0,0,1] neg_hi:[0,0,1]
	v_mov_b32_e32 v78, v15
	v_pk_fma_f32 v[108:109], v[108:109], v[156:157], v[118:119] neg_lo:[0,0,1] neg_hi:[0,0,1]
	v_pk_fma_f32 v[44:45], v[44:45], v[156:157], v[114:115]
	s_waitcnt vmcnt(0) lgkmcnt(0)
	v_pk_mul_f32 v[184:185], v[46:47], v[190:191]
	v_pk_mul_f32 v[46:47], v[110:111], v[190:191]
	v_pk_mul_f32 v[110:111], v[14:15], v[178:179]
	v_mov_b32_e32 v149, v184
	v_mov_b32_e32 v151, v185
	v_mov_b32_e32 v161, v110
	v_mov_b32_e32 v175, v111
	v_pk_add_f32 v[148:149], v[148:149], v[150:151] neg_lo:[0,1] neg_hi:[0,1]
	v_pk_add_f32 v[150:151], v[160:161], v[174:175] neg_lo:[0,1] neg_hi:[0,1]
	v_pk_mul_f32 v[14:15], v[78:79], v[178:179]
	v_mov_b32_e32 v159, v46
	v_mov_b32_e32 v181, v14
	v_mov_b32_e32 v177, v15
	v_pk_add_f32 v[14:15], v[180:181], v[176:177]
	v_mul_f32_e32 v160, v74, v94
	v_mul_f32_e32 v162, v10, v95
	v_mul_f32_e32 v94, v10, v94
	v_or_b32_e32 v10, 0x60, v154
	v_mul_f32_e32 v174, v74, v95
	v_lshrrev_b32_e32 v74, 6, v10
	v_cndmask_b32_e32 v10, v10, v74, vcc
	v_lshlrev_b32_e32 v10, 5, v10
	v_and_or_b32 v10, v10, s54, v170
	v_lshlrev_b32_e32 v134, 3, v10
	v_or_b32_e32 v10, 0x61, v154
	v_lshrrev_b32_e32 v74, 6, v10
	v_cndmask_b32_e32 v10, v10, v74, vcc
	v_lshlrev_b32_e32 v10, 5, v10
	v_and_or_b32 v10, v10, s54, v170
	v_lshl_add_u64 v[176:177], s[4:5], 0, v[134:135]
	v_lshlrev_b32_e32 v134, 3, v10
	v_or_b32_e32 v10, 0x62, v154
	v_lshrrev_b32_e32 v74, 6, v10
	v_cndmask_b32_e32 v10, v10, v74, vcc
	v_lshlrev_b32_e32 v10, 5, v10
	v_and_or_b32 v10, v10, s54, v170
	v_lshl_add_u64 v[178:179], s[4:5], 0, v[134:135]
	v_lshlrev_b32_e32 v134, 3, v10
	v_or_b32_e32 v10, 0x63, v154
	v_lshrrev_b32_e32 v74, 6, v10
	v_cndmask_b32_e32 v10, v10, v74, vcc
	v_lshlrev_b32_e32 v10, 5, v10
	v_mov_b32_e32 v153, v47
	v_and_or_b32 v10, v10, s54, v170
	v_pk_add_f32 v[46:47], v[158:159], v[152:153]
	v_mul_f32_e32 v152, v42, v197
	v_mul_f32_e32 v158, v42, v196
	v_mov_b32_e32 v42, v107
	v_lshl_add_u64 v[184:185], s[4:5], 0, v[134:135]
	v_lshlrev_b32_e32 v134, 3, v10
	v_or_b32_e32 v10, 0x70, v154
	v_mov_b32_e32 v78, v91
	v_mov_b32_e32 v79, v193
	v_mov_b32_e32 v91, v192
	v_pk_mul_f32 v[192:193], v[42:43], v[82:83]
	v_lshrrev_b32_e32 v42, 6, v10
	v_cndmask_b32_e32 v10, v10, v42, vcc
	v_lshlrev_b32_e32 v10, 5, v10
	v_and_or_b32 v10, v10, s54, v170
	v_lshl_add_u64 v[188:189], s[4:5], 0, v[134:135]
	v_lshlrev_b32_e32 v134, 3, v10
	v_or_b32_e32 v10, 0x71, v154
	v_lshrrev_b32_e32 v74, 6, v10
	v_cndmask_b32_e32 v10, v10, v74, vcc
	v_lshlrev_b32_e32 v10, 5, v10
	v_and_or_b32 v10, v10, s54, v170
	v_mul_f32_e32 v126, v106, v196
	v_mul_f32_e32 v156, v106, v197
	v_mov_b32_e32 v127, v192
	v_mov_b32_e32 v153, v193
	v_mov_b32_e32 v106, v43
	v_lshl_add_u64 v[42:43], s[4:5], 0, v[134:135]
	v_lshlrev_b32_e32 v134, 3, v10
	v_pk_mul_f32 v[114:115], v[40:41], v[78:79]
	v_pk_add_f32 v[152:153], v[126:127], v[152:153] neg_lo:[0,1] neg_hi:[0,1]
	v_lshl_add_u64 v[126:127], s[4:5], 0, v[134:135]
	v_or_b32_e32 v10, 0x72, v154
	v_pk_mul_f32 v[110:111], v[104:105], v[78:79]
	v_mov_b32_e32 v118, v87
	v_mov_b32_e32 v119, v195
	v_mov_b32_e32 v87, v194
	flat_load_dwordx2 v[180:181], v[176:177]
	flat_load_dwordx2 v[182:183], v[178:179]
	s_nop 0
	flat_load_dwordx2 v[178:179], v[178:179] offset:128
	s_nop 0
	flat_load_dwordx2 v[176:177], v[176:177] offset:128
	s_nop 0
	flat_load_dwordx2 v[186:187], v[184:185]
	s_nop 0
	flat_load_dwordx2 v[184:185], v[184:185] offset:128
	v_pk_fma_f32 v[104:105], v[104:105], v[90:91], v[114:115] neg_lo:[0,0,1] neg_hi:[0,0,1]
	flat_load_dwordx2 v[190:191], v[188:189]
	flat_load_dwordx2 v[114:115], v[188:189] offset:128
	s_nop 0
	flat_load_dwordx2 v[188:189], v[42:43]
	flat_load_dwordx2 v[192:193], v[126:127]
	s_nop 0
	flat_load_dwordx2 v[126:127], v[126:127] offset:128
	s_nop 0
	flat_load_dwordx2 v[194:195], v[42:43] offset:128
	v_lshrrev_b32_e32 v42, 6, v10
	v_cndmask_b32_e32 v10, v10, v42, vcc
	v_lshlrev_b32_e32 v10, 5, v10
	v_and_or_b32 v10, v10, s54, v170
	v_lshlrev_b32_e32 v134, 3, v10
	v_lshl_add_u64 v[42:43], s[4:5], 0, v[134:135]
	v_or_b32_e32 v10, 0x73, v154
	flat_load_dwordx2 v[196:197], v[42:43]
	flat_load_dwordx2 v[198:199], v[42:43] offset:128
	v_lshrrev_b32_e32 v42, 6, v10
	v_cndmask_b32_e32 v10, v10, v42, vcc
	v_lshlrev_b32_e32 v10, 5, v10
	v_and_or_b32 v10, v10, s54, v170
	v_lshlrev_b32_e32 v134, 3, v10
	v_mov_b32_e32 v10, v75
	v_lshl_add_u64 v[200:201], s[4:5], 0, v[134:135]
	v_pk_mul_f32 v[42:43], v[106:107], v[82:83]
	v_pk_mul_f32 v[82:83], v[10:11], v[122:123]
	flat_load_dwordx2 v[202:203], v[200:201]
	v_mov_b32_e32 v161, v82
	v_mov_b32_e32 v163, v83
	flat_load_dwordx2 v[82:83], v[200:201] offset:128
	v_mov_b32_e32 v74, v11
	v_pk_mul_f32 v[78:79], v[72:73], v[118:119]
	v_pk_mul_f32 v[118:119], v[8:9], v[118:119]
	v_mov_b32_e32 v159, v42
	v_mov_b32_e32 v157, v43
	v_pk_mul_f32 v[10:11], v[74:75], v[122:123]
	v_pk_add_f32 v[42:43], v[158:159], v[156:157]
	v_pk_fma_f32 v[72:73], v[72:73], v[86:87], v[118:119] neg_lo:[0,0,1] neg_hi:[0,0,1]
	v_pk_add_f32 v[154:155], v[160:161], v[162:163] neg_lo:[0,1] neg_hi:[0,1]
	v_mov_b32_e32 v95, v10
	v_mov_b32_e32 v175, v11
	v_pk_fma_f32 v[8:9], v[8:9], v[86:87], v[78:79]
	v_pk_fma_f32 v[40:41], v[40:41], v[90:91], v[110:111]
	v_pk_add_f32 v[10:11], v[94:95], v[174:175]
	v_mov_b32_e32 v134, v173
	s_waitcnt vmcnt(0) lgkmcnt(0)
	v_mov_b32_e32 v74, v181
	v_mov_b32_e32 v75, v183
	v_pk_mul_f32 v[78:79], v[100:101], v[74:75]
	v_mov_b32_e32 v181, v182
	v_pk_mul_f32 v[74:75], v[36:37], v[74:75]
	v_mul_f32_e32 v106, v38, v187
	v_mul_f32_e32 v118, v38, v186
	v_mul_f32_e32 v158, v2, v185
	v_mul_f32_e32 v162, v2, v184
	v_mov_b32_e32 v38, v103
	v_mov_b32_e32 v2, v71
	v_mul_f32_e32 v94, v102, v186
	v_mul_f32_e32 v110, v102, v187
	v_mul_f32_e32 v122, v70, v184
	v_mul_f32_e32 v160, v70, v185
	v_pk_mul_f32 v[156:157], v[38:39], v[190:191]
	v_pk_fma_f32 v[100:101], v[100:101], v[180:181], v[74:75] neg_lo:[0,0,1] neg_hi:[0,0,1]
	v_mov_b32_e32 v102, v39
	v_pk_mul_f32 v[74:75], v[2:3], v[114:115]
	v_mov_b32_e32 v70, v3
	v_mov_b32_e32 v86, v177
	v_mov_b32_e32 v87, v179
	v_mov_b32_e32 v95, v156
	v_mov_b32_e32 v107, v157
	v_pk_mul_f32 v[38:39], v[102:103], v[190:191]
	v_mov_b32_e32 v123, v74
	v_mov_b32_e32 v159, v75
	v_pk_mul_f32 v[2:3], v[70:71], v[114:115]
	v_mov_b32_e32 v70, v189
	v_mov_b32_e32 v71, v193
	v_pk_mul_f32 v[90:91], v[68:69], v[86:87]
	v_mov_b32_e32 v177, v178
	v_pk_add_f32 v[156:157], v[94:95], v[106:107] neg_lo:[0,1] neg_hi:[0,1]
	v_mov_b32_e32 v119, v38
	v_mov_b32_e32 v111, v39
	v_pk_add_f32 v[158:159], v[122:123], v[158:159] neg_lo:[0,1] neg_hi:[0,1]
	v_pk_mul_f32 v[74:75], v[96:97], v[70:71]
	v_mov_b32_e32 v189, v192
	v_pk_mul_f32 v[70:71], v[32:33], v[70:71]
	v_mul_f32_e32 v94, v34, v197
	v_mul_f32_e32 v106, v34, v196
	v_mul_f32_e32 v114, v6, v199
	v_mul_f32_e32 v122, v6, v198
	v_mov_b32_e32 v34, v99
	v_mov_b32_e32 v6, v67
	v_pk_mul_f32 v[86:87], v[0:1], v[86:87]
	v_pk_fma_f32 v[36:37], v[36:37], v[180:181], v[78:79]
	v_pk_add_f32 v[38:39], v[118:119], v[110:111]
	v_pk_fma_f32 v[0:1], v[0:1], v[176:177], v[90:91]
	v_mov_b32_e32 v78, v195
	v_mov_b32_e32 v79, v127
	v_mov_b32_e32 v195, v126
	v_mul_f32_e32 v90, v98, v196
	v_mul_f32_e32 v102, v98, v197
	v_mul_f32_e32 v110, v66, v198
	v_mul_f32_e32 v118, v66, v199
	v_pk_mul_f32 v[126:127], v[34:35], v[202:203]
	v_pk_fma_f32 v[96:97], v[96:97], v[188:189], v[70:71] neg_lo:[0,0,1] neg_hi:[0,0,1]
	v_mov_b32_e32 v98, v35
	v_pk_mul_f32 v[70:71], v[6:7], v[82:83]
	v_mov_b32_e32 v66, v7
	v_mov_b32_e32 v163, v2
	v_mov_b32_e32 v161, v3
	v_mov_b32_e32 v91, v126
	v_mov_b32_e32 v95, v127
	v_pk_mul_f32 v[34:35], v[98:99], v[202:203]
	v_mov_b32_e32 v111, v70
	v_mov_b32_e32 v115, v71
	v_pk_mul_f32 v[6:7], v[66:67], v[82:83]
	v_pk_fma_f32 v[68:69], v[68:69], v[176:177], v[86:87] neg_lo:[0,0,1] neg_hi:[0,0,1]
	v_pk_add_f32 v[2:3], v[162:163], v[160:161]
	v_pk_mul_f32 v[86:87], v[64:65], v[78:79]
	v_pk_mul_f32 v[78:79], v[4:5], v[78:79]
	v_pk_add_f32 v[160:161], v[90:91], v[94:95] neg_lo:[0,1] neg_hi:[0,1]
	v_mov_b32_e32 v107, v34
	v_mov_b32_e32 v103, v35
	v_pk_add_f32 v[162:163], v[110:111], v[114:115] neg_lo:[0,1] neg_hi:[0,1]
	v_mov_b32_e32 v123, v6
	v_mov_b32_e32 v119, v7
	v_pk_fma_f32 v[32:33], v[32:33], v[188:189], v[74:75]
	v_pk_add_f32 v[34:35], v[106:107], v[102:103]
	v_pk_fma_f32 v[64:65], v[64:65], v[194:195], v[78:79] neg_lo:[0,0,1] neg_hi:[0,0,1]
	v_pk_fma_f32 v[4:5], v[4:5], v[194:195], v[86:87]
	v_pk_add_f32 v[6:7], v[122:123], v[118:119]
	v_mov_b32_e32 v119, v129
	v_mov_b32_e32 v118, v128
	v_mov_b32_e32 v87, v131
	v_mov_b32_e32 v86, v130
	v_mov_b32_e32 v127, v137
	v_mov_b32_e32 v126, v136
	v_mov_b32_e32 v95, v139
	v_mov_b32_e32 v94, v138
	v_mov_b32_e32 v123, v141
	v_mov_b32_e32 v122, v140
	v_mov_b32_e32 v91, v143
	v_mov_b32_e32 v90, v142
	v_mov_b32_e32 v115, v145
	v_mov_b32_e32 v114, v144
	v_mov_b32_e32 v83, v147
	v_mov_b32_e32 v82, v146
	v_mov_b32_e32 v111, v149
	v_mov_b32_e32 v110, v148
	v_mov_b32_e32 v79, v151
	v_mov_b32_e32 v78, v150
	v_mov_b32_e32 v107, v153
	v_mov_b32_e32 v106, v152
	v_mov_b32_e32 v75, v155
	v_mov_b32_e32 v74, v154
	v_mov_b32_e32 v103, v157
	v_mov_b32_e32 v102, v156
	v_mov_b32_e32 v71, v159
	v_mov_b32_e32 v70, v158
	v_mov_b32_e32 v99, v161
	v_mov_b32_e32 v98, v160
	v_mov_b32_e32 v67, v163
	v_mov_b32_e32 v66, v162
	s_cbranch_execz .LBB0_155
	s_mov_b64 s[4:5], 0x10800000
	s_mov_b64 s[42:43], 0x12800000
	s_mov_b64 s[36:37], 12
	s_branch .LBB0_156

.LBB0_165:
	s_and_b32 s27, s6, 0x10000
	s_xor_b32 s34, s27, 0x10000
	s_add_i32 s27, s27, 0
	s_add_i32 s101, s100, s34
	s_cmpk_eq_i32 s30, 0
	s_cbranch_scc1 .Lg1n_165
	s_waitcnt lgkmcnt(3)
	v_mfma_f32_16x16x32_bf16 v[108:111], v[184:187], v[168:171], v[108:111]
	v_mfma_f32_16x16x32_bf16 v[92:95], v[184:187], v[172:175], v[92:95]
	v_mfma_f32_16x16x32_bf16 v[76:79], v[184:187], v[176:179], v[76:79]
	v_mfma_f32_16x16x32_bf16 v[60:63], v[184:187], v[180:183], v[60:63]
	ds_read_b128 v[240:243], v202
	ds_read_b128 v[244:247], v203
	s_add_i32 m0, s101, 0x4000
	v_lshl_add_u64 v[144:145], v[144:145], 0, s[98:99]
	global_load_lds_dwordx4 v[144:145], off
	s_waitcnt lgkmcnt(4)
	v_mfma_f32_16x16x32_bf16 v[104:107], v[188:191], v[168:171], v[104:107]
	v_mfma_f32_16x16x32_bf16 v[88:91], v[188:191], v[172:175], v[88:91]
	v_mfma_f32_16x16x32_bf16 v[72:75], v[188:191], v[176:179], v[72:75]
	v_mfma_f32_16x16x32_bf16 v[56:59], v[188:191], v[180:183], v[56:59]
	ds_read_b128 v[248:251], v204
	ds_read_b128 v[252:255], v205
	s_add_i32 m0, s101, 0xc000
	v_lshl_add_u64 v[136:137], v[136:137], 0, s[98:99]
	global_load_lds_dwordx4 v[136:137], off
	s_waitcnt lgkmcnt(5)
	v_mfma_f32_16x16x32_bf16 v[100:103], v[192:195], v[168:171], v[100:103]
	v_mfma_f32_16x16x32_bf16 v[84:87], v[192:195], v[172:175], v[84:87]
	v_mfma_f32_16x16x32_bf16 v[68:71], v[192:195], v[176:179], v[68:71]
	v_mfma_f32_16x16x32_bf16 v[52:55], v[192:195], v[180:183], v[52:55]
	s_add_i32 m0, s101, 0x6000
	v_lshl_add_u64 v[142:143], v[142:143], 0, s[98:99]
	global_load_lds_dwordx4 v[142:143], off
	s_waitcnt lgkmcnt(4)
	v_mfma_f32_16x16x32_bf16 v[96:99], v[196:199], v[168:171], v[96:99]
	v_mfma_f32_16x16x32_bf16 v[80:83], v[196:199], v[172:175], v[80:83]
	v_mfma_f32_16x16x32_bf16 v[64:67], v[196:199], v[176:179], v[64:67]
	v_mfma_f32_16x16x32_bf16 v[48:51], v[196:199], v[180:183], v[48:51]
	s_add_i32 m0, s101, 0xe000
	v_lshl_add_u64 v[130:131], v[130:131], 0, s[98:99]
	global_load_lds_dwordx4 v[130:131], off
.Lg2_165:
	ds_read_b128 v[168:171], v162 offset:1024
	ds_read_b128 v[172:175], v163 offset:1024
	ds_read_b128 v[176:179], v200 offset:1024
	ds_read_b128 v[180:183], v201 offset:1024
	s_waitcnt lgkmcnt(4)
	v_mfma_f32_16x16x32_bf16 v[44:47], v[184:187], v[240:243], v[44:47]
	v_mfma_f32_16x16x32_bf16 v[28:31], v[184:187], v[244:247], v[28:31]
	v_mfma_f32_16x16x32_bf16 v[12:15], v[184:187], v[248:251], v[12:15]
	v_mfma_f32_16x16x32_bf16 v[112:115], v[184:187], v[252:255], v[112:115]
	ds_read_b128 v[184:187], v134 offset:33792
	v_mfma_f32_16x16x32_bf16 v[40:43], v[188:191], v[240:243], v[40:43]
	v_mfma_f32_16x16x32_bf16 v[24:27], v[188:191], v[244:247], v[24:27]
	v_mfma_f32_16x16x32_bf16 v[8:11], v[188:191], v[248:251], v[8:11]
	v_mfma_f32_16x16x32_bf16 v[116:119], v[188:191], v[252:255], v[116:119]
	ds_read_b128 v[188:191], v134 offset:35840
	v_mfma_f32_16x16x32_bf16 v[36:39], v[192:195], v[240:243], v[36:39]
	v_mfma_f32_16x16x32_bf16 v[20:23], v[192:195], v[244:247], v[20:23]
	v_mfma_f32_16x16x32_bf16 v[4:7], v[192:195], v[248:251], v[4:7]
	v_mfma_f32_16x16x32_bf16 v[120:123], v[192:195], v[252:255], v[120:123]
	ds_read_b128 v[192:195], v134 offset:37888
	v_mfma_f32_16x16x32_bf16 v[32:35], v[196:199], v[240:243], v[32:35]
	v_mfma_f32_16x16x32_bf16 v[16:19], v[196:199], v[244:247], v[16:19]
	v_mfma_f32_16x16x32_bf16 v[0:3], v[196:199], v[248:251], v[0:3]
	v_mfma_f32_16x16x32_bf16 v[124:127], v[196:199], v[252:255], v[124:127]
	ds_read_b128 v[196:199], v134 offset:39936
	s_waitcnt lgkmcnt(3)
	v_mfma_f32_16x16x32_bf16 v[108:111], v[184:187], v[168:171], v[108:111]
	v_mfma_f32_16x16x32_bf16 v[92:95], v[184:187], v[172:175], v[92:95]
	v_mfma_f32_16x16x32_bf16 v[76:79], v[184:187], v[176:179], v[76:79]
	v_mfma_f32_16x16x32_bf16 v[60:63], v[184:187], v[180:183], v[60:63]
	ds_read_b128 v[240:243], v202 offset:1024
	ds_read_b128 v[244:247], v203 offset:1024
	s_waitcnt lgkmcnt(4)
	v_mfma_f32_16x16x32_bf16 v[104:107], v[188:191], v[168:171], v[104:107]
	v_mfma_f32_16x16x32_bf16 v[88:91], v[188:191], v[172:175], v[88:91]
	v_mfma_f32_16x16x32_bf16 v[72:75], v[188:191], v[176:179], v[72:75]
	v_mfma_f32_16x16x32_bf16 v[56:59], v[188:191], v[180:183], v[56:59]
	ds_read_b128 v[248:251], v204 offset:1024
	ds_read_b128 v[252:255], v205 offset:1024
	s_waitcnt lgkmcnt(5)
	v_mfma_f32_16x16x32_bf16 v[100:103], v[192:195], v[168:171], v[100:103]
	v_mfma_f32_16x16x32_bf16 v[84:87], v[192:195], v[172:175], v[84:87]
	v_mfma_f32_16x16x32_bf16 v[68:71], v[192:195], v[176:179], v[68:71]
	v_mfma_f32_16x16x32_bf16 v[52:55], v[192:195], v[180:183], v[52:55]
	s_waitcnt lgkmcnt(4)
	v_mfma_f32_16x16x32_bf16 v[96:99], v[196:199], v[168:171], v[96:99]
	v_mfma_f32_16x16x32_bf16 v[80:83], v[196:199], v[172:175], v[80:83]
	v_mfma_f32_16x16x32_bf16 v[64:67], v[196:199], v[176:179], v[64:67]
	v_mfma_f32_16x16x32_bf16 v[48:51], v[196:199], v[180:183], v[48:51]
	s_waitcnt vmcnt(0) lgkmcnt(0)
	s_barrier
	s_add_i32 s101, s100, s27
	s_cmpk_eq_i32 s30, 0x700
	s_cbranch_scc1 .Lg4n_165
	v_mfma_f32_16x16x32_bf16 v[44:47], v[184:187], v[240:243], v[44:47]
	v_mfma_f32_16x16x32_bf16 v[28:31], v[184:187], v[244:247], v[28:31]
	v_mfma_f32_16x16x32_bf16 v[12:15], v[184:187], v[248:251], v[12:15]
	v_mfma_f32_16x16x32_bf16 v[112:115], v[184:187], v[252:255], v[112:115]
	v_add3_u32 v134, s34, v151, v152
	ds_read_b128 v[184:187], v134 offset:32768
	v_add3_u32 v162, s34, v151, v153
	v_add3_u32 v163, s34, v155, v154
	v_add3_u32 v200, s34, v155, v156
	v_add3_u32 v201, s34, v155, v157
	ds_read_b128 v[168:171], v162
	ds_read_b128 v[172:175], v163
	ds_read_b128 v[176:179], v200
	ds_read_b128 v[180:183], v201
	s_mov_b32 m0, s101
	v_lshl_add_u64 v[148:149], v[148:149], 0, s[98:99]
	global_load_lds_dwordx4 v[148:149], off
	v_mfma_f32_16x16x32_bf16 v[40:43], v[188:191], v[240:243], v[40:43]
	v_mfma_f32_16x16x32_bf16 v[24:27], v[188:191], v[244:247], v[24:27]
	v_mfma_f32_16x16x32_bf16 v[8:11], v[188:191], v[248:251], v[8:11]
	v_mfma_f32_16x16x32_bf16 v[116:119], v[188:191], v[252:255], v[116:119]
	ds_read_b128 v[188:191], v134 offset:34816
	v_add3_u32 v202, s34, v155, v158
	v_add3_u32 v203, s34, v155, v159
	v_add3_u32 v204, s34, v155, v160
	v_add3_u32 v205, s34, v155, v161
	s_add_i32 m0, s101, 0x8000
	v_lshl_add_u64 v[140:141], v[140:141], 0, s[98:99]
	global_load_lds_dwordx4 v[140:141], off
	v_mfma_f32_16x16x32_bf16 v[36:39], v[192:195], v[240:243], v[36:39]
	v_mfma_f32_16x16x32_bf16 v[20:23], v[192:195], v[244:247], v[20:23]
	v_mfma_f32_16x16x32_bf16 v[4:7], v[192:195], v[248:251], v[4:7]
	v_mfma_f32_16x16x32_bf16 v[120:123], v[192:195], v[252:255], v[120:123]
	ds_read_b128 v[192:195], v134 offset:36864
	s_add_i32 m0, s101, 0x2000
	v_lshl_add_u64 v[146:147], v[146:147], 0, s[98:99]
	global_load_lds_dwordx4 v[146:147], off
	v_mfma_f32_16x16x32_bf16 v[32:35], v[196:199], v[240:243], v[32:35]
	v_mfma_f32_16x16x32_bf16 v[16:19], v[196:199], v[244:247], v[16:19]
	v_mfma_f32_16x16x32_bf16 v[0:3], v[196:199], v[248:251], v[0:3]
	v_mfma_f32_16x16x32_bf16 v[124:127], v[196:199], v[252:255], v[124:127]
	ds_read_b128 v[196:199], v134 offset:38912
	s_add_i32 m0, s101, 0xa000
	v_lshl_add_u64 v[138:139], v[138:139], 0, s[98:99]
	global_load_lds_dwordx4 v[138:139], off
.Ltl_165:
	s_add_i32 s6, s6, 0x10000
	s_add_u32 s30, s30, 0x80
	s_addc_u32 s31, s31, 0
	s_cmpk_lg_i32 s30, 0x780
	s_cbranch_scc1 .LBB0_165
	s_branch .Lex_165
.Lg1n_165:
	s_waitcnt lgkmcnt(3)
	v_mfma_f32_16x16x32_bf16 v[108:111], v[184:187], v[168:171], v[108:111]
	v_mfma_f32_16x16x32_bf16 v[92:95], v[184:187], v[172:175], v[92:95]
	v_mfma_f32_16x16x32_bf16 v[76:79], v[184:187], v[176:179], v[76:79]
	v_mfma_f32_16x16x32_bf16 v[60:63], v[184:187], v[180:183], v[60:63]
	ds_read_b128 v[240:243], v202
	ds_read_b128 v[244:247], v203
	s_waitcnt lgkmcnt(4)
	v_mfma_f32_16x16x32_bf16 v[104:107], v[188:191], v[168:171], v[104:107]
	v_mfma_f32_16x16x32_bf16 v[88:91], v[188:191], v[172:175], v[88:91]
	v_mfma_f32_16x16x32_bf16 v[72:75], v[188:191], v[176:179], v[72:75]
	v_mfma_f32_16x16x32_bf16 v[56:59], v[188:191], v[180:183], v[56:59]
	ds_read_b128 v[248:251], v204
	ds_read_b128 v[252:255], v205
	s_waitcnt lgkmcnt(5)
	v_mfma_f32_16x16x32_bf16 v[100:103], v[192:195], v[168:171], v[100:103]
	v_mfma_f32_16x16x32_bf16 v[84:87], v[192:195], v[172:175], v[84:87]
	v_mfma_f32_16x16x32_bf16 v[68:71], v[192:195], v[176:179], v[68:71]
	v_mfma_f32_16x16x32_bf16 v[52:55], v[192:195], v[180:183], v[52:55]
	s_waitcnt lgkmcnt(4)
	v_mfma_f32_16x16x32_bf16 v[96:99], v[196:199], v[168:171], v[96:99]
	v_mfma_f32_16x16x32_bf16 v[80:83], v[196:199], v[172:175], v[80:83]
	v_mfma_f32_16x16x32_bf16 v[64:67], v[196:199], v[176:179], v[64:67]
	v_mfma_f32_16x16x32_bf16 v[48:51], v[196:199], v[180:183], v[48:51]
	s_branch .Lg2_165
.Lg4n_165:
	v_mfma_f32_16x16x32_bf16 v[44:47], v[184:187], v[240:243], v[44:47]
	v_mfma_f32_16x16x32_bf16 v[28:31], v[184:187], v[244:247], v[28:31]
	v_mfma_f32_16x16x32_bf16 v[12:15], v[184:187], v[248:251], v[12:15]
	v_mfma_f32_16x16x32_bf16 v[112:115], v[184:187], v[252:255], v[112:115]
	v_add3_u32 v134, s34, v151, v152
	ds_read_b128 v[184:187], v134 offset:32768
	v_add3_u32 v162, s34, v151, v153
	v_add3_u32 v163, s34, v155, v154
	v_add3_u32 v200, s34, v155, v156
	v_add3_u32 v201, s34, v155, v157
	ds_read_b128 v[168:171], v162
	ds_read_b128 v[172:175], v163
	ds_read_b128 v[176:179], v200
	ds_read_b128 v[180:183], v201
	v_mfma_f32_16x16x32_bf16 v[40:43], v[188:191], v[240:243], v[40:43]
	v_mfma_f32_16x16x32_bf16 v[24:27], v[188:191], v[244:247], v[24:27]
	v_mfma_f32_16x16x32_bf16 v[8:11], v[188:191], v[248:251], v[8:11]
	v_mfma_f32_16x16x32_bf16 v[116:119], v[188:191], v[252:255], v[116:119]
	ds_read_b128 v[188:191], v134 offset:34816
	v_add3_u32 v202, s34, v155, v158
	v_add3_u32 v203, s34, v155, v159
	v_add3_u32 v204, s34, v155, v160
	v_add3_u32 v205, s34, v155, v161
	v_mfma_f32_16x16x32_bf16 v[36:39], v[192:195], v[240:243], v[36:39]
	v_mfma_f32_16x16x32_bf16 v[20:23], v[192:195], v[244:247], v[20:23]
	v_mfma_f32_16x16x32_bf16 v[4:7], v[192:195], v[248:251], v[4:7]
	v_mfma_f32_16x16x32_bf16 v[120:123], v[192:195], v[252:255], v[120:123]
	ds_read_b128 v[192:195], v134 offset:36864
	v_mfma_f32_16x16x32_bf16 v[32:35], v[196:199], v[240:243], v[32:35]
	v_mfma_f32_16x16x32_bf16 v[16:19], v[196:199], v[244:247], v[16:19]
	v_mfma_f32_16x16x32_bf16 v[0:3], v[196:199], v[248:251], v[0:3]
	v_mfma_f32_16x16x32_bf16 v[124:127], v[196:199], v[252:255], v[124:127]
	ds_read_b128 v[196:199], v134 offset:38912
	s_branch .Ltl_165
.Lex_165:
	s_waitcnt lgkmcnt(0)
	s_add_i32 s27, 0, 0x10000
	v_add3_u32 v130, s27, v155, v161
	v_add3_u32 v131, s27, v155, v160
	v_add3_u32 v134, s27, v155, v159
	v_add3_u32 v192, s27, v155, v158
	v_add3_u32 v193, s27, v155, v157
	v_add3_u32 v162, s27, v155, v156
	v_add3_u32 v163, s27, v155, v154
	v_add3_u32 v153, s27, v151, v153
	v_add3_u32 v152, s52, v151, v152
	ds_read_b128 v[136:139], v130
	ds_read_b128 v[140:143], v131
	ds_read_b128 v[144:147], v134
	ds_read_b128 v[158:161], v192
	ds_read_b128 v[168:171], v193
	ds_read_b128 v[172:175], v162
	ds_read_b128 v[154:157], v163
	ds_read_b128 v[176:179], v153
	ds_read_b128 v[148:151], v152
	s_waitcnt lgkmcnt(0)
	v_mfma_f32_16x16x32_bf16 v[12:15], v[148:151], v[140:143], v[12:15]
	v_mfma_f32_16x16x32_bf16 v[180:183], v[148:151], v[136:139], v[112:115]
	s_nop 2
	ds_read_b128 v[112:115], v152 offset:2048
	s_waitcnt lgkmcnt(0)
	v_mfma_f32_16x16x32_bf16 v[8:11], v[112:115], v[140:143], v[8:11]
	v_mfma_f32_16x16x32_bf16 v[184:187], v[112:115], v[136:139], v[116:119]
	s_nop 2
	ds_read_b128 v[116:119], v152 offset:4096
	s_waitcnt lgkmcnt(0)
	v_mfma_f32_16x16x32_bf16 v[4:7], v[116:119], v[140:143], v[4:7]
	v_mfma_f32_16x16x32_bf16 v[108:111], v[148:151], v[176:179], v[108:111]
	v_mfma_f32_16x16x32_bf16 v[92:95], v[148:151], v[154:157], v[92:95]
	v_mfma_f32_16x16x32_bf16 v[76:79], v[148:151], v[172:175], v[76:79]
	v_mfma_f32_16x16x32_bf16 v[104:107], v[112:115], v[176:179], v[104:107]
	v_mfma_f32_16x16x32_bf16 v[88:91], v[112:115], v[154:157], v[88:91]
	v_mfma_f32_16x16x32_bf16 v[72:75], v[112:115], v[172:175], v[72:75]
	v_mfma_f32_16x16x32_bf16 v[188:191], v[116:119], v[136:139], v[120:123]
	v_mfma_f32_16x16x32_bf16 v[100:103], v[116:119], v[176:179], v[100:103]
	v_mfma_f32_16x16x32_bf16 v[84:87], v[116:119], v[154:157], v[84:87]
	v_mfma_f32_16x16x32_bf16 v[68:71], v[116:119], v[172:175], v[68:71]
	ds_read_b128 v[120:123], v152 offset:6144
	s_waitcnt lgkmcnt(0)
	v_mfma_f32_16x16x32_bf16 v[136:139], v[120:123], v[136:139], v[124:127]
	v_mfma_f32_16x16x32_bf16 v[96:99], v[120:123], v[176:179], v[96:99]
	v_mfma_f32_16x16x32_bf16 v[80:83], v[120:123], v[154:157], v[80:83]
	v_mfma_f32_16x16x32_bf16 v[64:67], v[120:123], v[172:175], v[64:67]
	v_mfma_f32_16x16x32_bf16 v[48:51], v[120:123], v[168:171], v[48:51]
	v_mfma_f32_16x16x32_bf16 v[52:55], v[116:119], v[168:171], v[52:55]
	v_mfma_f32_16x16x32_bf16 v[56:59], v[112:115], v[168:171], v[56:59]
	v_mfma_f32_16x16x32_bf16 v[60:63], v[148:151], v[168:171], v[60:63]
	v_mfma_f32_16x16x32_bf16 v[44:47], v[148:151], v[158:161], v[44:47]
	v_mfma_f32_16x16x32_bf16 v[40:43], v[112:115], v[158:161], v[40:43]
	v_mfma_f32_16x16x32_bf16 v[36:39], v[116:119], v[158:161], v[36:39]
	v_mfma_f32_16x16x32_bf16 v[32:35], v[120:123], v[158:161], v[32:35]
	v_mfma_f32_16x16x32_bf16 v[28:31], v[148:151], v[144:147], v[28:31]
	v_mfma_f32_16x16x32_bf16 v[24:27], v[112:115], v[144:147], v[24:27]
	v_mfma_f32_16x16x32_bf16 v[20:23], v[116:119], v[144:147], v[20:23]
	v_mfma_f32_16x16x32_bf16 v[16:19], v[120:123], v[144:147], v[16:19]
	v_mfma_f32_16x16x32_bf16 v[0:3], v[120:123], v[140:143], v[0:3]
	ds_read_b128 v[140:143], v152 offset:1024
	ds_read_b128 v[144:147], v152 offset:3072
	ds_read_b128 v[148:151], v152 offset:5120
	ds_read_b128 v[112:115], v153 offset:1024
	ds_read_b128 v[152:155], v152 offset:7168
	ds_read_b128 v[156:159], v163 offset:1024
	ds_read_b128 v[160:163], v162 offset:1024
	ds_read_b128 v[168:171], v193 offset:1024
	s_waitcnt lgkmcnt(4)
	v_mfma_f32_16x16x32_bf16 v[124:127], v[140:143], v[112:115], v[108:111]
	v_mfma_f32_16x16x32_bf16 v[120:123], v[144:147], v[112:115], v[104:107]
	v_mfma_f32_16x16x32_bf16 v[116:119], v[148:151], v[112:115], v[100:103]
	s_waitcnt lgkmcnt(3)
	v_mfma_f32_16x16x32_bf16 v[108:111], v[152:155], v[112:115], v[96:99]
	ds_read_b128 v[172:175], v192 offset:1024
	s_waitcnt lgkmcnt(3)
	v_mfma_f32_16x16x32_bf16 v[112:115], v[140:143], v[156:159], v[92:95]
	v_mfma_f32_16x16x32_bf16 v[104:107], v[144:147], v[156:159], v[88:91]
	v_mfma_f32_16x16x32_bf16 v[100:103], v[148:151], v[156:159], v[84:87]
	v_mfma_f32_16x16x32_bf16 v[96:99], v[152:155], v[156:159], v[80:83]
	ds_read_b128 v[156:159], v134 offset:1024
	s_waitcnt lgkmcnt(3)
	v_mfma_f32_16x16x32_bf16 v[92:95], v[140:143], v[160:163], v[76:79]
	v_mfma_f32_16x16x32_bf16 v[88:91], v[144:147], v[160:163], v[72:75]
	v_mfma_f32_16x16x32_bf16 v[84:87], v[148:151], v[160:163], v[68:71]
	v_mfma_f32_16x16x32_bf16 v[80:83], v[152:155], v[160:163], v[64:67]
	ds_read_b128 v[160:163], v131 offset:1024
	s_waitcnt lgkmcnt(3)
	v_mfma_f32_16x16x32_bf16 v[76:79], v[140:143], v[168:171], v[60:63]
	v_mfma_f32_16x16x32_bf16 v[72:75], v[144:147], v[168:171], v[56:59]
	v_mfma_f32_16x16x32_bf16 v[68:71], v[148:151], v[168:171], v[52:55]
	v_mfma_f32_16x16x32_bf16 v[64:67], v[152:155], v[168:171], v[48:51]
	ds_read_b128 v[168:171], v130 offset:1024
	s_waitcnt lgkmcnt(3)
	v_mfma_f32_16x16x32_bf16 v[60:63], v[140:143], v[172:175], v[44:47]
	v_mfma_f32_16x16x32_bf16 v[56:59], v[144:147], v[172:175], v[40:43]
	v_mfma_f32_16x16x32_bf16 v[52:55], v[148:151], v[172:175], v[36:39]
	v_mfma_f32_16x16x32_bf16 v[48:51], v[152:155], v[172:175], v[32:35]
	s_waitcnt lgkmcnt(2)
	v_mfma_f32_16x16x32_bf16 v[44:47], v[140:143], v[156:159], v[28:31]
	v_mfma_f32_16x16x32_bf16 v[40:43], v[144:147], v[156:159], v[24:27]
	v_mfma_f32_16x16x32_bf16 v[36:39], v[148:151], v[156:159], v[20:23]
	v_mfma_f32_16x16x32_bf16 v[32:35], v[152:155], v[156:159], v[16:19]
	s_waitcnt lgkmcnt(1)
	v_mfma_f32_16x16x32_bf16 v[28:31], v[140:143], v[160:163], v[12:15]
	v_mfma_f32_16x16x32_bf16 v[24:27], v[144:147], v[160:163], v[8:11]
	v_mfma_f32_16x16x32_bf16 v[20:23], v[148:151], v[160:163], v[4:7]
	v_mfma_f32_16x16x32_bf16 v[16:19], v[152:155], v[160:163], v[0:3]
	s_waitcnt lgkmcnt(0)
	v_mfma_f32_16x16x32_bf16 v[12:15], v[140:143], v[168:171], v[180:183]
	v_mfma_f32_16x16x32_bf16 v[8:11], v[144:147], v[168:171], v[184:187]
	v_mfma_f32_16x16x32_bf16 v[0:3], v[148:151], v[168:171], v[188:191]
	v_mfma_f32_16x16x32_bf16 v[4:7], v[152:155], v[168:171], v[136:139]
	s_waitcnt vmcnt(0)
	s_nop 2
	v_mov_b32_e32 v138, v132
	s_cmp_gt_u32 s26, 1
	s_barrier
	s_cbranch_scc0 .LBB0_169
	v_mov_b32_e32 v130, s19
	ds_read_b64 v[136:137], v130
	s_cmp_gt_u32 s26, 3
	s_cbranch_scc0 .LBB0_170
	s_lshl_b32 s6, s26, 8
	s_waitcnt lgkmcnt(0)
	v_lshl_add_u64 v[130:131], v[136:137], 0, s[20:21]
	s_add_i32 s34, s6, 0xfffff200
	s_mov_b64 s[30:31], 0x400
	s_cbranch_execz .LBB0_171
	s_branch .LBB0_172

.LBB0_177:
	s_and_b32 s27, s6, 0x10000
	s_xor_b32 s30, s27, 0x10000
	s_add_i32 s27, s27, 0
	s_add_i32 s101, s100, s30
	s_cmpk_eq_i32 s4, 0
	s_cbranch_scc1 .Lg1n_177
	s_waitcnt lgkmcnt(3)
	v_mfma_f32_16x16x32_bf16 v[108:111], v[160:163], v[180:183], v[108:111]
	v_mfma_f32_16x16x32_bf16 v[92:95], v[168:171], v[180:183], v[92:95]
	v_mfma_f32_16x16x32_bf16 v[76:79], v[172:175], v[180:183], v[76:79]
	v_mfma_f32_16x16x32_bf16 v[60:63], v[176:179], v[180:183], v[60:63]
	ds_read_b128 v[240:243], v200
	ds_read_b128 v[244:247], v201
	s_add_i32 m0, s101, 0x4000
	v_lshl_add_u64 v[142:143], v[142:143], 0, s[98:99]
	global_load_lds_dwordx4 v[142:143], off
	s_waitcnt lgkmcnt(4)
	v_mfma_f32_16x16x32_bf16 v[104:107], v[160:163], v[184:187], v[104:107]
	v_mfma_f32_16x16x32_bf16 v[88:91], v[168:171], v[184:187], v[88:91]
	v_mfma_f32_16x16x32_bf16 v[72:75], v[172:175], v[184:187], v[72:75]
	v_mfma_f32_16x16x32_bf16 v[56:59], v[176:179], v[184:187], v[56:59]
	ds_read_b128 v[248:251], v202
	ds_read_b128 v[252:255], v203
	s_add_i32 m0, s101, 0xc000
	v_lshl_add_u64 v[130:131], v[130:131], 0, s[98:99]
	global_load_lds_dwordx4 v[130:131], off
	s_waitcnt lgkmcnt(5)
	v_mfma_f32_16x16x32_bf16 v[100:103], v[160:163], v[188:191], v[100:103]
	v_mfma_f32_16x16x32_bf16 v[84:87], v[168:171], v[188:191], v[84:87]
	v_mfma_f32_16x16x32_bf16 v[68:71], v[172:175], v[188:191], v[68:71]
	v_mfma_f32_16x16x32_bf16 v[52:55], v[176:179], v[188:191], v[52:55]
	s_add_i32 m0, s101, 0x6000
	v_lshl_add_u64 v[140:141], v[140:141], 0, s[98:99]
	global_load_lds_dwordx4 v[140:141], off
	s_waitcnt lgkmcnt(4)
	v_mfma_f32_16x16x32_bf16 v[96:99], v[160:163], v[192:195], v[96:99]
	v_mfma_f32_16x16x32_bf16 v[80:83], v[168:171], v[192:195], v[80:83]
	v_mfma_f32_16x16x32_bf16 v[64:67], v[172:175], v[192:195], v[64:67]
	v_mfma_f32_16x16x32_bf16 v[48:51], v[176:179], v[192:195], v[48:51]
	s_add_i32 m0, s101, 0xe000
	v_lshl_add_u64 v[128:129], v[128:129], 0, s[98:99]
	global_load_lds_dwordx4 v[128:129], off
.Lg2_177:
	ds_read_b128 v[160:163], v196 offset:1024
	ds_read_b128 v[168:171], v197 offset:1024
	ds_read_b128 v[172:175], v198 offset:1024
	ds_read_b128 v[176:179], v199 offset:1024
	s_waitcnt lgkmcnt(4)
	v_mfma_f32_16x16x32_bf16 v[44:47], v[240:243], v[180:183], v[44:47]
	v_mfma_f32_16x16x32_bf16 v[28:31], v[244:247], v[180:183], v[28:31]
	v_mfma_f32_16x16x32_bf16 v[12:15], v[248:251], v[180:183], v[12:15]
	v_mfma_f32_16x16x32_bf16 v[112:115], v[252:255], v[180:183], v[112:115]
	ds_read_b128 v[180:183], v134 offset:33792
	v_mfma_f32_16x16x32_bf16 v[40:43], v[240:243], v[184:187], v[40:43]
	v_mfma_f32_16x16x32_bf16 v[24:27], v[244:247], v[184:187], v[24:27]
	v_mfma_f32_16x16x32_bf16 v[8:11], v[248:251], v[184:187], v[8:11]
	v_mfma_f32_16x16x32_bf16 v[116:119], v[252:255], v[184:187], v[116:119]
	ds_read_b128 v[184:187], v134 offset:35840
	v_mfma_f32_16x16x32_bf16 v[36:39], v[240:243], v[188:191], v[36:39]
	v_mfma_f32_16x16x32_bf16 v[20:23], v[244:247], v[188:191], v[20:23]
	v_mfma_f32_16x16x32_bf16 v[4:7], v[248:251], v[188:191], v[4:7]
	v_mfma_f32_16x16x32_bf16 v[120:123], v[252:255], v[188:191], v[120:123]
	ds_read_b128 v[188:191], v134 offset:37888
	v_mfma_f32_16x16x32_bf16 v[32:35], v[240:243], v[192:195], v[32:35]
	v_mfma_f32_16x16x32_bf16 v[16:19], v[244:247], v[192:195], v[16:19]
	v_mfma_f32_16x16x32_bf16 v[0:3], v[248:251], v[192:195], v[0:3]
	v_mfma_f32_16x16x32_bf16 v[124:127], v[252:255], v[192:195], v[124:127]
	ds_read_b128 v[192:195], v134 offset:39936
	s_waitcnt lgkmcnt(3)
	v_mfma_f32_16x16x32_bf16 v[108:111], v[160:163], v[180:183], v[108:111]
	v_mfma_f32_16x16x32_bf16 v[92:95], v[168:171], v[180:183], v[92:95]
	v_mfma_f32_16x16x32_bf16 v[76:79], v[172:175], v[180:183], v[76:79]
	v_mfma_f32_16x16x32_bf16 v[60:63], v[176:179], v[180:183], v[60:63]
	ds_read_b128 v[240:243], v200 offset:1024
	ds_read_b128 v[244:247], v201 offset:1024
	s_waitcnt lgkmcnt(4)
	v_mfma_f32_16x16x32_bf16 v[104:107], v[160:163], v[184:187], v[104:107]
	v_mfma_f32_16x16x32_bf16 v[88:91], v[168:171], v[184:187], v[88:91]
	v_mfma_f32_16x16x32_bf16 v[72:75], v[172:175], v[184:187], v[72:75]
	v_mfma_f32_16x16x32_bf16 v[56:59], v[176:179], v[184:187], v[56:59]
	ds_read_b128 v[248:251], v202 offset:1024
	ds_read_b128 v[252:255], v203 offset:1024
	s_waitcnt lgkmcnt(5)
	v_mfma_f32_16x16x32_bf16 v[100:103], v[160:163], v[188:191], v[100:103]
	v_mfma_f32_16x16x32_bf16 v[84:87], v[168:171], v[188:191], v[84:87]
	v_mfma_f32_16x16x32_bf16 v[68:71], v[172:175], v[188:191], v[68:71]
	v_mfma_f32_16x16x32_bf16 v[52:55], v[176:179], v[188:191], v[52:55]
	s_waitcnt lgkmcnt(4)
	v_mfma_f32_16x16x32_bf16 v[96:99], v[160:163], v[192:195], v[96:99]
	v_mfma_f32_16x16x32_bf16 v[80:83], v[168:171], v[192:195], v[80:83]
	v_mfma_f32_16x16x32_bf16 v[64:67], v[172:175], v[192:195], v[64:67]
	v_mfma_f32_16x16x32_bf16 v[48:51], v[176:179], v[192:195], v[48:51]
	s_waitcnt vmcnt(0) lgkmcnt(0)
	s_barrier
	s_add_i32 s101, s100, s27
	s_cmpk_eq_i32 s4, 0x700
	s_cbranch_scc1 .Lg4n_177
	v_mfma_f32_16x16x32_bf16 v[44:47], v[240:243], v[180:183], v[44:47]
	v_mfma_f32_16x16x32_bf16 v[28:31], v[244:247], v[180:183], v[28:31]
	v_mfma_f32_16x16x32_bf16 v[12:15], v[248:251], v[180:183], v[12:15]
	v_mfma_f32_16x16x32_bf16 v[112:115], v[252:255], v[180:183], v[112:115]
	v_add3_u32 v134, s30, v149, v150
	ds_read_b128 v[180:183], v134 offset:32768
	v_add3_u32 v196, s30, v149, v151
	v_add3_u32 v197, s30, v153, v152
	v_add3_u32 v198, s30, v153, v154
	v_add3_u32 v199, s30, v153, v155
	ds_read_b128 v[160:163], v196
	ds_read_b128 v[168:171], v197
	ds_read_b128 v[172:175], v198
	ds_read_b128 v[176:179], v199
	s_mov_b32 m0, s101
	v_lshl_add_u64 v[146:147], v[146:147], 0, s[98:99]
	global_load_lds_dwordx4 v[146:147], off
	v_mfma_f32_16x16x32_bf16 v[40:43], v[240:243], v[184:187], v[40:43]
	v_mfma_f32_16x16x32_bf16 v[24:27], v[244:247], v[184:187], v[24:27]
	v_mfma_f32_16x16x32_bf16 v[8:11], v[248:251], v[184:187], v[8:11]
	v_mfma_f32_16x16x32_bf16 v[116:119], v[252:255], v[184:187], v[116:119]
	ds_read_b128 v[184:187], v134 offset:34816
	v_add3_u32 v200, s30, v153, v156
	v_add3_u32 v201, s30, v153, v157
	v_add3_u32 v202, s30, v153, v158
	v_add3_u32 v203, s30, v153, v159
	s_add_i32 m0, s101, 0x8000
	v_lshl_add_u64 v[138:139], v[138:139], 0, s[98:99]
	global_load_lds_dwordx4 v[138:139], off
	v_mfma_f32_16x16x32_bf16 v[36:39], v[240:243], v[188:191], v[36:39]
	v_mfma_f32_16x16x32_bf16 v[20:23], v[244:247], v[188:191], v[20:23]
	v_mfma_f32_16x16x32_bf16 v[4:7], v[248:251], v[188:191], v[4:7]
	v_mfma_f32_16x16x32_bf16 v[120:123], v[252:255], v[188:191], v[120:123]
	ds_read_b128 v[188:191], v134 offset:36864
	s_add_i32 m0, s101, 0x2000
	v_lshl_add_u64 v[144:145], v[144:145], 0, s[98:99]
	global_load_lds_dwordx4 v[144:145], off
	v_mfma_f32_16x16x32_bf16 v[32:35], v[240:243], v[192:195], v[32:35]
	v_mfma_f32_16x16x32_bf16 v[16:19], v[244:247], v[192:195], v[16:19]
	v_mfma_f32_16x16x32_bf16 v[0:3], v[248:251], v[192:195], v[0:3]
	v_mfma_f32_16x16x32_bf16 v[124:127], v[252:255], v[192:195], v[124:127]
	ds_read_b128 v[192:195], v134 offset:38912
	s_add_i32 m0, s101, 0xa000
	v_lshl_add_u64 v[136:137], v[136:137], 0, s[98:99]
	global_load_lds_dwordx4 v[136:137], off
.Ltl_177:
	s_add_i32 s6, s6, 0x10000
	s_add_u32 s4, s4, 0x80
	s_addc_u32 s5, s5, 0
	s_cmpk_lg_i32 s4, 0x780
	s_cbranch_scc1 .LBB0_177
	s_branch .Lex_177
.Lg1n_177:
	s_waitcnt lgkmcnt(3)
	v_mfma_f32_16x16x32_bf16 v[108:111], v[160:163], v[180:183], v[108:111]
	v_mfma_f32_16x16x32_bf16 v[92:95], v[168:171], v[180:183], v[92:95]
	v_mfma_f32_16x16x32_bf16 v[76:79], v[172:175], v[180:183], v[76:79]
	v_mfma_f32_16x16x32_bf16 v[60:63], v[176:179], v[180:183], v[60:63]
	ds_read_b128 v[240:243], v200
	ds_read_b128 v[244:247], v201
	s_waitcnt lgkmcnt(4)
	v_mfma_f32_16x16x32_bf16 v[104:107], v[160:163], v[184:187], v[104:107]
	v_mfma_f32_16x16x32_bf16 v[88:91], v[168:171], v[184:187], v[88:91]
	v_mfma_f32_16x16x32_bf16 v[72:75], v[172:175], v[184:187], v[72:75]
	v_mfma_f32_16x16x32_bf16 v[56:59], v[176:179], v[184:187], v[56:59]
	ds_read_b128 v[248:251], v202
	ds_read_b128 v[252:255], v203
	s_waitcnt lgkmcnt(5)
	v_mfma_f32_16x16x32_bf16 v[100:103], v[160:163], v[188:191], v[100:103]
	v_mfma_f32_16x16x32_bf16 v[84:87], v[168:171], v[188:191], v[84:87]
	v_mfma_f32_16x16x32_bf16 v[68:71], v[172:175], v[188:191], v[68:71]
	v_mfma_f32_16x16x32_bf16 v[52:55], v[176:179], v[188:191], v[52:55]
	s_waitcnt lgkmcnt(4)
	v_mfma_f32_16x16x32_bf16 v[96:99], v[160:163], v[192:195], v[96:99]
	v_mfma_f32_16x16x32_bf16 v[80:83], v[168:171], v[192:195], v[80:83]
	v_mfma_f32_16x16x32_bf16 v[64:67], v[172:175], v[192:195], v[64:67]
	v_mfma_f32_16x16x32_bf16 v[48:51], v[176:179], v[192:195], v[48:51]
	s_branch .Lg2_177
.Lg4n_177:
	v_mfma_f32_16x16x32_bf16 v[44:47], v[240:243], v[180:183], v[44:47]
	v_mfma_f32_16x16x32_bf16 v[28:31], v[244:247], v[180:183], v[28:31]
	v_mfma_f32_16x16x32_bf16 v[12:15], v[248:251], v[180:183], v[12:15]
	v_mfma_f32_16x16x32_bf16 v[112:115], v[252:255], v[180:183], v[112:115]
	v_add3_u32 v134, s30, v149, v150
	ds_read_b128 v[180:183], v134 offset:32768
	v_add3_u32 v196, s30, v149, v151
	v_add3_u32 v197, s30, v153, v152
	v_add3_u32 v198, s30, v153, v154
	v_add3_u32 v199, s30, v153, v155
	ds_read_b128 v[160:163], v196
	ds_read_b128 v[168:171], v197
	ds_read_b128 v[172:175], v198
	ds_read_b128 v[176:179], v199
	v_mfma_f32_16x16x32_bf16 v[40:43], v[240:243], v[184:187], v[40:43]
	v_mfma_f32_16x16x32_bf16 v[24:27], v[244:247], v[184:187], v[24:27]
	v_mfma_f32_16x16x32_bf16 v[8:11], v[248:251], v[184:187], v[8:11]
	v_mfma_f32_16x16x32_bf16 v[116:119], v[252:255], v[184:187], v[116:119]
	ds_read_b128 v[184:187], v134 offset:34816
	v_add3_u32 v200, s30, v153, v156
	v_add3_u32 v201, s30, v153, v157
	v_add3_u32 v202, s30, v153, v158
	v_add3_u32 v203, s30, v153, v159
	v_mfma_f32_16x16x32_bf16 v[36:39], v[240:243], v[188:191], v[36:39]
	v_mfma_f32_16x16x32_bf16 v[20:23], v[244:247], v[188:191], v[20:23]
	v_mfma_f32_16x16x32_bf16 v[4:7], v[248:251], v[188:191], v[4:7]
	v_mfma_f32_16x16x32_bf16 v[120:123], v[252:255], v[188:191], v[120:123]
	ds_read_b128 v[188:191], v134 offset:36864
	v_mfma_f32_16x16x32_bf16 v[32:35], v[240:243], v[192:195], v[32:35]
	v_mfma_f32_16x16x32_bf16 v[16:19], v[244:247], v[192:195], v[16:19]
	v_mfma_f32_16x16x32_bf16 v[0:3], v[248:251], v[192:195], v[0:3]
	v_mfma_f32_16x16x32_bf16 v[124:127], v[252:255], v[192:195], v[124:127]
	ds_read_b128 v[192:195], v134 offset:38912
	s_branch .Ltl_177
.Lex_177:
	s_waitcnt lgkmcnt(0)
	s_add_i32 s5, 0, 0x10000
	v_add3_u32 v184, s5, v153, v158
	ds_read_b128 v[136:139], v184
	v_add3_u32 v134, s5, v153, v159
	v_add3_u32 v185, s5, v153, v157
	v_add3_u32 v186, s5, v153, v156
	v_add3_u32 v187, s5, v153, v155
	v_add3_u32 v188, s5, v153, v154
	v_add3_u32 v189, s5, v153, v152
	v_add3_u32 v190, s5, v149, v151
	v_add3_u32 v191, s52, v149, v150
	ds_read_b128 v[128:131], v134
	ds_read_b128 v[140:143], v185
	ds_read_b128 v[144:147], v186
	ds_read_b128 v[156:159], v187
	ds_read_b128 v[160:163], v188
	ds_read_b128 v[152:155], v189
	ds_read_b128 v[168:171], v190
	ds_read_b128 v[176:179], v191 offset:4096
	s_waitcnt lgkmcnt(0)
	v_mfma_f32_16x16x32_bf16 v[4:7], v[136:139], v[176:179], v[4:7]
	ds_read_b128 v[148:151], v191
	s_waitcnt lgkmcnt(0)
	v_mfma_f32_16x16x32_bf16 v[112:115], v[128:131], v[148:151], v[112:115]
	v_mfma_f32_16x16x32_bf16 v[60:63], v[156:159], v[148:151], v[60:63]
	ds_read_b128 v[172:175], v191 offset:2048
	s_waitcnt lgkmcnt(0)
	v_mfma_f32_16x16x32_bf16 v[116:119], v[128:131], v[172:175], v[116:119]
	v_mfma_f32_16x16x32_bf16 v[56:59], v[156:159], v[172:175], v[56:59]
	v_mfma_f32_16x16x32_bf16 v[120:123], v[128:131], v[176:179], v[120:123]
	ds_read_b128 v[180:183], v191 offset:6144
	s_waitcnt lgkmcnt(0)
	v_mfma_f32_16x16x32_bf16 v[124:127], v[128:131], v[180:183], v[124:127]
	v_mfma_f32_16x16x32_bf16 v[128:131], v[156:159], v[180:183], v[48:51]
	v_mfma_f32_16x16x32_bf16 v[48:51], v[168:171], v[176:179], v[100:103]
	v_mfma_f32_16x16x32_bf16 v[100:103], v[156:159], v[176:179], v[52:55]
	v_mfma_f32_16x16x32_bf16 v[156:159], v[136:139], v[172:175], v[8:11]
	v_mfma_f32_16x16x32_bf16 v[92:95], v[152:155], v[148:151], v[92:95]
	v_mfma_f32_16x16x32_bf16 v[76:79], v[160:163], v[148:151], v[76:79]
	v_mfma_f32_16x16x32_bf16 v[44:47], v[144:147], v[148:151], v[44:47]
	v_mfma_f32_16x16x32_bf16 v[52:55], v[168:171], v[172:175], v[104:107]
	v_mfma_f32_16x16x32_bf16 v[104:107], v[168:171], v[148:151], v[108:111]
	v_mfma_f32_16x16x32_bf16 v[28:31], v[140:143], v[148:151], v[28:31]
	v_mfma_f32_16x16x32_bf16 v[148:151], v[136:139], v[148:151], v[12:15]
	v_mfma_f32_16x16x32_bf16 v[88:91], v[152:155], v[172:175], v[88:91]
	v_mfma_f32_16x16x32_bf16 v[72:75], v[160:163], v[172:175], v[72:75]
	v_mfma_f32_16x16x32_bf16 v[84:87], v[152:155], v[176:179], v[84:87]
	v_mfma_f32_16x16x32_bf16 v[68:71], v[160:163], v[176:179], v[68:71]
	v_mfma_f32_16x16x32_bf16 v[96:99], v[168:171], v[180:183], v[96:99]
	v_mfma_f32_16x16x32_bf16 v[80:83], v[152:155], v[180:183], v[80:83]
	v_mfma_f32_16x16x32_bf16 v[64:67], v[160:163], v[180:183], v[64:67]
	v_mfma_f32_16x16x32_bf16 v[40:43], v[144:147], v[172:175], v[40:43]
	v_mfma_f32_16x16x32_bf16 v[36:39], v[144:147], v[176:179], v[36:39]
	v_mfma_f32_16x16x32_bf16 v[108:111], v[144:147], v[180:183], v[32:35]
	v_mfma_f32_16x16x32_bf16 v[144:147], v[140:143], v[172:175], v[24:27]
	v_mfma_f32_16x16x32_bf16 v[152:155], v[140:143], v[176:179], v[20:23]
	v_mfma_f32_16x16x32_bf16 v[140:143], v[140:143], v[180:183], v[16:19]
	v_mfma_f32_16x16x32_bf16 v[136:139], v[136:139], v[180:183], v[0:3]
	s_nop 2
	ds_read_b128 v[0:3], v190 offset:1024
	ds_read_b128 v[8:11], v189 offset:1024
	ds_read_b128 v[16:19], v188 offset:1024
	ds_read_b128 v[20:23], v187 offset:1024
	ds_read_b128 v[160:163], v191 offset:1024
	ds_read_b128 v[168:171], v191 offset:3072
	ds_read_b128 v[172:175], v191 offset:5120
	ds_read_b128 v[176:179], v191 offset:7168
	s_waitcnt lgkmcnt(3)
	v_mfma_f32_16x16x32_bf16 v[104:107], v[0:3], v[160:163], v[104:107]
	s_waitcnt lgkmcnt(2)
	v_mfma_f32_16x16x32_bf16 v[180:183], v[0:3], v[168:171], v[52:55]
	s_waitcnt lgkmcnt(1)
	v_mfma_f32_16x16x32_bf16 v[32:35], v[0:3], v[172:175], v[48:51]
	s_waitcnt lgkmcnt(0)
	v_mfma_f32_16x16x32_bf16 v[0:3], v[0:3], v[176:179], v[96:99]
	ds_read_b128 v[24:27], v186 offset:1024
	v_mfma_f32_16x16x32_bf16 v[92:95], v[8:11], v[160:163], v[92:95]
	v_mfma_f32_16x16x32_bf16 v[88:91], v[8:11], v[168:171], v[88:91]
	v_mfma_f32_16x16x32_bf16 v[48:51], v[8:11], v[172:175], v[84:87]
	v_mfma_f32_16x16x32_bf16 v[12:15], v[8:11], v[176:179], v[80:83]
	ds_read_b128 v[8:11], v185 offset:1024
	v_mfma_f32_16x16x32_bf16 v[76:79], v[16:19], v[160:163], v[76:79]
	v_mfma_f32_16x16x32_bf16 v[72:75], v[16:19], v[168:171], v[72:75]
	v_mfma_f32_16x16x32_bf16 v[52:55], v[16:19], v[172:175], v[68:71]
	v_mfma_f32_16x16x32_bf16 v[16:19], v[16:19], v[176:179], v[64:67]
	s_nop 2
	ds_read_b128 v[64:67], v184 offset:1024
	v_mfma_f32_16x16x32_bf16 v[68:71], v[20:23], v[160:163], v[60:63]
	v_mfma_f32_16x16x32_bf16 v[80:83], v[20:23], v[168:171], v[56:59]
	v_mfma_f32_16x16x32_bf16 v[56:59], v[20:23], v[172:175], v[100:103]
	v_mfma_f32_16x16x32_bf16 v[20:23], v[20:23], v[176:179], v[128:131]
	ds_read_b128 v[84:87], v134 offset:1024
	s_waitcnt lgkmcnt(3)
	v_mfma_f32_16x16x32_bf16 v[96:99], v[24:27], v[160:163], v[44:47]
	v_mfma_f32_16x16x32_bf16 v[100:103], v[24:27], v[168:171], v[40:43]
	v_mfma_f32_16x16x32_bf16 v[60:63], v[24:27], v[172:175], v[36:39]
	v_mfma_f32_16x16x32_bf16 v[24:27], v[24:27], v[176:179], v[108:111]
	s_waitcnt lgkmcnt(2)
	v_mfma_f32_16x16x32_bf16 v[108:111], v[8:11], v[160:163], v[28:31]
	v_mfma_f32_16x16x32_bf16 v[128:131], v[8:11], v[168:171], v[144:147]
	v_mfma_f32_16x16x32_bf16 v[44:47], v[8:11], v[172:175], v[152:155]
	v_mfma_f32_16x16x32_bf16 v[8:11], v[8:11], v[176:179], v[140:143]
	s_waitcnt lgkmcnt(1)
	v_mfma_f32_16x16x32_bf16 v[140:143], v[64:67], v[160:163], v[148:151]
	v_mfma_f32_16x16x32_bf16 v[144:147], v[64:67], v[168:171], v[156:159]
	v_mfma_f32_16x16x32_bf16 v[40:43], v[64:67], v[172:175], v[4:7]
	v_mfma_f32_16x16x32_bf16 v[4:7], v[64:67], v[176:179], v[136:139]
	s_waitcnt lgkmcnt(0)
	v_mfma_f32_16x16x32_bf16 v[112:115], v[84:87], v[160:163], v[112:115]
	v_mfma_f32_16x16x32_bf16 v[116:119], v[84:87], v[168:171], v[116:119]
	v_mfma_f32_16x16x32_bf16 v[36:39], v[84:87], v[172:175], v[120:123]
	v_mfma_f32_16x16x32_bf16 v[28:31], v[84:87], v[176:179], v[124:127]
	v_mov_b32_e32 v65, v132
	v_mov_b32_e32 v64, s19
	s_waitcnt vmcnt(0)
	s_barrier
	ds_read_b64 v[66:67], v64
	s_and_b32 s4, s26, 14
	s_and_b64 s[30:31], exec, s[28:29]
	s_cselect_b32 s6, s59, 0x14800000
	s_cselect_b32 s27, s60, 0xa800000
	s_cmp_eq_u32 s4, 4
	s_cselect_b32 s6, s27, s6
	s_cselect_b32 s4, 0xfffffc00, s61
	s_cselect_b32 s27, 9, 10
	s_waitcnt lgkmcnt(0)
	v_lshl_add_u64 v[66:67], v[66:67], 0, s[6:7]
	s_lshl_b32 s6, s26, 8
	s_add_i32 s6, s4, s6
	s_and_b32 s34, s66, 0xf00
	s_and_b64 s[30:31], exec, s[28:29]
	s_cselect_b32 s4, 8, 12
	s_ashr_i32 s30, s66, s4
	s_ashr_i32 s31, s30, 31
	s_lshl_b64 s[30:31], s[30:31], s27
	s_ashr_i32 s27, s6, 31
	s_add_u32 s6, s30, s6
	v_and_b32_e32 v84, 0xc0, v65
	s_addc_u32 s27, s31, s27
	v_or_b32_e32 v84, s6, v84
	v_mov_b32_e32 v85, s27
	v_lshlrev_b64 v[84:85], s4, v[84:85]
	s_and_b64 s[30:31], exec, s[28:29]
	v_lshl_add_u64 v[66:67], v[84:85], 1, v[66:67]
	s_cselect_b32 s6, 0, s34
	v_ashrrev_i32_e32 v84, 1, v65
	s_lshl_b32 s6, s6, 1
	v_and_b32_e32 v84, 0xffffff80, v84
	v_lshrrev_b32_e32 v87, 6, v65
	v_lshl_add_u64 v[66:67], v[66:67], 0, s[6:7]
	v_ashrrev_i32_e32 v85, 31, v84
	v_bfe_u32 v64, v65, 4, 2
	v_and_b32_e32 v86, 15, v65
	v_lshl_add_u64 v[84:85], v[84:85], 1, v[66:67]
	v_mul_lo_u32 v66, v87, s55
	v_lshlrev_b32_e32 v65, 4, v65
	v_add_u32_e32 v66, s5, v66
	v_lshlrev_b32_e32 v67, 3, v64
	v_mul_u32_u24_e32 v86, 0x110, v86
	v_and_b32_e32 v134, 0xf0, v65
	v_mul_u32_u24_e32 v65, 0x110, v64
	v_add3_u32 v86, v66, v67, v86
	v_add3_u32 v87, v66, v134, v65
	v_cvt_pk_bf16_f32 v66, v104, v105
	v_cvt_pk_bf16_f32 v67, v106, v107
	ds_write_b64 v86, v[66:67]
	v_cvt_pk_bf16_f32 v66, v92, v93
	v_cvt_pk_bf16_f32 v67, v94, v95
	ds_write_b64 v86, v[66:67] offset:32
	v_cvt_pk_bf16_f32 v66, v76, v77
	v_cvt_pk_bf16_f32 v67, v78, v79
	ds_write_b64 v86, v[66:67] offset:64
	v_cvt_pk_bf16_f32 v66, v68, v69
	v_cvt_pk_bf16_f32 v67, v70, v71
	ds_write_b64 v86, v[66:67] offset:96
	v_cvt_pk_bf16_f32 v66, v96, v97
	v_cvt_pk_bf16_f32 v67, v98, v99
	ds_write_b64 v86, v[66:67] offset:128
	v_cvt_pk_bf16_f32 v66, v108, v109
	v_cvt_pk_bf16_f32 v67, v110, v111
	ds_write_b64 v86, v[66:67] offset:160
	v_cvt_pk_bf16_f32 v66, v140, v141
	v_cvt_pk_bf16_f32 v67, v142, v143
	ds_write_b64 v86, v[66:67] offset:192
	v_cvt_pk_bf16_f32 v66, v112, v113
	v_cvt_pk_bf16_f32 v67, v114, v115
	ds_write_b64 v86, v[66:67] offset:224
	v_cvt_pk_bf16_f32 v66, v180, v181
	v_cvt_pk_bf16_f32 v67, v182, v183
	ds_write_b64 v86, v[66:67] offset:4352
	v_cvt_pk_bf16_f32 v66, v88, v89
	v_cvt_pk_bf16_f32 v67, v90, v91
	ds_write_b64 v86, v[66:67] offset:4384
	v_cvt_pk_bf16_f32 v66, v72, v73
	v_cvt_pk_bf16_f32 v67, v74, v75
	ds_write_b64 v86, v[66:67] offset:4416
	v_cvt_pk_bf16_f32 v66, v80, v81
	v_cvt_pk_bf16_f32 v67, v82, v83
	ds_write_b64 v86, v[66:67] offset:4448
	v_cvt_pk_bf16_f32 v66, v100, v101
	v_cvt_pk_bf16_f32 v67, v102, v103
	ds_write_b64 v86, v[66:67] offset:4480
	v_cvt_pk_bf16_f32 v66, v128, v129
	v_cvt_pk_bf16_f32 v67, v130, v131
	ds_write_b64 v86, v[66:67] offset:4512
	v_cvt_pk_bf16_f32 v66, v144, v145
	v_cvt_pk_bf16_f32 v67, v146, v147
	ds_write_b64 v86, v[66:67] offset:4544
	v_cvt_pk_bf16_f32 v66, v116, v117
	v_cvt_pk_bf16_f32 v67, v118, v119
	ds_write_b64 v86, v[66:67] offset:4576
	ds_read_b128 v[66:69], v87
	v_mov_b32_e32 v65, v135
	v_lshl_add_u64 v[70:71], v[84:85], 0, v[134:135]
	v_lshlrev_b64 v[72:73], s4, v[64:65]
	v_lshl_add_u64 v[72:73], v[72:73], 1, v[70:71]
	s_waitcnt lgkmcnt(0)
	flat_store_dwordx4 v[72:73], v[66:69] nt
	ds_read_b128 v[66:69], v87 offset:1088
	v_or_b32_e32 v134, 4, v64
	v_lshlrev_b64 v[72:73], s4, v[134:135]
	v_lshl_add_u64 v[72:73], v[72:73], 1, v[70:71]
	v_or_b32_e32 v134, 8, v64
	s_waitcnt lgkmcnt(0)
	flat_store_dwordx4 v[72:73], v[66:69] nt
	ds_read_b128 v[66:69], v87 offset:2176
	v_lshlrev_b64 v[72:73], s4, v[134:135]
	v_lshl_add_u64 v[72:73], v[72:73], 1, v[70:71]
	v_or_b32_e32 v134, 12, v64
	v_cvt_pk_bf16_f32 v32, v32, v33
	s_waitcnt lgkmcnt(0)
	flat_store_dwordx4 v[72:73], v[66:69] nt
	ds_read_b128 v[66:69], v87 offset:3264
	v_lshlrev_b64 v[72:73], s4, v[134:135]
	v_lshl_add_u64 v[72:73], v[72:73], 1, v[70:71]
	v_or_b32_e32 v134, 16, v64
	v_cvt_pk_bf16_f32 v33, v34, v35
	s_waitcnt lgkmcnt(0)
	flat_store_dwordx4 v[72:73], v[66:69] nt
	ds_read_b128 v[66:69], v87 offset:4352
	v_lshlrev_b64 v[72:73], s4, v[134:135]
	v_lshl_add_u64 v[72:73], v[72:73], 1, v[70:71]
	v_or_b32_e32 v134, 20, v64
	v_cvt_pk_bf16_f32 v0, v0, v1
	s_waitcnt lgkmcnt(0)
	flat_store_dwordx4 v[72:73], v[66:69] nt
	ds_read_b128 v[66:69], v87 offset:5440
	v_lshlrev_b64 v[72:73], s4, v[134:135]
	v_lshl_add_u64 v[72:73], v[72:73], 1, v[70:71]
	v_or_b32_e32 v134, 24, v64
	v_cvt_pk_bf16_f32 v1, v2, v3
	s_waitcnt lgkmcnt(0)
	flat_store_dwordx4 v[72:73], v[66:69] nt
	ds_read_b128 v[66:69], v87 offset:6528
	v_lshlrev_b64 v[72:73], s4, v[134:135]
	v_lshl_add_u64 v[72:73], v[72:73], 1, v[70:71]
	v_or_b32_e32 v134, 28, v64
	s_waitcnt lgkmcnt(0)
	flat_store_dwordx4 v[72:73], v[66:69] nt
	ds_read_b128 v[66:69], v87 offset:7616
	v_lshlrev_b64 v[72:73], s4, v[134:135]
	v_lshl_add_u64 v[72:73], v[72:73], 1, v[70:71]
	v_or_b32_e32 v134, 32, v64
	s_waitcnt lgkmcnt(0)
	flat_store_dwordx4 v[72:73], v[66:69] nt
	ds_write_b64 v86, v[32:33]
	v_cvt_pk_bf16_f32 v32, v48, v49
	v_cvt_pk_bf16_f32 v33, v50, v51
	ds_write_b64 v86, v[0:1] offset:4352
	v_cvt_pk_bf16_f32 v0, v12, v13
	v_cvt_pk_bf16_f32 v1, v14, v15
	ds_write_b64 v86, v[32:33] offset:32
	v_cvt_pk_bf16_f32 v32, v52, v53
	v_cvt_pk_bf16_f32 v33, v54, v55
	ds_write_b64 v86, v[0:1] offset:4384
	v_cvt_pk_bf16_f32 v0, v16, v17
	v_cvt_pk_bf16_f32 v1, v18, v19
	ds_write_b64 v86, v[32:33] offset:64
	v_cvt_pk_bf16_f32 v32, v56, v57
	v_cvt_pk_bf16_f32 v33, v58, v59
	ds_write_b64 v86, v[0:1] offset:4416
	v_cvt_pk_bf16_f32 v0, v20, v21
	v_cvt_pk_bf16_f32 v1, v22, v23
	ds_write_b64 v86, v[32:33] offset:96
	v_cvt_pk_bf16_f32 v32, v60, v61
	v_cvt_pk_bf16_f32 v33, v62, v63
	ds_write_b64 v86, v[0:1] offset:4448
	v_cvt_pk_bf16_f32 v0, v24, v25
	v_cvt_pk_bf16_f32 v1, v26, v27
	ds_write_b64 v86, v[32:33] offset:128
	v_cvt_pk_bf16_f32 v32, v44, v45
	v_cvt_pk_bf16_f32 v33, v46, v47
	ds_write_b64 v86, v[0:1] offset:4480
	v_cvt_pk_bf16_f32 v0, v8, v9
	v_cvt_pk_bf16_f32 v1, v10, v11
	ds_write_b64 v86, v[32:33] offset:160
	v_cvt_pk_bf16_f32 v32, v40, v41
	v_cvt_pk_bf16_f32 v33, v42, v43
	ds_write_b64 v86, v[0:1] offset:4512
	v_cvt_pk_bf16_f32 v0, v4, v5
	v_cvt_pk_bf16_f32 v1, v6, v7
	ds_write_b64 v86, v[32:33] offset:192
	v_cvt_pk_bf16_f32 v32, v36, v37
	v_cvt_pk_bf16_f32 v33, v38, v39
	ds_write_b64 v86, v[0:1] offset:4544
	v_cvt_pk_bf16_f32 v0, v28, v29
	v_cvt_pk_bf16_f32 v1, v30, v31
	ds_write_b64 v86, v[32:33] offset:224
	ds_write_b64 v86, v[0:1] offset:4576
	ds_read_b128 v[0:3], v87
	v_lshlrev_b64 v[4:5], s4, v[134:135]
	v_lshl_add_u64 v[4:5], v[4:5], 1, v[70:71]
	v_or_b32_e32 v134, 36, v64
	s_waitcnt lgkmcnt(0)
	flat_store_dwordx4 v[4:5], v[0:3] nt
	ds_read_b128 v[0:3], v87 offset:1088
	v_lshlrev_b64 v[4:5], s4, v[134:135]
	v_lshl_add_u64 v[4:5], v[4:5], 1, v[70:71]
	v_or_b32_e32 v134, 40, v64
	s_waitcnt lgkmcnt(0)
	flat_store_dwordx4 v[4:5], v[0:3] nt
	ds_read_b128 v[0:3], v87 offset:2176
	v_lshlrev_b64 v[4:5], s4, v[134:135]
	v_lshl_add_u64 v[4:5], v[4:5], 1, v[70:71]
	v_or_b32_e32 v134, 44, v64
	s_waitcnt lgkmcnt(0)
	flat_store_dwordx4 v[4:5], v[0:3] nt
	ds_read_b128 v[0:3], v87 offset:3264
	v_lshlrev_b64 v[4:5], s4, v[134:135]
	v_lshl_add_u64 v[4:5], v[4:5], 1, v[70:71]
	v_or_b32_e32 v134, 48, v64
	s_waitcnt lgkmcnt(0)
	flat_store_dwordx4 v[4:5], v[0:3] nt
	ds_read_b128 v[0:3], v87 offset:4352
	v_lshlrev_b64 v[4:5], s4, v[134:135]
	v_lshl_add_u64 v[4:5], v[4:5], 1, v[70:71]
	v_or_b32_e32 v134, 52, v64
	s_waitcnt lgkmcnt(0)
	flat_store_dwordx4 v[4:5], v[0:3] nt
	ds_read_b128 v[0:3], v87 offset:5440
	v_lshlrev_b64 v[4:5], s4, v[134:135]
	v_lshl_add_u64 v[4:5], v[4:5], 1, v[70:71]
	v_or_b32_e32 v134, 56, v64
	s_waitcnt lgkmcnt(0)
	flat_store_dwordx4 v[4:5], v[0:3] nt
	ds_read_b128 v[0:3], v87 offset:6528
	v_lshlrev_b64 v[4:5], s4, v[134:135]
	v_lshl_add_u64 v[4:5], v[4:5], 1, v[70:71]
	v_or_b32_e32 v134, 60, v64
	s_waitcnt lgkmcnt(0)
	flat_store_dwordx4 v[4:5], v[0:3] nt
	ds_read_b128 v[0:3], v87 offset:7616
	v_lshlrev_b64 v[4:5], s4, v[134:135]
	v_lshl_add_u64 v[4:5], v[4:5], 1, v[70:71]
	s_waitcnt lgkmcnt(0)
	flat_store_dwordx4 v[4:5], v[0:3] nt

.LBB0_181:
	s_and_b32 s27, s6, 0x10000
	s_xor_b32 s28, s27, 0x10000
	s_add_i32 s27, s27, 0
	s_add_i32 s101, s100, s28
	s_cmpk_eq_i32 s4, 0
	s_cbranch_scc1 .Lg1n_181
	s_waitcnt lgkmcnt(3)
	v_mfma_f32_16x16x32_bf16 v[124:127], v[184:187], v[168:171], v[124:127]
	v_mfma_f32_16x16x32_bf16 v[108:111], v[184:187], v[172:175], v[108:111]
	v_mfma_f32_16x16x32_bf16 v[92:95], v[184:187], v[176:179], v[92:95]
	v_mfma_f32_16x16x32_bf16 v[76:79], v[184:187], v[180:183], v[76:79]
	ds_read_b128 v[240:243], v202
	ds_read_b128 v[244:247], v203
	s_add_i32 m0, s101, 0x4000
	v_lshl_add_u64 v[144:145], v[144:145], 0, s[98:99]
	global_load_lds_dwordx4 v[144:145], off
	s_waitcnt lgkmcnt(4)
	v_mfma_f32_16x16x32_bf16 v[120:123], v[188:191], v[168:171], v[120:123]
	v_mfma_f32_16x16x32_bf16 v[104:107], v[188:191], v[172:175], v[104:107]
	v_mfma_f32_16x16x32_bf16 v[88:91], v[188:191], v[176:179], v[88:91]
	v_mfma_f32_16x16x32_bf16 v[72:75], v[188:191], v[180:183], v[72:75]
	ds_read_b128 v[248:251], v204
	ds_read_b128 v[252:255], v205
	s_add_i32 m0, s101, 0xc000
	v_lshl_add_u64 v[136:137], v[136:137], 0, s[98:99]
	global_load_lds_dwordx4 v[136:137], off
	s_waitcnt lgkmcnt(5)
	v_mfma_f32_16x16x32_bf16 v[116:119], v[192:195], v[168:171], v[116:119]
	v_mfma_f32_16x16x32_bf16 v[100:103], v[192:195], v[172:175], v[100:103]
	v_mfma_f32_16x16x32_bf16 v[84:87], v[192:195], v[176:179], v[84:87]
	v_mfma_f32_16x16x32_bf16 v[68:71], v[192:195], v[180:183], v[68:71]
	s_add_i32 m0, s101, 0x6000
	v_lshl_add_u64 v[142:143], v[142:143], 0, s[98:99]
	global_load_lds_dwordx4 v[142:143], off
	s_waitcnt lgkmcnt(4)
	v_mfma_f32_16x16x32_bf16 v[112:115], v[196:199], v[168:171], v[112:115]
	v_mfma_f32_16x16x32_bf16 v[96:99], v[196:199], v[172:175], v[96:99]
	v_mfma_f32_16x16x32_bf16 v[80:83], v[196:199], v[176:179], v[80:83]
	v_mfma_f32_16x16x32_bf16 v[64:67], v[196:199], v[180:183], v[64:67]
	s_add_i32 m0, s101, 0xe000
	v_lshl_add_u64 v[130:131], v[130:131], 0, s[98:99]
	global_load_lds_dwordx4 v[130:131], off
.Lg2_181:
	ds_read_b128 v[168:171], v162 offset:1024
	ds_read_b128 v[172:175], v163 offset:1024
	ds_read_b128 v[176:179], v200 offset:1024
	ds_read_b128 v[180:183], v201 offset:1024
	s_waitcnt lgkmcnt(4)
	v_mfma_f32_16x16x32_bf16 v[60:63], v[184:187], v[240:243], v[60:63]
	v_mfma_f32_16x16x32_bf16 v[44:47], v[184:187], v[244:247], v[44:47]
	v_mfma_f32_16x16x32_bf16 v[16:19], v[184:187], v[248:251], v[16:19]
	v_mfma_f32_16x16x32_bf16 v[36:39], v[184:187], v[252:255], v[36:39]
	ds_read_b128 v[184:187], v161 offset:33792
	v_mfma_f32_16x16x32_bf16 v[56:59], v[188:191], v[240:243], v[56:59]
	v_mfma_f32_16x16x32_bf16 v[40:43], v[188:191], v[244:247], v[40:43]
	v_mfma_f32_16x16x32_bf16 v[12:15], v[188:191], v[248:251], v[12:15]
	v_mfma_f32_16x16x32_bf16 v[28:31], v[188:191], v[252:255], v[28:31]
	ds_read_b128 v[188:191], v161 offset:35840
	v_mfma_f32_16x16x32_bf16 v[52:55], v[192:195], v[240:243], v[52:55]
	v_mfma_f32_16x16x32_bf16 v[32:35], v[192:195], v[244:247], v[32:35]
	v_mfma_f32_16x16x32_bf16 v[4:7], v[192:195], v[248:251], v[4:7]
	v_mfma_f32_16x16x32_bf16 v[20:23], v[192:195], v[252:255], v[20:23]
	ds_read_b128 v[192:195], v161 offset:37888
	v_mfma_f32_16x16x32_bf16 v[48:51], v[196:199], v[240:243], v[48:51]
	v_mfma_f32_16x16x32_bf16 v[24:27], v[196:199], v[244:247], v[24:27]
	v_mfma_f32_16x16x32_bf16 v[0:3], v[196:199], v[248:251], v[0:3]
	v_mfma_f32_16x16x32_bf16 v[8:11], v[196:199], v[252:255], v[8:11]
	ds_read_b128 v[196:199], v161 offset:39936
	s_waitcnt lgkmcnt(3)
	v_mfma_f32_16x16x32_bf16 v[124:127], v[184:187], v[168:171], v[124:127]
	v_mfma_f32_16x16x32_bf16 v[108:111], v[184:187], v[172:175], v[108:111]
	v_mfma_f32_16x16x32_bf16 v[92:95], v[184:187], v[176:179], v[92:95]
	v_mfma_f32_16x16x32_bf16 v[76:79], v[184:187], v[180:183], v[76:79]
	ds_read_b128 v[240:243], v202 offset:1024
	ds_read_b128 v[244:247], v203 offset:1024
	s_waitcnt lgkmcnt(4)
	v_mfma_f32_16x16x32_bf16 v[120:123], v[188:191], v[168:171], v[120:123]
	v_mfma_f32_16x16x32_bf16 v[104:107], v[188:191], v[172:175], v[104:107]
	v_mfma_f32_16x16x32_bf16 v[88:91], v[188:191], v[176:179], v[88:91]
	v_mfma_f32_16x16x32_bf16 v[72:75], v[188:191], v[180:183], v[72:75]
	ds_read_b128 v[248:251], v204 offset:1024
	ds_read_b128 v[252:255], v205 offset:1024
	s_waitcnt lgkmcnt(5)
	v_mfma_f32_16x16x32_bf16 v[116:119], v[192:195], v[168:171], v[116:119]
	v_mfma_f32_16x16x32_bf16 v[100:103], v[192:195], v[172:175], v[100:103]
	v_mfma_f32_16x16x32_bf16 v[84:87], v[192:195], v[176:179], v[84:87]
	v_mfma_f32_16x16x32_bf16 v[68:71], v[192:195], v[180:183], v[68:71]
	s_waitcnt lgkmcnt(4)
	v_mfma_f32_16x16x32_bf16 v[112:115], v[196:199], v[168:171], v[112:115]
	v_mfma_f32_16x16x32_bf16 v[96:99], v[196:199], v[172:175], v[96:99]
	v_mfma_f32_16x16x32_bf16 v[80:83], v[196:199], v[176:179], v[80:83]
	v_mfma_f32_16x16x32_bf16 v[64:67], v[196:199], v[180:183], v[64:67]
	s_waitcnt vmcnt(0) lgkmcnt(0)
	s_barrier
	s_add_i32 s101, s100, s27
	s_cmpk_eq_i32 s4, 0x700
	s_cbranch_scc1 .Lg4n_181
	v_mfma_f32_16x16x32_bf16 v[60:63], v[184:187], v[240:243], v[60:63]
	v_mfma_f32_16x16x32_bf16 v[44:47], v[184:187], v[244:247], v[44:47]
	v_mfma_f32_16x16x32_bf16 v[16:19], v[184:187], v[248:251], v[16:19]
	v_mfma_f32_16x16x32_bf16 v[36:39], v[184:187], v[252:255], v[36:39]
	v_add3_u32 v161, s28, v151, v152
	ds_read_b128 v[184:187], v161 offset:32768
	v_add3_u32 v162, s28, v151, v153
	v_add3_u32 v163, s28, v154, v134
	v_add3_u32 v200, s28, v154, v155
	v_add3_u32 v201, s28, v154, v156
	ds_read_b128 v[168:171], v162
	ds_read_b128 v[172:175], v163
	ds_read_b128 v[176:179], v200
	ds_read_b128 v[180:183], v201
	s_mov_b32 m0, s101
	v_lshl_add_u64 v[148:149], v[148:149], 0, s[98:99]
	global_load_lds_dwordx4 v[148:149], off
	v_mfma_f32_16x16x32_bf16 v[56:59], v[188:191], v[240:243], v[56:59]
	v_mfma_f32_16x16x32_bf16 v[40:43], v[188:191], v[244:247], v[40:43]
	v_mfma_f32_16x16x32_bf16 v[12:15], v[188:191], v[248:251], v[12:15]
	v_mfma_f32_16x16x32_bf16 v[28:31], v[188:191], v[252:255], v[28:31]
	ds_read_b128 v[188:191], v161 offset:34816
	v_add3_u32 v202, s28, v154, v157
	v_add3_u32 v203, s28, v154, v158
	v_add3_u32 v204, s28, v154, v159
	v_add3_u32 v205, s28, v154, v160
	s_add_i32 m0, s101, 0x8000
	v_lshl_add_u64 v[140:141], v[140:141], 0, s[98:99]
	global_load_lds_dwordx4 v[140:141], off
	v_mfma_f32_16x16x32_bf16 v[52:55], v[192:195], v[240:243], v[52:55]
	v_mfma_f32_16x16x32_bf16 v[32:35], v[192:195], v[244:247], v[32:35]
	v_mfma_f32_16x16x32_bf16 v[4:7], v[192:195], v[248:251], v[4:7]
	v_mfma_f32_16x16x32_bf16 v[20:23], v[192:195], v[252:255], v[20:23]
	ds_read_b128 v[192:195], v161 offset:36864
	s_add_i32 m0, s101, 0x2000
	v_lshl_add_u64 v[146:147], v[146:147], 0, s[98:99]
	global_load_lds_dwordx4 v[146:147], off
	v_mfma_f32_16x16x32_bf16 v[48:51], v[196:199], v[240:243], v[48:51]
	v_mfma_f32_16x16x32_bf16 v[24:27], v[196:199], v[244:247], v[24:27]
	v_mfma_f32_16x16x32_bf16 v[0:3], v[196:199], v[248:251], v[0:3]
	v_mfma_f32_16x16x32_bf16 v[8:11], v[196:199], v[252:255], v[8:11]
	ds_read_b128 v[196:199], v161 offset:38912
	s_add_i32 m0, s101, 0xa000
	v_lshl_add_u64 v[138:139], v[138:139], 0, s[98:99]
	global_load_lds_dwordx4 v[138:139], off

.Lg1n_181:
	s_waitcnt lgkmcnt(3)
	v_mfma_f32_16x16x32_bf16 v[124:127], v[184:187], v[168:171], v[124:127]
	v_mfma_f32_16x16x32_bf16 v[108:111], v[184:187], v[172:175], v[108:111]
	v_mfma_f32_16x16x32_bf16 v[92:95], v[184:187], v[176:179], v[92:95]
	v_mfma_f32_16x16x32_bf16 v[76:79], v[184:187], v[180:183], v[76:79]
	ds_read_b128 v[240:243], v202
	ds_read_b128 v[244:247], v203
	s_waitcnt lgkmcnt(4)
	v_mfma_f32_16x16x32_bf16 v[120:123], v[188:191], v[168:171], v[120:123]
	v_mfma_f32_16x16x32_bf16 v[104:107], v[188:191], v[172:175], v[104:107]
	v_mfma_f32_16x16x32_bf16 v[88:91], v[188:191], v[176:179], v[88:91]
	v_mfma_f32_16x16x32_bf16 v[72:75], v[188:191], v[180:183], v[72:75]
	ds_read_b128 v[248:251], v204
	ds_read_b128 v[252:255], v205
	s_waitcnt lgkmcnt(5)
	v_mfma_f32_16x16x32_bf16 v[116:119], v[192:195], v[168:171], v[116:119]
	v_mfma_f32_16x16x32_bf16 v[100:103], v[192:195], v[172:175], v[100:103]
	v_mfma_f32_16x16x32_bf16 v[84:87], v[192:195], v[176:179], v[84:87]
	v_mfma_f32_16x16x32_bf16 v[68:71], v[192:195], v[180:183], v[68:71]
	s_waitcnt lgkmcnt(4)
	v_mfma_f32_16x16x32_bf16 v[112:115], v[196:199], v[168:171], v[112:115]
	v_mfma_f32_16x16x32_bf16 v[96:99], v[196:199], v[172:175], v[96:99]
	v_mfma_f32_16x16x32_bf16 v[80:83], v[196:199], v[176:179], v[80:83]
	v_mfma_f32_16x16x32_bf16 v[64:67], v[196:199], v[180:183], v[64:67]
	s_branch .Lg2_181
.Lg4n_181:
	v_mfma_f32_16x16x32_bf16 v[60:63], v[184:187], v[240:243], v[60:63]
	v_mfma_f32_16x16x32_bf16 v[44:47], v[184:187], v[244:247], v[44:47]
	v_mfma_f32_16x16x32_bf16 v[16:19], v[184:187], v[248:251], v[16:19]
	v_mfma_f32_16x16x32_bf16 v[36:39], v[184:187], v[252:255], v[36:39]
	v_add3_u32 v161, s28, v151, v152
	ds_read_b128 v[184:187], v161 offset:32768
	v_add3_u32 v162, s28, v151, v153
	v_add3_u32 v163, s28, v154, v134
	v_add3_u32 v200, s28, v154, v155
	v_add3_u32 v201, s28, v154, v156
	ds_read_b128 v[168:171], v162
	ds_read_b128 v[172:175], v163
	ds_read_b128 v[176:179], v200
	ds_read_b128 v[180:183], v201
	v_mfma_f32_16x16x32_bf16 v[56:59], v[188:191], v[240:243], v[56:59]
	v_mfma_f32_16x16x32_bf16 v[40:43], v[188:191], v[244:247], v[40:43]
	v_mfma_f32_16x16x32_bf16 v[12:15], v[188:191], v[248:251], v[12:15]
	v_mfma_f32_16x16x32_bf16 v[28:31], v[188:191], v[252:255], v[28:31]
	ds_read_b128 v[188:191], v161 offset:34816
	v_add3_u32 v202, s28, v154, v157
	v_add3_u32 v203, s28, v154, v158
	v_add3_u32 v204, s28, v154, v159
	v_add3_u32 v205, s28, v154, v160
	v_mfma_f32_16x16x32_bf16 v[52:55], v[192:195], v[240:243], v[52:55]
	v_mfma_f32_16x16x32_bf16 v[32:35], v[192:195], v[244:247], v[32:35]
	v_mfma_f32_16x16x32_bf16 v[4:7], v[192:195], v[248:251], v[4:7]
	v_mfma_f32_16x16x32_bf16 v[20:23], v[192:195], v[252:255], v[20:23]
	ds_read_b128 v[192:195], v161 offset:36864
	v_mfma_f32_16x16x32_bf16 v[48:51], v[196:199], v[240:243], v[48:51]
	v_mfma_f32_16x16x32_bf16 v[24:27], v[196:199], v[244:247], v[24:27]
	v_mfma_f32_16x16x32_bf16 v[0:3], v[196:199], v[248:251], v[0:3]
	v_mfma_f32_16x16x32_bf16 v[8:11], v[196:199], v[252:255], v[8:11]
	ds_read_b128 v[196:199], v161 offset:38912
	s_branch .Ltl_181
.Lex_181:
	s_waitcnt lgkmcnt(0)
	s_add_i32 s4, 0, 0x10000
	v_add3_u32 v130, s4, v154, v160
	v_add3_u32 v131, s4, v154, v159
	v_add3_u32 v212, s4, v154, v158
	v_add3_u32 v213, s4, v154, v157
	v_add3_u32 v214, s4, v154, v156
	v_add3_u32 v215, s4, v154, v155
	v_add3_u32 v134, s4, v154, v134
	v_add3_u32 v216, s4, v151, v153
	v_add3_u32 v217, s52, v151, v152
	ds_read_b128 v[136:139], v130
	ds_read_b128 v[140:143], v131
	ds_read_b128 v[144:147], v212
	ds_read_b128 v[158:161], v213
	ds_read_b128 v[168:171], v214
	ds_read_b128 v[172:175], v215
	ds_read_b128 v[154:157], v134
	ds_read_b128 v[176:179], v216
	ds_read_b128 v[148:151], v217
	s_waitcnt lgkmcnt(0)
	v_mfma_f32_16x16x32_bf16 v[16:19], v[148:151], v[140:143], v[16:19]
	v_mfma_f32_16x16x32_bf16 v[180:183], v[148:151], v[136:139], v[36:39]
	s_nop 2
	ds_read_b128 v[36:39], v217 offset:2048
	s_waitcnt lgkmcnt(0)
	v_mfma_f32_16x16x32_bf16 v[12:15], v[36:39], v[140:143], v[12:15]
	v_mfma_f32_16x16x32_bf16 v[184:187], v[36:39], v[136:139], v[28:31]
	s_nop 2
	ds_read_b128 v[28:31], v217 offset:4096
	s_waitcnt lgkmcnt(0)
	v_mfma_f32_16x16x32_bf16 v[4:7], v[28:31], v[140:143], v[4:7]
	v_mfma_f32_16x16x32_bf16 v[92:95], v[148:151], v[172:175], v[92:95]
	v_mfma_f32_16x16x32_bf16 v[76:79], v[148:151], v[168:171], v[76:79]
	v_mfma_f32_16x16x32_bf16 v[60:63], v[148:151], v[158:161], v[60:63]
	v_mfma_f32_16x16x32_bf16 v[204:207], v[36:39], v[172:175], v[88:91]
	v_mfma_f32_16x16x32_bf16 v[208:211], v[36:39], v[168:171], v[72:75]
	v_mfma_f32_16x16x32_bf16 v[72:75], v[148:151], v[176:179], v[124:127]
	v_mfma_f32_16x16x32_bf16 v[188:191], v[28:31], v[136:139], v[20:23]
	v_mfma_f32_16x16x32_bf16 v[84:87], v[28:31], v[172:175], v[84:87]
	v_mfma_f32_16x16x32_bf16 v[68:71], v[28:31], v[168:171], v[68:71]
	v_mfma_f32_16x16x32_bf16 v[88:91], v[148:151], v[154:157], v[108:111]
	ds_read_b128 v[20:23], v217 offset:6144
	s_waitcnt lgkmcnt(0)
	v_mfma_f32_16x16x32_bf16 v[136:139], v[20:23], v[136:139], v[8:11]
	v_mfma_f32_16x16x32_bf16 v[8:11], v[20:23], v[176:179], v[112:115]
	v_mfma_f32_16x16x32_bf16 v[192:195], v[20:23], v[154:157], v[96:99]
	v_mfma_f32_16x16x32_bf16 v[196:199], v[20:23], v[172:175], v[80:83]
	v_mfma_f32_16x16x32_bf16 v[200:203], v[20:23], v[168:171], v[64:67]
	v_mfma_f32_16x16x32_bf16 v[64:67], v[28:31], v[176:179], v[116:119]
	v_mfma_f32_16x16x32_bf16 v[80:83], v[28:31], v[154:157], v[100:103]
	v_mfma_f32_16x16x32_bf16 v[96:99], v[36:39], v[176:179], v[120:123]
	v_mfma_f32_16x16x32_bf16 v[100:103], v[36:39], v[154:157], v[104:107]
	v_mfma_f32_16x16x32_bf16 v[152:155], v[36:39], v[158:161], v[56:59]
	v_mfma_f32_16x16x32_bf16 v[52:55], v[28:31], v[158:161], v[52:55]
	v_mfma_f32_16x16x32_bf16 v[156:159], v[20:23], v[158:161], v[48:51]
	v_mfma_f32_16x16x32_bf16 v[44:47], v[148:151], v[144:147], v[44:47]
	v_mfma_f32_16x16x32_bf16 v[160:163], v[36:39], v[144:147], v[40:43]
	v_mfma_f32_16x16x32_bf16 v[168:171], v[28:31], v[144:147], v[32:35]
	v_mfma_f32_16x16x32_bf16 v[24:27], v[20:23], v[144:147], v[24:27]
	v_mfma_f32_16x16x32_bf16 v[0:3], v[20:23], v[140:143], v[0:3]
	ds_read_b128 v[140:143], v217 offset:1024
	ds_read_b128 v[144:147], v217 offset:3072
	ds_read_b128 v[148:151], v217 offset:5120
	ds_read_b128 v[172:175], v217 offset:7168
	ds_read_b128 v[20:23], v216 offset:1024
	ds_read_b128 v[28:31], v134 offset:1024
	ds_read_b128 v[32:35], v215 offset:1024
	ds_read_b128 v[36:39], v214 offset:1024
	s_waitcnt lgkmcnt(3)
	v_mfma_f32_16x16x32_bf16 v[108:111], v[140:143], v[20:23], v[72:75]
	v_mfma_f32_16x16x32_bf16 v[104:107], v[144:147], v[20:23], v[96:99]
	v_mfma_f32_16x16x32_bf16 v[116:119], v[148:151], v[20:23], v[64:67]
	v_mfma_f32_16x16x32_bf16 v[112:115], v[172:175], v[20:23], v[8:11]
	s_nop 2
	ds_read_b128 v[8:11], v213 offset:1024
	s_waitcnt lgkmcnt(3)
	v_mfma_f32_16x16x32_bf16 v[120:123], v[140:143], v[28:31], v[88:91]
	v_mfma_f32_16x16x32_bf16 v[96:99], v[144:147], v[28:31], v[100:103]
	v_mfma_f32_16x16x32_bf16 v[124:127], v[148:151], v[28:31], v[80:83]
	v_mfma_f32_16x16x32_bf16 v[100:103], v[172:175], v[28:31], v[192:195]
	ds_read_b128 v[20:23], v212 offset:1024
	s_waitcnt lgkmcnt(3)
	v_mfma_f32_16x16x32_bf16 v[88:91], v[140:143], v[32:35], v[92:95]
	v_mfma_f32_16x16x32_bf16 v[80:83], v[144:147], v[32:35], v[204:207]
	v_mfma_f32_16x16x32_bf16 v[92:95], v[148:151], v[32:35], v[84:87]
	v_mfma_f32_16x16x32_bf16 v[84:87], v[172:175], v[32:35], v[196:199]
	ds_read_b128 v[176:179], v131 offset:1024
	s_waitcnt lgkmcnt(3)
	v_mfma_f32_16x16x32_bf16 v[72:75], v[140:143], v[36:39], v[76:79]
	v_mfma_f32_16x16x32_bf16 v[64:67], v[144:147], v[36:39], v[208:211]
	v_mfma_f32_16x16x32_bf16 v[76:79], v[148:151], v[36:39], v[68:71]
	v_mfma_f32_16x16x32_bf16 v[68:71], v[172:175], v[36:39], v[200:203]
	ds_read_b128 v[192:195], v130 offset:1024
	s_waitcnt lgkmcnt(3)
	v_mfma_f32_16x16x32_bf16 v[56:59], v[140:143], v[8:11], v[60:63]
	v_mfma_f32_16x16x32_bf16 v[48:51], v[144:147], v[8:11], v[152:155]
	v_mfma_f32_16x16x32_bf16 v[60:63], v[148:151], v[8:11], v[52:55]
	v_mfma_f32_16x16x32_bf16 v[52:55], v[172:175], v[8:11], v[156:159]
	s_waitcnt lgkmcnt(2)
	v_mfma_f32_16x16x32_bf16 v[40:43], v[140:143], v[20:23], v[44:47]
	v_mfma_f32_16x16x32_bf16 v[32:35], v[144:147], v[20:23], v[160:163]
	v_mfma_f32_16x16x32_bf16 v[44:47], v[148:151], v[20:23], v[168:171]
	v_mfma_f32_16x16x32_bf16 v[36:39], v[172:175], v[20:23], v[24:27]
	s_waitcnt lgkmcnt(1)
	v_mfma_f32_16x16x32_bf16 v[24:27], v[140:143], v[176:179], v[16:19]
	v_mfma_f32_16x16x32_bf16 v[16:19], v[144:147], v[176:179], v[12:15]
	v_mfma_f32_16x16x32_bf16 v[28:31], v[148:151], v[176:179], v[4:7]
	v_mfma_f32_16x16x32_bf16 v[20:23], v[172:175], v[176:179], v[0:3]
	s_waitcnt lgkmcnt(0)
	v_mfma_f32_16x16x32_bf16 v[8:11], v[140:143], v[192:195], v[180:183]
	v_mfma_f32_16x16x32_bf16 v[0:3], v[144:147], v[192:195], v[184:187]
	v_mfma_f32_16x16x32_bf16 v[12:15], v[148:151], v[192:195], v[188:191]
	v_mfma_f32_16x16x32_bf16 v[4:7], v[172:175], v[192:195], v[136:139]
	v_mov_b32_e32 v147, v132
	s_waitcnt vmcnt(0)
	s_barrier
	s_lshl_b32 s26, s26, 8
	v_and_b32_e32 v146, 15, v147
	v_ashrrev_i32_e32 v130, 1, v147
	v_bfe_u32 v148, v147, 4, 2
	v_and_b32_e32 v149, 0xffffff80, v130
	v_or_b32_e32 v130, s66, v146
	v_add_u32_e32 v150, v130, v149
	v_and_b32_e32 v130, 64, v147
	v_lshlrev_b32_e32 v134, 5, v148
	v_lshl_add_u64 v[128:129], v[128:129], 0, v[134:135]
	v_lshrrev_b32_e32 v151, 6, v150
	v_cmp_eq_u32_e32 vcc, 0, v130
	v_lshl_add_u64 v[136:137], v[128:129], 0, s[14:15]
	v_or_b32_e32 v130, 48, v146
	v_cndmask_b32_e32 v128, v146, v151, vcc
	v_lshlrev_b32_e32 v128, 8, v128
	v_and_b32_e32 v134, 0x3f00, v128
	v_lshl_add_u64 v[128:129], v[136:137], 0, v[134:135]
	flat_load_dwordx4 v[138:141], v[128:129]
	flat_load_dwordx4 v[142:145], v[128:129] offset:16
	flat_load_dwordx4 v[152:155], v[128:129] offset:128
	flat_load_dwordx4 v[156:159], v[128:129] offset:144
	v_or_b32_e32 v128, 16, v146
	v_cndmask_b32_e32 v128, v128, v151, vcc
	v_lshlrev_b32_e32 v128, 8, v128
	v_and_b32_e32 v134, 0x3f00, v128
	v_lshl_add_u64 v[128:129], v[136:137], 0, v[134:135]
	flat_load_dwordx4 v[160:163], v[128:129]
	flat_load_dwordx4 v[168:171], v[128:129] offset:16
	flat_load_dwordx4 v[172:175], v[128:129] offset:128
	flat_load_dwordx4 v[176:179], v[128:129] offset:144
	v_or_b32_e32 v128, 32, v146
	v_cndmask_b32_e32 v128, v128, v151, vcc
	v_lshlrev_b32_e32 v128, 8, v128
	v_and_b32_e32 v134, 0x3f00, v128
	v_lshl_add_u64 v[128:129], v[136:137], 0, v[134:135]
	flat_load_dwordx4 v[180:183], v[128:129]
	flat_load_dwordx4 v[184:187], v[128:129] offset:16
	flat_load_dwordx4 v[188:191], v[128:129] offset:128
	flat_load_dwordx4 v[192:195], v[128:129] offset:144
	v_cndmask_b32_e32 v130, v130, v151, vcc
	v_lshlrev_b32_e32 v130, 8, v130
	v_and_b32_e32 v134, 0x3f00, v130
	v_lshl_add_u64 v[204:205], v[136:137], 0, v[134:135]
	flat_load_dwordx4 v[196:199], v[204:205]
	flat_load_dwordx4 v[200:203], v[204:205] offset:16
	flat_load_dwordx4 v[128:131], v[204:205] offset:128
	v_or_b32_e32 v134, 1, v151
	v_cndmask_b32_e32 v134, v146, v134, vcc
	v_lshlrev_b32_e32 v134, 8, v134
	v_and_b32_e32 v134, 0x3f00, v134
	s_ashr_i32 s27, s26, 31
	s_waitcnt vmcnt(0) lgkmcnt(0)
	v_mov_b32_e32 v206, v139
	v_mov_b32_e32 v207, v141
	v_mov_b32_e32 v139, v140
	v_mov_b32_e32 v140, v143
	v_mov_b32_e32 v141, v145
	v_mov_b32_e32 v143, v144
	v_mov_b32_e32 v144, v153
	v_mov_b32_e32 v145, v155
	v_mov_b32_e32 v153, v154
	v_mov_b32_e32 v154, v157
	v_mov_b32_e32 v155, v159
	v_mov_b32_e32 v157, v158
	v_pk_mul_f32 v[158:159], v[108:109], v[206:207]
	v_pk_mul_f32 v[206:207], v[116:117], v[206:207]
	v_pk_mul_f32 v[208:209], v[110:111], v[140:141]
	v_pk_mul_f32 v[210:211], v[118:119], v[140:141]
	v_pk_mul_f32 v[214:215], v[112:113], v[144:145]
	v_pk_mul_f32 v[216:217], v[106:107], v[154:155]
	v_pk_mul_f32 v[154:155], v[114:115], v[154:155]
	v_mov_b32_e32 v218, v161
	v_mov_b32_e32 v219, v163
	v_mov_b32_e32 v161, v162
	v_mov_b32_e32 v162, v169
	v_mov_b32_e32 v163, v171
	v_pk_mul_f32 v[212:213], v[104:105], v[144:145]
	v_mov_b32_e32 v169, v170
	v_pk_fma_f32 v[116:117], v[116:117], v[138:139], v[158:159]
	v_pk_fma_f32 v[140:141], v[108:109], v[138:139], v[206:207] neg_lo:[0,0,1] neg_hi:[0,0,1]
	v_pk_fma_f32 v[118:119], v[118:119], v[142:143], v[208:209]
	v_pk_fma_f32 v[144:145], v[110:111], v[142:143], v[210:211] neg_lo:[0,0,1] neg_hi:[0,0,1]
	v_pk_fma_f32 v[138:139], v[104:105], v[152:153], v[214:215] neg_lo:[0,0,1] neg_hi:[0,0,1]
	v_pk_fma_f32 v[142:143], v[106:107], v[156:157], v[154:155] neg_lo:[0,0,1] neg_hi:[0,0,1]
	v_pk_mul_f32 v[104:105], v[120:121], v[218:219]
	v_pk_mul_f32 v[106:107], v[124:125], v[218:219]
	v_pk_mul_f32 v[108:109], v[122:123], v[162:163]
	v_pk_fma_f32 v[110:111], v[112:113], v[152:153], v[212:213]
	v_pk_fma_f32 v[112:113], v[114:115], v[156:157], v[216:217]
	v_pk_mul_f32 v[152:153], v[126:127], v[162:163]
	v_pk_fma_f32 v[104:105], v[124:125], v[160:161], v[104:105]
	v_pk_fma_f32 v[114:115], v[120:121], v[160:161], v[106:107] neg_lo:[0,0,1] neg_hi:[0,0,1]
	v_pk_fma_f32 v[106:107], v[126:127], v[168:169], v[108:109]
	flat_load_dwordx4 v[124:127], v[204:205] offset:144
	v_pk_fma_f32 v[120:121], v[122:123], v[168:169], v[152:153] neg_lo:[0,0,1] neg_hi:[0,0,1]
	v_lshl_add_u64 v[168:169], v[136:137], 0, v[134:135]
	flat_load_dwordx4 v[152:155], v[168:169]
	flat_load_dwordx4 v[156:159], v[168:169] offset:16
	v_mov_b32_e32 v122, v173
	v_mov_b32_e32 v123, v175
	v_pk_mul_f32 v[108:109], v[96:97], v[122:123]
	v_mov_b32_e32 v173, v174
	v_pk_fma_f32 v[108:109], v[100:101], v[172:173], v[108:109]
	v_pk_mul_f32 v[100:101], v[100:101], v[122:123]
	v_mov_b32_e32 v122, v177
	v_mov_b32_e32 v123, v179
	v_pk_fma_f32 v[96:97], v[96:97], v[172:173], v[100:101] neg_lo:[0,0,1] neg_hi:[0,0,1]
	v_pk_mul_f32 v[100:101], v[98:99], v[122:123]
	v_mov_b32_e32 v177, v178
	v_pk_fma_f32 v[100:101], v[102:103], v[176:177], v[100:101]
	v_pk_mul_f32 v[102:103], v[102:103], v[122:123]
	v_mov_b32_e32 v122, v181
	v_mov_b32_e32 v123, v183
	v_pk_fma_f32 v[102:103], v[98:99], v[176:177], v[102:103] neg_lo:[0,0,1] neg_hi:[0,0,1]
	v_pk_mul_f32 v[98:99], v[88:89], v[122:123]
	v_mov_b32_e32 v181, v182
	v_pk_fma_f32 v[98:99], v[92:93], v[180:181], v[98:99]
	v_pk_mul_f32 v[92:93], v[92:93], v[122:123]
	v_mov_b32_e32 v122, v185
	v_mov_b32_e32 v123, v187
	v_pk_fma_f32 v[92:93], v[88:89], v[180:181], v[92:93] neg_lo:[0,0,1] neg_hi:[0,0,1]
	v_pk_mul_f32 v[88:89], v[90:91], v[122:123]
	v_mov_b32_e32 v185, v186
	v_pk_fma_f32 v[88:89], v[94:95], v[184:185], v[88:89]
	v_pk_mul_f32 v[94:95], v[94:95], v[122:123]
	v_mov_b32_e32 v122, v189
	v_mov_b32_e32 v123, v191
	v_pk_fma_f32 v[94:95], v[90:91], v[184:185], v[94:95] neg_lo:[0,0,1] neg_hi:[0,0,1]
	v_pk_mul_f32 v[90:91], v[80:81], v[122:123]
	v_mov_b32_e32 v189, v190
	v_pk_fma_f32 v[90:91], v[84:85], v[188:189], v[90:91]
	v_pk_mul_f32 v[84:85], v[84:85], v[122:123]
	v_mov_b32_e32 v122, v193
	v_mov_b32_e32 v123, v195
	v_pk_fma_f32 v[84:85], v[80:81], v[188:189], v[84:85] neg_lo:[0,0,1] neg_hi:[0,0,1]
	v_pk_mul_f32 v[80:81], v[82:83], v[122:123]
	v_mov_b32_e32 v193, v194
	v_pk_fma_f32 v[80:81], v[86:87], v[192:193], v[80:81]
	v_pk_mul_f32 v[86:87], v[86:87], v[122:123]
	v_or_b32_e32 v122, 0x50, v150
	flat_load_dwordx4 v[160:163], v[168:169] offset:128
	v_lshrrev_b32_e32 v123, 6, v122
	v_cndmask_b32_e32 v122, v122, v123, vcc
	v_lshlrev_b32_e32 v122, 8, v122
	flat_load_dwordx4 v[168:171], v[168:169] offset:144
	v_and_b32_e32 v134, 0x3f00, v122
	v_lshl_add_u64 v[122:123], v[136:137], 0, v[134:135]
	v_mov_b32_e32 v180, v197
	v_mov_b32_e32 v181, v199
	flat_load_dwordx4 v[172:175], v[122:123]
	v_pk_fma_f32 v[86:87], v[82:83], v[192:193], v[86:87] neg_lo:[0,0,1] neg_hi:[0,0,1]
	v_pk_mul_f32 v[82:83], v[72:73], v[180:181]
	v_mov_b32_e32 v197, v198
	v_pk_fma_f32 v[82:83], v[76:77], v[196:197], v[82:83]
	v_pk_mul_f32 v[76:77], v[76:77], v[180:181]
	v_mov_b32_e32 v184, v201
	v_mov_b32_e32 v185, v203
	flat_load_dwordx4 v[176:179], v[122:123] offset:16
	v_pk_fma_f32 v[72:73], v[72:73], v[196:197], v[76:77] neg_lo:[0,0,1] neg_hi:[0,0,1]
	v_pk_mul_f32 v[76:77], v[74:75], v[184:185]
	v_mov_b32_e32 v201, v202
	flat_load_dwordx4 v[180:183], v[122:123] offset:128
	v_pk_fma_f32 v[76:77], v[78:79], v[200:201], v[76:77]
	v_pk_mul_f32 v[78:79], v[78:79], v[184:185]
	flat_load_dwordx4 v[184:187], v[122:123] offset:144
	v_or_b32_e32 v122, 0x60, v150
	v_lshrrev_b32_e32 v123, 6, v122
	v_cndmask_b32_e32 v122, v122, v123, vcc
	v_lshlrev_b32_e32 v122, 8, v122
	v_and_b32_e32 v134, 0x3f00, v122
	v_mov_b32_e32 v192, v129
	v_mov_b32_e32 v193, v131
	v_lshl_add_u64 v[194:195], v[136:137], 0, v[134:135]
	v_pk_fma_f32 v[74:75], v[74:75], v[200:201], v[78:79] neg_lo:[0,0,1] neg_hi:[0,0,1]
	v_pk_mul_f32 v[78:79], v[64:65], v[192:193]
	flat_load_dwordx4 v[188:191], v[194:195]
	v_mov_b32_e32 v129, v130
	v_pk_fma_f32 v[78:79], v[68:69], v[128:129], v[78:79]
	v_pk_mul_f32 v[68:69], v[68:69], v[192:193]
	v_cvt_pk_bf16_f32 v96, v96, v97
	v_pk_fma_f32 v[68:69], v[64:65], v[128:129], v[68:69] neg_lo:[0,0,1] neg_hi:[0,0,1]
	s_waitcnt vmcnt(0) lgkmcnt(0)
	v_mov_b32_e32 v64, v125
	v_mov_b32_e32 v65, v127
	flat_load_dwordx4 v[128:131], v[194:195] offset:16
	v_pk_mul_f32 v[122:123], v[66:67], v[64:65]
	v_mov_b32_e32 v125, v126
	v_pk_mul_f32 v[64:65], v[70:71], v[64:65]
	v_pk_fma_f32 v[122:123], v[70:71], v[124:125], v[122:123]
	v_pk_fma_f32 v[66:67], v[66:67], v[124:125], v[64:65] neg_lo:[0,0,1] neg_hi:[0,0,1]
	flat_load_dwordx4 v[124:127], v[194:195] offset:128
	v_mov_b32_e32 v70, v153
	v_mov_b32_e32 v71, v155
	v_pk_mul_f32 v[64:65], v[56:57], v[70:71]
	v_mov_b32_e32 v153, v154
	v_pk_fma_f32 v[64:65], v[60:61], v[152:153], v[64:65]
	v_pk_mul_f32 v[60:61], v[60:61], v[70:71]
	v_mov_b32_e32 v70, v157
	v_pk_fma_f32 v[56:57], v[56:57], v[152:153], v[60:61] neg_lo:[0,0,1] neg_hi:[0,0,1]
	v_or_b32_e32 v60, 0x70, v150
	v_lshrrev_b32_e32 v61, 6, v60
	v_cndmask_b32_e32 v60, v60, v61, vcc
	v_lshlrev_b32_e32 v60, 8, v60
	flat_load_dwordx4 v[152:155], v[194:195] offset:144
	v_and_b32_e32 v134, 0x3f00, v60
	v_lshl_add_u64 v[136:137], v[136:137], 0, v[134:135]
	flat_load_dwordx4 v[192:195], v[136:137]
	v_mov_b32_e32 v71, v159
	v_pk_mul_f32 v[60:61], v[58:59], v[70:71]
	v_mov_b32_e32 v157, v158
	flat_load_dwordx4 v[196:199], v[136:137] offset:16
	v_pk_fma_f32 v[60:61], v[62:63], v[156:157], v[60:61]
	v_pk_mul_f32 v[62:63], v[62:63], v[70:71]
	v_cvt_pk_bf16_f32 v97, v102, v103
	v_pk_fma_f32 v[62:63], v[58:59], v[156:157], v[62:63] neg_lo:[0,0,1] neg_hi:[0,0,1]
	flat_load_dwordx4 v[156:159], v[136:137] offset:128
	v_cvt_pk_bf16_f32 v84, v84, v85
	v_cvt_pk_bf16_f32 v85, v86, v87
	v_cvt_pk_bf16_f32 v110, v110, v111
	v_cvt_pk_bf16_f32 v111, v112, v113
	v_cvt_pk_bf16_f32 v68, v68, v69
	v_mov_b32_e32 v70, v161
	v_mov_b32_e32 v71, v163
	v_pk_mul_f32 v[58:59], v[48:49], v[70:71]
	v_mov_b32_e32 v161, v162
	v_pk_fma_f32 v[58:59], v[52:53], v[160:161], v[58:59]
	v_pk_mul_f32 v[52:53], v[52:53], v[70:71]
	v_cvt_pk_bf16_f32 v69, v66, v67
	v_pk_fma_f32 v[70:71], v[48:49], v[160:161], v[52:53] neg_lo:[0,0,1] neg_hi:[0,0,1]
	v_mov_b32_e32 v48, v169
	v_mov_b32_e32 v49, v171
	v_pk_mul_f32 v[52:53], v[50:51], v[48:49]
	v_mov_b32_e32 v169, v170
	v_pk_fma_f32 v[52:53], v[54:55], v[168:169], v[52:53]
	v_pk_mul_f32 v[48:49], v[54:55], v[48:49]
	v_mov_b32_e32 v54, v173
	v_mov_b32_e32 v55, v175
	v_pk_fma_f32 v[50:51], v[50:51], v[168:169], v[48:49] neg_lo:[0,0,1] neg_hi:[0,0,1]
	v_pk_mul_f32 v[48:49], v[40:41], v[54:55]
	v_mov_b32_e32 v173, v174
	v_pk_fma_f32 v[48:49], v[44:45], v[172:173], v[48:49]
	v_pk_mul_f32 v[44:45], v[44:45], v[54:55]
	v_mov_b32_e32 v54, v177
	v_mov_b32_e32 v55, v179
	v_pk_fma_f32 v[44:45], v[40:41], v[172:173], v[44:45] neg_lo:[0,0,1] neg_hi:[0,0,1]
	v_pk_mul_f32 v[40:41], v[42:43], v[54:55]
	v_mov_b32_e32 v177, v178
	v_pk_fma_f32 v[40:41], v[46:47], v[176:177], v[40:41]
	v_pk_mul_f32 v[46:47], v[46:47], v[54:55]
	v_mov_b32_e32 v54, v181
	v_mov_b32_e32 v55, v183
	v_pk_fma_f32 v[46:47], v[42:43], v[176:177], v[46:47] neg_lo:[0,0,1] neg_hi:[0,0,1]
	v_pk_mul_f32 v[42:43], v[32:33], v[54:55]
	v_mov_b32_e32 v181, v182
	v_pk_fma_f32 v[42:43], v[36:37], v[180:181], v[42:43]
	v_pk_mul_f32 v[36:37], v[36:37], v[54:55]
	v_cvt_pk_bf16_f32 v66, v82, v83
	v_pk_fma_f32 v[54:55], v[32:33], v[180:181], v[36:37] neg_lo:[0,0,1] neg_hi:[0,0,1]
	v_mov_b32_e32 v32, v185
	v_mov_b32_e32 v33, v187
	v_pk_mul_f32 v[36:37], v[34:35], v[32:33]
	v_mov_b32_e32 v185, v186
	v_pk_fma_f32 v[36:37], v[38:39], v[184:185], v[36:37]
	v_pk_mul_f32 v[32:33], v[38:39], v[32:33]
	v_mov_b32_e32 v38, v189
	v_mov_b32_e32 v39, v191
	v_pk_fma_f32 v[34:35], v[34:35], v[184:185], v[32:33] neg_lo:[0,0,1] neg_hi:[0,0,1]
	v_pk_mul_f32 v[32:33], v[24:25], v[38:39]
	v_mov_b32_e32 v189, v190
	v_pk_fma_f32 v[32:33], v[28:29], v[188:189], v[32:33]
	v_pk_mul_f32 v[28:29], v[28:29], v[38:39]
	s_waitcnt vmcnt(0) lgkmcnt(0)
	v_mov_b32_e32 v38, v129
	v_mov_b32_e32 v39, v131
	v_pk_fma_f32 v[28:29], v[24:25], v[188:189], v[28:29] neg_lo:[0,0,1] neg_hi:[0,0,1]
	v_pk_mul_f32 v[24:25], v[26:27], v[38:39]
	v_mov_b32_e32 v129, v130
	v_pk_fma_f32 v[24:25], v[30:31], v[128:129], v[24:25]
	v_pk_mul_f32 v[30:31], v[30:31], v[38:39]
	v_mov_b32_e32 v38, v125
	v_mov_b32_e32 v39, v127
	v_pk_fma_f32 v[30:31], v[26:27], v[128:129], v[30:31] neg_lo:[0,0,1] neg_hi:[0,0,1]
	v_pk_mul_f32 v[26:27], v[16:17], v[38:39]
	v_mov_b32_e32 v125, v126
	v_pk_fma_f32 v[26:27], v[20:21], v[124:125], v[26:27]
	v_pk_mul_f32 v[20:21], v[20:21], v[38:39]
	v_add_u32_e32 v128, s66, v149
	v_pk_fma_f32 v[38:39], v[16:17], v[124:125], v[20:21] neg_lo:[0,0,1] neg_hi:[0,0,1]
	flat_load_dwordx4 v[124:127], v[136:137] offset:144
	v_mov_b32_e32 v16, v153
	v_mov_b32_e32 v17, v155
	v_pk_mul_f32 v[20:21], v[18:19], v[16:17]
	v_mov_b32_e32 v153, v154
	v_pk_fma_f32 v[20:21], v[22:23], v[152:153], v[20:21]
	v_pk_mul_f32 v[16:17], v[22:23], v[16:17]
	v_mov_b32_e32 v22, v193
	v_mov_b32_e32 v23, v195
	v_pk_fma_f32 v[18:19], v[18:19], v[152:153], v[16:17] neg_lo:[0,0,1] neg_hi:[0,0,1]
	v_pk_mul_f32 v[16:17], v[8:9], v[22:23]
	v_mov_b32_e32 v193, v194
	v_pk_fma_f32 v[16:17], v[12:13], v[192:193], v[16:17]
	v_pk_mul_f32 v[12:13], v[12:13], v[22:23]
	v_mov_b32_e32 v22, v197
	v_mov_b32_e32 v23, v199
	v_pk_fma_f32 v[12:13], v[8:9], v[192:193], v[12:13] neg_lo:[0,0,1] neg_hi:[0,0,1]
	v_pk_mul_f32 v[8:9], v[10:11], v[22:23]
	v_mov_b32_e32 v197, v198
	v_pk_fma_f32 v[8:9], v[14:15], v[196:197], v[8:9]
	v_pk_mul_f32 v[14:15], v[14:15], v[22:23]
	v_mov_b32_e32 v22, v157
	v_mov_b32_e32 v23, v159
	v_pk_fma_f32 v[10:11], v[10:11], v[196:197], v[14:15] neg_lo:[0,0,1] neg_hi:[0,0,1]
	v_pk_mul_f32 v[14:15], v[0:1], v[22:23]
	v_mov_b32_e32 v157, v158
	v_pk_fma_f32 v[14:15], v[4:5], v[156:157], v[14:15]
	v_pk_mul_f32 v[4:5], v[4:5], v[22:23]
	v_mov_b32_e32 v22, s19
	ds_read_b64 v[22:23], v22
	v_ashrrev_i32_e32 v129, 31, v128
	v_lshlrev_b64 v[128:129], 10, v[128:129]
	v_lshrrev_b32_e32 v130, 6, v147
	v_mul_u32_u24_e32 v136, 0x90, v146
	s_waitcnt lgkmcnt(0)
	v_lshl_add_u64 v[22:23], v[22:23], 0, v[128:129]
	v_and_b32_e32 v128, 0xc0, v147
	v_lshl_add_u64 v[22:23], s[26:27], 1, v[22:23]
	v_lshlrev_b32_e32 v134, 1, v128
	v_mul_lo_u32 v128, v130, s55
	v_lshlrev_b32_e32 v130, 4, v147
	v_lshl_add_u64 v[22:23], v[22:23], 0, v[134:135]
	v_add_u32_e32 v128, s4, v128
	v_lshlrev_b32_e32 v129, 3, v148
	v_and_b32_e32 v134, 0x70, v130
	v_bfe_u32 v130, v147, 3, 3
	v_mul_u32_u24_e32 v131, 0x90, v130
	v_add3_u32 v136, v128, v129, v136
	v_add3_u32 v131, v128, v134, v131
	v_cvt_pk_bf16_f32 v128, v140, v141
	v_cvt_pk_bf16_f32 v129, v144, v145
	ds_write_b64 v136, v[96:97] offset:2336
	v_cvt_pk_bf16_f32 v96, v104, v105
	v_cvt_pk_bf16_f32 v97, v106, v107
	ds_write_b64 v136, v[84:85] offset:4640
	v_cvt_pk_bf16_f32 v84, v98, v99
	v_cvt_pk_bf16_f32 v85, v88, v89
	v_cvt_pk_bf16_f32 v67, v76, v77
	ds_write_b64 v136, v[128:129]
	v_cvt_pk_bf16_f32 v128, v138, v139
	v_cvt_pk_bf16_f32 v129, v142, v143
	v_cvt_pk_bf16_f32 v116, v116, v117
	v_cvt_pk_bf16_f32 v117, v118, v119
	ds_write_b64 v136, v[110:111] offset:96
	v_cvt_pk_bf16_f32 v110, v114, v115
	v_cvt_pk_bf16_f32 v111, v120, v121
	ds_write_b64 v136, v[96:97] offset:2368
	v_cvt_pk_bf16_f32 v96, v108, v109
	v_cvt_pk_bf16_f32 v97, v100, v101
	v_cvt_pk_bf16_f32 v92, v92, v93
	v_cvt_pk_bf16_f32 v93, v94, v95
	ds_write_b64 v136, v[84:85] offset:4672
	v_cvt_pk_bf16_f32 v84, v90, v91
	v_cvt_pk_bf16_f32 v85, v80, v81
	v_cvt_pk_bf16_f32 v72, v72, v73
	v_cvt_pk_bf16_f32 v73, v74, v75
	ds_write_b64 v136, v[66:67] offset:6976
	v_cvt_pk_bf16_f32 v66, v78, v79
	v_cvt_pk_bf16_f32 v67, v122, v123
	ds_write_b64 v136, v[128:129] offset:32
	ds_write_b64 v136, v[116:117] offset:64
	ds_write_b64 v136, v[110:111] offset:2304
	ds_write_b64 v136, v[96:97] offset:2400
	ds_write_b64 v136, v[92:93] offset:4608
	ds_write_b64 v136, v[84:85] offset:4704
	ds_write_b64 v136, v[72:73] offset:6912
	ds_write_b64 v136, v[68:69] offset:6944
	ds_write_b64 v136, v[66:67] offset:7008
	ds_read_b128 v[66:69], v131
	v_lshl_add_u64 v[22:23], v[22:23], 0, v[134:135]
	v_lshl_add_u64 v[22:23], v[22:23], 0, s[24:25]
	v_lshlrev_b32_e32 v134, 10, v130
	v_lshl_add_u64 v[72:73], v[22:23], 0, v[134:135]
	s_waitcnt lgkmcnt(0)
	flat_store_dwordx4 v[72:73], v[66:69] nt
	ds_read_b128 v[66:69], v131 offset:1152
	v_pk_fma_f32 v[0:1], v[0:1], v[156:157], v[4:5] neg_lo:[0,0,1] neg_hi:[0,0,1]
	v_or_b32_e32 v4, 0x2000, v134
	v_mov_b32_e32 v5, v135
	v_lshl_add_u64 v[4:5], v[22:23], 0, v[4:5]
	s_waitcnt lgkmcnt(0)
	flat_store_dwordx4 v[4:5], v[66:69] nt
	ds_read_b128 v[66:69], v131 offset:2304
	v_or_b32_e32 v74, 0x4000, v134
	v_mov_b32_e32 v75, v135
	v_lshl_add_u64 v[74:75], v[22:23], 0, v[74:75]
	v_or_b32_e32 v76, 0x8000, v134
	s_waitcnt lgkmcnt(0)
	flat_store_dwordx4 v[74:75], v[66:69] nt
	ds_read_b128 v[66:69], v131 offset:3456
	v_or_b32_e32 v74, 0x6000, v134
	v_mov_b32_e32 v75, v135
	v_lshl_add_u64 v[74:75], v[22:23], 0, v[74:75]
	v_mov_b32_e32 v77, v135
	s_waitcnt lgkmcnt(0)
	flat_store_dwordx4 v[74:75], v[66:69] nt
	ds_read_b128 v[66:69], v131 offset:4608
	v_lshl_add_u64 v[76:77], v[22:23], 0, v[76:77]
	s_waitcnt vmcnt(0)
	v_mov_b32_e32 v4, v125
	v_mov_b32_e32 v5, v127
	v_pk_mul_f32 v[74:75], v[2:3], v[4:5]
	s_waitcnt lgkmcnt(0)
	flat_store_dwordx4 v[76:77], v[66:69] nt
	ds_read_b128 v[66:69], v131 offset:5760
	v_or_b32_e32 v76, 0xa000, v134
	v_mov_b32_e32 v77, v135
	v_lshl_add_u64 v[76:77], v[22:23], 0, v[76:77]
	v_mov_b32_e32 v125, v126
	s_waitcnt lgkmcnt(0)
	flat_store_dwordx4 v[76:77], v[66:69] nt
	ds_read_b128 v[66:69], v131 offset:6912
	v_or_b32_e32 v76, 0xc000, v134
	v_mov_b32_e32 v77, v135
	v_lshl_add_u64 v[76:77], v[22:23], 0, v[76:77]
	v_pk_mul_f32 v[4:5], v[6:7], v[4:5]
	s_waitcnt lgkmcnt(0)
	flat_store_dwordx4 v[76:77], v[66:69] nt
	ds_read_b128 v[66:69], v131 offset:8064
	v_or_b32_e32 v134, 0xe000, v134
	v_pk_fma_f32 v[2:3], v[2:3], v[124:125], v[4:5] neg_lo:[0,0,1] neg_hi:[0,0,1]
	v_lshl_add_u64 v[4:5], v[22:23], 0, v[134:135]
	v_cvt_pk_bf16_f32 v0, v0, v1
	s_waitcnt lgkmcnt(0)
	flat_store_dwordx4 v[4:5], v[66:69] nt
	v_cvt_pk_bf16_f32 v4, v56, v57
	v_cvt_pk_bf16_f32 v5, v62, v63
	ds_write_b64 v136, v[4:5]
	v_cvt_pk_bf16_f32 v4, v70, v71
	v_cvt_pk_bf16_f32 v5, v50, v51
	ds_write_b64 v136, v[4:5] offset:32
	v_cvt_pk_bf16_f32 v4, v64, v65
	v_cvt_pk_bf16_f32 v5, v60, v61
	ds_write_b64 v136, v[4:5] offset:64
	v_cvt_pk_bf16_f32 v4, v58, v59
	v_cvt_pk_bf16_f32 v5, v52, v53
	ds_write_b64 v136, v[4:5] offset:96
	v_cvt_pk_bf16_f32 v4, v44, v45
	v_cvt_pk_bf16_f32 v5, v46, v47
	ds_write_b64 v136, v[4:5] offset:2304
	v_cvt_pk_bf16_f32 v4, v54, v55
	v_cvt_pk_bf16_f32 v5, v34, v35
	ds_write_b64 v136, v[4:5] offset:2336
	v_cvt_pk_bf16_f32 v4, v48, v49
	v_cvt_pk_bf16_f32 v5, v40, v41
	ds_write_b64 v136, v[4:5] offset:2368
	v_cvt_pk_bf16_f32 v4, v42, v43
	v_cvt_pk_bf16_f32 v5, v36, v37
	ds_write_b64 v136, v[4:5] offset:2400
	v_cvt_pk_bf16_f32 v4, v28, v29
	v_cvt_pk_bf16_f32 v5, v30, v31
	ds_write_b64 v136, v[4:5] offset:4608
	v_cvt_pk_bf16_f32 v4, v38, v39
	v_cvt_pk_bf16_f32 v5, v18, v19
	ds_write_b64 v136, v[4:5] offset:4640
	v_cvt_pk_bf16_f32 v4, v32, v33
	v_cvt_pk_bf16_f32 v5, v24, v25
	v_cvt_pk_bf16_f32 v1, v2, v3
	v_pk_fma_f32 v[74:75], v[6:7], v[124:125], v[74:75]
	ds_write_b64 v136, v[4:5] offset:4672
	v_cvt_pk_bf16_f32 v4, v26, v27
	v_cvt_pk_bf16_f32 v5, v20, v21
	ds_write_b64 v136, v[0:1] offset:6944
	v_cvt_pk_bf16_f32 v0, v16, v17
	v_cvt_pk_bf16_f32 v1, v8, v9
	ds_write_b64 v136, v[4:5] offset:4704
	v_cvt_pk_bf16_f32 v4, v12, v13
	v_cvt_pk_bf16_f32 v5, v10, v11
	ds_write_b64 v136, v[0:1] offset:6976
	v_cvt_pk_bf16_f32 v0, v14, v15
	v_cvt_pk_bf16_f32 v1, v74, v75
	ds_write_b64 v136, v[4:5] offset:6912
	ds_write_b64 v136, v[0:1] offset:7008
	ds_read_b128 v[0:3], v131
	v_add_co_u32_e32 v4, vcc, s50, v72
	s_nop 1
	v_addc_co_u32_e32 v5, vcc, 0, v73, vcc
	s_waitcnt lgkmcnt(0)
	flat_store_dwordx4 v[4:5], v[0:3] nt
	ds_read_b128 v[0:3], v131 offset:1152
	v_add_co_u32_e32 v4, vcc, s62, v72
	s_nop 1
	v_addc_co_u32_e32 v5, vcc, 0, v73, vcc
	s_waitcnt lgkmcnt(0)
	flat_store_dwordx4 v[4:5], v[0:3] nt
	ds_read_b128 v[0:3], v131 offset:2304
	v_add_co_u32_e32 v4, vcc, s63, v72
	s_nop 1
	v_addc_co_u32_e32 v5, vcc, 0, v73, vcc
	s_waitcnt lgkmcnt(0)
	flat_store_dwordx4 v[4:5], v[0:3] nt
	ds_read_b128 v[0:3], v131 offset:3456
	v_add_co_u32_e32 v4, vcc, s64, v72
	s_nop 1
	v_addc_co_u32_e32 v5, vcc, 0, v73, vcc
	s_waitcnt lgkmcnt(0)
	flat_store_dwordx4 v[4:5], v[0:3] nt
	ds_read_b128 v[0:3], v131 offset:4608
	v_add_co_u32_e32 v4, vcc, s51, v72
	s_nop 1
	v_addc_co_u32_e32 v5, vcc, 0, v73, vcc
	s_waitcnt lgkmcnt(0)
	flat_store_dwordx4 v[4:5], v[0:3] nt
	ds_read_b128 v[0:3], v131 offset:5760
	v_add_co_u32_e32 v4, vcc, 0x1a000, v72
	s_nop 1
	v_addc_co_u32_e32 v5, vcc, 0, v73, vcc
	s_waitcnt lgkmcnt(0)
	flat_store_dwordx4 v[4:5], v[0:3] nt
	ds_read_b128 v[0:3], v131 offset:6912
	v_add_co_u32_e32 v4, vcc, 0x1c000, v72
	s_nop 1
	v_addc_co_u32_e32 v5, vcc, 0, v73, vcc
	s_waitcnt lgkmcnt(0)
	flat_store_dwordx4 v[4:5], v[0:3] nt
	ds_read_b128 v[0:3], v131 offset:8064
	v_add_co_u32_e32 v4, vcc, 0x1e000, v72
	s_nop 1
	v_addc_co_u32_e32 v5, vcc, 0, v73, vcc
	s_waitcnt lgkmcnt(0)
	flat_store_dwordx4 v[4:5], v[0:3] nt
	s_branch .LBB0_137

.LBB0_793:
	s_and_b32 s31, s0, 0x10000
	s_xor_b32 s42, s31, 0x10000
	s_add_i32 s31, s31, 0
	s_add_i32 s101, s100, s42
	s_cmpk_eq_i32 s38, 0
	s_cbranch_scc1 .Lg1n_793
	s_waitcnt lgkmcnt(3)
	v_mfma_f32_16x16x32_bf16 v[126:129], v[180:183], v[164:167], v[126:129]
	v_mfma_f32_16x16x32_bf16 v[110:113], v[180:183], v[168:171], v[110:113]
	v_mfma_f32_16x16x32_bf16 v[94:97], v[180:183], v[172:175], v[94:97]
	v_mfma_f32_16x16x32_bf16 v[78:81], v[180:183], v[176:179], v[78:81]
	ds_read_b128 v[240:243], v199
	ds_read_b128 v[244:247], v200
	s_add_i32 m0, s101, 0x4000
	v_lshl_add_u64 v[144:145], v[144:145], 0, s[98:99]
	global_load_lds_dwordx4 v[144:145], off
	s_waitcnt lgkmcnt(4)
	v_mfma_f32_16x16x32_bf16 v[122:125], v[184:187], v[164:167], v[122:125]
	v_mfma_f32_16x16x32_bf16 v[106:109], v[184:187], v[168:171], v[106:109]
	v_mfma_f32_16x16x32_bf16 v[90:93], v[184:187], v[172:175], v[90:93]
	v_mfma_f32_16x16x32_bf16 v[74:77], v[184:187], v[176:179], v[74:77]
	ds_read_b128 v[248:251], v201
	ds_read_b128 v[252:255], v202
	s_add_i32 m0, s101, 0xc000
	v_lshl_add_u64 v[136:137], v[136:137], 0, s[98:99]
	global_load_lds_dwordx4 v[136:137], off
	s_waitcnt lgkmcnt(5)
	v_mfma_f32_16x16x32_bf16 v[118:121], v[188:191], v[164:167], v[118:121]
	v_mfma_f32_16x16x32_bf16 v[102:105], v[188:191], v[168:171], v[102:105]
	v_mfma_f32_16x16x32_bf16 v[86:89], v[188:191], v[172:175], v[86:89]
	v_mfma_f32_16x16x32_bf16 v[70:73], v[188:191], v[176:179], v[70:73]
	s_add_i32 m0, s101, 0x6000
	v_lshl_add_u64 v[142:143], v[142:143], 0, s[98:99]
	global_load_lds_dwordx4 v[142:143], off
	s_waitcnt lgkmcnt(4)
	v_mfma_f32_16x16x32_bf16 v[114:117], v[192:195], v[164:167], v[114:117]
	v_mfma_f32_16x16x32_bf16 v[98:101], v[192:195], v[168:171], v[98:101]
	v_mfma_f32_16x16x32_bf16 v[82:85], v[192:195], v[172:175], v[82:85]
	v_mfma_f32_16x16x32_bf16 v[66:69], v[192:195], v[176:179], v[66:69]
	s_add_i32 m0, s101, 0xe000
	v_lshl_add_u64 v[134:135], v[134:135], 0, s[98:99]
	global_load_lds_dwordx4 v[134:135], off
.Lg2_793:
	ds_read_b128 v[164:167], v163 offset:1024
	ds_read_b128 v[168:171], v196 offset:1024
	ds_read_b128 v[172:175], v197 offset:1024
	ds_read_b128 v[176:179], v198 offset:1024
	s_waitcnt lgkmcnt(4)
	v_mfma_f32_16x16x32_bf16 v[62:65], v[180:183], v[240:243], v[62:65]
	v_mfma_f32_16x16x32_bf16 v[46:49], v[180:183], v[244:247], v[46:49]
	v_mfma_f32_16x16x32_bf16 v[18:21], v[180:183], v[248:251], v[18:21]
	v_mfma_f32_16x16x32_bf16 v[38:41], v[180:183], v[252:255], v[38:41]
	ds_read_b128 v[180:183], v130 offset:33792
	v_mfma_f32_16x16x32_bf16 v[58:61], v[184:187], v[240:243], v[58:61]
	v_mfma_f32_16x16x32_bf16 v[42:45], v[184:187], v[244:247], v[42:45]
	v_mfma_f32_16x16x32_bf16 v[10:13], v[184:187], v[248:251], v[10:13]
	v_mfma_f32_16x16x32_bf16 v[30:33], v[184:187], v[252:255], v[30:33]
	ds_read_b128 v[184:187], v130 offset:35840
	v_mfma_f32_16x16x32_bf16 v[54:57], v[188:191], v[240:243], v[54:57]
	v_mfma_f32_16x16x32_bf16 v[34:37], v[188:191], v[244:247], v[34:37]
	v_mfma_f32_16x16x32_bf16 v[6:9], v[188:191], v[248:251], v[6:9]
	v_mfma_f32_16x16x32_bf16 v[22:25], v[188:191], v[252:255], v[22:25]
	ds_read_b128 v[188:191], v130 offset:37888
	v_mfma_f32_16x16x32_bf16 v[50:53], v[192:195], v[240:243], v[50:53]
	v_mfma_f32_16x16x32_bf16 v[26:29], v[192:195], v[244:247], v[26:29]
	v_mfma_f32_16x16x32_bf16 v[2:5], v[192:195], v[248:251], v[2:5]
	v_mfma_f32_16x16x32_bf16 v[14:17], v[192:195], v[252:255], v[14:17]
	ds_read_b128 v[192:195], v130 offset:39936
	s_waitcnt lgkmcnt(3)
	v_mfma_f32_16x16x32_bf16 v[126:129], v[180:183], v[164:167], v[126:129]
	v_mfma_f32_16x16x32_bf16 v[110:113], v[180:183], v[168:171], v[110:113]
	v_mfma_f32_16x16x32_bf16 v[94:97], v[180:183], v[172:175], v[94:97]
	v_mfma_f32_16x16x32_bf16 v[78:81], v[180:183], v[176:179], v[78:81]
	ds_read_b128 v[240:243], v199 offset:1024
	ds_read_b128 v[244:247], v200 offset:1024
	s_waitcnt lgkmcnt(4)
	v_mfma_f32_16x16x32_bf16 v[122:125], v[184:187], v[164:167], v[122:125]
	v_mfma_f32_16x16x32_bf16 v[106:109], v[184:187], v[168:171], v[106:109]
	v_mfma_f32_16x16x32_bf16 v[90:93], v[184:187], v[172:175], v[90:93]
	v_mfma_f32_16x16x32_bf16 v[74:77], v[184:187], v[176:179], v[74:77]
	ds_read_b128 v[248:251], v201 offset:1024
	ds_read_b128 v[252:255], v202 offset:1024
	s_waitcnt lgkmcnt(5)
	v_mfma_f32_16x16x32_bf16 v[118:121], v[188:191], v[164:167], v[118:121]
	v_mfma_f32_16x16x32_bf16 v[102:105], v[188:191], v[168:171], v[102:105]
	v_mfma_f32_16x16x32_bf16 v[86:89], v[188:191], v[172:175], v[86:89]
	v_mfma_f32_16x16x32_bf16 v[70:73], v[188:191], v[176:179], v[70:73]
	s_waitcnt lgkmcnt(4)
	v_mfma_f32_16x16x32_bf16 v[114:117], v[192:195], v[164:167], v[114:117]
	v_mfma_f32_16x16x32_bf16 v[98:101], v[192:195], v[168:171], v[98:101]
	v_mfma_f32_16x16x32_bf16 v[82:85], v[192:195], v[172:175], v[82:85]
	v_mfma_f32_16x16x32_bf16 v[66:69], v[192:195], v[176:179], v[66:69]
	s_waitcnt vmcnt(0) lgkmcnt(0)
	s_barrier
	s_add_i32 s101, s100, s31
	s_cmpk_eq_i32 s38, 0x700
	s_cbranch_scc1 .Lg4n_793
	v_mfma_f32_16x16x32_bf16 v[62:65], v[180:183], v[240:243], v[62:65]
	v_mfma_f32_16x16x32_bf16 v[46:49], v[180:183], v[244:247], v[46:49]
	v_mfma_f32_16x16x32_bf16 v[18:21], v[180:183], v[248:251], v[18:21]
	v_mfma_f32_16x16x32_bf16 v[38:41], v[180:183], v[252:255], v[38:41]
	v_add3_u32 v130, s42, v152, v153
	ds_read_b128 v[180:183], v130 offset:32768
	v_add3_u32 v163, s42, v152, v154
	v_add3_u32 v196, s42, v156, v155
	v_add3_u32 v197, s42, v156, v157
	v_add3_u32 v198, s42, v156, v158
	ds_read_b128 v[164:167], v163
	ds_read_b128 v[168:171], v196
	ds_read_b128 v[172:175], v197
	ds_read_b128 v[176:179], v198
	s_mov_b32 m0, s101
	v_lshl_add_u64 v[148:149], v[148:149], 0, s[98:99]
	global_load_lds_dwordx4 v[148:149], off
	v_mfma_f32_16x16x32_bf16 v[58:61], v[184:187], v[240:243], v[58:61]
	v_mfma_f32_16x16x32_bf16 v[42:45], v[184:187], v[244:247], v[42:45]
	v_mfma_f32_16x16x32_bf16 v[10:13], v[184:187], v[248:251], v[10:13]
	v_mfma_f32_16x16x32_bf16 v[30:33], v[184:187], v[252:255], v[30:33]
	ds_read_b128 v[184:187], v130 offset:34816
	v_add3_u32 v199, s42, v156, v159
	v_add3_u32 v200, s42, v156, v160
	v_add3_u32 v201, s42, v156, v161
	v_add3_u32 v202, s42, v156, v162
	s_add_i32 m0, s101, 0x8000
	v_lshl_add_u64 v[140:141], v[140:141], 0, s[98:99]
	global_load_lds_dwordx4 v[140:141], off
	v_mfma_f32_16x16x32_bf16 v[54:57], v[188:191], v[240:243], v[54:57]
	v_mfma_f32_16x16x32_bf16 v[34:37], v[188:191], v[244:247], v[34:37]
	v_mfma_f32_16x16x32_bf16 v[6:9], v[188:191], v[248:251], v[6:9]
	v_mfma_f32_16x16x32_bf16 v[22:25], v[188:191], v[252:255], v[22:25]
	ds_read_b128 v[188:191], v130 offset:36864
	s_add_i32 m0, s101, 0x2000
	v_lshl_add_u64 v[146:147], v[146:147], 0, s[98:99]
	global_load_lds_dwordx4 v[146:147], off
	v_mfma_f32_16x16x32_bf16 v[50:53], v[192:195], v[240:243], v[50:53]
	v_mfma_f32_16x16x32_bf16 v[26:29], v[192:195], v[244:247], v[26:29]
	v_mfma_f32_16x16x32_bf16 v[2:5], v[192:195], v[248:251], v[2:5]
	v_mfma_f32_16x16x32_bf16 v[14:17], v[192:195], v[252:255], v[14:17]
	ds_read_b128 v[192:195], v130 offset:38912
	s_add_i32 m0, s101, 0xa000
	v_lshl_add_u64 v[138:139], v[138:139], 0, s[98:99]
	global_load_lds_dwordx4 v[138:139], off
.Ltl_793:
	s_add_i32 s0, s0, 0x10000
	s_add_u32 s38, s38, 0x80
	s_addc_u32 s39, s39, 0
	s_cmpk_lg_i32 s38, 0x780
	s_cbranch_scc1 .LBB0_793
	s_branch .Lex_793
.Lg1n_793:
	s_waitcnt lgkmcnt(3)
	v_mfma_f32_16x16x32_bf16 v[126:129], v[180:183], v[164:167], v[126:129]
	v_mfma_f32_16x16x32_bf16 v[110:113], v[180:183], v[168:171], v[110:113]
	v_mfma_f32_16x16x32_bf16 v[94:97], v[180:183], v[172:175], v[94:97]
	v_mfma_f32_16x16x32_bf16 v[78:81], v[180:183], v[176:179], v[78:81]
	ds_read_b128 v[240:243], v199
	ds_read_b128 v[244:247], v200
	s_waitcnt lgkmcnt(4)
	v_mfma_f32_16x16x32_bf16 v[122:125], v[184:187], v[164:167], v[122:125]
	v_mfma_f32_16x16x32_bf16 v[106:109], v[184:187], v[168:171], v[106:109]
	v_mfma_f32_16x16x32_bf16 v[90:93], v[184:187], v[172:175], v[90:93]
	v_mfma_f32_16x16x32_bf16 v[74:77], v[184:187], v[176:179], v[74:77]
	ds_read_b128 v[248:251], v201
	ds_read_b128 v[252:255], v202
	s_waitcnt lgkmcnt(5)
	v_mfma_f32_16x16x32_bf16 v[118:121], v[188:191], v[164:167], v[118:121]
	v_mfma_f32_16x16x32_bf16 v[102:105], v[188:191], v[168:171], v[102:105]
	v_mfma_f32_16x16x32_bf16 v[86:89], v[188:191], v[172:175], v[86:89]
	v_mfma_f32_16x16x32_bf16 v[70:73], v[188:191], v[176:179], v[70:73]
	s_waitcnt lgkmcnt(4)
	v_mfma_f32_16x16x32_bf16 v[114:117], v[192:195], v[164:167], v[114:117]
	v_mfma_f32_16x16x32_bf16 v[98:101], v[192:195], v[168:171], v[98:101]
	v_mfma_f32_16x16x32_bf16 v[82:85], v[192:195], v[172:175], v[82:85]
	v_mfma_f32_16x16x32_bf16 v[66:69], v[192:195], v[176:179], v[66:69]
	s_branch .Lg2_793
.Lg4n_793:
	v_mfma_f32_16x16x32_bf16 v[62:65], v[180:183], v[240:243], v[62:65]
	v_mfma_f32_16x16x32_bf16 v[46:49], v[180:183], v[244:247], v[46:49]
	v_mfma_f32_16x16x32_bf16 v[18:21], v[180:183], v[248:251], v[18:21]
	v_mfma_f32_16x16x32_bf16 v[38:41], v[180:183], v[252:255], v[38:41]
	v_add3_u32 v130, s42, v152, v153
	ds_read_b128 v[180:183], v130 offset:32768
	v_add3_u32 v163, s42, v152, v154
	v_add3_u32 v196, s42, v156, v155
	v_add3_u32 v197, s42, v156, v157
	v_add3_u32 v198, s42, v156, v158
	ds_read_b128 v[164:167], v163
	ds_read_b128 v[168:171], v196
	ds_read_b128 v[172:175], v197
	ds_read_b128 v[176:179], v198
	v_mfma_f32_16x16x32_bf16 v[58:61], v[184:187], v[240:243], v[58:61]
	v_mfma_f32_16x16x32_bf16 v[42:45], v[184:187], v[244:247], v[42:45]
	v_mfma_f32_16x16x32_bf16 v[10:13], v[184:187], v[248:251], v[10:13]
	v_mfma_f32_16x16x32_bf16 v[30:33], v[184:187], v[252:255], v[30:33]
	ds_read_b128 v[184:187], v130 offset:34816
	v_add3_u32 v199, s42, v156, v159
	v_add3_u32 v200, s42, v156, v160
	v_add3_u32 v201, s42, v156, v161
	v_add3_u32 v202, s42, v156, v162
	v_mfma_f32_16x16x32_bf16 v[54:57], v[188:191], v[240:243], v[54:57]
	v_mfma_f32_16x16x32_bf16 v[34:37], v[188:191], v[244:247], v[34:37]
	v_mfma_f32_16x16x32_bf16 v[6:9], v[188:191], v[248:251], v[6:9]
	v_mfma_f32_16x16x32_bf16 v[22:25], v[188:191], v[252:255], v[22:25]
	ds_read_b128 v[188:191], v130 offset:36864
	v_mfma_f32_16x16x32_bf16 v[50:53], v[192:195], v[240:243], v[50:53]
	v_mfma_f32_16x16x32_bf16 v[26:29], v[192:195], v[244:247], v[26:29]
	v_mfma_f32_16x16x32_bf16 v[2:5], v[192:195], v[248:251], v[2:5]
	v_mfma_f32_16x16x32_bf16 v[14:17], v[192:195], v[252:255], v[14:17]
	ds_read_b128 v[192:195], v130 offset:38912
	s_branch .Ltl_793
.Lex_793:
	s_waitcnt lgkmcnt(0)
	v_add3_u32 v130, s46, v156, v162
	v_add3_u32 v151, s46, v156, v161
	v_add3_u32 v202, s46, v156, v160
	v_add3_u32 v198, s46, v156, v159
	v_add3_u32 v186, s46, v156, v158
	v_add3_u32 v187, s46, v156, v157
	v_add3_u32 v188, s46, v156, v155
	v_add3_u32 v189, s46, v152, v154
	v_add3_u32 v190, s47, v152, v153
	ds_read_b128 v[134:137], v130
	ds_read_b128 v[138:141], v151
	ds_read_b128 v[142:145], v202
	ds_read_b128 v[146:149], v198
	ds_read_b128 v[158:161], v186
	ds_read_b128 v[162:165], v187
	ds_read_b128 v[166:169], v188
	ds_read_b128 v[154:157], v189
	ds_read_b128 v[170:173], v190
	s_waitcnt lgkmcnt(0)
	v_mfma_f32_16x16x32_bf16 v[18:21], v[170:173], v[138:141], v[18:21]
	v_mfma_f32_16x16x32_bf16 v[174:177], v[170:173], v[134:137], v[38:41]
	s_nop 2
	ds_read_b128 v[38:41], v190 offset:2048
	s_waitcnt lgkmcnt(0)
	v_mfma_f32_16x16x32_bf16 v[10:13], v[38:41], v[138:141], v[10:13]
	v_mfma_f32_16x16x32_bf16 v[62:65], v[170:173], v[146:149], v[62:65]
	v_mfma_f32_16x16x32_bf16 v[30:33], v[38:41], v[134:137], v[30:33]
	v_mfma_f32_16x16x32_bf16 v[58:61], v[38:41], v[146:149], v[58:61]
	ds_read_b128 v[178:181], v190 offset:4096
	s_waitcnt lgkmcnt(0)
	v_mfma_f32_16x16x32_bf16 v[182:185], v[178:181], v[134:137], v[22:25]
	v_mfma_f32_16x16x32_bf16 v[54:57], v[178:181], v[146:149], v[54:57]
	s_nop 1
	ds_read_b128 v[22:25], v190 offset:6144
	s_waitcnt lgkmcnt(0)
	v_mfma_f32_16x16x32_bf16 v[134:137], v[22:25], v[134:137], v[14:17]
	v_mfma_f32_16x16x32_bf16 v[14:17], v[22:25], v[154:157], v[114:117]
	v_mfma_f32_16x16x32_bf16 v[114:117], v[22:25], v[158:161], v[66:69]
	v_mfma_f32_16x16x32_bf16 v[66:69], v[178:181], v[154:157], v[118:121]
	v_mfma_f32_16x16x32_bf16 v[118:121], v[178:181], v[158:161], v[70:73]
	v_mfma_f32_16x16x32_bf16 v[70:73], v[38:41], v[154:157], v[122:125]
	v_mfma_f32_16x16x32_bf16 v[122:125], v[38:41], v[158:161], v[74:77]
	v_mfma_f32_16x16x32_bf16 v[74:77], v[170:173], v[154:157], v[126:129]
	v_mfma_f32_16x16x32_bf16 v[126:129], v[170:173], v[158:161], v[78:81]
	v_mfma_f32_16x16x32_bf16 v[50:53], v[22:25], v[146:149], v[50:53]
	v_mfma_f32_16x16x32_bf16 v[146:149], v[170:173], v[142:145], v[46:49]
	v_mfma_f32_16x16x32_bf16 v[152:155], v[38:41], v[142:145], v[42:45]
	v_mfma_f32_16x16x32_bf16 v[156:159], v[178:181], v[142:145], v[34:37]
	v_mfma_f32_16x16x32_bf16 v[26:29], v[22:25], v[142:145], v[26:29]
	v_mfma_f32_16x16x32_bf16 v[142:145], v[178:181], v[138:141], v[6:9]
	v_mfma_f32_16x16x32_bf16 v[110:113], v[170:173], v[166:169], v[110:113]
	v_mfma_f32_16x16x32_bf16 v[94:97], v[170:173], v[162:165], v[94:97]
	v_mfma_f32_16x16x32_bf16 v[106:109], v[38:41], v[166:169], v[106:109]
	v_mfma_f32_16x16x32_bf16 v[90:93], v[38:41], v[162:165], v[90:93]
	v_mfma_f32_16x16x32_bf16 v[102:105], v[178:181], v[166:169], v[102:105]
	v_mfma_f32_16x16x32_bf16 v[86:89], v[178:181], v[162:165], v[86:89]
	v_mfma_f32_16x16x32_bf16 v[98:101], v[22:25], v[166:169], v[98:101]
	v_mfma_f32_16x16x32_bf16 v[82:85], v[22:25], v[162:165], v[82:85]
	v_mfma_f32_16x16x32_bf16 v[22:25], v[22:25], v[138:141], v[2:5]
	ds_read_b128 v[138:141], v190 offset:1024
	ds_read_b128 v[160:163], v190 offset:3072
	ds_read_b128 v[164:167], v190 offset:5120
	ds_read_b128 v[168:171], v190 offset:7168
	ds_read_b128 v[2:5], v189 offset:1024
	ds_read_b128 v[6:9], v188 offset:1024
	ds_read_b128 v[34:37], v187 offset:1024
	ds_read_b128 v[38:41], v186 offset:1024
	s_waitcnt lgkmcnt(3)
	v_mfma_f32_16x16x32_bf16 v[178:181], v[138:141], v[2:5], v[74:77]
	v_mfma_f32_16x16x32_bf16 v[186:189], v[160:163], v[2:5], v[70:73]
	v_mfma_f32_16x16x32_bf16 v[190:193], v[164:167], v[2:5], v[66:69]
	v_mfma_f32_16x16x32_bf16 v[194:197], v[168:171], v[2:5], v[14:17]
	ds_read_b128 v[2:5], v198 offset:1024
	s_waitcnt lgkmcnt(3)
	v_mfma_f32_16x16x32_bf16 v[110:113], v[138:141], v[6:9], v[110:113]
	v_mfma_f32_16x16x32_bf16 v[106:109], v[160:163], v[6:9], v[106:109]
	v_mfma_f32_16x16x32_bf16 v[102:105], v[164:167], v[6:9], v[102:105]
	v_mfma_f32_16x16x32_bf16 v[198:201], v[168:171], v[6:9], v[98:101]
	ds_read_b128 v[6:9], v202 offset:1024
	s_waitcnt lgkmcnt(3)
	v_mfma_f32_16x16x32_bf16 v[66:69], v[138:141], v[34:37], v[94:97]
	v_mfma_f32_16x16x32_bf16 v[70:73], v[160:163], v[34:37], v[90:93]
	v_mfma_f32_16x16x32_bf16 v[74:77], v[164:167], v[34:37], v[86:89]
	v_mfma_f32_16x16x32_bf16 v[78:81], v[168:171], v[34:37], v[82:85]
	ds_read_b128 v[14:17], v151 offset:1024
	s_waitcnt lgkmcnt(3)
	v_mfma_f32_16x16x32_bf16 v[82:85], v[138:141], v[38:41], v[126:129]
	v_mfma_f32_16x16x32_bf16 v[86:89], v[160:163], v[38:41], v[122:125]
	v_mfma_f32_16x16x32_bf16 v[90:93], v[164:167], v[38:41], v[118:121]
	v_mfma_f32_16x16x32_bf16 v[94:97], v[168:171], v[38:41], v[114:117]
	ds_read_b128 v[98:101], v130 offset:1024
	s_waitcnt lgkmcnt(3)
	v_mfma_f32_16x16x32_bf16 v[34:37], v[138:141], v[2:5], v[62:65]
	v_mfma_f32_16x16x32_bf16 v[38:41], v[160:163], v[2:5], v[58:61]
	v_mfma_f32_16x16x32_bf16 v[42:45], v[164:167], v[2:5], v[54:57]
	v_mfma_f32_16x16x32_bf16 v[46:49], v[168:171], v[2:5], v[50:53]
	s_waitcnt lgkmcnt(2)
	v_mfma_f32_16x16x32_bf16 v[50:53], v[138:141], v[6:9], v[146:149]
	v_mfma_f32_16x16x32_bf16 v[54:57], v[160:163], v[6:9], v[152:155]
	v_mfma_f32_16x16x32_bf16 v[58:61], v[164:167], v[6:9], v[156:159]
	v_mfma_f32_16x16x32_bf16 v[62:65], v[168:171], v[6:9], v[26:29]
	s_waitcnt lgkmcnt(1)
	v_mfma_f32_16x16x32_bf16 v[2:5], v[138:141], v[14:17], v[18:21]
	v_mfma_f32_16x16x32_bf16 v[6:9], v[160:163], v[14:17], v[10:13]
	v_mfma_f32_16x16x32_bf16 v[10:13], v[164:167], v[14:17], v[142:145]
	v_mfma_f32_16x16x32_bf16 v[14:17], v[168:171], v[14:17], v[22:25]
	s_waitcnt lgkmcnt(0)
	v_mfma_f32_16x16x32_bf16 v[18:21], v[138:141], v[98:101], v[174:177]
	v_mfma_f32_16x16x32_bf16 v[22:25], v[160:163], v[98:101], v[30:33]
	v_mfma_f32_16x16x32_bf16 v[26:29], v[164:167], v[98:101], v[182:185]
	v_mfma_f32_16x16x32_bf16 v[30:33], v[168:171], v[98:101], v[134:137]
	v_lshrrev_b32_e32 v98, 6, v150
	v_mul_lo_u32 v98, v98, s48
	v_add_u32_e32 v101, s46, v98
	v_lshlrev_b32_e32 v98, 2, v150
	v_and_b32_e32 v100, 15, v150
	v_and_b32_e32 v115, 60, v98
	v_ashrrev_i32_e32 v98, 1, v150
	v_bfe_u32 v99, v150, 4, 2
	v_and_b32_e32 v114, 48, v150
	v_and_b32_e32 v116, 0xffffff80, v98
	v_lshlrev_b32_e32 v98, 2, v115
	v_mul_u32_u24_e32 v117, 0x110, v99
	v_mul_u32_u24_e32 v100, 0x110, v100
	v_add3_u32 v98, v101, v98, v117
	v_add3_u32 v101, v101, v114, v100
	s_waitcnt vmcnt(0)
	s_barrier
	ds_write_b128 v101, v[178:181]
	ds_write_b128 v101, v[186:189] offset:64
	ds_write_b128 v101, v[190:193] offset:128
	ds_write_b128 v101, v[194:197] offset:192
	ds_write_b128 v101, v[110:113] offset:4352
	ds_write_b128 v101, v[106:109] offset:4416
	ds_write_b128 v101, v[102:105] offset:4480
	ds_write_b128 v101, v[198:201] offset:4544
	ds_read_b128 v[102:105], v98
	v_add_u32_e32 v100, s28, v116
	s_ashr_i32 s31, s30, 31
	v_and_or_b32 v106, v150, s49, v115
	s_lshl_b64 s[38:39], s[30:31], 1
	s_waitcnt lgkmcnt(0)
	v_mul_f32_e32 v102, 0xbfb8aa3b, v102
	v_mul_f32_e32 v103, 0xbfb8aa3b, v103
	v_mul_f32_e32 v104, 0xbfb8aa3b, v104
	v_mul_f32_e32 v105, 0xbfb8aa3b, v105
	v_exp_f32_e32 v102, v102
	v_exp_f32_e32 v103, v103
	v_exp_f32_e32 v104, v104
	v_exp_f32_e32 v105, v105
	v_add_f32_e32 v102, 1.0, v102
	v_add_f32_e32 v103, 1.0, v103
	v_add_f32_e32 v104, 1.0, v104
	v_add_f32_e32 v105, 1.0, v105
	v_rcp_f32_e32 v102, v102
	v_rcp_f32_e32 v103, v103
	v_rcp_f32_e32 v104, v104
	v_rcp_f32_e32 v105, v105
	v_lshl_add_u64 v[0:1], v[0:1], 0, s[38:39]
	v_cvt_pk_bf16_f32 v102, v102, v103
	v_lshlrev_b32_e32 v130, 1, v106
	v_cvt_pk_bf16_f32 v103, v104, v105
	v_or_b32_e32 v104, v100, v99
	v_ashrrev_i32_e32 v105, 31, v104
	v_lshl_add_u64 v[0:1], v[0:1], 0, v[130:131]
	v_lshlrev_b64 v[104:105], 11, v[104:105]
	v_lshl_add_u64 v[104:105], v[0:1], 0, v[104:105]
	flat_store_dwordx2 v[104:105], v[102:103]
	ds_read_b128 v[102:105], v98 offset:1088
	s_lshl_b64 s[42:43], s[28:29], 10
	s_mov_b32 s29, 0
	s_waitcnt lgkmcnt(0)
	v_mul_f32_e32 v102, 0xbfb8aa3b, v102
	v_exp_f32_e32 v102, v102
	v_mul_f32_e32 v103, 0xbfb8aa3b, v103
	v_exp_f32_e32 v103, v103
	v_add_f32_e32 v102, 1.0, v102
	v_rcp_f32_e32 v106, v102
	v_add_f32_e32 v102, 1.0, v103
	v_mul_f32_e32 v103, 0xbfb8aa3b, v104
	v_exp_f32_e32 v103, v103
	v_mul_f32_e32 v104, 0xbfb8aa3b, v105
	v_exp_f32_e32 v104, v104
	v_rcp_f32_e32 v105, v102
	v_add_f32_e32 v102, 1.0, v103
	v_rcp_f32_e32 v103, v102
	v_add_f32_e32 v102, 1.0, v104
	v_rcp_f32_e32 v107, v102
	v_or_b32_e32 v102, 4, v99
	v_cvt_pk_bf16_f32 v104, v106, v105
	v_or_b32_e32 v106, v100, v102
	v_cvt_pk_bf16_f32 v105, v103, v107
	v_ashrrev_i32_e32 v107, 31, v106
	v_lshlrev_b64 v[106:107], 11, v[106:107]
	v_lshl_add_u64 v[106:107], v[0:1], 0, v[106:107]
	flat_store_dwordx2 v[106:107], v[104:105]
	ds_read_b128 v[104:107], v98 offset:2176
	s_waitcnt lgkmcnt(0)
	v_mul_f32_e32 v103, 0xbfb8aa3b, v104
	v_exp_f32_e32 v103, v103
	v_mul_f32_e32 v104, 0xbfb8aa3b, v105
	v_exp_f32_e32 v104, v104
	v_add_f32_e32 v103, 1.0, v103
	v_rcp_f32_e32 v105, v103
	v_add_f32_e32 v103, 1.0, v104
	v_mul_f32_e32 v104, 0xbfb8aa3b, v106
	v_exp_f32_e32 v104, v104
	v_mul_f32_e32 v106, 0xbfb8aa3b, v107
	v_exp_f32_e32 v106, v106
	v_rcp_f32_e32 v107, v103
	v_add_f32_e32 v103, 1.0, v104
	v_rcp_f32_e32 v108, v103
	v_add_f32_e32 v103, 1.0, v106
	v_rcp_f32_e32 v106, v103
	v_or_b32_e32 v103, 8, v99
	v_cvt_pk_bf16_f32 v104, v105, v107
	v_cvt_pk_bf16_f32 v105, v108, v106
	v_or_b32_e32 v106, v100, v103
	v_ashrrev_i32_e32 v107, 31, v106
	v_lshlrev_b64 v[106:107], 11, v[106:107]
	v_lshl_add_u64 v[106:107], v[0:1], 0, v[106:107]
	flat_store_dwordx2 v[106:107], v[104:105]
	ds_read_b128 v[104:107], v98 offset:3264
	s_waitcnt lgkmcnt(0)
	v_mul_f32_e32 v104, 0xbfb8aa3b, v104
	v_exp_f32_e32 v104, v104
	v_mul_f32_e32 v105, 0xbfb8aa3b, v105
	v_exp_f32_e32 v105, v105
	v_add_f32_e32 v104, 1.0, v104
	v_rcp_f32_e32 v108, v104
	v_add_f32_e32 v104, 1.0, v105
	v_mul_f32_e32 v105, 0xbfb8aa3b, v106
	v_exp_f32_e32 v105, v105
	v_mul_f32_e32 v106, 0xbfb8aa3b, v107
	v_exp_f32_e32 v106, v106
	v_rcp_f32_e32 v107, v104
	v_add_f32_e32 v104, 1.0, v105
	v_rcp_f32_e32 v105, v104
	v_add_f32_e32 v104, 1.0, v106
	v_rcp_f32_e32 v109, v104
	v_or_b32_e32 v104, 12, v99
	v_cvt_pk_bf16_f32 v106, v108, v107
	v_or_b32_e32 v108, v100, v104
	v_cvt_pk_bf16_f32 v107, v105, v109
	v_ashrrev_i32_e32 v109, 31, v108
	v_lshlrev_b64 v[108:109], 11, v[108:109]
	v_lshl_add_u64 v[108:109], v[0:1], 0, v[108:109]
	flat_store_dwordx2 v[108:109], v[106:107]
	ds_read_b128 v[106:109], v98 offset:4352
	s_waitcnt lgkmcnt(0)
	v_mul_f32_e32 v105, 0xbfb8aa3b, v106
	v_exp_f32_e32 v105, v105
	v_mul_f32_e32 v106, 0xbfb8aa3b, v107
	v_exp_f32_e32 v106, v106
	v_add_f32_e32 v105, 1.0, v105
	v_rcp_f32_e32 v107, v105
	v_add_f32_e32 v105, 1.0, v106
	v_mul_f32_e32 v106, 0xbfb8aa3b, v108
	v_exp_f32_e32 v106, v106
	v_mul_f32_e32 v108, 0xbfb8aa3b, v109
	v_exp_f32_e32 v108, v108
	v_rcp_f32_e32 v109, v105
	v_add_f32_e32 v105, 1.0, v106
	v_rcp_f32_e32 v110, v105
	v_add_f32_e32 v105, 1.0, v108
	v_rcp_f32_e32 v108, v105
	v_or_b32_e32 v105, 16, v99
	v_cvt_pk_bf16_f32 v106, v107, v109
	v_cvt_pk_bf16_f32 v107, v110, v108
	v_or_b32_e32 v108, v100, v105
	v_ashrrev_i32_e32 v109, 31, v108
	v_lshlrev_b64 v[108:109], 11, v[108:109]
	v_lshl_add_u64 v[108:109], v[0:1], 0, v[108:109]
	flat_store_dwordx2 v[108:109], v[106:107]
	ds_read_b128 v[106:109], v98 offset:5440
	s_waitcnt lgkmcnt(0)
	v_mul_f32_e32 v106, 0xbfb8aa3b, v106
	v_exp_f32_e32 v106, v106
	v_mul_f32_e32 v107, 0xbfb8aa3b, v107
	v_exp_f32_e32 v107, v107
	v_add_f32_e32 v106, 1.0, v106
	v_rcp_f32_e32 v110, v106
	v_add_f32_e32 v106, 1.0, v107
	v_mul_f32_e32 v107, 0xbfb8aa3b, v108
	v_exp_f32_e32 v107, v107
	v_mul_f32_e32 v108, 0xbfb8aa3b, v109
	v_exp_f32_e32 v108, v108
	v_rcp_f32_e32 v109, v106
	v_add_f32_e32 v106, 1.0, v107
	v_rcp_f32_e32 v107, v106
	v_add_f32_e32 v106, 1.0, v108
	v_rcp_f32_e32 v111, v106
	v_or_b32_e32 v106, 20, v99
	v_cvt_pk_bf16_f32 v108, v110, v109
	v_or_b32_e32 v110, v100, v106
	v_cvt_pk_bf16_f32 v109, v107, v111
	v_ashrrev_i32_e32 v111, 31, v110
	v_lshlrev_b64 v[110:111], 11, v[110:111]
	v_lshl_add_u64 v[110:111], v[0:1], 0, v[110:111]
	flat_store_dwordx2 v[110:111], v[108:109]
	ds_read_b128 v[108:111], v98 offset:6528
	s_waitcnt lgkmcnt(0)
	v_mul_f32_e32 v107, 0xbfb8aa3b, v108
	v_exp_f32_e32 v107, v107
	v_mul_f32_e32 v108, 0xbfb8aa3b, v109
	v_exp_f32_e32 v108, v108
	v_add_f32_e32 v107, 1.0, v107
	v_rcp_f32_e32 v109, v107
	v_add_f32_e32 v107, 1.0, v108
	v_mul_f32_e32 v108, 0xbfb8aa3b, v110
	v_exp_f32_e32 v108, v108
	v_mul_f32_e32 v110, 0xbfb8aa3b, v111
	v_exp_f32_e32 v110, v110
	v_rcp_f32_e32 v111, v107
	v_add_f32_e32 v107, 1.0, v108
	v_rcp_f32_e32 v112, v107
	v_add_f32_e32 v107, 1.0, v110
	v_rcp_f32_e32 v110, v107
	v_or_b32_e32 v107, 24, v99
	v_cvt_pk_bf16_f32 v108, v109, v111
	v_cvt_pk_bf16_f32 v109, v112, v110
	v_or_b32_e32 v110, v100, v107
	v_ashrrev_i32_e32 v111, 31, v110
	v_lshlrev_b64 v[110:111], 11, v[110:111]
	v_lshl_add_u64 v[110:111], v[0:1], 0, v[110:111]
	flat_store_dwordx2 v[110:111], v[108:109]
	ds_read_b128 v[108:111], v98 offset:7616
	s_waitcnt lgkmcnt(0)
	v_mul_f32_e32 v108, 0xbfb8aa3b, v108
	v_exp_f32_e32 v108, v108
	v_mul_f32_e32 v109, 0xbfb8aa3b, v109
	v_exp_f32_e32 v109, v109
	v_add_f32_e32 v108, 1.0, v108
	v_rcp_f32_e32 v112, v108
	v_add_f32_e32 v108, 1.0, v109
	v_mul_f32_e32 v109, 0xbfb8aa3b, v110
	v_exp_f32_e32 v109, v109
	v_mul_f32_e32 v110, 0xbfb8aa3b, v111
	v_exp_f32_e32 v110, v110
	v_rcp_f32_e32 v111, v108
	v_add_f32_e32 v108, 1.0, v109
	v_rcp_f32_e32 v109, v108
	v_add_f32_e32 v108, 1.0, v110
	v_rcp_f32_e32 v113, v108
	v_or_b32_e32 v108, 28, v99
	v_cvt_pk_bf16_f32 v110, v112, v111
	v_or_b32_e32 v112, v100, v108
	v_cvt_pk_bf16_f32 v111, v109, v113
	v_ashrrev_i32_e32 v113, 31, v112
	v_lshlrev_b64 v[112:113], 11, v[112:113]
	v_lshl_add_u64 v[112:113], v[0:1], 0, v[112:113]
	flat_store_dwordx2 v[112:113], v[110:111]
	ds_write_b128 v101, v[66:69]
	ds_write_b128 v101, v[70:73] offset:64
	ds_write_b128 v101, v[74:77] offset:128
	ds_write_b128 v101, v[78:81] offset:192
	ds_write_b128 v101, v[82:85] offset:4352
	ds_write_b128 v101, v[86:89] offset:4416
	ds_write_b128 v101, v[90:93] offset:4480
	ds_write_b128 v101, v[94:97] offset:4544
	ds_read_b128 v[66:69], v98
	v_or_b32_e32 v70, 32, v100
	s_waitcnt lgkmcnt(0)
	v_mul_f32_e32 v66, 0xbfb8aa3b, v66
	v_mul_f32_e32 v67, 0xbfb8aa3b, v67
	v_mul_f32_e32 v68, 0xbfb8aa3b, v68
	v_mul_f32_e32 v69, 0xbfb8aa3b, v69
	v_exp_f32_e32 v66, v66
	v_exp_f32_e32 v67, v67
	v_exp_f32_e32 v68, v68
	v_exp_f32_e32 v69, v69
	v_add_f32_e32 v66, 1.0, v66
	v_add_f32_e32 v67, 1.0, v67
	v_add_f32_e32 v68, 1.0, v68
	v_add_f32_e32 v69, 1.0, v69
	v_rcp_f32_e32 v66, v66
	v_rcp_f32_e32 v67, v67
	v_rcp_f32_e32 v68, v68
	v_rcp_f32_e32 v69, v69
	v_cvt_pk_bf16_f32 v66, v66, v67
	v_cvt_pk_bf16_f32 v67, v68, v69
	v_or_b32_e32 v68, v70, v99
	v_ashrrev_i32_e32 v69, 31, v68
	v_lshlrev_b64 v[68:69], 11, v[68:69]
	v_lshl_add_u64 v[68:69], v[0:1], 0, v[68:69]
	flat_store_dwordx2 v[68:69], v[66:67]
	ds_read_b128 v[66:69], v98 offset:1088
	s_waitcnt lgkmcnt(0)
	v_mul_f32_e32 v66, 0xbfb8aa3b, v66
	v_mul_f32_e32 v67, 0xbfb8aa3b, v67
	v_mul_f32_e32 v68, 0xbfb8aa3b, v68
	v_mul_f32_e32 v69, 0xbfb8aa3b, v69
	v_exp_f32_e32 v66, v66
	v_exp_f32_e32 v67, v67
	v_exp_f32_e32 v68, v68
	v_exp_f32_e32 v69, v69
	v_add_f32_e32 v66, 1.0, v66
	v_add_f32_e32 v67, 1.0, v67
	v_add_f32_e32 v68, 1.0, v68
	v_add_f32_e32 v69, 1.0, v69
	v_rcp_f32_e32 v66, v66
	v_rcp_f32_e32 v67, v67
	v_rcp_f32_e32 v68, v68
	v_rcp_f32_e32 v69, v69
	v_cvt_pk_bf16_f32 v66, v66, v67
	v_cvt_pk_bf16_f32 v67, v68, v69
	v_or_b32_e32 v68, v70, v102
	v_ashrrev_i32_e32 v69, 31, v68
	v_lshlrev_b64 v[68:69], 11, v[68:69]
	v_lshl_add_u64 v[68:69], v[0:1], 0, v[68:69]
	flat_store_dwordx2 v[68:69], v[66:67]
	ds_read_b128 v[66:69], v98 offset:2176
	s_waitcnt lgkmcnt(0)
	v_mul_f32_e32 v66, 0xbfb8aa3b, v66
	v_mul_f32_e32 v67, 0xbfb8aa3b, v67
	v_mul_f32_e32 v68, 0xbfb8aa3b, v68
	v_mul_f32_e32 v69, 0xbfb8aa3b, v69
	v_exp_f32_e32 v66, v66
	v_exp_f32_e32 v67, v67
	v_exp_f32_e32 v68, v68
	v_exp_f32_e32 v69, v69
	v_add_f32_e32 v66, 1.0, v66
	v_add_f32_e32 v67, 1.0, v67
	v_add_f32_e32 v68, 1.0, v68
	v_add_f32_e32 v69, 1.0, v69
	v_rcp_f32_e32 v66, v66
	v_rcp_f32_e32 v67, v67
	v_rcp_f32_e32 v68, v68
	v_rcp_f32_e32 v69, v69
	v_cvt_pk_bf16_f32 v66, v66, v67
	v_cvt_pk_bf16_f32 v67, v68, v69
	v_or_b32_e32 v68, v70, v103
	v_ashrrev_i32_e32 v69, 31, v68
	v_lshlrev_b64 v[68:69], 11, v[68:69]
	v_lshl_add_u64 v[68:69], v[0:1], 0, v[68:69]
	flat_store_dwordx2 v[68:69], v[66:67]
	ds_read_b128 v[66:69], v98 offset:3264
	s_waitcnt lgkmcnt(0)
	v_mul_f32_e32 v66, 0xbfb8aa3b, v66
	v_mul_f32_e32 v67, 0xbfb8aa3b, v67
	v_mul_f32_e32 v68, 0xbfb8aa3b, v68
	v_mul_f32_e32 v69, 0xbfb8aa3b, v69
	v_exp_f32_e32 v66, v66
	v_exp_f32_e32 v67, v67
	v_exp_f32_e32 v68, v68
	v_exp_f32_e32 v69, v69
	v_add_f32_e32 v66, 1.0, v66
	v_add_f32_e32 v67, 1.0, v67
	v_add_f32_e32 v68, 1.0, v68
	v_add_f32_e32 v69, 1.0, v69
	v_rcp_f32_e32 v66, v66
	v_rcp_f32_e32 v67, v67
	v_rcp_f32_e32 v68, v68
	v_rcp_f32_e32 v69, v69
	v_cvt_pk_bf16_f32 v66, v66, v67
	v_cvt_pk_bf16_f32 v67, v68, v69
	v_or_b32_e32 v68, v70, v104
	v_ashrrev_i32_e32 v69, 31, v68
	v_lshlrev_b64 v[68:69], 11, v[68:69]
	v_lshl_add_u64 v[68:69], v[0:1], 0, v[68:69]
	flat_store_dwordx2 v[68:69], v[66:67]
	ds_read_b128 v[66:69], v98 offset:4352
	s_waitcnt lgkmcnt(0)
	v_mul_f32_e32 v66, 0xbfb8aa3b, v66
	v_mul_f32_e32 v67, 0xbfb8aa3b, v67
	v_mul_f32_e32 v68, 0xbfb8aa3b, v68
	v_mul_f32_e32 v69, 0xbfb8aa3b, v69
	v_exp_f32_e32 v66, v66
	v_exp_f32_e32 v67, v67
	v_exp_f32_e32 v68, v68
	v_exp_f32_e32 v69, v69
	v_add_f32_e32 v66, 1.0, v66
	v_add_f32_e32 v67, 1.0, v67
	v_add_f32_e32 v68, 1.0, v68
	v_add_f32_e32 v69, 1.0, v69
	v_rcp_f32_e32 v66, v66
	v_rcp_f32_e32 v67, v67
	v_rcp_f32_e32 v68, v68
	v_rcp_f32_e32 v69, v69
	v_cvt_pk_bf16_f32 v66, v66, v67
	v_cvt_pk_bf16_f32 v67, v68, v69
	v_or_b32_e32 v68, v70, v105
	v_ashrrev_i32_e32 v69, 31, v68
	v_lshlrev_b64 v[68:69], 11, v[68:69]
	v_lshl_add_u64 v[68:69], v[0:1], 0, v[68:69]
	flat_store_dwordx2 v[68:69], v[66:67]
	ds_read_b128 v[66:69], v98 offset:5440
	s_waitcnt lgkmcnt(0)
	v_mul_f32_e32 v66, 0xbfb8aa3b, v66
	v_mul_f32_e32 v67, 0xbfb8aa3b, v67
	v_mul_f32_e32 v68, 0xbfb8aa3b, v68
	v_mul_f32_e32 v69, 0xbfb8aa3b, v69
	v_exp_f32_e32 v66, v66
	v_exp_f32_e32 v67, v67
	v_exp_f32_e32 v68, v68
	v_exp_f32_e32 v69, v69
	v_add_f32_e32 v66, 1.0, v66
	v_add_f32_e32 v67, 1.0, v67
	v_add_f32_e32 v68, 1.0, v68
	v_add_f32_e32 v69, 1.0, v69
	v_rcp_f32_e32 v66, v66
	v_rcp_f32_e32 v67, v67
	v_rcp_f32_e32 v68, v68
	v_rcp_f32_e32 v69, v69
	v_cvt_pk_bf16_f32 v66, v66, v67
	v_cvt_pk_bf16_f32 v67, v68, v69
	v_or_b32_e32 v68, v70, v106
	v_ashrrev_i32_e32 v69, 31, v68
	v_lshlrev_b64 v[68:69], 11, v[68:69]
	v_lshl_add_u64 v[68:69], v[0:1], 0, v[68:69]
	flat_store_dwordx2 v[68:69], v[66:67]
	ds_read_b128 v[66:69], v98 offset:6528
	s_waitcnt lgkmcnt(0)
	v_mul_f32_e32 v66, 0xbfb8aa3b, v66
	v_mul_f32_e32 v67, 0xbfb8aa3b, v67
	v_mul_f32_e32 v68, 0xbfb8aa3b, v68
	v_mul_f32_e32 v69, 0xbfb8aa3b, v69
	v_exp_f32_e32 v66, v66
	v_exp_f32_e32 v67, v67
	v_exp_f32_e32 v68, v68
	v_exp_f32_e32 v69, v69
	v_add_f32_e32 v66, 1.0, v66
	v_add_f32_e32 v67, 1.0, v67
	v_add_f32_e32 v68, 1.0, v68
	v_add_f32_e32 v69, 1.0, v69
	v_rcp_f32_e32 v66, v66
	v_rcp_f32_e32 v67, v67
	v_rcp_f32_e32 v68, v68
	v_rcp_f32_e32 v69, v69
	v_cvt_pk_bf16_f32 v66, v66, v67
	v_cvt_pk_bf16_f32 v67, v68, v69
	v_or_b32_e32 v68, v70, v107
	v_ashrrev_i32_e32 v69, 31, v68
	v_lshlrev_b64 v[68:69], 11, v[68:69]
	v_lshl_add_u64 v[68:69], v[0:1], 0, v[68:69]
	flat_store_dwordx2 v[68:69], v[66:67]
	ds_read_b128 v[66:69], v98 offset:7616
	s_waitcnt lgkmcnt(0)
	v_mul_f32_e32 v66, 0xbfb8aa3b, v66
	v_mul_f32_e32 v67, 0xbfb8aa3b, v67
	v_mul_f32_e32 v68, 0xbfb8aa3b, v68
	v_mul_f32_e32 v69, 0xbfb8aa3b, v69
	v_exp_f32_e32 v66, v66
	v_exp_f32_e32 v67, v67
	v_exp_f32_e32 v68, v68
	v_exp_f32_e32 v69, v69
	v_add_f32_e32 v66, 1.0, v66
	v_add_f32_e32 v67, 1.0, v67
	v_add_f32_e32 v68, 1.0, v68
	v_add_f32_e32 v69, 1.0, v69
	v_rcp_f32_e32 v66, v66
	v_rcp_f32_e32 v67, v67
	v_rcp_f32_e32 v68, v68
	v_rcp_f32_e32 v69, v69
	v_cvt_pk_bf16_f32 v66, v66, v67
	v_cvt_pk_bf16_f32 v67, v68, v69
	v_or_b32_e32 v68, v70, v108
	v_ashrrev_i32_e32 v69, 31, v68
	v_lshlrev_b64 v[68:69], 11, v[68:69]
	v_lshl_add_u64 v[68:69], v[0:1], 0, v[68:69]
	flat_store_dwordx2 v[68:69], v[66:67]
	ds_write_b128 v101, v[34:37]
	ds_write_b128 v101, v[38:41] offset:64
	ds_write_b128 v101, v[42:45] offset:128
	ds_write_b128 v101, v[46:49] offset:192
	ds_write_b128 v101, v[50:53] offset:4352
	ds_write_b128 v101, v[54:57] offset:4416
	ds_write_b128 v101, v[58:61] offset:4480
	ds_write_b128 v101, v[62:65] offset:4544
	ds_read_b128 v[34:37], v98
	v_or_b32_e32 v38, 64, v100
	s_waitcnt lgkmcnt(0)
	v_mul_f32_e32 v34, 0xbfb8aa3b, v34
	v_mul_f32_e32 v35, 0xbfb8aa3b, v35
	v_mul_f32_e32 v36, 0xbfb8aa3b, v36
	v_mul_f32_e32 v37, 0xbfb8aa3b, v37
	v_exp_f32_e32 v34, v34
	v_exp_f32_e32 v35, v35
	v_exp_f32_e32 v36, v36
	v_exp_f32_e32 v37, v37
	v_add_f32_e32 v34, 1.0, v34
	v_add_f32_e32 v35, 1.0, v35
	v_add_f32_e32 v36, 1.0, v36
	v_add_f32_e32 v37, 1.0, v37
	v_rcp_f32_e32 v34, v34
	v_rcp_f32_e32 v35, v35
	v_rcp_f32_e32 v36, v36
	v_rcp_f32_e32 v37, v37
	v_cvt_pk_bf16_f32 v34, v34, v35
	v_cvt_pk_bf16_f32 v35, v36, v37
	v_or_b32_e32 v36, v38, v99
	v_ashrrev_i32_e32 v37, 31, v36
	v_lshlrev_b64 v[36:37], 11, v[36:37]
	v_lshl_add_u64 v[36:37], v[0:1], 0, v[36:37]
	flat_store_dwordx2 v[36:37], v[34:35]
	ds_read_b128 v[34:37], v98 offset:1088
	s_waitcnt lgkmcnt(0)
	v_mul_f32_e32 v34, 0xbfb8aa3b, v34
	v_mul_f32_e32 v35, 0xbfb8aa3b, v35
	v_mul_f32_e32 v36, 0xbfb8aa3b, v36
	v_mul_f32_e32 v37, 0xbfb8aa3b, v37
	v_exp_f32_e32 v34, v34
	v_exp_f32_e32 v35, v35
	v_exp_f32_e32 v36, v36
	v_exp_f32_e32 v37, v37
	v_add_f32_e32 v34, 1.0, v34
	v_add_f32_e32 v35, 1.0, v35
	v_add_f32_e32 v36, 1.0, v36
	v_add_f32_e32 v37, 1.0, v37
	v_rcp_f32_e32 v34, v34
	v_rcp_f32_e32 v35, v35
	v_rcp_f32_e32 v36, v36
	v_rcp_f32_e32 v37, v37
	v_cvt_pk_bf16_f32 v34, v34, v35
	v_cvt_pk_bf16_f32 v35, v36, v37
	v_or_b32_e32 v36, v38, v102
	v_ashrrev_i32_e32 v37, 31, v36
	v_lshlrev_b64 v[36:37], 11, v[36:37]
	v_lshl_add_u64 v[36:37], v[0:1], 0, v[36:37]
	flat_store_dwordx2 v[36:37], v[34:35]
	ds_read_b128 v[34:37], v98 offset:2176
	s_waitcnt lgkmcnt(0)
	v_mul_f32_e32 v34, 0xbfb8aa3b, v34
	v_mul_f32_e32 v35, 0xbfb8aa3b, v35
	v_mul_f32_e32 v36, 0xbfb8aa3b, v36
	v_mul_f32_e32 v37, 0xbfb8aa3b, v37
	v_exp_f32_e32 v34, v34
	v_exp_f32_e32 v35, v35
	v_exp_f32_e32 v36, v36
	v_exp_f32_e32 v37, v37
	v_add_f32_e32 v34, 1.0, v34
	v_add_f32_e32 v35, 1.0, v35
	v_add_f32_e32 v36, 1.0, v36
	v_add_f32_e32 v37, 1.0, v37
	v_rcp_f32_e32 v34, v34
	v_rcp_f32_e32 v35, v35
	v_rcp_f32_e32 v36, v36
	v_rcp_f32_e32 v37, v37
	v_cvt_pk_bf16_f32 v34, v34, v35
	v_cvt_pk_bf16_f32 v35, v36, v37
	v_or_b32_e32 v36, v38, v103
	v_ashrrev_i32_e32 v37, 31, v36
	v_lshlrev_b64 v[36:37], 11, v[36:37]
	v_lshl_add_u64 v[36:37], v[0:1], 0, v[36:37]
	flat_store_dwordx2 v[36:37], v[34:35]
	ds_read_b128 v[34:37], v98 offset:3264
	s_waitcnt lgkmcnt(0)
	v_mul_f32_e32 v34, 0xbfb8aa3b, v34
	v_mul_f32_e32 v35, 0xbfb8aa3b, v35
	v_mul_f32_e32 v36, 0xbfb8aa3b, v36
	v_mul_f32_e32 v37, 0xbfb8aa3b, v37
	v_exp_f32_e32 v34, v34
	v_exp_f32_e32 v35, v35
	v_exp_f32_e32 v36, v36
	v_exp_f32_e32 v37, v37
	v_add_f32_e32 v34, 1.0, v34
	v_add_f32_e32 v35, 1.0, v35
	v_add_f32_e32 v36, 1.0, v36
	v_add_f32_e32 v37, 1.0, v37
	v_rcp_f32_e32 v34, v34
	v_rcp_f32_e32 v35, v35
	v_rcp_f32_e32 v36, v36
	v_rcp_f32_e32 v37, v37
	v_cvt_pk_bf16_f32 v34, v34, v35
	v_cvt_pk_bf16_f32 v35, v36, v37
	v_or_b32_e32 v36, v38, v104
	v_ashrrev_i32_e32 v37, 31, v36
	v_lshlrev_b64 v[36:37], 11, v[36:37]
	v_lshl_add_u64 v[36:37], v[0:1], 0, v[36:37]
	flat_store_dwordx2 v[36:37], v[34:35]
	ds_read_b128 v[34:37], v98 offset:4352
	s_waitcnt lgkmcnt(0)
	v_mul_f32_e32 v34, 0xbfb8aa3b, v34
	v_mul_f32_e32 v35, 0xbfb8aa3b, v35
	v_mul_f32_e32 v36, 0xbfb8aa3b, v36
	v_mul_f32_e32 v37, 0xbfb8aa3b, v37
	v_exp_f32_e32 v34, v34
	v_exp_f32_e32 v35, v35
	v_exp_f32_e32 v36, v36
	v_exp_f32_e32 v37, v37
	v_add_f32_e32 v34, 1.0, v34
	v_add_f32_e32 v35, 1.0, v35
	v_add_f32_e32 v36, 1.0, v36
	v_add_f32_e32 v37, 1.0, v37
	v_rcp_f32_e32 v34, v34
	v_rcp_f32_e32 v35, v35
	v_rcp_f32_e32 v36, v36
	v_rcp_f32_e32 v37, v37
	v_cvt_pk_bf16_f32 v34, v34, v35
	v_cvt_pk_bf16_f32 v35, v36, v37
	v_or_b32_e32 v36, v38, v105
	v_ashrrev_i32_e32 v37, 31, v36
	v_lshlrev_b64 v[36:37], 11, v[36:37]
	v_lshl_add_u64 v[36:37], v[0:1], 0, v[36:37]
	flat_store_dwordx2 v[36:37], v[34:35]
	ds_read_b128 v[34:37], v98 offset:5440
	s_waitcnt lgkmcnt(0)
	v_mul_f32_e32 v34, 0xbfb8aa3b, v34
	v_mul_f32_e32 v35, 0xbfb8aa3b, v35
	v_mul_f32_e32 v36, 0xbfb8aa3b, v36
	v_mul_f32_e32 v37, 0xbfb8aa3b, v37
	v_exp_f32_e32 v34, v34
	v_exp_f32_e32 v35, v35
	v_exp_f32_e32 v36, v36
	v_exp_f32_e32 v37, v37
	v_add_f32_e32 v34, 1.0, v34
	v_add_f32_e32 v35, 1.0, v35
	v_add_f32_e32 v36, 1.0, v36
	v_add_f32_e32 v37, 1.0, v37
	v_rcp_f32_e32 v34, v34
	v_rcp_f32_e32 v35, v35
	v_rcp_f32_e32 v36, v36
	v_rcp_f32_e32 v37, v37
	v_cvt_pk_bf16_f32 v34, v34, v35
	v_cvt_pk_bf16_f32 v35, v36, v37
	v_or_b32_e32 v36, v38, v106
	v_ashrrev_i32_e32 v37, 31, v36
	v_lshlrev_b64 v[36:37], 11, v[36:37]
	v_lshl_add_u64 v[36:37], v[0:1], 0, v[36:37]
	flat_store_dwordx2 v[36:37], v[34:35]
	ds_read_b128 v[34:37], v98 offset:6528
	s_waitcnt lgkmcnt(0)
	v_mul_f32_e32 v34, 0xbfb8aa3b, v34
	v_mul_f32_e32 v35, 0xbfb8aa3b, v35
	v_mul_f32_e32 v36, 0xbfb8aa3b, v36
	v_mul_f32_e32 v37, 0xbfb8aa3b, v37
	v_exp_f32_e32 v34, v34
	v_exp_f32_e32 v35, v35
	v_exp_f32_e32 v36, v36
	v_exp_f32_e32 v37, v37
	v_add_f32_e32 v34, 1.0, v34
	v_add_f32_e32 v35, 1.0, v35
	v_add_f32_e32 v36, 1.0, v36
	v_add_f32_e32 v37, 1.0, v37
	v_rcp_f32_e32 v34, v34
	v_rcp_f32_e32 v35, v35
	v_rcp_f32_e32 v36, v36
	v_rcp_f32_e32 v37, v37
	v_cvt_pk_bf16_f32 v34, v34, v35
	v_cvt_pk_bf16_f32 v35, v36, v37
	v_or_b32_e32 v36, v38, v107
	v_ashrrev_i32_e32 v37, 31, v36
	v_lshlrev_b64 v[36:37], 11, v[36:37]
	v_lshl_add_u64 v[36:37], v[0:1], 0, v[36:37]
	flat_store_dwordx2 v[36:37], v[34:35]
	ds_read_b128 v[34:37], v98 offset:7616
	s_waitcnt lgkmcnt(0)
	v_mul_f32_e32 v34, 0xbfb8aa3b, v34
	v_mul_f32_e32 v35, 0xbfb8aa3b, v35
	v_mul_f32_e32 v36, 0xbfb8aa3b, v36
	v_mul_f32_e32 v37, 0xbfb8aa3b, v37
	v_exp_f32_e32 v34, v34
	v_exp_f32_e32 v35, v35
	v_exp_f32_e32 v36, v36
	v_exp_f32_e32 v37, v37
	v_add_f32_e32 v34, 1.0, v34
	v_add_f32_e32 v35, 1.0, v35
	v_add_f32_e32 v36, 1.0, v36
	v_add_f32_e32 v37, 1.0, v37
	v_rcp_f32_e32 v34, v34
	v_rcp_f32_e32 v35, v35
	v_rcp_f32_e32 v36, v36
	v_rcp_f32_e32 v37, v37
	v_cvt_pk_bf16_f32 v34, v34, v35
	v_cvt_pk_bf16_f32 v35, v36, v37
	v_or_b32_e32 v36, v38, v108
	v_ashrrev_i32_e32 v37, 31, v36
	v_lshlrev_b64 v[36:37], 11, v[36:37]
	v_lshl_add_u64 v[36:37], v[0:1], 0, v[36:37]
	flat_store_dwordx2 v[36:37], v[34:35]
	ds_write_b128 v101, v[2:5]
	ds_write_b128 v101, v[6:9] offset:64
	ds_write_b128 v101, v[10:13] offset:128
	ds_write_b128 v101, v[14:17] offset:192
	ds_write_b128 v101, v[18:21] offset:4352
	ds_write_b128 v101, v[22:25] offset:4416
	ds_write_b128 v101, v[26:29] offset:4480
	ds_write_b128 v101, v[30:33] offset:4544
	ds_read_b128 v[2:5], v98
	v_or_b32_e32 v6, 0x60, v100
	v_mov_b32_e32 v20, v132
	v_mov_b32_e32 v7, v131
	v_mov_b32_e32 v11, v131
	s_waitcnt lgkmcnt(0)
	v_mul_f32_e32 v2, 0xbfb8aa3b, v2
	v_mul_f32_e32 v3, 0xbfb8aa3b, v3
	v_mul_f32_e32 v4, 0xbfb8aa3b, v4
	v_mul_f32_e32 v5, 0xbfb8aa3b, v5
	v_exp_f32_e32 v2, v2
	v_exp_f32_e32 v3, v3
	v_exp_f32_e32 v4, v4
	v_exp_f32_e32 v5, v5
	v_add_f32_e32 v2, 1.0, v2
	v_add_f32_e32 v3, 1.0, v3
	v_add_f32_e32 v4, 1.0, v4
	v_add_f32_e32 v5, 1.0, v5
	v_rcp_f32_e32 v2, v2
	v_rcp_f32_e32 v3, v3
	v_rcp_f32_e32 v4, v4
	v_rcp_f32_e32 v5, v5
	v_mov_b32_e32 v19, v131
	v_cvt_pk_bf16_f32 v2, v2, v3
	v_cvt_pk_bf16_f32 v3, v4, v5
	v_or_b32_e32 v4, v6, v99
	v_ashrrev_i32_e32 v5, 31, v4
	v_lshlrev_b64 v[4:5], 11, v[4:5]
	v_lshl_add_u64 v[4:5], v[0:1], 0, v[4:5]
	flat_store_dwordx2 v[4:5], v[2:3]
	ds_read_b128 v[2:5], v98 offset:1088
	s_waitcnt lgkmcnt(0)
	v_mul_f32_e32 v2, 0xbfb8aa3b, v2
	v_mul_f32_e32 v3, 0xbfb8aa3b, v3
	v_mul_f32_e32 v4, 0xbfb8aa3b, v4
	v_mul_f32_e32 v5, 0xbfb8aa3b, v5
	v_exp_f32_e32 v2, v2
	v_exp_f32_e32 v3, v3
	v_exp_f32_e32 v4, v4
	v_exp_f32_e32 v5, v5
	v_add_f32_e32 v2, 1.0, v2
	v_add_f32_e32 v3, 1.0, v3
	v_add_f32_e32 v4, 1.0, v4
	v_add_f32_e32 v5, 1.0, v5
	v_rcp_f32_e32 v2, v2
	v_rcp_f32_e32 v3, v3
	v_rcp_f32_e32 v4, v4
	v_rcp_f32_e32 v5, v5
	v_cvt_pk_bf16_f32 v2, v2, v3
	v_cvt_pk_bf16_f32 v3, v4, v5
	v_or_b32_e32 v4, v6, v102
	v_ashrrev_i32_e32 v5, 31, v4
	v_lshlrev_b64 v[4:5], 11, v[4:5]
	v_lshl_add_u64 v[4:5], v[0:1], 0, v[4:5]
	flat_store_dwordx2 v[4:5], v[2:3]
	ds_read_b128 v[2:5], v98 offset:2176
	s_waitcnt lgkmcnt(0)
	v_mul_f32_e32 v2, 0xbfb8aa3b, v2
	v_mul_f32_e32 v3, 0xbfb8aa3b, v3
	v_mul_f32_e32 v4, 0xbfb8aa3b, v4
	v_mul_f32_e32 v5, 0xbfb8aa3b, v5
	v_exp_f32_e32 v2, v2
	v_exp_f32_e32 v3, v3
	v_exp_f32_e32 v4, v4
	v_exp_f32_e32 v5, v5
	v_add_f32_e32 v2, 1.0, v2
	v_add_f32_e32 v3, 1.0, v3
	v_add_f32_e32 v4, 1.0, v4
	v_add_f32_e32 v5, 1.0, v5
	v_rcp_f32_e32 v2, v2
	v_rcp_f32_e32 v3, v3
	v_rcp_f32_e32 v4, v4
	v_rcp_f32_e32 v5, v5
	v_cvt_pk_bf16_f32 v2, v2, v3
	v_cvt_pk_bf16_f32 v3, v4, v5
	v_or_b32_e32 v4, v6, v103
	v_ashrrev_i32_e32 v5, 31, v4
	v_lshlrev_b64 v[4:5], 11, v[4:5]
	v_lshl_add_u64 v[4:5], v[0:1], 0, v[4:5]
	flat_store_dwordx2 v[4:5], v[2:3]
	ds_read_b128 v[2:5], v98 offset:3264
	s_waitcnt lgkmcnt(0)
	v_mul_f32_e32 v2, 0xbfb8aa3b, v2
	v_mul_f32_e32 v3, 0xbfb8aa3b, v3
	v_mul_f32_e32 v4, 0xbfb8aa3b, v4
	v_mul_f32_e32 v5, 0xbfb8aa3b, v5
	v_exp_f32_e32 v2, v2
	v_exp_f32_e32 v3, v3
	v_exp_f32_e32 v4, v4
	v_exp_f32_e32 v5, v5
	v_add_f32_e32 v2, 1.0, v2
	v_add_f32_e32 v3, 1.0, v3
	v_add_f32_e32 v4, 1.0, v4
	v_add_f32_e32 v5, 1.0, v5
	v_rcp_f32_e32 v2, v2
	v_rcp_f32_e32 v3, v3
	v_rcp_f32_e32 v4, v4
	v_rcp_f32_e32 v5, v5
	v_cvt_pk_bf16_f32 v2, v2, v3
	v_cvt_pk_bf16_f32 v3, v4, v5
	v_or_b32_e32 v4, v6, v104
	v_ashrrev_i32_e32 v5, 31, v4
	v_lshlrev_b64 v[4:5], 11, v[4:5]
	v_lshl_add_u64 v[4:5], v[0:1], 0, v[4:5]
	flat_store_dwordx2 v[4:5], v[2:3]
	ds_read_b128 v[2:5], v98 offset:4352
	s_waitcnt lgkmcnt(0)
	v_mul_f32_e32 v2, 0xbfb8aa3b, v2
	v_mul_f32_e32 v3, 0xbfb8aa3b, v3
	v_mul_f32_e32 v4, 0xbfb8aa3b, v4
	v_mul_f32_e32 v5, 0xbfb8aa3b, v5
	v_exp_f32_e32 v2, v2
	v_exp_f32_e32 v3, v3
	v_exp_f32_e32 v4, v4
	v_exp_f32_e32 v5, v5
	v_add_f32_e32 v2, 1.0, v2
	v_add_f32_e32 v3, 1.0, v3
	v_add_f32_e32 v4, 1.0, v4
	v_add_f32_e32 v5, 1.0, v5
	v_rcp_f32_e32 v2, v2
	v_rcp_f32_e32 v3, v3
	v_rcp_f32_e32 v4, v4
	v_rcp_f32_e32 v5, v5
	v_cvt_pk_bf16_f32 v2, v2, v3
	v_cvt_pk_bf16_f32 v3, v4, v5
	v_or_b32_e32 v4, v6, v105
	v_ashrrev_i32_e32 v5, 31, v4
	v_lshlrev_b64 v[4:5], 11, v[4:5]
	v_lshl_add_u64 v[4:5], v[0:1], 0, v[4:5]
	flat_store_dwordx2 v[4:5], v[2:3]
	ds_read_b128 v[2:5], v98 offset:5440
	s_waitcnt lgkmcnt(0)
	v_mul_f32_e32 v2, 0xbfb8aa3b, v2
	v_mul_f32_e32 v3, 0xbfb8aa3b, v3
	v_mul_f32_e32 v4, 0xbfb8aa3b, v4
	v_mul_f32_e32 v5, 0xbfb8aa3b, v5
	v_exp_f32_e32 v2, v2
	v_exp_f32_e32 v3, v3
	v_exp_f32_e32 v4, v4
	v_exp_f32_e32 v5, v5
	v_add_f32_e32 v2, 1.0, v2
	v_add_f32_e32 v3, 1.0, v3
	v_add_f32_e32 v4, 1.0, v4
	v_add_f32_e32 v5, 1.0, v5
	v_rcp_f32_e32 v2, v2
	v_rcp_f32_e32 v3, v3
	v_rcp_f32_e32 v4, v4
	v_rcp_f32_e32 v5, v5
	v_cvt_pk_bf16_f32 v2, v2, v3
	v_cvt_pk_bf16_f32 v3, v4, v5
	v_or_b32_e32 v4, v6, v106
	v_ashrrev_i32_e32 v5, 31, v4
	v_lshlrev_b64 v[4:5], 11, v[4:5]
	v_lshl_add_u64 v[4:5], v[0:1], 0, v[4:5]
	flat_store_dwordx2 v[4:5], v[2:3]
	ds_read_b128 v[2:5], v98 offset:6528
	s_waitcnt lgkmcnt(0)
	v_mul_f32_e32 v2, 0xbfb8aa3b, v2
	v_mul_f32_e32 v3, 0xbfb8aa3b, v3
	v_mul_f32_e32 v4, 0xbfb8aa3b, v4
	v_mul_f32_e32 v5, 0xbfb8aa3b, v5
	v_exp_f32_e32 v2, v2
	v_exp_f32_e32 v3, v3
	v_exp_f32_e32 v4, v4
	v_exp_f32_e32 v5, v5
	v_add_f32_e32 v2, 1.0, v2
	v_add_f32_e32 v3, 1.0, v3
	v_add_f32_e32 v4, 1.0, v4
	v_add_f32_e32 v5, 1.0, v5
	v_rcp_f32_e32 v2, v2
	v_rcp_f32_e32 v3, v3
	v_rcp_f32_e32 v4, v4
	v_rcp_f32_e32 v5, v5
	v_cvt_pk_bf16_f32 v2, v2, v3
	v_cvt_pk_bf16_f32 v3, v4, v5
	v_or_b32_e32 v4, v6, v107
	v_ashrrev_i32_e32 v5, 31, v4
	v_lshlrev_b64 v[4:5], 11, v[4:5]
	v_lshl_add_u64 v[4:5], v[0:1], 0, v[4:5]
	flat_store_dwordx2 v[4:5], v[2:3]
	ds_read_b128 v[2:5], v98 offset:7616
	v_mov_b32_e32 v98, v132
	s_waitcnt lgkmcnt(0)
	v_mul_f32_e32 v2, 0xbfb8aa3b, v2
	v_mul_f32_e32 v3, 0xbfb8aa3b, v3
	v_mul_f32_e32 v4, 0xbfb8aa3b, v4
	v_mul_f32_e32 v5, 0xbfb8aa3b, v5
	v_exp_f32_e32 v2, v2
	v_exp_f32_e32 v3, v3
	v_exp_f32_e32 v4, v4
	v_exp_f32_e32 v5, v5
	v_add_f32_e32 v2, 1.0, v2
	v_add_f32_e32 v3, 1.0, v3
	v_add_f32_e32 v4, 1.0, v4
	v_add_f32_e32 v5, 1.0, v5
	v_rcp_f32_e32 v2, v2
	v_rcp_f32_e32 v3, v3
	v_rcp_f32_e32 v4, v4
	v_rcp_f32_e32 v5, v5
	v_cvt_pk_bf16_f32 v2, v2, v3
	v_cvt_pk_bf16_f32 v3, v4, v5
	v_or_b32_e32 v4, v6, v108
	v_ashrrev_i32_e32 v5, 31, v4
	v_lshlrev_b64 v[4:5], 11, v[4:5]
	v_lshl_add_u64 v[0:1], v[0:1], 0, v[4:5]
	flat_store_dwordx2 v[0:1], v[2:3]
	v_mov_b32_e32 v0, s3
	ds_read_b128 v[0:3], v0
	s_waitcnt lgkmcnt(0)
	v_lshl_add_u64 v[4:5], v[2:3], 0, s[42:43]
	s_lshl_b64 s[42:43], s[30:31], 10
	v_lshl_add_u64 v[2:3], v[2:3], 0, s[42:43]
	v_lshl_add_u64 v[16:17], v[2:3], 0, s[12:13]
	v_lshlrev_b32_e32 v2, 4, v20
	v_and_b32_e32 v3, 32, v20
	v_bitop3_b32 v3, v2, v3, 48 bitop3:0x6c
	v_lshl_add_u64 v[14:15], v[4:5], 0, s[10:11]
	v_lshrrev_b32_e32 v5, 1, v20
	v_lshrrev_b32_e32 v3, 1, v3
	v_bfe_u32 v4, v20, 2, 4
	v_and_or_b32 v3, v5, 32, v3
	v_lshrrev_b32_e32 v5, 3, v20
	v_and_or_b32 v5, v5, s50, v4
	v_lshl_or_b32 v130, v5, 9, v3
	v_add_u32_e32 v5, 0x2000, v2
	v_lshrrev_b32_e32 v5, 7, v5
	v_and_or_b32 v5, v5, s50, v4
	v_lshl_or_b32 v6, v5, 9, v3
	v_add_u32_e32 v5, 0x4000, v2
	v_and_b32_e32 v21, 0xfffffc00, v2
	v_lshrrev_b32_e32 v5, 7, v5
	v_add_u32_e32 v2, 0x6000, v2
	v_and_or_b32 v5, v5, s50, v4
	v_lshrrev_b32_e32 v2, 7, v2
	v_add_u32_e32 v45, 0, v21
	v_lshl_or_b32 v10, v5, 9, v3
	v_and_or_b32 v2, v2, s50, v4
	v_add_u32_e32 v44, 0x8000, v45
	v_lshlrev_b64 v[4:5], 1, v[130:131]
	v_readfirstlane_b32 s60, v45
	v_lshl_or_b32 v18, v2, 9, v3
	v_lshl_add_u64 v[2:3], v[14:15], 0, v[4:5]
	s_mov_b32 m0, s60
	v_readfirstlane_b32 s58, v44
	v_add_u32_e32 v46, 0x2000, v45
	global_load_lds_dwordx4 v[2:3], off
	v_lshl_add_u64 v[4:5], v[16:17], 0, v[4:5]
	s_mov_b32 m0, s58
	v_lshlrev_b64 v[8:9], 1, v[6:7]
	v_readfirstlane_b32 s59, v46
	v_add_u32_e32 v47, 0xa000, v45
	global_load_lds_dwordx4 v[4:5], off
	v_lshl_add_u64 v[6:7], v[14:15], 0, v[8:9]
	s_mov_b32 m0, s59
	v_readfirstlane_b32 s61, v47
	v_add_u32_e32 v48, 0x4000, v45
	global_load_lds_dwordx4 v[6:7], off
	v_lshl_add_u64 v[8:9], v[16:17], 0, v[8:9]
	s_mov_b32 m0, s61
	v_lshlrev_b64 v[12:13], 1, v[10:11]
	v_readfirstlane_b32 s62, v48
	v_add_u32_e32 v49, 0xc000, v45
	v_lshlrev_b64 v[18:19], 1, v[18:19]
	v_and_b32_e32 v22, 15, v20
	global_load_lds_dwordx4 v[8:9], off
	v_lshl_add_u64 v[10:11], v[14:15], 0, v[12:13]
	s_mov_b32 m0, s62
	v_lshl_add_u64 v[12:13], v[16:17], 0, v[12:13]
	v_readfirstlane_b32 s63, v49
	v_lshl_add_u64 v[14:15], v[14:15], 0, v[18:19]
	v_add_u32_e32 v50, 0x6000, v45
	v_lshl_add_u64 v[16:17], v[16:17], 0, v[18:19]
	v_lshlrev_b32_e32 v19, 2, v20
	global_load_lds_dwordx4 v[10:11], off
	s_mov_b32 m0, s63
	v_readfirstlane_b32 s64, v50
	v_add_u32_e32 v51, 0xe000, v45
	v_and_b32_e32 v23, 48, v20
	v_lshlrev_b32_e32 v18, 6, v22
	v_and_b32_e32 v22, 32, v19
	global_load_lds_dwordx4 v[12:13], off
	s_mov_b32 m0, s64
	v_readfirstlane_b32 s65, v51
	v_bitop3_b32 v96, v18, v22, v23 bitop3:0x36
	v_lshlrev_b32_e32 v18, 7, v20
	v_add_u32_e32 v37, s46, v21
	global_load_lds_dwordx4 v[14:15], off
	s_mov_b32 m0, s65
	v_and_b32_e32 v97, 0x6000, v18
	v_lshlrev_b32_e32 v18, 6, v20
	v_add_u32_e32 v36, s47, v21
	v_readfirstlane_b32 s53, v37
	global_load_lds_dwordx4 v[16:17], off
	v_and_b32_e32 v99, 0xffffc000, v18
	v_and_b32_e32 v20, 0x3c0, v18
	v_lshl_add_u64 v[18:19], v[2:3], 0, s[6:7]
	s_mov_b32 m0, s53
	v_readfirstlane_b32 s0, v36
	v_add_u32_e32 v38, 0x2000, v37
	s_waitcnt vmcnt(0)
	s_waitcnt vmcnt(0) lgkmcnt(0)
	s_barrier
	global_load_lds_dwordx4 v[18:19], off
	v_lshl_add_u64 v[18:19], v[4:5], 0, s[6:7]
	s_mov_b32 m0, s0
	v_readfirstlane_b32 s42, v38
	v_add_u32_e32 v39, 0x2000, v36
	global_load_lds_dwordx4 v[18:19], off
	v_lshl_add_u64 v[18:19], v[6:7], 0, s[6:7]
	s_mov_b32 m0, s42
	v_readfirstlane_b32 s43, v39
	v_add_u32_e32 v40, 0x4000, v37
	global_load_lds_dwordx4 v[18:19], off
	v_lshl_add_u64 v[18:19], v[8:9], 0, s[6:7]
	s_mov_b32 m0, s43
	v_readfirstlane_b32 s54, v40
	v_add_u32_e32 v41, 0x4000, v36
	global_load_lds_dwordx4 v[18:19], off
	v_lshl_add_u64 v[18:19], v[10:11], 0, s[6:7]
	s_mov_b32 m0, s54
	v_readfirstlane_b32 s55, v41
	v_add_u32_e32 v42, 0x6000, v37
	global_load_lds_dwordx4 v[18:19], off
	v_lshl_add_u64 v[18:19], v[12:13], 0, s[6:7]
	s_mov_b32 m0, s55
	v_readfirstlane_b32 s56, v42
	v_add_u32_e32 v43, 0x6000, v36
	global_load_lds_dwordx4 v[18:19], off
	v_lshl_add_u64 v[18:19], v[14:15], 0, s[6:7]
	s_mov_b32 m0, s56
	v_readfirstlane_b32 s57, v43
	global_load_lds_dwordx4 v[18:19], off
	v_lshl_add_u64 v[18:19], v[16:17], 0, s[6:7]
	s_mov_b32 m0, s57
	v_add_u32_e32 v129, 0, v96
	global_load_lds_dwordx4 v[18:19], off
	v_add_u32_e32 v18, v129, v97
	ds_read_b128 v[24:27], v18 offset:32768
	ds_read_b128 v[56:59], v18 offset:34816
	ds_read_b128 v[64:67], v18 offset:36864
	ds_read_b128 v[72:75], v18 offset:38912
	v_bitop3_b32 v130, v20, v22, v23 bitop3:0x36
	v_add_u32_e32 v23, 0, v130
	v_or_b32_e32 v222, 0x3000, v99
	v_add_u32_e32 v20, v23, v222
	ds_read_b128 v[32:35], v20
	v_or_b32_e32 v223, 0x2800, v99
	v_add_u32_e32 v21, v23, v223
	s_waitcnt lgkmcnt(0)
	v_mfma_f32_16x16x32_bf16 v[76:79], v[24:27], v[32:35], 0
	v_or_b32_e32 v128, 0x3800, v99
	v_or_b32_e32 v218, 0x2000, v99
	v_or_b32_e32 v219, 0x1000, v99
	v_mfma_f32_16x16x32_bf16 v[80:83], v[56:59], v[32:35], 0
	v_or_b32_e32 v220, 0x1800, v99
	v_add_u32_e32 v19, v23, v128
	v_add_u32_e32 v22, v23, v218
	v_mfma_f32_16x16x32_bf16 v[84:87], v[64:67], v[32:35], 0
	ds_read_b128 v[28:31], v19
	ds_read_b128 v[112:115], v22
	v_mfma_f32_16x16x32_bf16 v[88:91], v[72:75], v[32:35], 0
	ds_read_b128 v[32:35], v21
	s_waitcnt lgkmcnt(0)
	v_mfma_f32_16x16x32_bf16 v[92:95], v[24:27], v[32:35], 0
	v_mfma_f32_16x16x32_bf16 v[100:103], v[56:59], v[32:35], 0
	v_mfma_f32_16x16x32_bf16 v[104:107], v[64:67], v[32:35], 0
	v_mfma_f32_16x16x32_bf16 v[108:111], v[72:75], v[32:35], 0
	v_add_u32_e32 v32, v129, v99
	v_or_b32_e32 v129, 0x800, v99
	v_add_u32_e32 v33, v23, v129
	v_add_u32_e32 v34, v23, v219
	v_add_u32_e32 v35, v23, v220
	ds_read_b128 v[134:137], v32
	ds_read_b128 v[150:153], v33
	ds_read_b128 v[166:169], v34
	ds_read_b128 v[182:185], v35
	s_waitcnt lgkmcnt(0)
	v_mfma_f32_16x16x32_bf16 v[178:181], v[64:67], v[166:169], 0
	v_mfma_f32_16x16x32_bf16 v[162:165], v[64:67], v[150:153], 0
	v_mfma_f32_16x16x32_bf16 v[146:149], v[64:67], v[134:137], 0
	v_mfma_f32_16x16x32_bf16 v[68:71], v[64:67], v[28:31], 0
	v_mfma_f32_16x16x32_bf16 v[124:127], v[64:67], v[112:115], 0
	v_mfma_f32_16x16x32_bf16 v[64:67], v[64:67], v[182:185], 0
	v_mfma_f32_16x16x32_bf16 v[174:177], v[56:59], v[166:169], 0
	v_mfma_f32_16x16x32_bf16 v[158:161], v[56:59], v[150:153], 0
	v_mfma_f32_16x16x32_bf16 v[142:145], v[56:59], v[134:137], 0
	v_mfma_f32_16x16x32_bf16 v[60:63], v[56:59], v[28:31], 0
	v_mfma_f32_16x16x32_bf16 v[120:123], v[56:59], v[112:115], 0
	v_mfma_f32_16x16x32_bf16 v[56:59], v[56:59], v[182:185], 0
	v_mfma_f32_16x16x32_bf16 v[170:173], v[24:27], v[166:169], 0
	v_mfma_f32_16x16x32_bf16 v[154:157], v[24:27], v[150:153], 0
	v_mfma_f32_16x16x32_bf16 v[138:141], v[24:27], v[134:137], 0
	v_mfma_f32_16x16x32_bf16 v[52:55], v[24:27], v[28:31], 0
	v_mfma_f32_16x16x32_bf16 v[116:119], v[24:27], v[112:115], 0
	v_mfma_f32_16x16x32_bf16 v[24:27], v[24:27], v[182:185], 0
	v_mfma_f32_16x16x32_bf16 v[166:169], v[72:75], v[166:169], 0
	v_mfma_f32_16x16x32_bf16 v[150:153], v[72:75], v[150:153], 0
	v_mfma_f32_16x16x32_bf16 v[134:137], v[72:75], v[134:137], 0
	v_mfma_f32_16x16x32_bf16 v[28:31], v[72:75], v[28:31], 0
	v_mfma_f32_16x16x32_bf16 v[112:115], v[72:75], v[112:115], 0
	v_mfma_f32_16x16x32_bf16 v[72:75], v[72:75], v[182:185], 0
	ds_read_b128 v[182:185], v18 offset:33792
	ds_read_b128 v[186:189], v18 offset:35840
	ds_read_b128 v[190:193], v18 offset:37888
	ds_read_b128 v[198:201], v18 offset:39936
	ds_read_b128 v[194:197], v32 offset:1024
	ds_read_b128 v[202:205], v33 offset:1024
	ds_read_b128 v[206:209], v34 offset:1024
	ds_read_b128 v[210:213], v35 offset:1024
	s_waitcnt lgkmcnt(0)
	v_mfma_f32_16x16x32_bf16 v[138:141], v[182:185], v[194:197], v[138:141]
	v_mfma_f32_16x16x32_bf16 v[142:145], v[186:189], v[194:197], v[142:145]
	v_mfma_f32_16x16x32_bf16 v[146:149], v[190:193], v[194:197], v[146:149]
	v_mfma_f32_16x16x32_bf16 v[134:137], v[198:201], v[194:197], v[134:137]
	ds_read_b128 v[194:197], v22 offset:1024
	v_mfma_f32_16x16x32_bf16 v[154:157], v[182:185], v[202:205], v[154:157]
	v_mfma_f32_16x16x32_bf16 v[158:161], v[186:189], v[202:205], v[158:161]
	v_mfma_f32_16x16x32_bf16 v[162:165], v[190:193], v[202:205], v[162:165]
	v_mfma_f32_16x16x32_bf16 v[150:153], v[198:201], v[202:205], v[150:153]
	ds_read_b128 v[202:205], v21 offset:1024
	v_mfma_f32_16x16x32_bf16 v[170:173], v[182:185], v[206:209], v[170:173]
	v_mfma_f32_16x16x32_bf16 v[174:177], v[186:189], v[206:209], v[174:177]
	v_mfma_f32_16x16x32_bf16 v[178:181], v[190:193], v[206:209], v[178:181]
	v_mfma_f32_16x16x32_bf16 v[166:169], v[198:201], v[206:209], v[166:169]
	ds_read_b128 v[206:209], v20 offset:1024
	v_mfma_f32_16x16x32_bf16 v[214:217], v[182:185], v[210:213], v[24:27]
	v_mfma_f32_16x16x32_bf16 v[56:59], v[186:189], v[210:213], v[56:59]
	v_mfma_f32_16x16x32_bf16 v[64:67], v[190:193], v[210:213], v[64:67]
	v_mfma_f32_16x16x32_bf16 v[72:75], v[198:201], v[210:213], v[72:75]
	ds_read_b128 v[24:27], v19 offset:1024
	s_waitcnt lgkmcnt(0)
	v_mfma_f32_16x16x32_bf16 v[116:119], v[182:185], v[194:197], v[116:119]
	v_mfma_f32_16x16x32_bf16 v[120:123], v[186:189], v[194:197], v[120:123]
	v_mfma_f32_16x16x32_bf16 v[124:127], v[190:193], v[194:197], v[124:127]
	v_mfma_f32_16x16x32_bf16 v[112:115], v[198:201], v[194:197], v[112:115]
	v_mfma_f32_16x16x32_bf16 v[92:95], v[182:185], v[202:205], v[92:95]
	v_mfma_f32_16x16x32_bf16 v[100:103], v[186:189], v[202:205], v[100:103]
	v_mfma_f32_16x16x32_bf16 v[104:107], v[190:193], v[202:205], v[104:107]
	v_mfma_f32_16x16x32_bf16 v[108:111], v[198:201], v[202:205], v[108:111]
	v_mfma_f32_16x16x32_bf16 v[76:79], v[182:185], v[206:209], v[76:79]
	v_mfma_f32_16x16x32_bf16 v[80:83], v[186:189], v[206:209], v[80:83]
	v_mfma_f32_16x16x32_bf16 v[84:87], v[190:193], v[206:209], v[84:87]
	v_mfma_f32_16x16x32_bf16 v[88:91], v[198:201], v[206:209], v[88:91]
	v_mfma_f32_16x16x32_bf16 v[52:55], v[182:185], v[24:27], v[52:55]
	v_mfma_f32_16x16x32_bf16 v[60:63], v[186:189], v[24:27], v[60:63]
	v_mfma_f32_16x16x32_bf16 v[68:71], v[190:193], v[24:27], v[68:71]
	v_mfma_f32_16x16x32_bf16 v[182:185], v[198:201], v[24:27], v[28:31]
	s_mov_b32 m0, s60
	v_lshl_add_u64 v[24:25], v[2:3], 0, s[14:15]
	s_waitcnt vmcnt(0)
	s_waitcnt vmcnt(0)
	s_barrier
	global_load_lds_dwordx4 v[24:25], off
	v_lshl_add_u64 v[24:25], v[4:5], 0, s[14:15]
	s_mov_b32 m0, s58
	v_add3_u32 v23, s47, v96, v97
	global_load_lds_dwordx4 v[24:25], off
	v_lshl_add_u64 v[24:25], v[6:7], 0, s[14:15]
	s_mov_b32 m0, s59
	s_nop 0
	global_load_lds_dwordx4 v[24:25], off
	v_lshl_add_u64 v[24:25], v[8:9], 0, s[14:15]
	s_mov_b32 m0, s61
	s_nop 0
	global_load_lds_dwordx4 v[24:25], off
	v_lshl_add_u64 v[24:25], v[10:11], 0, s[14:15]
	s_mov_b32 m0, s62
	s_nop 0
	global_load_lds_dwordx4 v[24:25], off
	v_lshl_add_u64 v[24:25], v[12:13], 0, s[14:15]
	s_mov_b32 m0, s63
	s_nop 0
	global_load_lds_dwordx4 v[24:25], off
	v_lshl_add_u64 v[24:25], v[14:15], 0, s[14:15]
	s_mov_b32 m0, s64
	s_nop 0
	global_load_lds_dwordx4 v[24:25], off
	v_lshl_add_u64 v[24:25], v[16:17], 0, s[14:15]
	s_mov_b32 m0, s65
	s_nop 0
	global_load_lds_dwordx4 v[24:25], off
	ds_read_b128 v[186:189], v23
	ds_read_b128 v[190:193], v23 offset:2048
	ds_read_b128 v[194:197], v23 offset:4096
	ds_read_b128 v[198:201], v23 offset:6144
	v_add3_u32 v24, s46, v96, v99
	v_add_u32_e32 v96, s46, v130
	ds_read_b128 v[28:31], v24
	v_add_u32_e32 v25, v96, v129
	v_add_u32_e32 v26, v96, v219
	v_add_u32_e32 v27, v96, v220
	ds_read_b128 v[202:205], v25
	ds_read_b128 v[206:209], v26
	ds_read_b128 v[210:213], v27
	s_waitcnt lgkmcnt(0)
	v_mfma_f32_16x16x32_bf16 v[138:141], v[186:189], v[28:31], v[138:141]
	v_mfma_f32_16x16x32_bf16 v[142:145], v[190:193], v[28:31], v[142:145]
	v_mfma_f32_16x16x32_bf16 v[146:149], v[194:197], v[28:31], v[146:149]
	v_mfma_f32_16x16x32_bf16 v[134:137], v[198:201], v[28:31], v[134:137]
	v_add_u32_e32 v28, v96, v218
	v_add_u32_e32 v29, v96, v223
	v_add_u32_e32 v30, v96, v222
	v_add_u32_e32 v31, v96, v128
	ds_read_b128 v[218:221], v28
	v_mfma_f32_16x16x32_bf16 v[154:157], v[186:189], v[202:205], v[154:157]
	v_mfma_f32_16x16x32_bf16 v[158:161], v[190:193], v[202:205], v[158:161]
	v_mfma_f32_16x16x32_bf16 v[162:165], v[194:197], v[202:205], v[162:165]
	v_mfma_f32_16x16x32_bf16 v[150:153], v[198:201], v[202:205], v[150:153]
	ds_read_b128 v[202:205], v29
	v_mfma_f32_16x16x32_bf16 v[170:173], v[186:189], v[206:209], v[170:173]
	v_mfma_f32_16x16x32_bf16 v[174:177], v[190:193], v[206:209], v[174:177]
	v_mfma_f32_16x16x32_bf16 v[178:181], v[194:197], v[206:209], v[178:181]
	v_mfma_f32_16x16x32_bf16 v[166:169], v[198:201], v[206:209], v[166:169]
	ds_read_b128 v[206:209], v30
	v_mfma_f32_16x16x32_bf16 v[214:217], v[186:189], v[210:213], v[214:217]
	v_mfma_f32_16x16x32_bf16 v[56:59], v[190:193], v[210:213], v[56:59]
	v_mfma_f32_16x16x32_bf16 v[64:67], v[194:197], v[210:213], v[64:67]
	v_mfma_f32_16x16x32_bf16 v[72:75], v[198:201], v[210:213], v[72:75]
	ds_read_b128 v[210:213], v31
	s_waitcnt lgkmcnt(0)
	v_mfma_f32_16x16x32_bf16 v[116:119], v[186:189], v[218:221], v[116:119]
	v_mfma_f32_16x16x32_bf16 v[120:123], v[190:193], v[218:221], v[120:123]
	v_mfma_f32_16x16x32_bf16 v[124:127], v[194:197], v[218:221], v[124:127]
	v_mfma_f32_16x16x32_bf16 v[112:115], v[198:201], v[218:221], v[112:115]
	v_mfma_f32_16x16x32_bf16 v[92:95], v[186:189], v[202:205], v[92:95]
	v_mfma_f32_16x16x32_bf16 v[100:103], v[190:193], v[202:205], v[100:103]
	v_mfma_f32_16x16x32_bf16 v[104:107], v[194:197], v[202:205], v[104:107]
	v_mfma_f32_16x16x32_bf16 v[108:111], v[198:201], v[202:205], v[108:111]
	v_mfma_f32_16x16x32_bf16 v[76:79], v[186:189], v[206:209], v[76:79]
	v_mfma_f32_16x16x32_bf16 v[80:83], v[190:193], v[206:209], v[80:83]
	v_mfma_f32_16x16x32_bf16 v[84:87], v[194:197], v[206:209], v[84:87]
	v_mfma_f32_16x16x32_bf16 v[88:91], v[198:201], v[206:209], v[88:91]
	v_mfma_f32_16x16x32_bf16 v[52:55], v[186:189], v[210:213], v[52:55]
	v_mfma_f32_16x16x32_bf16 v[60:63], v[190:193], v[210:213], v[60:63]
	v_mfma_f32_16x16x32_bf16 v[68:71], v[194:197], v[210:213], v[68:71]
	v_mfma_f32_16x16x32_bf16 v[182:185], v[198:201], v[210:213], v[182:185]
	ds_read_b128 v[186:189], v23 offset:1024
	ds_read_b128 v[190:193], v23 offset:3072
	ds_read_b128 v[194:197], v23 offset:5120
	ds_read_b128 v[202:205], v23 offset:7168
	ds_read_b128 v[198:201], v24 offset:1024
	ds_read_b128 v[206:209], v25 offset:1024
	ds_read_b128 v[210:213], v26 offset:1024
	ds_read_b128 v[218:221], v27 offset:1024
	s_waitcnt lgkmcnt(0)
	v_mfma_f32_16x16x32_bf16 v[138:141], v[186:189], v[198:201], v[138:141]
	v_mfma_f32_16x16x32_bf16 v[142:145], v[190:193], v[198:201], v[142:145]
	v_mfma_f32_16x16x32_bf16 v[146:149], v[194:197], v[198:201], v[146:149]
	v_mfma_f32_16x16x32_bf16 v[134:137], v[202:205], v[198:201], v[134:137]
	ds_read_b128 v[198:201], v28 offset:1024
	v_mfma_f32_16x16x32_bf16 v[154:157], v[186:189], v[206:209], v[154:157]
	v_mfma_f32_16x16x32_bf16 v[158:161], v[190:193], v[206:209], v[158:161]
	v_mfma_f32_16x16x32_bf16 v[162:165], v[194:197], v[206:209], v[162:165]
	v_mfma_f32_16x16x32_bf16 v[150:153], v[202:205], v[206:209], v[150:153]
	ds_read_b128 v[206:209], v29 offset:1024
	v_mfma_f32_16x16x32_bf16 v[170:173], v[186:189], v[210:213], v[170:173]
	v_mfma_f32_16x16x32_bf16 v[174:177], v[190:193], v[210:213], v[174:177]
	v_mfma_f32_16x16x32_bf16 v[178:181], v[194:197], v[210:213], v[178:181]
	v_mfma_f32_16x16x32_bf16 v[166:169], v[202:205], v[210:213], v[166:169]
	ds_read_b128 v[210:213], v30 offset:1024
	v_mfma_f32_16x16x32_bf16 v[214:217], v[186:189], v[218:221], v[214:217]
	v_mfma_f32_16x16x32_bf16 v[56:59], v[190:193], v[218:221], v[56:59]
	v_mfma_f32_16x16x32_bf16 v[64:67], v[194:197], v[218:221], v[64:67]
	v_mfma_f32_16x16x32_bf16 v[72:75], v[202:205], v[218:221], v[72:75]
	ds_read_b128 v[218:221], v31 offset:1024
	s_waitcnt lgkmcnt(0)
	v_mfma_f32_16x16x32_bf16 v[116:119], v[186:189], v[198:201], v[116:119]
	v_mfma_f32_16x16x32_bf16 v[120:123], v[190:193], v[198:201], v[120:123]
	v_mfma_f32_16x16x32_bf16 v[124:127], v[194:197], v[198:201], v[124:127]
	v_mfma_f32_16x16x32_bf16 v[112:115], v[202:205], v[198:201], v[112:115]
	v_mfma_f32_16x16x32_bf16 v[92:95], v[186:189], v[206:209], v[92:95]
	v_mfma_f32_16x16x32_bf16 v[100:103], v[190:193], v[206:209], v[100:103]
	v_mfma_f32_16x16x32_bf16 v[104:107], v[194:197], v[206:209], v[104:107]
	v_mfma_f32_16x16x32_bf16 v[108:111], v[202:205], v[206:209], v[108:111]
	v_mfma_f32_16x16x32_bf16 v[76:79], v[186:189], v[210:213], v[76:79]
	v_mfma_f32_16x16x32_bf16 v[80:83], v[190:193], v[210:213], v[80:83]
	v_mfma_f32_16x16x32_bf16 v[84:87], v[194:197], v[210:213], v[84:87]
	v_mfma_f32_16x16x32_bf16 v[88:91], v[202:205], v[210:213], v[88:91]
	v_mfma_f32_16x16x32_bf16 v[52:55], v[186:189], v[218:221], v[52:55]
	v_mfma_f32_16x16x32_bf16 v[60:63], v[190:193], v[218:221], v[60:63]
	v_mfma_f32_16x16x32_bf16 v[68:71], v[194:197], v[218:221], v[68:71]
	v_mfma_f32_16x16x32_bf16 v[182:185], v[202:205], v[218:221], v[182:185]
	s_mov_b32 m0, s53
	v_lshl_add_u64 v[96:97], v[2:3], 0, s[16:17]
	s_waitcnt vmcnt(0)
	s_waitcnt vmcnt(0)
	s_barrier
	global_load_lds_dwordx4 v[96:97], off
	v_lshl_add_u64 v[96:97], v[4:5], 0, s[16:17]
	s_mov_b32 m0, s0
	s_nop 0
	global_load_lds_dwordx4 v[96:97], off
	v_lshl_add_u64 v[96:97], v[6:7], 0, s[16:17]
	s_mov_b32 m0, s42
	s_nop 0
	global_load_lds_dwordx4 v[96:97], off
	v_lshl_add_u64 v[96:97], v[8:9], 0, s[16:17]
	s_mov_b32 m0, s43
	s_nop 0
	global_load_lds_dwordx4 v[96:97], off
	v_lshl_add_u64 v[96:97], v[10:11], 0, s[16:17]
	s_mov_b32 m0, s54
	s_nop 0
	global_load_lds_dwordx4 v[96:97], off
	v_lshl_add_u64 v[96:97], v[12:13], 0, s[16:17]
	s_mov_b32 m0, s55
	s_nop 0
	global_load_lds_dwordx4 v[96:97], off
	v_lshl_add_u64 v[96:97], v[14:15], 0, s[16:17]
	s_mov_b32 m0, s56
	s_nop 0
	global_load_lds_dwordx4 v[96:97], off
	v_lshl_add_u64 v[96:97], v[16:17], 0, s[16:17]
	s_mov_b32 m0, s57
	s_nop 0
	global_load_lds_dwordx4 v[96:97], off
	ds_read_b128 v[186:189], v18 offset:32768
	ds_read_b128 v[190:193], v18 offset:34816
	ds_read_b128 v[194:197], v18 offset:36864
	ds_read_b128 v[202:205], v18 offset:38912
	ds_read_b128 v[198:201], v32
	ds_read_b128 v[206:209], v33
	ds_read_b128 v[210:213], v34
	ds_read_b128 v[218:221], v35
	s_waitcnt lgkmcnt(0)
	v_mfma_f32_16x16x32_bf16 v[138:141], v[186:189], v[198:201], v[138:141]
	v_mfma_f32_16x16x32_bf16 v[142:145], v[190:193], v[198:201], v[142:145]
	v_mfma_f32_16x16x32_bf16 v[146:149], v[194:197], v[198:201], v[146:149]
	v_mfma_f32_16x16x32_bf16 v[134:137], v[202:205], v[198:201], v[134:137]
	ds_read_b128 v[198:201], v22
	v_mfma_f32_16x16x32_bf16 v[154:157], v[186:189], v[206:209], v[154:157]
	v_mfma_f32_16x16x32_bf16 v[158:161], v[190:193], v[206:209], v[158:161]
	v_mfma_f32_16x16x32_bf16 v[162:165], v[194:197], v[206:209], v[162:165]
	v_mfma_f32_16x16x32_bf16 v[150:153], v[202:205], v[206:209], v[150:153]
	ds_read_b128 v[206:209], v21
	v_mfma_f32_16x16x32_bf16 v[170:173], v[186:189], v[210:213], v[170:173]
	v_mfma_f32_16x16x32_bf16 v[174:177], v[190:193], v[210:213], v[174:177]
	v_mfma_f32_16x16x32_bf16 v[178:181], v[194:197], v[210:213], v[178:181]
	v_mfma_f32_16x16x32_bf16 v[166:169], v[202:205], v[210:213], v[166:169]
	ds_read_b128 v[210:213], v20
	v_mfma_f32_16x16x32_bf16 v[214:217], v[186:189], v[218:221], v[214:217]
	v_mfma_f32_16x16x32_bf16 v[56:59], v[190:193], v[218:221], v[56:59]
	v_mfma_f32_16x16x32_bf16 v[64:67], v[194:197], v[218:221], v[64:67]
	v_mfma_f32_16x16x32_bf16 v[72:75], v[202:205], v[218:221], v[72:75]
	ds_read_b128 v[218:221], v19
	s_waitcnt lgkmcnt(0)
	v_mfma_f32_16x16x32_bf16 v[116:119], v[186:189], v[198:201], v[116:119]
	v_mfma_f32_16x16x32_bf16 v[120:123], v[190:193], v[198:201], v[120:123]
	v_mfma_f32_16x16x32_bf16 v[124:127], v[194:197], v[198:201], v[124:127]
	v_mfma_f32_16x16x32_bf16 v[112:115], v[202:205], v[198:201], v[112:115]
	v_mfma_f32_16x16x32_bf16 v[92:95], v[186:189], v[206:209], v[92:95]
	v_mfma_f32_16x16x32_bf16 v[100:103], v[190:193], v[206:209], v[100:103]
	v_mfma_f32_16x16x32_bf16 v[104:107], v[194:197], v[206:209], v[104:107]
	v_mfma_f32_16x16x32_bf16 v[108:111], v[202:205], v[206:209], v[108:111]
	v_mfma_f32_16x16x32_bf16 v[76:79], v[186:189], v[210:213], v[76:79]
	v_mfma_f32_16x16x32_bf16 v[80:83], v[190:193], v[210:213], v[80:83]
	v_mfma_f32_16x16x32_bf16 v[84:87], v[194:197], v[210:213], v[84:87]
	v_mfma_f32_16x16x32_bf16 v[88:91], v[202:205], v[210:213], v[88:91]
	v_mfma_f32_16x16x32_bf16 v[52:55], v[186:189], v[218:221], v[52:55]
	v_mfma_f32_16x16x32_bf16 v[60:63], v[190:193], v[218:221], v[60:63]
	v_mfma_f32_16x16x32_bf16 v[68:71], v[194:197], v[218:221], v[68:71]
	v_mfma_f32_16x16x32_bf16 v[182:185], v[202:205], v[218:221], v[182:185]
	ds_read_b128 v[186:189], v18 offset:33792
	ds_read_b128 v[190:193], v18 offset:35840
	ds_read_b128 v[194:197], v18 offset:37888
	ds_read_b128 v[202:205], v18 offset:39936
	ds_read_b128 v[198:201], v32 offset:1024
	ds_read_b128 v[206:209], v33 offset:1024
	ds_read_b128 v[210:213], v34 offset:1024
	ds_read_b128 v[218:221], v35 offset:1024
	s_waitcnt lgkmcnt(0)
	v_mfma_f32_16x16x32_bf16 v[138:141], v[186:189], v[198:201], v[138:141]
	v_mfma_f32_16x16x32_bf16 v[142:145], v[190:193], v[198:201], v[142:145]
	v_mfma_f32_16x16x32_bf16 v[146:149], v[194:197], v[198:201], v[146:149]
	v_mfma_f32_16x16x32_bf16 v[134:137], v[202:205], v[198:201], v[134:137]
	ds_read_b128 v[198:201], v22 offset:1024
	v_mfma_f32_16x16x32_bf16 v[154:157], v[186:189], v[206:209], v[154:157]
	v_mfma_f32_16x16x32_bf16 v[158:161], v[190:193], v[206:209], v[158:161]
	v_mfma_f32_16x16x32_bf16 v[162:165], v[194:197], v[206:209], v[162:165]
	v_mfma_f32_16x16x32_bf16 v[150:153], v[202:205], v[206:209], v[150:153]
	ds_read_b128 v[206:209], v21 offset:1024
	v_mfma_f32_16x16x32_bf16 v[170:173], v[186:189], v[210:213], v[170:173]
	v_mfma_f32_16x16x32_bf16 v[174:177], v[190:193], v[210:213], v[174:177]
	v_mfma_f32_16x16x32_bf16 v[178:181], v[194:197], v[210:213], v[178:181]
	v_mfma_f32_16x16x32_bf16 v[166:169], v[202:205], v[210:213], v[166:169]
	ds_read_b128 v[210:213], v20 offset:1024
	v_mfma_f32_16x16x32_bf16 v[214:217], v[186:189], v[218:221], v[214:217]
	v_mfma_f32_16x16x32_bf16 v[56:59], v[190:193], v[218:221], v[56:59]
	v_mfma_f32_16x16x32_bf16 v[64:67], v[194:197], v[218:221], v[64:67]
	v_mfma_f32_16x16x32_bf16 v[72:75], v[202:205], v[218:221], v[72:75]
	ds_read_b128 v[218:221], v19 offset:1024
	s_waitcnt lgkmcnt(0)
	v_mfma_f32_16x16x32_bf16 v[116:119], v[186:189], v[198:201], v[116:119]
	v_mfma_f32_16x16x32_bf16 v[120:123], v[190:193], v[198:201], v[120:123]
	v_mfma_f32_16x16x32_bf16 v[124:127], v[194:197], v[198:201], v[124:127]
	v_mfma_f32_16x16x32_bf16 v[112:115], v[202:205], v[198:201], v[112:115]
	v_mfma_f32_16x16x32_bf16 v[92:95], v[186:189], v[206:209], v[92:95]
	v_mfma_f32_16x16x32_bf16 v[100:103], v[190:193], v[206:209], v[100:103]
	v_mfma_f32_16x16x32_bf16 v[104:107], v[194:197], v[206:209], v[104:107]
	v_mfma_f32_16x16x32_bf16 v[108:111], v[202:205], v[206:209], v[108:111]
	v_mfma_f32_16x16x32_bf16 v[76:79], v[186:189], v[210:213], v[76:79]
	v_mfma_f32_16x16x32_bf16 v[80:83], v[190:193], v[210:213], v[80:83]
	v_mfma_f32_16x16x32_bf16 v[84:87], v[194:197], v[210:213], v[84:87]
	v_mfma_f32_16x16x32_bf16 v[88:91], v[202:205], v[210:213], v[88:91]
	v_mfma_f32_16x16x32_bf16 v[52:55], v[186:189], v[218:221], v[52:55]
	v_mfma_f32_16x16x32_bf16 v[60:63], v[190:193], v[218:221], v[60:63]
	v_mfma_f32_16x16x32_bf16 v[68:71], v[194:197], v[218:221], v[68:71]
	v_mfma_f32_16x16x32_bf16 v[182:185], v[202:205], v[218:221], v[182:185]
	v_readfirstlane_b32 s56, v45
	v_lshl_add_u64 v[96:97], v[2:3], 0, s[18:19]
	s_mov_b32 m0, s56
	v_readfirstlane_b32 s0, v44
	s_waitcnt vmcnt(0)
	s_waitcnt vmcnt(0)
	s_barrier
	global_load_lds_dwordx4 v[96:97], off
	v_lshl_add_u64 v[96:97], v[4:5], 0, s[18:19]
	s_mov_b32 m0, s0
	v_readfirstlane_b32 s42, v46
	global_load_lds_dwordx4 v[96:97], off
	v_lshl_add_u64 v[44:45], v[6:7], 0, s[18:19]
	s_mov_b32 m0, s42
	v_readfirstlane_b32 s43, v47
	global_load_lds_dwordx4 v[44:45], off
	v_lshl_add_u64 v[44:45], v[8:9], 0, s[18:19]
	s_mov_b32 m0, s43
	v_readfirstlane_b32 s53, v48
	global_load_lds_dwordx4 v[44:45], off
	v_lshl_add_u64 v[44:45], v[10:11], 0, s[18:19]
	s_mov_b32 m0, s53
	v_readfirstlane_b32 s54, v49
	global_load_lds_dwordx4 v[44:45], off
	v_lshl_add_u64 v[44:45], v[12:13], 0, s[18:19]
	s_mov_b32 m0, s54
	v_readfirstlane_b32 s55, v50
	global_load_lds_dwordx4 v[44:45], off
	v_lshl_add_u64 v[44:45], v[14:15], 0, s[18:19]
	s_mov_b32 m0, s55
	v_readfirstlane_b32 s57, v51
	global_load_lds_dwordx4 v[44:45], off
	v_lshl_add_u64 v[44:45], v[16:17], 0, s[18:19]
	s_mov_b32 m0, s57
	s_nop 0
	global_load_lds_dwordx4 v[44:45], off
	ds_read_b128 v[44:47], v23
	ds_read_b128 v[48:51], v23 offset:2048
	ds_read_b128 v[186:189], v23 offset:4096
	ds_read_b128 v[194:197], v23 offset:6144
	ds_read_b128 v[190:193], v24
	ds_read_b128 v[198:201], v25
	ds_read_b128 v[202:205], v26
	ds_read_b128 v[206:209], v27
	s_waitcnt lgkmcnt(0)
	v_mfma_f32_16x16x32_bf16 v[138:141], v[44:47], v[190:193], v[138:141]
	v_mfma_f32_16x16x32_bf16 v[142:145], v[48:51], v[190:193], v[142:145]
	v_mfma_f32_16x16x32_bf16 v[146:149], v[186:189], v[190:193], v[146:149]
	v_mfma_f32_16x16x32_bf16 v[134:137], v[194:197], v[190:193], v[134:137]
	ds_read_b128 v[190:193], v28
	v_mfma_f32_16x16x32_bf16 v[154:157], v[44:47], v[198:201], v[154:157]
	v_mfma_f32_16x16x32_bf16 v[158:161], v[48:51], v[198:201], v[158:161]
	v_mfma_f32_16x16x32_bf16 v[162:165], v[186:189], v[198:201], v[162:165]
	v_mfma_f32_16x16x32_bf16 v[150:153], v[194:197], v[198:201], v[150:153]
	ds_read_b128 v[198:201], v29
	v_mfma_f32_16x16x32_bf16 v[170:173], v[44:47], v[202:205], v[170:173]
	v_mfma_f32_16x16x32_bf16 v[174:177], v[48:51], v[202:205], v[174:177]
	v_mfma_f32_16x16x32_bf16 v[178:181], v[186:189], v[202:205], v[178:181]
	v_mfma_f32_16x16x32_bf16 v[166:169], v[194:197], v[202:205], v[166:169]
	ds_read_b128 v[202:205], v30
	v_mfma_f32_16x16x32_bf16 v[210:213], v[44:47], v[206:209], v[214:217]
	v_mfma_f32_16x16x32_bf16 v[56:59], v[48:51], v[206:209], v[56:59]
	v_mfma_f32_16x16x32_bf16 v[64:67], v[186:189], v[206:209], v[64:67]
	v_mfma_f32_16x16x32_bf16 v[72:75], v[194:197], v[206:209], v[72:75]
	ds_read_b128 v[206:209], v31
	s_waitcnt lgkmcnt(0)
	v_mfma_f32_16x16x32_bf16 v[116:119], v[44:47], v[190:193], v[116:119]
	v_mfma_f32_16x16x32_bf16 v[120:123], v[48:51], v[190:193], v[120:123]
	v_mfma_f32_16x16x32_bf16 v[124:127], v[186:189], v[190:193], v[124:127]
	v_mfma_f32_16x16x32_bf16 v[112:115], v[194:197], v[190:193], v[112:115]
	v_mfma_f32_16x16x32_bf16 v[92:95], v[44:47], v[198:201], v[92:95]
	v_mfma_f32_16x16x32_bf16 v[100:103], v[48:51], v[198:201], v[100:103]
	v_mfma_f32_16x16x32_bf16 v[104:107], v[186:189], v[198:201], v[104:107]
	v_mfma_f32_16x16x32_bf16 v[108:111], v[194:197], v[198:201], v[108:111]
	v_mfma_f32_16x16x32_bf16 v[76:79], v[44:47], v[202:205], v[76:79]
	v_mfma_f32_16x16x32_bf16 v[80:83], v[48:51], v[202:205], v[80:83]
	v_mfma_f32_16x16x32_bf16 v[84:87], v[186:189], v[202:205], v[84:87]
	v_mfma_f32_16x16x32_bf16 v[88:91], v[194:197], v[202:205], v[88:91]
	v_mfma_f32_16x16x32_bf16 v[44:47], v[44:47], v[206:209], v[52:55]
	v_mfma_f32_16x16x32_bf16 v[48:51], v[48:51], v[206:209], v[60:63]
	v_mfma_f32_16x16x32_bf16 v[52:55], v[186:189], v[206:209], v[68:71]
	v_mfma_f32_16x16x32_bf16 v[60:63], v[194:197], v[206:209], v[182:185]
	s_nop 1
	ds_read_b128 v[68:71], v23 offset:1024
	ds_read_b128 v[182:185], v23 offset:3072
	ds_read_b128 v[186:189], v23 offset:5120
	ds_read_b128 v[194:197], v23 offset:7168
	ds_read_b128 v[190:193], v24 offset:1024
	ds_read_b128 v[198:201], v25 offset:1024
	ds_read_b128 v[202:205], v26 offset:1024
	ds_read_b128 v[206:209], v27 offset:1024
	s_waitcnt lgkmcnt(0)
	v_mfma_f32_16x16x32_bf16 v[138:141], v[68:71], v[190:193], v[138:141]
	v_mfma_f32_16x16x32_bf16 v[142:145], v[182:185], v[190:193], v[142:145]
	v_mfma_f32_16x16x32_bf16 v[146:149], v[186:189], v[190:193], v[146:149]
	v_mfma_f32_16x16x32_bf16 v[134:137], v[194:197], v[190:193], v[134:137]
	ds_read_b128 v[190:193], v28 offset:1024
	v_mfma_f32_16x16x32_bf16 v[154:157], v[68:71], v[198:201], v[154:157]
	v_mfma_f32_16x16x32_bf16 v[158:161], v[182:185], v[198:201], v[158:161]
	v_mfma_f32_16x16x32_bf16 v[162:165], v[186:189], v[198:201], v[162:165]
	v_mfma_f32_16x16x32_bf16 v[150:153], v[194:197], v[198:201], v[150:153]
	ds_read_b128 v[198:201], v29 offset:1024
	v_mfma_f32_16x16x32_bf16 v[170:173], v[68:71], v[202:205], v[170:173]
	v_mfma_f32_16x16x32_bf16 v[174:177], v[182:185], v[202:205], v[174:177]
	v_mfma_f32_16x16x32_bf16 v[178:181], v[186:189], v[202:205], v[178:181]
	v_mfma_f32_16x16x32_bf16 v[166:169], v[194:197], v[202:205], v[166:169]
	ds_read_b128 v[202:205], v30 offset:1024
	v_mfma_f32_16x16x32_bf16 v[210:213], v[68:71], v[206:209], v[210:213]
	v_mfma_f32_16x16x32_bf16 v[56:59], v[182:185], v[206:209], v[56:59]
	v_mfma_f32_16x16x32_bf16 v[64:67], v[186:189], v[206:209], v[64:67]
	v_mfma_f32_16x16x32_bf16 v[72:75], v[194:197], v[206:209], v[72:75]
	ds_read_b128 v[206:209], v31 offset:1024
	s_waitcnt lgkmcnt(0)
	v_mfma_f32_16x16x32_bf16 v[116:119], v[68:71], v[190:193], v[116:119]
	v_mfma_f32_16x16x32_bf16 v[120:123], v[182:185], v[190:193], v[120:123]
	v_mfma_f32_16x16x32_bf16 v[124:127], v[186:189], v[190:193], v[124:127]
	v_mfma_f32_16x16x32_bf16 v[112:115], v[194:197], v[190:193], v[112:115]
	v_mfma_f32_16x16x32_bf16 v[92:95], v[68:71], v[198:201], v[92:95]
	v_mfma_f32_16x16x32_bf16 v[100:103], v[182:185], v[198:201], v[100:103]
	v_mfma_f32_16x16x32_bf16 v[104:107], v[186:189], v[198:201], v[104:107]
	v_mfma_f32_16x16x32_bf16 v[108:111], v[194:197], v[198:201], v[108:111]
	v_mfma_f32_16x16x32_bf16 v[76:79], v[68:71], v[202:205], v[76:79]
	v_mfma_f32_16x16x32_bf16 v[80:83], v[182:185], v[202:205], v[80:83]
	v_mfma_f32_16x16x32_bf16 v[84:87], v[186:189], v[202:205], v[84:87]
	v_mfma_f32_16x16x32_bf16 v[88:91], v[194:197], v[202:205], v[88:91]
	v_mfma_f32_16x16x32_bf16 v[44:47], v[68:71], v[206:209], v[44:47]
	v_mfma_f32_16x16x32_bf16 v[48:51], v[182:185], v[206:209], v[48:51]
	v_mfma_f32_16x16x32_bf16 v[52:55], v[186:189], v[206:209], v[52:55]
	v_mfma_f32_16x16x32_bf16 v[60:63], v[194:197], v[206:209], v[60:63]
	v_readfirstlane_b32 s64, v37
	v_lshl_add_u64 v[68:69], v[2:3], 0, s[20:21]
	s_mov_b32 m0, s64
	v_readfirstlane_b32 s58, v36
	s_waitcnt vmcnt(0)
	s_waitcnt vmcnt(0)
	s_barrier
	global_load_lds_dwordx4 v[68:69], off
	v_lshl_add_u64 v[68:69], v[4:5], 0, s[20:21]
	s_mov_b32 m0, s58
	v_readfirstlane_b32 s59, v38
	global_load_lds_dwordx4 v[68:69], off
	v_lshl_add_u64 v[36:37], v[6:7], 0, s[20:21]
	s_mov_b32 m0, s59
	v_readfirstlane_b32 s60, v39
	global_load_lds_dwordx4 v[36:37], off
	v_lshl_add_u64 v[36:37], v[8:9], 0, s[20:21]
	s_mov_b32 m0, s60
	v_readfirstlane_b32 s61, v40
	global_load_lds_dwordx4 v[36:37], off
	v_lshl_add_u64 v[36:37], v[10:11], 0, s[20:21]
	s_mov_b32 m0, s61
	v_readfirstlane_b32 s62, v41
	global_load_lds_dwordx4 v[36:37], off
	v_lshl_add_u64 v[36:37], v[12:13], 0, s[20:21]
	s_mov_b32 m0, s62
	v_readfirstlane_b32 s63, v42
	global_load_lds_dwordx4 v[36:37], off
	v_lshl_add_u64 v[36:37], v[14:15], 0, s[20:21]
	s_mov_b32 m0, s63
	v_readfirstlane_b32 s65, v43
	global_load_lds_dwordx4 v[36:37], off
	v_lshl_add_u64 v[36:37], v[16:17], 0, s[20:21]
	s_mov_b32 m0, s65
	s_nop 0
	global_load_lds_dwordx4 v[36:37], off
	ds_read_b128 v[36:39], v18 offset:32768
	ds_read_b128 v[40:43], v18 offset:34816
	ds_read_b128 v[68:71], v18 offset:36864
	ds_read_b128 v[186:189], v18 offset:38912
	ds_read_b128 v[182:185], v32
	ds_read_b128 v[190:193], v33
	ds_read_b128 v[194:197], v34
	ds_read_b128 v[198:201], v35
	s_waitcnt lgkmcnt(0)
	v_mfma_f32_16x16x32_bf16 v[138:141], v[36:39], v[182:185], v[138:141]
	v_mfma_f32_16x16x32_bf16 v[142:145], v[40:43], v[182:185], v[142:145]
	v_mfma_f32_16x16x32_bf16 v[146:149], v[68:71], v[182:185], v[146:149]
	v_mfma_f32_16x16x32_bf16 v[134:137], v[186:189], v[182:185], v[134:137]
	ds_read_b128 v[182:185], v22
	v_mfma_f32_16x16x32_bf16 v[154:157], v[36:39], v[190:193], v[154:157]
	v_mfma_f32_16x16x32_bf16 v[158:161], v[40:43], v[190:193], v[158:161]
	v_mfma_f32_16x16x32_bf16 v[162:165], v[68:71], v[190:193], v[162:165]
	v_mfma_f32_16x16x32_bf16 v[150:153], v[186:189], v[190:193], v[150:153]
	ds_read_b128 v[190:193], v21
	v_mfma_f32_16x16x32_bf16 v[170:173], v[36:39], v[194:197], v[170:173]
	v_mfma_f32_16x16x32_bf16 v[174:177], v[40:43], v[194:197], v[174:177]
	v_mfma_f32_16x16x32_bf16 v[178:181], v[68:71], v[194:197], v[178:181]
	v_mfma_f32_16x16x32_bf16 v[166:169], v[186:189], v[194:197], v[166:169]
	ds_read_b128 v[194:197], v20
	v_mfma_f32_16x16x32_bf16 v[202:205], v[36:39], v[198:201], v[210:213]
	v_mfma_f32_16x16x32_bf16 v[56:59], v[40:43], v[198:201], v[56:59]
	v_mfma_f32_16x16x32_bf16 v[64:67], v[68:71], v[198:201], v[64:67]
	v_mfma_f32_16x16x32_bf16 v[72:75], v[186:189], v[198:201], v[72:75]
	ds_read_b128 v[198:201], v19
	s_waitcnt lgkmcnt(0)
	v_mfma_f32_16x16x32_bf16 v[116:119], v[36:39], v[182:185], v[116:119]
	v_mfma_f32_16x16x32_bf16 v[120:123], v[40:43], v[182:185], v[120:123]
	v_mfma_f32_16x16x32_bf16 v[124:127], v[68:71], v[182:185], v[124:127]
	v_mfma_f32_16x16x32_bf16 v[112:115], v[186:189], v[182:185], v[112:115]
	v_mfma_f32_16x16x32_bf16 v[92:95], v[36:39], v[190:193], v[92:95]
	v_mfma_f32_16x16x32_bf16 v[100:103], v[40:43], v[190:193], v[100:103]
	v_mfma_f32_16x16x32_bf16 v[104:107], v[68:71], v[190:193], v[104:107]
	v_mfma_f32_16x16x32_bf16 v[108:111], v[186:189], v[190:193], v[108:111]
	v_mfma_f32_16x16x32_bf16 v[76:79], v[36:39], v[194:197], v[76:79]
	v_mfma_f32_16x16x32_bf16 v[80:83], v[40:43], v[194:197], v[80:83]
	v_mfma_f32_16x16x32_bf16 v[84:87], v[68:71], v[194:197], v[84:87]
	v_mfma_f32_16x16x32_bf16 v[88:91], v[186:189], v[194:197], v[88:91]
	v_mfma_f32_16x16x32_bf16 v[36:39], v[36:39], v[198:201], v[44:47]
	v_mfma_f32_16x16x32_bf16 v[40:43], v[40:43], v[198:201], v[48:51]
	v_mfma_f32_16x16x32_bf16 v[44:47], v[68:71], v[198:201], v[52:55]
	v_mfma_f32_16x16x32_bf16 v[48:51], v[186:189], v[198:201], v[60:63]
	s_nop 1
	ds_read_b128 v[52:55], v18 offset:33792
	ds_read_b128 v[60:63], v18 offset:35840
	ds_read_b128 v[68:71], v18 offset:37888
	ds_read_b128 v[186:189], v18 offset:39936
	ds_read_b128 v[182:185], v32 offset:1024
	ds_read_b128 v[190:193], v33 offset:1024
	ds_read_b128 v[194:197], v34 offset:1024
	ds_read_b128 v[198:201], v35 offset:1024
	s_waitcnt lgkmcnt(0)
	v_mfma_f32_16x16x32_bf16 v[138:141], v[52:55], v[182:185], v[138:141]
	v_mfma_f32_16x16x32_bf16 v[142:145], v[60:63], v[182:185], v[142:145]
	v_mfma_f32_16x16x32_bf16 v[146:149], v[68:71], v[182:185], v[146:149]
	v_mfma_f32_16x16x32_bf16 v[134:137], v[186:189], v[182:185], v[134:137]
	ds_read_b128 v[182:185], v22 offset:1024
	v_mfma_f32_16x16x32_bf16 v[154:157], v[52:55], v[190:193], v[154:157]
	v_mfma_f32_16x16x32_bf16 v[158:161], v[60:63], v[190:193], v[158:161]
	v_mfma_f32_16x16x32_bf16 v[162:165], v[68:71], v[190:193], v[162:165]
	v_mfma_f32_16x16x32_bf16 v[150:153], v[186:189], v[190:193], v[150:153]
	ds_read_b128 v[190:193], v21 offset:1024
	v_mfma_f32_16x16x32_bf16 v[170:173], v[52:55], v[194:197], v[170:173]
	v_mfma_f32_16x16x32_bf16 v[174:177], v[60:63], v[194:197], v[174:177]
	v_mfma_f32_16x16x32_bf16 v[178:181], v[68:71], v[194:197], v[178:181]
	v_mfma_f32_16x16x32_bf16 v[166:169], v[186:189], v[194:197], v[166:169]
	ds_read_b128 v[194:197], v20 offset:1024
	v_mfma_f32_16x16x32_bf16 v[202:205], v[52:55], v[198:201], v[202:205]
	v_mfma_f32_16x16x32_bf16 v[56:59], v[60:63], v[198:201], v[56:59]
	v_mfma_f32_16x16x32_bf16 v[64:67], v[68:71], v[198:201], v[64:67]
	v_mfma_f32_16x16x32_bf16 v[72:75], v[186:189], v[198:201], v[72:75]
	ds_read_b128 v[198:201], v19 offset:1024
	s_waitcnt lgkmcnt(0)
	v_mfma_f32_16x16x32_bf16 v[116:119], v[52:55], v[182:185], v[116:119]
	v_mfma_f32_16x16x32_bf16 v[120:123], v[60:63], v[182:185], v[120:123]
	v_mfma_f32_16x16x32_bf16 v[124:127], v[68:71], v[182:185], v[124:127]
	v_mfma_f32_16x16x32_bf16 v[112:115], v[186:189], v[182:185], v[112:115]
	v_mfma_f32_16x16x32_bf16 v[92:95], v[52:55], v[190:193], v[92:95]
	v_mfma_f32_16x16x32_bf16 v[100:103], v[60:63], v[190:193], v[100:103]
	v_mfma_f32_16x16x32_bf16 v[104:107], v[68:71], v[190:193], v[104:107]
	v_mfma_f32_16x16x32_bf16 v[108:111], v[186:189], v[190:193], v[108:111]
	v_mfma_f32_16x16x32_bf16 v[76:79], v[52:55], v[194:197], v[76:79]
	v_mfma_f32_16x16x32_bf16 v[80:83], v[60:63], v[194:197], v[80:83]
	v_mfma_f32_16x16x32_bf16 v[84:87], v[68:71], v[194:197], v[84:87]
	v_mfma_f32_16x16x32_bf16 v[88:91], v[186:189], v[194:197], v[88:91]
	v_mfma_f32_16x16x32_bf16 v[36:39], v[52:55], v[198:201], v[36:39]
	v_mfma_f32_16x16x32_bf16 v[40:43], v[60:63], v[198:201], v[40:43]
	v_mfma_f32_16x16x32_bf16 v[44:47], v[68:71], v[198:201], v[44:47]
	v_mfma_f32_16x16x32_bf16 v[48:51], v[186:189], v[198:201], v[48:51]
	s_mov_b32 m0, s56
	v_lshl_add_u64 v[52:53], v[2:3], 0, s[22:23]
	s_waitcnt vmcnt(0)
	s_waitcnt vmcnt(0)
	s_barrier
	global_load_lds_dwordx4 v[52:53], off
	v_lshl_add_u64 v[52:53], v[4:5], 0, s[22:23]
	s_mov_b32 m0, s0
	s_nop 0
	global_load_lds_dwordx4 v[52:53], off
	v_lshl_add_u64 v[52:53], v[6:7], 0, s[22:23]
	s_mov_b32 m0, s42
	s_nop 0
	global_load_lds_dwordx4 v[52:53], off
	v_lshl_add_u64 v[52:53], v[8:9], 0, s[22:23]
	s_mov_b32 m0, s43
	s_nop 0
	global_load_lds_dwordx4 v[52:53], off
	v_lshl_add_u64 v[52:53], v[10:11], 0, s[22:23]
	s_mov_b32 m0, s53
	s_nop 0
	global_load_lds_dwordx4 v[52:53], off
	v_lshl_add_u64 v[52:53], v[12:13], 0, s[22:23]
	s_mov_b32 m0, s54
	s_nop 0
	global_load_lds_dwordx4 v[52:53], off
	v_lshl_add_u64 v[52:53], v[14:15], 0, s[22:23]
	s_mov_b32 m0, s55
	s_nop 0
	global_load_lds_dwordx4 v[52:53], off
	v_lshl_add_u64 v[52:53], v[16:17], 0, s[22:23]
	s_mov_b32 m0, s57
	s_nop 0
	global_load_lds_dwordx4 v[52:53], off
	ds_read_b128 v[52:55], v23
	ds_read_b128 v[60:63], v23 offset:2048
	ds_read_b128 v[68:71], v23 offset:4096
	ds_read_b128 v[186:189], v23 offset:6144
	ds_read_b128 v[182:185], v24
	ds_read_b128 v[190:193], v25
	ds_read_b128 v[194:197], v26
	ds_read_b128 v[198:201], v27
	s_waitcnt lgkmcnt(0)
	v_mfma_f32_16x16x32_bf16 v[138:141], v[52:55], v[182:185], v[138:141]
	v_mfma_f32_16x16x32_bf16 v[142:145], v[60:63], v[182:185], v[142:145]
	v_mfma_f32_16x16x32_bf16 v[146:149], v[68:71], v[182:185], v[146:149]
	v_mfma_f32_16x16x32_bf16 v[134:137], v[186:189], v[182:185], v[134:137]
	ds_read_b128 v[182:185], v28
	v_mfma_f32_16x16x32_bf16 v[154:157], v[52:55], v[190:193], v[154:157]
	v_mfma_f32_16x16x32_bf16 v[158:161], v[60:63], v[190:193], v[158:161]
	v_mfma_f32_16x16x32_bf16 v[162:165], v[68:71], v[190:193], v[162:165]
	v_mfma_f32_16x16x32_bf16 v[150:153], v[186:189], v[190:193], v[150:153]
	ds_read_b128 v[190:193], v29
	v_mfma_f32_16x16x32_bf16 v[170:173], v[52:55], v[194:197], v[170:173]
	v_mfma_f32_16x16x32_bf16 v[174:177], v[60:63], v[194:197], v[174:177]
	v_mfma_f32_16x16x32_bf16 v[178:181], v[68:71], v[194:197], v[178:181]
	v_mfma_f32_16x16x32_bf16 v[166:169], v[186:189], v[194:197], v[166:169]
	ds_read_b128 v[194:197], v30
	v_mfma_f32_16x16x32_bf16 v[202:205], v[52:55], v[198:201], v[202:205]
	v_mfma_f32_16x16x32_bf16 v[56:59], v[60:63], v[198:201], v[56:59]
	v_mfma_f32_16x16x32_bf16 v[64:67], v[68:71], v[198:201], v[64:67]
	v_mfma_f32_16x16x32_bf16 v[72:75], v[186:189], v[198:201], v[72:75]
	ds_read_b128 v[198:201], v31
	s_waitcnt lgkmcnt(0)
	v_mfma_f32_16x16x32_bf16 v[116:119], v[52:55], v[182:185], v[116:119]
	v_mfma_f32_16x16x32_bf16 v[120:123], v[60:63], v[182:185], v[120:123]
	v_mfma_f32_16x16x32_bf16 v[124:127], v[68:71], v[182:185], v[124:127]
	v_mfma_f32_16x16x32_bf16 v[112:115], v[186:189], v[182:185], v[112:115]
	v_mfma_f32_16x16x32_bf16 v[92:95], v[52:55], v[190:193], v[92:95]
	v_mfma_f32_16x16x32_bf16 v[100:103], v[60:63], v[190:193], v[100:103]
	v_mfma_f32_16x16x32_bf16 v[104:107], v[68:71], v[190:193], v[104:107]
	v_mfma_f32_16x16x32_bf16 v[108:111], v[186:189], v[190:193], v[108:111]
	v_mfma_f32_16x16x32_bf16 v[76:79], v[52:55], v[194:197], v[76:79]
	v_mfma_f32_16x16x32_bf16 v[80:83], v[60:63], v[194:197], v[80:83]
	v_mfma_f32_16x16x32_bf16 v[84:87], v[68:71], v[194:197], v[84:87]
	v_mfma_f32_16x16x32_bf16 v[88:91], v[186:189], v[194:197], v[88:91]
	v_mfma_f32_16x16x32_bf16 v[36:39], v[52:55], v[198:201], v[36:39]
	v_mfma_f32_16x16x32_bf16 v[40:43], v[60:63], v[198:201], v[40:43]
	v_mfma_f32_16x16x32_bf16 v[44:47], v[68:71], v[198:201], v[44:47]
	v_mfma_f32_16x16x32_bf16 v[48:51], v[186:189], v[198:201], v[48:51]
	ds_read_b128 v[52:55], v23 offset:1024
	ds_read_b128 v[60:63], v23 offset:3072
	ds_read_b128 v[68:71], v23 offset:5120
	ds_read_b128 v[186:189], v23 offset:7168
	ds_read_b128 v[182:185], v24 offset:1024
	ds_read_b128 v[190:193], v25 offset:1024
	ds_read_b128 v[194:197], v26 offset:1024
	ds_read_b128 v[198:201], v27 offset:1024
	s_waitcnt lgkmcnt(0)
	v_mfma_f32_16x16x32_bf16 v[138:141], v[52:55], v[182:185], v[138:141]
	v_mfma_f32_16x16x32_bf16 v[142:145], v[60:63], v[182:185], v[142:145]
	v_mfma_f32_16x16x32_bf16 v[146:149], v[68:71], v[182:185], v[146:149]
	v_mfma_f32_16x16x32_bf16 v[134:137], v[186:189], v[182:185], v[134:137]
	ds_read_b128 v[182:185], v28 offset:1024
	v_mfma_f32_16x16x32_bf16 v[154:157], v[52:55], v[190:193], v[154:157]
	v_mfma_f32_16x16x32_bf16 v[158:161], v[60:63], v[190:193], v[158:161]
	v_mfma_f32_16x16x32_bf16 v[162:165], v[68:71], v[190:193], v[162:165]
	v_mfma_f32_16x16x32_bf16 v[150:153], v[186:189], v[190:193], v[150:153]
	ds_read_b128 v[190:193], v29 offset:1024
	v_mfma_f32_16x16x32_bf16 v[170:173], v[52:55], v[194:197], v[170:173]
	v_mfma_f32_16x16x32_bf16 v[174:177], v[60:63], v[194:197], v[174:177]
	v_mfma_f32_16x16x32_bf16 v[178:181], v[68:71], v[194:197], v[178:181]
	v_mfma_f32_16x16x32_bf16 v[166:169], v[186:189], v[194:197], v[166:169]
	ds_read_b128 v[194:197], v30 offset:1024
	v_mfma_f32_16x16x32_bf16 v[202:205], v[52:55], v[198:201], v[202:205]
	v_mfma_f32_16x16x32_bf16 v[56:59], v[60:63], v[198:201], v[56:59]
	v_mfma_f32_16x16x32_bf16 v[64:67], v[68:71], v[198:201], v[64:67]
	v_mfma_f32_16x16x32_bf16 v[72:75], v[186:189], v[198:201], v[72:75]
	ds_read_b128 v[198:201], v31 offset:1024
	s_waitcnt lgkmcnt(0)
	v_mfma_f32_16x16x32_bf16 v[116:119], v[52:55], v[182:185], v[116:119]
	v_mfma_f32_16x16x32_bf16 v[120:123], v[60:63], v[182:185], v[120:123]
	v_mfma_f32_16x16x32_bf16 v[124:127], v[68:71], v[182:185], v[124:127]
	v_mfma_f32_16x16x32_bf16 v[112:115], v[186:189], v[182:185], v[112:115]
	v_mfma_f32_16x16x32_bf16 v[92:95], v[52:55], v[190:193], v[92:95]
	v_mfma_f32_16x16x32_bf16 v[100:103], v[60:63], v[190:193], v[100:103]
	v_mfma_f32_16x16x32_bf16 v[104:107], v[68:71], v[190:193], v[104:107]
	v_mfma_f32_16x16x32_bf16 v[108:111], v[186:189], v[190:193], v[108:111]
	v_mfma_f32_16x16x32_bf16 v[76:79], v[52:55], v[194:197], v[76:79]
	v_mfma_f32_16x16x32_bf16 v[80:83], v[60:63], v[194:197], v[80:83]
	v_mfma_f32_16x16x32_bf16 v[84:87], v[68:71], v[194:197], v[84:87]
	v_mfma_f32_16x16x32_bf16 v[88:91], v[186:189], v[194:197], v[88:91]
	v_mfma_f32_16x16x32_bf16 v[36:39], v[52:55], v[198:201], v[36:39]
	v_mfma_f32_16x16x32_bf16 v[40:43], v[60:63], v[198:201], v[40:43]
	v_mfma_f32_16x16x32_bf16 v[44:47], v[68:71], v[198:201], v[44:47]
	v_mfma_f32_16x16x32_bf16 v[48:51], v[186:189], v[198:201], v[48:51]
	s_mov_b32 m0, s64
	v_lshl_add_u64 v[2:3], v[2:3], 0, s[24:25]
	s_waitcnt vmcnt(0)
	s_waitcnt vmcnt(0)
	s_barrier
	global_load_lds_dwordx4 v[2:3], off
	v_lshl_add_u64 v[2:3], v[4:5], 0, s[24:25]
	s_mov_b32 m0, s58
	s_nop 0
	global_load_lds_dwordx4 v[2:3], off
	v_lshl_add_u64 v[2:3], v[6:7], 0, s[24:25]
	s_mov_b32 m0, s59
	s_nop 0
	global_load_lds_dwordx4 v[2:3], off
	v_lshl_add_u64 v[2:3], v[8:9], 0, s[24:25]
	s_mov_b32 m0, s60
	s_nop 0
	global_load_lds_dwordx4 v[2:3], off
	v_lshl_add_u64 v[2:3], v[10:11], 0, s[24:25]
	s_mov_b32 m0, s61
	s_nop 0
	global_load_lds_dwordx4 v[2:3], off
	v_lshl_add_u64 v[2:3], v[12:13], 0, s[24:25]
	s_mov_b32 m0, s62
	s_nop 0
	global_load_lds_dwordx4 v[2:3], off
	v_lshl_add_u64 v[2:3], v[14:15], 0, s[24:25]
	s_mov_b32 m0, s63
	s_nop 0
	global_load_lds_dwordx4 v[2:3], off
	v_lshl_add_u64 v[2:3], v[16:17], 0, s[24:25]
	s_mov_b32 m0, s65
	s_nop 0
	global_load_lds_dwordx4 v[2:3], off
	ds_read_b128 v[2:5], v18 offset:32768
	ds_read_b128 v[6:9], v18 offset:34816
	ds_read_b128 v[10:13], v18 offset:36864
	ds_read_b128 v[52:55], v18 offset:38912
	ds_read_b128 v[14:17], v32
	ds_read_b128 v[60:63], v33
	ds_read_b128 v[68:71], v34
	ds_read_b128 v[182:185], v35
	s_waitcnt lgkmcnt(0)
	v_mfma_f32_16x16x32_bf16 v[138:141], v[2:5], v[14:17], v[138:141]
	v_mfma_f32_16x16x32_bf16 v[142:145], v[6:9], v[14:17], v[142:145]
	v_mfma_f32_16x16x32_bf16 v[146:149], v[10:13], v[14:17], v[146:149]
	v_mfma_f32_16x16x32_bf16 v[14:17], v[52:55], v[14:17], v[134:137]
	s_nop 2
	ds_read_b128 v[134:137], v22
	v_mfma_f32_16x16x32_bf16 v[154:157], v[2:5], v[60:63], v[154:157]
	v_mfma_f32_16x16x32_bf16 v[158:161], v[6:9], v[60:63], v[158:161]
	v_mfma_f32_16x16x32_bf16 v[162:165], v[10:13], v[60:63], v[162:165]
	v_mfma_f32_16x16x32_bf16 v[60:63], v[52:55], v[60:63], v[150:153]
	s_nop 2
	ds_read_b128 v[150:153], v21
	v_mfma_f32_16x16x32_bf16 v[170:173], v[2:5], v[68:71], v[170:173]
	v_mfma_f32_16x16x32_bf16 v[174:177], v[6:9], v[68:71], v[174:177]
	v_mfma_f32_16x16x32_bf16 v[178:181], v[10:13], v[68:71], v[178:181]
	v_mfma_f32_16x16x32_bf16 v[68:71], v[52:55], v[68:71], v[166:169]
	s_nop 2
	ds_read_b128 v[166:169], v20
	v_mfma_f32_16x16x32_bf16 v[186:189], v[2:5], v[182:185], v[202:205]
	v_mfma_f32_16x16x32_bf16 v[56:59], v[6:9], v[182:185], v[56:59]
	v_mfma_f32_16x16x32_bf16 v[64:67], v[10:13], v[182:185], v[64:67]
	v_mfma_f32_16x16x32_bf16 v[72:75], v[52:55], v[182:185], v[72:75]
	ds_read_b128 v[182:185], v19
	s_waitcnt lgkmcnt(0)
	v_mfma_f32_16x16x32_bf16 v[116:119], v[2:5], v[134:137], v[116:119]
	v_mfma_f32_16x16x32_bf16 v[120:123], v[6:9], v[134:137], v[120:123]
	v_mfma_f32_16x16x32_bf16 v[124:127], v[10:13], v[134:137], v[124:127]
	v_mfma_f32_16x16x32_bf16 v[112:115], v[52:55], v[134:137], v[112:115]
	v_mfma_f32_16x16x32_bf16 v[92:95], v[2:5], v[150:153], v[92:95]
	v_mfma_f32_16x16x32_bf16 v[100:103], v[6:9], v[150:153], v[100:103]
	v_mfma_f32_16x16x32_bf16 v[104:107], v[10:13], v[150:153], v[104:107]
	v_mfma_f32_16x16x32_bf16 v[108:111], v[52:55], v[150:153], v[108:111]
	v_mfma_f32_16x16x32_bf16 v[76:79], v[2:5], v[166:169], v[76:79]
	v_mfma_f32_16x16x32_bf16 v[80:83], v[6:9], v[166:169], v[80:83]
	v_mfma_f32_16x16x32_bf16 v[84:87], v[10:13], v[166:169], v[84:87]
	v_mfma_f32_16x16x32_bf16 v[88:91], v[52:55], v[166:169], v[88:91]
	v_mfma_f32_16x16x32_bf16 v[2:5], v[2:5], v[182:185], v[36:39]
	v_mfma_f32_16x16x32_bf16 v[6:9], v[6:9], v[182:185], v[40:43]
	v_mfma_f32_16x16x32_bf16 v[10:13], v[10:13], v[182:185], v[44:47]
	v_mfma_f32_16x16x32_bf16 v[36:39], v[52:55], v[182:185], v[48:51]
	s_nop 0
	ds_read_b128 v[40:43], v18 offset:33792
	ds_read_b128 v[44:47], v18 offset:35840
	ds_read_b128 v[48:51], v18 offset:37888
	ds_read_b128 v[134:137], v18 offset:39936
	ds_read_b128 v[52:55], v32 offset:1024
	ds_read_b128 v[150:153], v33 offset:1024
	ds_read_b128 v[166:169], v34 offset:1024
	ds_read_b128 v[32:35], v35 offset:1024
	s_waitcnt lgkmcnt(0)
	v_mfma_f32_16x16x32_bf16 v[138:141], v[40:43], v[52:55], v[138:141]
	v_mfma_f32_16x16x32_bf16 v[142:145], v[44:47], v[52:55], v[142:145]
	v_mfma_f32_16x16x32_bf16 v[146:149], v[48:51], v[52:55], v[146:149]
	v_mfma_f32_16x16x32_bf16 v[14:17], v[134:137], v[52:55], v[14:17]
	ds_read_b128 v[52:55], v22 offset:1024
	v_mfma_f32_16x16x32_bf16 v[154:157], v[40:43], v[150:153], v[154:157]
	v_mfma_f32_16x16x32_bf16 v[158:161], v[44:47], v[150:153], v[158:161]
	v_mfma_f32_16x16x32_bf16 v[162:165], v[48:51], v[150:153], v[162:165]
	v_mfma_f32_16x16x32_bf16 v[60:63], v[134:137], v[150:153], v[60:63]
	ds_read_b128 v[150:153], v21 offset:1024
	v_mfma_f32_16x16x32_bf16 v[170:173], v[40:43], v[166:169], v[170:173]
	v_mfma_f32_16x16x32_bf16 v[174:177], v[44:47], v[166:169], v[174:177]
	v_mfma_f32_16x16x32_bf16 v[178:181], v[48:51], v[166:169], v[178:181]
	v_mfma_f32_16x16x32_bf16 v[68:71], v[134:137], v[166:169], v[68:71]
	ds_read_b128 v[166:169], v20 offset:1024
	v_mfma_f32_16x16x32_bf16 v[182:185], v[40:43], v[32:35], v[186:189]
	v_mfma_f32_16x16x32_bf16 v[56:59], v[44:47], v[32:35], v[56:59]
	v_mfma_f32_16x16x32_bf16 v[64:67], v[48:51], v[32:35], v[64:67]
	v_mfma_f32_16x16x32_bf16 v[32:35], v[134:137], v[32:35], v[72:75]
	ds_read_b128 v[18:21], v19 offset:1024
	s_waitcnt lgkmcnt(0)
	v_mfma_f32_16x16x32_bf16 v[72:75], v[40:43], v[52:55], v[116:119]
	v_mfma_f32_16x16x32_bf16 v[116:119], v[44:47], v[52:55], v[120:123]
	v_mfma_f32_16x16x32_bf16 v[120:123], v[48:51], v[52:55], v[124:127]
	v_mfma_f32_16x16x32_bf16 v[52:55], v[134:137], v[52:55], v[112:115]
	v_mfma_f32_16x16x32_bf16 v[92:95], v[40:43], v[150:153], v[92:95]
	v_mfma_f32_16x16x32_bf16 v[100:103], v[44:47], v[150:153], v[100:103]
	v_mfma_f32_16x16x32_bf16 v[104:107], v[48:51], v[150:153], v[104:107]
	v_mfma_f32_16x16x32_bf16 v[108:111], v[134:137], v[150:153], v[108:111]
	v_mfma_f32_16x16x32_bf16 v[76:79], v[40:43], v[166:169], v[76:79]
	v_mfma_f32_16x16x32_bf16 v[80:83], v[44:47], v[166:169], v[80:83]
	v_mfma_f32_16x16x32_bf16 v[84:87], v[48:51], v[166:169], v[84:87]
	v_mfma_f32_16x16x32_bf16 v[88:91], v[134:137], v[166:169], v[88:91]
	v_mfma_f32_16x16x32_bf16 v[2:5], v[40:43], v[18:21], v[2:5]
	v_mfma_f32_16x16x32_bf16 v[6:9], v[44:47], v[18:21], v[6:9]
	v_mfma_f32_16x16x32_bf16 v[10:13], v[48:51], v[18:21], v[10:13]
	v_mfma_f32_16x16x32_bf16 v[18:21], v[134:137], v[18:21], v[36:39]
	s_waitcnt vmcnt(0)
	s_waitcnt vmcnt(0)
	s_barrier
	s_nop 0
	ds_read_b128 v[36:39], v31
	ds_read_b128 v[40:43], v30
	ds_read_b128 v[44:47], v29
	ds_read_b128 v[48:51], v28
	ds_read_b128 v[112:115], v27
	ds_read_b128 v[124:127], v26
	ds_read_b128 v[134:137], v25
	ds_read_b128 v[150:153], v24
	ds_read_b128 v[166:169], v23
	s_waitcnt lgkmcnt(0)
	v_mfma_f32_16x16x32_bf16 v[186:189], v[166:169], v[36:39], v[2:5]
	s_nop 2
	ds_read_b128 v[2:5], v23 offset:2048
	s_waitcnt lgkmcnt(0)
	v_mfma_f32_16x16x32_bf16 v[190:193], v[2:5], v[36:39], v[6:9]
	s_nop 2
	ds_read_b128 v[6:9], v23 offset:4096
	s_waitcnt lgkmcnt(0)
	v_mfma_f32_16x16x32_bf16 v[194:197], v[6:9], v[36:39], v[10:13]
	s_nop 2
	ds_read_b128 v[10:13], v23 offset:6144
	s_waitcnt lgkmcnt(0)
	v_mfma_f32_16x16x32_bf16 v[198:201], v[10:13], v[36:39], v[18:21]
	v_mfma_f32_16x16x32_bf16 v[18:21], v[10:13], v[134:137], v[60:63]
	v_mfma_f32_16x16x32_bf16 v[36:39], v[10:13], v[124:127], v[68:71]
	v_mfma_f32_16x16x32_bf16 v[68:71], v[6:9], v[134:137], v[162:165]
	v_mfma_f32_16x16x32_bf16 v[162:165], v[6:9], v[112:115], v[64:67]
	v_mfma_f32_16x16x32_bf16 v[64:67], v[2:5], v[150:153], v[142:145]
	v_mfma_f32_16x16x32_bf16 v[142:145], v[2:5], v[134:137], v[158:161]
	v_mfma_f32_16x16x32_bf16 v[134:137], v[166:169], v[134:137], v[154:157]
	v_mfma_f32_16x16x32_bf16 v[154:157], v[166:169], v[40:43], v[76:79]
	v_mfma_f32_16x16x32_bf16 v[60:63], v[6:9], v[150:153], v[146:149]
	v_mfma_f32_16x16x32_bf16 v[146:149], v[6:9], v[124:127], v[178:181]
	v_mfma_f32_16x16x32_bf16 v[158:161], v[2:5], v[124:127], v[174:177]
	v_mfma_f32_16x16x32_bf16 v[124:127], v[166:169], v[124:127], v[170:173]
	v_mfma_f32_16x16x32_bf16 v[170:173], v[6:9], v[40:43], v[84:87]
	v_mfma_f32_16x16x32_bf16 v[138:141], v[166:169], v[150:153], v[138:141]
	v_mfma_f32_16x16x32_bf16 v[56:59], v[2:5], v[112:115], v[56:59]
	v_mfma_f32_16x16x32_bf16 v[116:119], v[2:5], v[48:51], v[116:119]
	v_mfma_f32_16x16x32_bf16 v[120:123], v[6:9], v[48:51], v[120:123]
	v_mfma_f32_16x16x32_bf16 v[14:17], v[10:13], v[150:153], v[14:17]
	v_mfma_f32_16x16x32_bf16 v[150:153], v[166:169], v[48:51], v[72:75]
	v_mfma_f32_16x16x32_bf16 v[48:51], v[10:13], v[48:51], v[52:55]
	v_mfma_f32_16x16x32_bf16 v[52:55], v[166:169], v[44:47], v[92:95]
	v_mfma_f32_16x16x32_bf16 v[32:35], v[10:13], v[112:115], v[32:35]
	v_mfma_f32_16x16x32_bf16 v[112:115], v[166:169], v[112:115], v[182:185]
	v_mfma_f32_16x16x32_bf16 v[166:169], v[2:5], v[40:43], v[80:83]
	v_mfma_f32_16x16x32_bf16 v[104:107], v[6:9], v[44:47], v[104:107]
	v_mfma_f32_16x16x32_bf16 v[108:111], v[10:13], v[44:47], v[108:111]
	v_mfma_f32_16x16x32_bf16 v[100:103], v[2:5], v[44:47], v[100:103]
	v_mfma_f32_16x16x32_bf16 v[174:177], v[10:13], v[40:43], v[88:91]
	ds_read_b128 v[178:181], v23 offset:1024
	ds_read_b128 v[182:185], v23 offset:3072
	ds_read_b128 v[202:205], v23 offset:5120
	ds_read_b128 v[206:209], v23 offset:7168
	ds_read_b128 v[2:5], v24 offset:1024
	ds_read_b128 v[6:9], v25 offset:1024
	ds_read_b128 v[10:13], v26 offset:1024
	ds_read_b128 v[22:25], v27 offset:1024
	s_waitcnt lgkmcnt(3)
	v_mfma_f32_16x16x32_bf16 v[138:141], v[178:181], v[2:5], v[138:141]
	v_mfma_f32_16x16x32_bf16 v[210:213], v[182:185], v[2:5], v[64:67]
	v_mfma_f32_16x16x32_bf16 v[214:217], v[202:205], v[2:5], v[60:63]
	v_mfma_f32_16x16x32_bf16 v[218:221], v[206:209], v[2:5], v[14:17]
	ds_read_b128 v[2:5], v28 offset:1024
	s_waitcnt lgkmcnt(3)
	v_mfma_f32_16x16x32_bf16 v[134:137], v[178:181], v[6:9], v[134:137]
	v_mfma_f32_16x16x32_bf16 v[142:145], v[182:185], v[6:9], v[142:145]
	v_mfma_f32_16x16x32_bf16 v[222:225], v[202:205], v[6:9], v[68:71]
	v_mfma_f32_16x16x32_bf16 v[226:229], v[206:209], v[6:9], v[18:21]
	ds_read_b128 v[6:9], v29 offset:1024
	s_waitcnt lgkmcnt(3)
	v_mfma_f32_16x16x32_bf16 v[66:69], v[178:181], v[10:13], v[124:127]
	v_mfma_f32_16x16x32_bf16 v[70:73], v[182:185], v[10:13], v[158:161]
	v_mfma_f32_16x16x32_bf16 v[74:77], v[202:205], v[10:13], v[146:149]
	v_mfma_f32_16x16x32_bf16 v[78:81], v[206:209], v[10:13], v[36:39]
	ds_read_b128 v[14:17], v30 offset:1024
	s_waitcnt lgkmcnt(3)
	v_mfma_f32_16x16x32_bf16 v[82:85], v[178:181], v[22:25], v[112:115]
	v_mfma_f32_16x16x32_bf16 v[86:89], v[182:185], v[22:25], v[56:59]
	v_mfma_f32_16x16x32_bf16 v[90:93], v[202:205], v[22:25], v[162:165]
	v_mfma_f32_16x16x32_bf16 v[94:97], v[206:209], v[22:25], v[32:35]
	s_nop 2
	ds_read_b128 v[30:33], v31 offset:1024
	s_waitcnt lgkmcnt(3)
	v_mfma_f32_16x16x32_bf16 v[34:37], v[178:181], v[2:5], v[150:153]
	v_mfma_f32_16x16x32_bf16 v[38:41], v[182:185], v[2:5], v[116:119]
	v_mfma_f32_16x16x32_bf16 v[42:45], v[202:205], v[2:5], v[120:123]
	v_mfma_f32_16x16x32_bf16 v[46:49], v[206:209], v[2:5], v[48:51]
	s_waitcnt lgkmcnt(2)
	v_mfma_f32_16x16x32_bf16 v[50:53], v[178:181], v[6:9], v[52:55]
	v_mfma_f32_16x16x32_bf16 v[54:57], v[182:185], v[6:9], v[100:103]
	v_mfma_f32_16x16x32_bf16 v[58:61], v[202:205], v[6:9], v[104:107]
	v_mfma_f32_16x16x32_bf16 v[62:65], v[206:209], v[6:9], v[108:111]
	s_waitcnt lgkmcnt(1)
	v_mfma_f32_16x16x32_bf16 v[2:5], v[178:181], v[14:17], v[154:157]
	v_mfma_f32_16x16x32_bf16 v[6:9], v[182:185], v[14:17], v[166:169]
	v_mfma_f32_16x16x32_bf16 v[10:13], v[202:205], v[14:17], v[170:173]
	v_mfma_f32_16x16x32_bf16 v[14:17], v[206:209], v[14:17], v[174:177]
	s_waitcnt lgkmcnt(0)
	v_mfma_f32_16x16x32_bf16 v[18:21], v[178:181], v[30:33], v[186:189]
	v_mfma_f32_16x16x32_bf16 v[22:25], v[182:185], v[30:33], v[190:193]
	v_mfma_f32_16x16x32_bf16 v[26:29], v[202:205], v[30:33], v[194:197]
	v_mfma_f32_16x16x32_bf16 v[30:33], v[206:209], v[30:33], v[198:201]
	v_lshlrev_b32_e32 v101, 2, v98
	v_and_b32_e32 v112, 60, v101
	v_ashrrev_i32_e32 v101, 1, v98
	v_lshrrev_b32_e32 v99, 6, v98
	v_and_b32_e32 v101, 0xffffff80, v101
	v_and_b32_e32 v100, 15, v98
	v_mul_lo_u32 v99, v99, s48
	v_add_u32_e32 v107, s28, v101
	v_bfe_u32 v108, v98, 4, 2
	v_add_u32_e32 v109, s46, v99
	v_and_b32_e32 v99, 48, v98
	v_and_or_b32 v102, v98, s49, v112
	v_mul_u32_u24_e32 v98, 0x110, v100
	v_or_b32_e32 v100, v107, v108
	v_lshl_add_u64 v[0:1], v[0:1], 0, s[38:39]
	v_lshlrev_b32_e32 v130, 1, v102
	v_ashrrev_i32_e32 v101, 31, v100
	v_lshl_add_u64 v[0:1], v[0:1], 0, v[130:131]
	v_add3_u32 v99, v109, v99, v98
	v_lshlrev_b64 v[100:101], 11, v[100:101]
	s_waitcnt vmcnt(0)
	s_barrier
	ds_write_b128 v99, v[138:141]
	ds_write_b128 v99, v[210:213] offset:64
	ds_write_b128 v99, v[214:217] offset:128
	ds_write_b128 v99, v[218:221] offset:192
	ds_write_b128 v99, v[134:137] offset:4352
	ds_write_b128 v99, v[142:145] offset:4416
	ds_write_b128 v99, v[222:225] offset:4480
	ds_write_b128 v99, v[226:229] offset:4544
	v_lshl_add_u64 v[114:115], v[0:1], 0, v[100:101]
	flat_load_dwordx2 v[116:117], v[114:115]
	v_or_b32_e32 v100, 4, v108
	v_or_b32_e32 v102, v107, v100
	v_ashrrev_i32_e32 v103, 31, v102
	v_lshlrev_b64 v[102:103], 11, v[102:103]
	v_lshl_add_u64 v[118:119], v[0:1], 0, v[102:103]
	flat_load_dwordx2 v[120:121], v[118:119]
	v_or_b32_e32 v101, 8, v108
	v_or_b32_e32 v102, v107, v101
	v_ashrrev_i32_e32 v103, 31, v102
	v_lshlrev_b64 v[102:103], 11, v[102:103]
	v_lshl_add_u64 v[122:123], v[0:1], 0, v[102:103]
	flat_load_dwordx2 v[124:125], v[122:123]
	v_or_b32_e32 v102, 12, v108
	v_or_b32_e32 v104, v107, v102
	v_ashrrev_i32_e32 v105, 31, v104
	v_lshlrev_b64 v[104:105], 11, v[104:105]
	v_lshl_add_u64 v[126:127], v[0:1], 0, v[104:105]
	flat_load_dwordx2 v[128:129], v[126:127]
	v_or_b32_e32 v103, 16, v108
	v_or_b32_e32 v104, v107, v103
	v_ashrrev_i32_e32 v105, 31, v104
	v_lshlrev_b64 v[104:105], 11, v[104:105]
	v_lshl_add_u64 v[134:135], v[0:1], 0, v[104:105]
	flat_load_dwordx2 v[136:137], v[134:135]
	v_or_b32_e32 v104, 20, v108
	v_or_b32_e32 v110, v107, v104
	v_ashrrev_i32_e32 v111, 31, v110
	v_lshlrev_b64 v[110:111], 11, v[110:111]
	v_lshl_add_u64 v[138:139], v[0:1], 0, v[110:111]
	flat_load_dwordx2 v[140:141], v[138:139]
	v_or_b32_e32 v105, 24, v108
	v_or_b32_e32 v110, v107, v105
	v_ashrrev_i32_e32 v111, 31, v110
	v_lshlrev_b64 v[110:111], 11, v[110:111]
	v_lshl_add_u64 v[142:143], v[0:1], 0, v[110:111]
	flat_load_dwordx2 v[144:145], v[142:143]
	v_or_b32_e32 v106, 28, v108
	v_or_b32_e32 v146, v107, v106
	v_ashrrev_i32_e32 v147, 31, v146
	v_lshlrev_b64 v[146:147], 11, v[146:147]
	v_lshl_add_u64 v[146:147], v[0:1], 0, v[146:147]
	flat_load_dwordx2 v[148:149], v[146:147]
	v_mul_u32_u24_e32 v98, 0x110, v108
	v_lshlrev_b32_e32 v110, 2, v112
	v_add3_u32 v98, v109, v110, v98
	ds_read_b128 v[110:113], v98
	s_add_i32 s0, s30, 0x1600
	s_lshl_b64 s[42:43], s[0:1], 11
	s_waitcnt vmcnt(0) lgkmcnt(0)
	v_and_b32_e32 v151, 0xffff0000, v116
	v_lshlrev_b32_e32 v150, 16, v116
	v_and_b32_e32 v153, 0xffff0000, v117
	v_lshlrev_b32_e32 v152, 16, v117
	v_pk_mul_f32 v[110:111], v[110:111], v[150:151]
	v_pk_mul_f32 v[112:113], v[112:113], v[152:153]
	v_cvt_pk_bf16_f32 v110, v110, v111
	v_cvt_pk_bf16_f32 v111, v112, v113
	flat_store_dwordx2 v[114:115], v[110:111]
	ds_read_b128 v[110:113], v98 offset:1088
	v_and_b32_e32 v115, 0xffff0000, v120
	v_lshlrev_b32_e32 v114, 16, v120
	v_and_b32_e32 v117, 0xffff0000, v121
	v_lshlrev_b32_e32 v116, 16, v121
	s_waitcnt lgkmcnt(0)
	v_pk_mul_f32 v[110:111], v[110:111], v[114:115]
	v_pk_mul_f32 v[112:113], v[112:113], v[116:117]
	v_cvt_pk_bf16_f32 v110, v110, v111
	v_cvt_pk_bf16_f32 v111, v112, v113
	flat_store_dwordx2 v[118:119], v[110:111]
	ds_read_b128 v[110:113], v98 offset:2176
	v_and_b32_e32 v115, 0xffff0000, v124
	v_lshlrev_b32_e32 v114, 16, v124
	v_and_b32_e32 v117, 0xffff0000, v125
	v_lshlrev_b32_e32 v116, 16, v125
	s_waitcnt lgkmcnt(0)
	v_pk_mul_f32 v[110:111], v[110:111], v[114:115]
	v_pk_mul_f32 v[112:113], v[112:113], v[116:117]
	v_cvt_pk_bf16_f32 v110, v110, v111
	v_cvt_pk_bf16_f32 v111, v112, v113
	flat_store_dwordx2 v[122:123], v[110:111]
	ds_read_b128 v[110:113], v98 offset:3264
	v_and_b32_e32 v115, 0xffff0000, v128
	v_lshlrev_b32_e32 v114, 16, v128
	v_mov_b32_e32 v150, v132
	s_waitcnt lgkmcnt(0)
	v_pk_mul_f32 v[110:111], v[110:111], v[114:115]
	v_and_b32_e32 v115, 0xffff0000, v129
	v_lshlrev_b32_e32 v114, 16, v129
	v_pk_mul_f32 v[112:113], v[112:113], v[114:115]
	v_cvt_pk_bf16_f32 v110, v110, v111
	v_cvt_pk_bf16_f32 v111, v112, v113
	flat_store_dwordx2 v[126:127], v[110:111]
	ds_read_b128 v[110:113], v98 offset:4352
	v_and_b32_e32 v115, 0xffff0000, v136
	v_lshlrev_b32_e32 v114, 16, v136
	s_waitcnt lgkmcnt(0)
	v_pk_mul_f32 v[110:111], v[110:111], v[114:115]
	v_and_b32_e32 v115, 0xffff0000, v137
	v_lshlrev_b32_e32 v114, 16, v137
	v_pk_mul_f32 v[112:113], v[112:113], v[114:115]
	v_cvt_pk_bf16_f32 v110, v110, v111
	v_cvt_pk_bf16_f32 v111, v112, v113
	flat_store_dwordx2 v[134:135], v[110:111]
	ds_read_b128 v[110:113], v98 offset:5440
	v_and_b32_e32 v115, 0xffff0000, v140
	v_lshlrev_b32_e32 v114, 16, v140
	s_waitcnt lgkmcnt(0)
	v_pk_mul_f32 v[110:111], v[110:111], v[114:115]
	v_and_b32_e32 v115, 0xffff0000, v141
	v_lshlrev_b32_e32 v114, 16, v141
	v_pk_mul_f32 v[112:113], v[112:113], v[114:115]
	v_cvt_pk_bf16_f32 v110, v110, v111
	v_cvt_pk_bf16_f32 v111, v112, v113
	flat_store_dwordx2 v[138:139], v[110:111]
	ds_read_b128 v[110:113], v98 offset:6528
	v_and_b32_e32 v115, 0xffff0000, v144
	v_lshlrev_b32_e32 v114, 16, v144
	s_waitcnt lgkmcnt(0)
	v_pk_mul_f32 v[110:111], v[110:111], v[114:115]
	v_and_b32_e32 v115, 0xffff0000, v145
	v_lshlrev_b32_e32 v114, 16, v145
	v_pk_mul_f32 v[112:113], v[112:113], v[114:115]
	v_cvt_pk_bf16_f32 v110, v110, v111
	v_cvt_pk_bf16_f32 v111, v112, v113
	flat_store_dwordx2 v[142:143], v[110:111]
	ds_read_b128 v[110:113], v98 offset:7616
	v_and_b32_e32 v115, 0xffff0000, v148
	v_lshlrev_b32_e32 v114, 16, v148
	s_waitcnt lgkmcnt(0)
	v_pk_mul_f32 v[110:111], v[110:111], v[114:115]
	v_and_b32_e32 v115, 0xffff0000, v149
	v_lshlrev_b32_e32 v114, 16, v149
	v_pk_mul_f32 v[112:113], v[112:113], v[114:115]
	v_cvt_pk_bf16_f32 v110, v110, v111
	v_cvt_pk_bf16_f32 v111, v112, v113
	flat_store_dwordx2 v[146:147], v[110:111]
	ds_write_b128 v99, v[66:69]
	v_or_b32_e32 v68, 32, v107
	v_or_b32_e32 v66, v68, v108
	v_ashrrev_i32_e32 v67, 31, v66
	v_lshlrev_b64 v[66:67], 11, v[66:67]
	ds_write_b128 v99, v[70:73] offset:64
	ds_write_b128 v99, v[74:77] offset:128
	ds_write_b128 v99, v[78:81] offset:192
	ds_write_b128 v99, v[82:85] offset:4352
	ds_write_b128 v99, v[86:89] offset:4416
	ds_write_b128 v99, v[90:93] offset:4480
	ds_write_b128 v99, v[94:97] offset:4544
	v_lshl_add_u64 v[70:71], v[0:1], 0, v[66:67]
	flat_load_dwordx2 v[72:73], v[70:71]
	v_or_b32_e32 v66, v68, v100
	v_ashrrev_i32_e32 v67, 31, v66
	v_lshlrev_b64 v[66:67], 11, v[66:67]
	v_lshl_add_u64 v[74:75], v[0:1], 0, v[66:67]
	flat_load_dwordx2 v[76:77], v[74:75]
	v_or_b32_e32 v66, v68, v101
	v_ashrrev_i32_e32 v67, 31, v66
	v_lshlrev_b64 v[66:67], 11, v[66:67]
	v_lshl_add_u64 v[78:79], v[0:1], 0, v[66:67]
	flat_load_dwordx2 v[80:81], v[78:79]
	v_or_b32_e32 v66, v68, v102
	v_ashrrev_i32_e32 v67, 31, v66
	v_lshlrev_b64 v[66:67], 11, v[66:67]
	v_lshl_add_u64 v[82:83], v[0:1], 0, v[66:67]
	flat_load_dwordx2 v[84:85], v[82:83]
	v_or_b32_e32 v66, v68, v103
	v_ashrrev_i32_e32 v67, 31, v66
	v_lshlrev_b64 v[66:67], 11, v[66:67]
	v_lshl_add_u64 v[86:87], v[0:1], 0, v[66:67]
	flat_load_dwordx2 v[88:89], v[86:87]
	v_or_b32_e32 v66, v68, v104
	v_ashrrev_i32_e32 v67, 31, v66
	v_lshlrev_b64 v[66:67], 11, v[66:67]
	v_lshl_add_u64 v[90:91], v[0:1], 0, v[66:67]
	flat_load_dwordx2 v[92:93], v[90:91]
	v_or_b32_e32 v66, v68, v105
	v_ashrrev_i32_e32 v67, 31, v66
	v_lshlrev_b64 v[66:67], 11, v[66:67]
	v_lshl_add_u64 v[94:95], v[0:1], 0, v[66:67]
	flat_load_dwordx2 v[96:97], v[94:95]
	v_or_b32_e32 v66, v68, v106
	v_ashrrev_i32_e32 v67, 31, v66
	v_lshlrev_b64 v[66:67], 11, v[66:67]
	v_lshl_add_u64 v[110:111], v[0:1], 0, v[66:67]
	flat_load_dwordx2 v[112:113], v[110:111]
	ds_read_b128 v[66:69], v98
	s_waitcnt vmcnt(0) lgkmcnt(0)
	v_and_b32_e32 v115, 0xffff0000, v72
	v_lshlrev_b32_e32 v114, 16, v72
	v_and_b32_e32 v117, 0xffff0000, v73
	v_lshlrev_b32_e32 v116, 16, v73
	v_pk_mul_f32 v[66:67], v[66:67], v[114:115]
	v_pk_mul_f32 v[68:69], v[68:69], v[116:117]
	v_cvt_pk_bf16_f32 v66, v66, v67
	v_cvt_pk_bf16_f32 v67, v68, v69
	flat_store_dwordx2 v[70:71], v[66:67]
	ds_read_b128 v[66:69], v98 offset:1088
	v_and_b32_e32 v71, 0xffff0000, v76
	v_lshlrev_b32_e32 v70, 16, v76
	v_and_b32_e32 v73, 0xffff0000, v77
	v_lshlrev_b32_e32 v72, 16, v77
	s_waitcnt lgkmcnt(0)
	v_pk_mul_f32 v[66:67], v[66:67], v[70:71]
	v_pk_mul_f32 v[68:69], v[68:69], v[72:73]
	v_cvt_pk_bf16_f32 v66, v66, v67
	v_cvt_pk_bf16_f32 v67, v68, v69
	flat_store_dwordx2 v[74:75], v[66:67]
	ds_read_b128 v[66:69], v98 offset:2176
	v_and_b32_e32 v71, 0xffff0000, v80
	v_lshlrev_b32_e32 v70, 16, v80
	v_and_b32_e32 v73, 0xffff0000, v81
	v_lshlrev_b32_e32 v72, 16, v81
	s_waitcnt lgkmcnt(0)
	v_pk_mul_f32 v[66:67], v[66:67], v[70:71]
	v_pk_mul_f32 v[68:69], v[68:69], v[72:73]
	v_cvt_pk_bf16_f32 v66, v66, v67
	v_cvt_pk_bf16_f32 v67, v68, v69
	flat_store_dwordx2 v[78:79], v[66:67]
	ds_read_b128 v[66:69], v98 offset:3264
	v_and_b32_e32 v71, 0xffff0000, v84
	v_lshlrev_b32_e32 v70, 16, v84
	v_and_b32_e32 v73, 0xffff0000, v85
	v_lshlrev_b32_e32 v72, 16, v85
	s_waitcnt lgkmcnt(0)
	v_pk_mul_f32 v[66:67], v[66:67], v[70:71]
	v_pk_mul_f32 v[68:69], v[68:69], v[72:73]
	v_cvt_pk_bf16_f32 v66, v66, v67
	v_cvt_pk_bf16_f32 v67, v68, v69
	flat_store_dwordx2 v[82:83], v[66:67]
	ds_read_b128 v[66:69], v98 offset:4352
	v_and_b32_e32 v71, 0xffff0000, v88
	v_lshlrev_b32_e32 v70, 16, v88
	v_and_b32_e32 v73, 0xffff0000, v89
	v_lshlrev_b32_e32 v72, 16, v89
	s_waitcnt lgkmcnt(0)
	v_pk_mul_f32 v[66:67], v[66:67], v[70:71]
	v_pk_mul_f32 v[68:69], v[68:69], v[72:73]
	v_cvt_pk_bf16_f32 v66, v66, v67
	v_cvt_pk_bf16_f32 v67, v68, v69
	flat_store_dwordx2 v[86:87], v[66:67]
	ds_read_b128 v[66:69], v98 offset:5440
	v_and_b32_e32 v71, 0xffff0000, v92
	v_lshlrev_b32_e32 v70, 16, v92
	v_and_b32_e32 v73, 0xffff0000, v93
	v_lshlrev_b32_e32 v72, 16, v93
	s_waitcnt lgkmcnt(0)
	v_pk_mul_f32 v[66:67], v[66:67], v[70:71]
	v_pk_mul_f32 v[68:69], v[68:69], v[72:73]
	v_cvt_pk_bf16_f32 v66, v66, v67
	v_cvt_pk_bf16_f32 v67, v68, v69
	flat_store_dwordx2 v[90:91], v[66:67]
	ds_read_b128 v[66:69], v98 offset:6528
	v_and_b32_e32 v71, 0xffff0000, v96
	v_lshlrev_b32_e32 v70, 16, v96
	v_and_b32_e32 v73, 0xffff0000, v97
	v_lshlrev_b32_e32 v72, 16, v97
	s_waitcnt lgkmcnt(0)
	v_pk_mul_f32 v[66:67], v[66:67], v[70:71]
	v_pk_mul_f32 v[68:69], v[68:69], v[72:73]
	v_cvt_pk_bf16_f32 v66, v66, v67
	v_cvt_pk_bf16_f32 v67, v68, v69
	flat_store_dwordx2 v[94:95], v[66:67]
	ds_read_b128 v[66:69], v98 offset:7616
	v_and_b32_e32 v71, 0xffff0000, v112
	v_lshlrev_b32_e32 v70, 16, v112
	v_and_b32_e32 v73, 0xffff0000, v113
	v_lshlrev_b32_e32 v72, 16, v113
	s_waitcnt lgkmcnt(0)
	v_pk_mul_f32 v[66:67], v[66:67], v[70:71]
	v_pk_mul_f32 v[68:69], v[68:69], v[72:73]
	v_cvt_pk_bf16_f32 v66, v66, v67
	v_cvt_pk_bf16_f32 v67, v68, v69
	flat_store_dwordx2 v[110:111], v[66:67]
	ds_write_b128 v99, v[34:37]
	v_or_b32_e32 v36, 64, v107
	v_or_b32_e32 v34, v36, v108
	v_ashrrev_i32_e32 v35, 31, v34
	v_lshlrev_b64 v[34:35], 11, v[34:35]
	ds_write_b128 v99, v[38:41] offset:64
	ds_write_b128 v99, v[42:45] offset:128
	ds_write_b128 v99, v[46:49] offset:192
	ds_write_b128 v99, v[50:53] offset:4352
	ds_write_b128 v99, v[54:57] offset:4416
	ds_write_b128 v99, v[58:61] offset:4480
	ds_write_b128 v99, v[62:65] offset:4544
	v_lshl_add_u64 v[38:39], v[0:1], 0, v[34:35]
	flat_load_dwordx2 v[40:41], v[38:39]
	v_or_b32_e32 v34, v36, v100
	v_ashrrev_i32_e32 v35, 31, v34
	v_lshlrev_b64 v[34:35], 11, v[34:35]
	v_lshl_add_u64 v[42:43], v[0:1], 0, v[34:35]
	flat_load_dwordx2 v[44:45], v[42:43]
	v_or_b32_e32 v34, v36, v101
	v_ashrrev_i32_e32 v35, 31, v34
	v_lshlrev_b64 v[34:35], 11, v[34:35]
	v_lshl_add_u64 v[46:47], v[0:1], 0, v[34:35]
	flat_load_dwordx2 v[48:49], v[46:47]
	v_or_b32_e32 v34, v36, v102
	v_ashrrev_i32_e32 v35, 31, v34
	v_lshlrev_b64 v[34:35], 11, v[34:35]
	v_lshl_add_u64 v[50:51], v[0:1], 0, v[34:35]
	flat_load_dwordx2 v[52:53], v[50:51]
	v_or_b32_e32 v34, v36, v103
	v_ashrrev_i32_e32 v35, 31, v34
	v_lshlrev_b64 v[34:35], 11, v[34:35]
	v_lshl_add_u64 v[54:55], v[0:1], 0, v[34:35]
	flat_load_dwordx2 v[56:57], v[54:55]
	v_or_b32_e32 v34, v36, v104
	v_ashrrev_i32_e32 v35, 31, v34
	v_lshlrev_b64 v[34:35], 11, v[34:35]
	v_lshl_add_u64 v[58:59], v[0:1], 0, v[34:35]
	flat_load_dwordx2 v[60:61], v[58:59]
	v_or_b32_e32 v34, v36, v105
	v_ashrrev_i32_e32 v35, 31, v34
	v_lshlrev_b64 v[34:35], 11, v[34:35]
	v_lshl_add_u64 v[62:63], v[0:1], 0, v[34:35]
	flat_load_dwordx2 v[64:65], v[62:63]
	v_or_b32_e32 v34, v36, v106
	v_ashrrev_i32_e32 v35, 31, v34
	v_lshlrev_b64 v[34:35], 11, v[34:35]
	v_lshl_add_u64 v[66:67], v[0:1], 0, v[34:35]
	flat_load_dwordx2 v[68:69], v[66:67]
	ds_read_b128 v[34:37], v98
	v_or_b32_e32 v76, 0x60, v107
	v_or_b32_e32 v70, v76, v108
	v_ashrrev_i32_e32 v71, 31, v70
	s_waitcnt vmcnt(0) lgkmcnt(0)
	v_and_b32_e32 v73, 0xffff0000, v40
	v_lshlrev_b32_e32 v72, 16, v40
	v_and_b32_e32 v75, 0xffff0000, v41
	v_lshlrev_b32_e32 v74, 16, v41
	v_pk_mul_f32 v[34:35], v[34:35], v[72:73]
	v_pk_mul_f32 v[36:37], v[36:37], v[74:75]
	v_cvt_pk_bf16_f32 v34, v34, v35
	v_cvt_pk_bf16_f32 v35, v36, v37
	flat_store_dwordx2 v[38:39], v[34:35]
	ds_read_b128 v[34:37], v98 offset:1088
	v_and_b32_e32 v39, 0xffff0000, v44
	v_lshlrev_b32_e32 v38, 16, v44
	v_and_b32_e32 v41, 0xffff0000, v45
	v_lshlrev_b32_e32 v40, 16, v45
	s_waitcnt lgkmcnt(0)
	v_pk_mul_f32 v[34:35], v[34:35], v[38:39]
	v_pk_mul_f32 v[36:37], v[36:37], v[40:41]
	v_cvt_pk_bf16_f32 v34, v34, v35
	v_cvt_pk_bf16_f32 v35, v36, v37
	flat_store_dwordx2 v[42:43], v[34:35]
	ds_read_b128 v[34:37], v98 offset:2176
	v_and_b32_e32 v39, 0xffff0000, v48
	v_lshlrev_b32_e32 v38, 16, v48
	v_and_b32_e32 v41, 0xffff0000, v49
	v_lshlrev_b32_e32 v40, 16, v49
	s_waitcnt lgkmcnt(0)
	v_pk_mul_f32 v[34:35], v[34:35], v[38:39]
	v_pk_mul_f32 v[36:37], v[36:37], v[40:41]
	v_cvt_pk_bf16_f32 v34, v34, v35
	v_cvt_pk_bf16_f32 v35, v36, v37
	flat_store_dwordx2 v[46:47], v[34:35]
	ds_read_b128 v[34:37], v98 offset:3264
	v_and_b32_e32 v39, 0xffff0000, v52
	v_lshlrev_b32_e32 v38, 16, v52
	v_and_b32_e32 v41, 0xffff0000, v53
	v_lshlrev_b32_e32 v40, 16, v53
	s_waitcnt lgkmcnt(0)
	v_pk_mul_f32 v[34:35], v[34:35], v[38:39]
	v_pk_mul_f32 v[36:37], v[36:37], v[40:41]
	v_cvt_pk_bf16_f32 v34, v34, v35
	v_cvt_pk_bf16_f32 v35, v36, v37
	flat_store_dwordx2 v[50:51], v[34:35]
	ds_read_b128 v[34:37], v98 offset:4352
	v_and_b32_e32 v39, 0xffff0000, v56
	v_lshlrev_b32_e32 v38, 16, v56
	v_and_b32_e32 v41, 0xffff0000, v57
	v_lshlrev_b32_e32 v40, 16, v57
	s_waitcnt lgkmcnt(0)
	v_pk_mul_f32 v[34:35], v[34:35], v[38:39]
	v_pk_mul_f32 v[36:37], v[36:37], v[40:41]
	v_cvt_pk_bf16_f32 v34, v34, v35
	v_cvt_pk_bf16_f32 v35, v36, v37
	flat_store_dwordx2 v[54:55], v[34:35]
	ds_read_b128 v[34:37], v98 offset:5440
	v_and_b32_e32 v39, 0xffff0000, v60
	v_lshlrev_b32_e32 v38, 16, v60
	v_and_b32_e32 v41, 0xffff0000, v61
	v_lshlrev_b32_e32 v40, 16, v61
	s_waitcnt lgkmcnt(0)
	v_pk_mul_f32 v[34:35], v[34:35], v[38:39]
	v_pk_mul_f32 v[36:37], v[36:37], v[40:41]
	v_cvt_pk_bf16_f32 v34, v34, v35
	v_cvt_pk_bf16_f32 v35, v36, v37
	flat_store_dwordx2 v[58:59], v[34:35]
	ds_read_b128 v[34:37], v98 offset:6528
	v_and_b32_e32 v39, 0xffff0000, v64
	v_lshlrev_b32_e32 v38, 16, v64
	v_and_b32_e32 v41, 0xffff0000, v65
	v_lshlrev_b32_e32 v40, 16, v65
	s_waitcnt lgkmcnt(0)
	v_pk_mul_f32 v[34:35], v[34:35], v[38:39]
	v_pk_mul_f32 v[36:37], v[36:37], v[40:41]
	v_cvt_pk_bf16_f32 v34, v34, v35
	v_cvt_pk_bf16_f32 v35, v36, v37
	flat_store_dwordx2 v[62:63], v[34:35]
	ds_read_b128 v[34:37], v98 offset:7616
	v_and_b32_e32 v39, 0xffff0000, v68
	v_lshlrev_b32_e32 v38, 16, v68
	v_and_b32_e32 v41, 0xffff0000, v69
	v_lshlrev_b32_e32 v40, 16, v69
	s_waitcnt lgkmcnt(0)
	v_pk_mul_f32 v[34:35], v[34:35], v[38:39]
	v_pk_mul_f32 v[36:37], v[36:37], v[40:41]
	v_cvt_pk_bf16_f32 v34, v34, v35
	v_cvt_pk_bf16_f32 v35, v36, v37
	flat_store_dwordx2 v[66:67], v[34:35]
	ds_write_b128 v99, v[2:5]
	v_lshlrev_b64 v[2:3], 11, v[70:71]
	ds_write_b128 v99, v[6:9] offset:64
	ds_write_b128 v99, v[10:13] offset:128
	ds_write_b128 v99, v[14:17] offset:192
	ds_write_b128 v99, v[18:21] offset:4352
	ds_write_b128 v99, v[22:25] offset:4416
	ds_write_b128 v99, v[26:29] offset:4480
	ds_write_b128 v99, v[30:33] offset:4544
	v_lshl_add_u64 v[4:5], v[0:1], 0, v[2:3]
	flat_load_dwordx2 v[6:7], v[4:5]
	v_or_b32_e32 v2, v76, v100
	v_ashrrev_i32_e32 v3, 31, v2
	v_lshlrev_b64 v[2:3], 11, v[2:3]
	v_lshl_add_u64 v[8:9], v[0:1], 0, v[2:3]
	flat_load_dwordx2 v[10:11], v[8:9]
	v_or_b32_e32 v2, v76, v101
	v_ashrrev_i32_e32 v3, 31, v2
	v_lshlrev_b64 v[2:3], 11, v[2:3]
	v_lshl_add_u64 v[12:13], v[0:1], 0, v[2:3]
	flat_load_dwordx2 v[14:15], v[12:13]
	v_or_b32_e32 v2, v76, v102
	v_ashrrev_i32_e32 v3, 31, v2
	v_lshlrev_b64 v[2:3], 11, v[2:3]
	v_lshl_add_u64 v[16:17], v[0:1], 0, v[2:3]
	flat_load_dwordx2 v[18:19], v[16:17]
	v_or_b32_e32 v2, v76, v103
	v_ashrrev_i32_e32 v3, 31, v2
	v_lshlrev_b64 v[2:3], 11, v[2:3]
	v_lshl_add_u64 v[20:21], v[0:1], 0, v[2:3]
	flat_load_dwordx2 v[22:23], v[20:21]
	v_or_b32_e32 v2, v76, v104
	v_ashrrev_i32_e32 v3, 31, v2
	v_lshlrev_b64 v[2:3], 11, v[2:3]
	v_lshl_add_u64 v[24:25], v[0:1], 0, v[2:3]
	flat_load_dwordx2 v[26:27], v[24:25]
	v_or_b32_e32 v2, v76, v105
	v_ashrrev_i32_e32 v3, 31, v2
	v_lshlrev_b64 v[2:3], 11, v[2:3]
	v_lshl_add_u64 v[28:29], v[0:1], 0, v[2:3]
	flat_load_dwordx2 v[30:31], v[28:29]
	v_or_b32_e32 v2, v76, v106
	v_ashrrev_i32_e32 v3, 31, v2
	v_lshlrev_b64 v[2:3], 11, v[2:3]
	v_lshl_add_u64 v[32:33], v[0:1], 0, v[2:3]
	flat_load_dwordx2 v[34:35], v[32:33]
	ds_read_b128 v[0:3], v98
	v_mov_b32_e32 v40, s51
	v_mov_b32_e32 v41, v132
	s_waitcnt vmcnt(0) lgkmcnt(0)
	v_and_b32_e32 v37, 0xffff0000, v6
	v_lshlrev_b32_e32 v36, 16, v6
	v_and_b32_e32 v39, 0xffff0000, v7
	v_lshlrev_b32_e32 v38, 16, v7
	v_pk_mul_f32 v[0:1], v[0:1], v[36:37]
	v_pk_mul_f32 v[2:3], v[2:3], v[38:39]
	v_cvt_pk_bf16_f32 v0, v0, v1
	v_cvt_pk_bf16_f32 v1, v2, v3
	flat_store_dwordx2 v[4:5], v[0:1]
	ds_read_b128 v[0:3], v98 offset:1088
	v_and_b32_e32 v5, 0xffff0000, v10
	v_lshlrev_b32_e32 v4, 16, v10
	v_and_b32_e32 v7, 0xffff0000, v11
	v_lshlrev_b32_e32 v6, 16, v11
	s_waitcnt lgkmcnt(0)
	v_pk_mul_f32 v[0:1], v[0:1], v[4:5]
	v_pk_mul_f32 v[2:3], v[2:3], v[6:7]
	v_cvt_pk_bf16_f32 v0, v0, v1
	v_cvt_pk_bf16_f32 v1, v2, v3
	flat_store_dwordx2 v[8:9], v[0:1]
	ds_read_b128 v[0:3], v98 offset:2176
	v_and_b32_e32 v5, 0xffff0000, v14
	v_lshlrev_b32_e32 v4, 16, v14
	v_and_b32_e32 v7, 0xffff0000, v15
	v_lshlrev_b32_e32 v6, 16, v15
	s_waitcnt lgkmcnt(0)
	v_pk_mul_f32 v[0:1], v[0:1], v[4:5]
	v_pk_mul_f32 v[2:3], v[2:3], v[6:7]
	v_cvt_pk_bf16_f32 v0, v0, v1
	v_cvt_pk_bf16_f32 v1, v2, v3
	flat_store_dwordx2 v[12:13], v[0:1]
	ds_read_b128 v[0:3], v98 offset:3264
	v_and_b32_e32 v5, 0xffff0000, v18
	v_lshlrev_b32_e32 v4, 16, v18
	v_and_b32_e32 v7, 0xffff0000, v19
	v_lshlrev_b32_e32 v6, 16, v19
	s_waitcnt lgkmcnt(0)
	v_pk_mul_f32 v[0:1], v[0:1], v[4:5]
	v_pk_mul_f32 v[2:3], v[2:3], v[6:7]
	v_cvt_pk_bf16_f32 v0, v0, v1
	v_cvt_pk_bf16_f32 v1, v2, v3
	flat_store_dwordx2 v[16:17], v[0:1]
	ds_read_b128 v[0:3], v98 offset:4352
	v_and_b32_e32 v5, 0xffff0000, v22
	v_lshlrev_b32_e32 v4, 16, v22
	v_and_b32_e32 v7, 0xffff0000, v23
	v_lshlrev_b32_e32 v6, 16, v23
	s_waitcnt lgkmcnt(0)
	v_pk_mul_f32 v[0:1], v[0:1], v[4:5]
	v_pk_mul_f32 v[2:3], v[2:3], v[6:7]
	v_cvt_pk_bf16_f32 v0, v0, v1
	v_cvt_pk_bf16_f32 v1, v2, v3
	flat_store_dwordx2 v[20:21], v[0:1]
	ds_read_b128 v[0:3], v98 offset:5440
	v_and_b32_e32 v5, 0xffff0000, v26
	v_lshlrev_b32_e32 v4, 16, v26
	v_and_b32_e32 v7, 0xffff0000, v27
	v_lshlrev_b32_e32 v6, 16, v27
	s_waitcnt lgkmcnt(0)
	v_pk_mul_f32 v[0:1], v[0:1], v[4:5]
	v_pk_mul_f32 v[2:3], v[2:3], v[6:7]
	v_cvt_pk_bf16_f32 v0, v0, v1
	v_cvt_pk_bf16_f32 v1, v2, v3
	flat_store_dwordx2 v[24:25], v[0:1]
	ds_read_b128 v[0:3], v98 offset:6528
	v_and_b32_e32 v5, 0xffff0000, v30
	v_lshlrev_b32_e32 v4, 16, v30
	v_and_b32_e32 v7, 0xffff0000, v31
	v_lshlrev_b32_e32 v6, 16, v31
	s_waitcnt lgkmcnt(0)
	v_pk_mul_f32 v[0:1], v[0:1], v[4:5]
	v_pk_mul_f32 v[2:3], v[2:3], v[6:7]
	v_cvt_pk_bf16_f32 v0, v0, v1
	v_cvt_pk_bf16_f32 v1, v2, v3
	flat_store_dwordx2 v[28:29], v[0:1]
	ds_read_b128 v[0:3], v98 offset:7616
	v_and_b32_e32 v5, 0xffff0000, v34
	v_lshlrev_b32_e32 v4, 16, v34
	v_and_b32_e32 v7, 0xffff0000, v35
	v_lshlrev_b32_e32 v6, 16, v35
	s_waitcnt lgkmcnt(0)
	v_pk_mul_f32 v[0:1], v[0:1], v[4:5]
	v_pk_mul_f32 v[2:3], v[2:3], v[6:7]
	v_cvt_pk_bf16_f32 v0, v0, v1
	v_cvt_pk_bf16_f32 v1, v2, v3
	flat_store_dwordx2 v[32:33], v[0:1]
	ds_read_b64 v[128:129], v40
	s_waitcnt lgkmcnt(0)
	v_lshl_add_u64 v[2:3], v[128:129], 0, s[42:43]
	v_lshlrev_b32_e32 v5, 4, v41
	v_and_b32_e32 v0, 32, v41
	v_lshrrev_b32_e32 v1, 1, v41
	v_bitop3_b32 v0, v5, v0, 48 bitop3:0x6c
	v_bfe_u32 v16, v41, 2, 4
	v_ashrrev_i32_e32 v17, 3, v41
	v_and_b32_e32 v9, 0xfffffc00, v5
	v_and_b32_e32 v18, 32, v1
	v_add_u32_e32 v1, 0x2000, v5
	v_lshrrev_b32_e32 v19, 1, v0
	v_add_u32_e32 v8, 0x4000, v5
	v_add_u32_e32 v5, 0x6000, v5
	v_and_or_b32 v4, v17, s44, v16
	v_ashrrev_i32_e32 v20, 7, v1
	v_or_b32_e32 v10, v19, v18
	v_ashrrev_i32_e32 v21, 7, v8
	v_ashrrev_i32_e32 v22, 7, v5
	v_and_or_b32 v6, v20, s44, v16
	v_lshl_add_u64 v[0:1], v[128:129], 0, s[36:37]
	v_lshl_or_b32 v130, v4, 10, v10
	v_and_or_b32 v8, v21, s44, v16
	v_and_or_b32 v5, v22, s44, v16
	v_add_u32_e32 v151, 0, v9
	v_lshl_or_b32 v4, v6, 10, v10
	v_lshl_add_u64 v[6:7], v[0:1], 0, s[4:5]
	v_lshl_or_b32 v8, v8, 10, v10
	v_lshl_or_b32 v10, v5, 10, v10
	v_add_u32_e32 v5, 0x8000, v151
	v_lshlrev_b64 v[12:13], 1, v[130:131]
	v_readfirstlane_b32 s0, v151
	v_lshl_add_u64 v[14:15], v[6:7], 0, v[12:13]
	s_mov_b32 m0, s0
	v_readfirstlane_b32 s0, v5
	v_mov_b32_e32 v5, v131
	v_add_u32_e32 v9, 0x2000, v151
	global_load_lds_dwordx4 v[14:15], off
	v_lshl_add_u64 v[12:13], v[2:3], 0, v[12:13]
	s_mov_b32 m0, s0
	v_lshlrev_b64 v[4:5], 1, v[4:5]
	v_readfirstlane_b32 s0, v9
	v_add_u32_e32 v9, 0xa000, v151
	global_load_lds_dwordx4 v[12:13], off
	v_lshl_add_u64 v[12:13], v[6:7], 0, v[4:5]
	s_mov_b32 m0, s0
	v_readfirstlane_b32 s0, v9
	global_load_lds_dwordx4 v[12:13], off
	v_lshl_add_u64 v[4:5], v[2:3], 0, v[4:5]
	s_mov_b32 m0, s0
	v_mov_b32_e32 v9, v131
	v_add_u32_e32 v11, 0x4000, v151
	global_load_lds_dwordx4 v[4:5], off
	v_lshlrev_b64 v[4:5], 1, v[8:9]
	v_readfirstlane_b32 s0, v11
	v_lshl_add_u64 v[8:9], v[6:7], 0, v[4:5]
	s_mov_b32 m0, s0
	v_lshl_add_u64 v[4:5], v[2:3], 0, v[4:5]
	global_load_lds_dwordx4 v[8:9], off
	v_add_u32_e32 v8, 0xc000, v151
	v_mov_b32_e32 v11, v131
	v_readfirstlane_b32 s0, v8
	s_mov_b32 m0, s0
	v_add_u32_e32 v8, 0x6000, v151
	global_load_lds_dwordx4 v[4:5], off
	v_lshlrev_b64 v[4:5], 1, v[10:11]
	v_readfirstlane_b32 s0, v8
	v_lshl_add_u64 v[6:7], v[6:7], 0, v[4:5]
	s_mov_b32 m0, s0
	v_lshl_add_u64 v[4:5], v[2:3], 0, v[4:5]
	global_load_lds_dwordx4 v[6:7], off
	v_add_u32_e32 v6, 0xe000, v151
	v_and_b32_e32 v23, 15, v41
	v_readfirstlane_b32 s0, v6
	s_mov_b32 m0, s0
	v_lshlrev_b32_e32 v6, 2, v41
	global_load_lds_dwordx4 v[4:5], off
	v_and_b32_e32 v4, 48, v41
	v_lshlrev_b32_e32 v5, 6, v23
	v_and_b32_e32 v6, 32, v6
	v_bitop3_b32 v152, v5, v6, v4 bitop3:0x36
	v_lshlrev_b32_e32 v5, 7, v41
	v_and_b32_e32 v153, 0x6000, v5
	v_lshlrev_b32_e32 v5, 6, v41
	v_and_b32_e32 v154, 0xffffc000, v5
	v_and_b32_e32 v5, 0x3c0, v5
	v_bitop3_b32 v156, v5, v6, v4 bitop3:0x36
	v_lshlrev_b32_e32 v4, 10, v22
	v_and_or_b32 v4, v4, s45, v19
	v_lshlrev_b32_e32 v10, 10, v16
	v_lshlrev_b32_e32 v6, 10, v21
	v_or3_b32 v130, v4, v10, v18
	v_and_or_b32 v6, v6, s45, v19
	v_lshlrev_b32_e32 v8, 10, v20
	v_lshlrev_b64 v[4:5], 1, v[130:131]
	v_or3_b32 v130, v6, v10, v18
	v_and_or_b32 v8, v8, s45, v19
	v_lshlrev_b32_e32 v11, 10, v17
	v_lshlrev_b64 v[6:7], 1, v[130:131]
	v_or3_b32 v130, v8, v10, v18
	v_and_or_b32 v11, v11, s45, v19
	s_waitcnt vmcnt(0)
	v_lshl_add_u64 v[2:3], v[2:3], 0, s[6:7]
	v_lshlrev_b64 v[8:9], 1, v[130:131]
	v_or3_b32 v130, v11, v10, v18
	v_lshl_add_u64 v[0:1], v[0:1], 0, s[8:9]
	v_lshl_add_u64 v[138:139], v[2:3], 0, v[8:9]
	v_lshlrev_b64 v[10:11], 1, v[130:131]
	v_lshl_add_u64 v[146:147], v[0:1], 0, v[8:9]
	v_mov_b32_e32 v8, 0
	v_or_b32_e32 v155, 0x800, v154
	v_or_b32_e32 v157, 0x1000, v154
	v_or_b32_e32 v158, 0x1800, v154
	v_or_b32_e32 v159, 0x2000, v154
	v_or_b32_e32 v160, 0x2800, v154
	v_or_b32_e32 v161, 0x3000, v154
	v_or_b32_e32 v162, 0x3800, v154
	v_lshl_add_u64 v[134:135], v[2:3], 0, v[4:5]
	v_lshl_add_u64 v[136:137], v[2:3], 0, v[6:7]
	v_lshl_add_u64 v[140:141], v[2:3], 0, v[10:11]
	v_lshl_add_u64 v[142:143], v[0:1], 0, v[4:5]
	v_lshl_add_u64 v[144:145], v[0:1], 0, v[6:7]
	v_lshl_add_u64 v[148:149], v[0:1], 0, v[10:11]
	s_mov_b64 s[42:43], 0
	v_mov_b32_e32 v9, v8
	v_mov_b32_e32 v10, v8
	v_mov_b32_e32 v11, v8
	v_mov_b32_e32 v20, v8
	v_mov_b32_e32 v21, v8
	v_mov_b32_e32 v22, v8
	v_mov_b32_e32 v23, v8
	v_mov_b32_e32 v28, v8
	v_mov_b32_e32 v29, v8
	v_mov_b32_e32 v30, v8
	v_mov_b32_e32 v31, v8
	v_mov_b32_e32 v36, v8
	v_mov_b32_e32 v37, v8
	v_mov_b32_e32 v38, v8
	v_mov_b32_e32 v39, v8
	v_mov_b32_e32 v0, v8
	v_mov_b32_e32 v1, v8
	v_mov_b32_e32 v2, v8
	v_mov_b32_e32 v3, v8
	v_mov_b32_e32 v4, v8
	v_mov_b32_e32 v5, v8
	v_mov_b32_e32 v6, v8
	v_mov_b32_e32 v7, v8
	v_mov_b32_e32 v12, v8
	v_mov_b32_e32 v13, v8
	v_mov_b32_e32 v14, v8
	v_mov_b32_e32 v15, v8
	v_mov_b32_e32 v16, v8
	v_mov_b32_e32 v17, v8
	v_mov_b32_e32 v18, v8
	v_mov_b32_e32 v19, v8
	v_mov_b32_e32 v24, v8
	v_mov_b32_e32 v25, v8
	v_mov_b32_e32 v26, v8
	v_mov_b32_e32 v27, v8
	v_mov_b32_e32 v32, v8
	v_mov_b32_e32 v33, v8
	v_mov_b32_e32 v34, v8
	v_mov_b32_e32 v35, v8
	v_mov_b32_e32 v40, v8
	v_mov_b32_e32 v41, v8
	v_mov_b32_e32 v42, v8
	v_mov_b32_e32 v43, v8
	v_mov_b32_e32 v44, v8
	v_mov_b32_e32 v45, v8
	v_mov_b32_e32 v46, v8
	v_mov_b32_e32 v47, v8
	v_mov_b32_e32 v48, v8
	v_mov_b32_e32 v49, v8
	v_mov_b32_e32 v50, v8
	v_mov_b32_e32 v51, v8
	v_mov_b32_e32 v52, v8
	v_mov_b32_e32 v53, v8
	v_mov_b32_e32 v54, v8
	v_mov_b32_e32 v55, v8
	v_mov_b32_e32 v56, v8
	v_mov_b32_e32 v57, v8
	v_mov_b32_e32 v58, v8
	v_mov_b32_e32 v59, v8
	v_mov_b32_e32 v60, v8
	v_mov_b32_e32 v61, v8
	v_mov_b32_e32 v62, v8
	v_mov_b32_e32 v63, v8
	v_mov_b32_e32 v64, v8
	v_mov_b32_e32 v65, v8
	v_mov_b32_e32 v66, v8
	v_mov_b32_e32 v67, v8
	v_mov_b32_e32 v68, v8
	v_mov_b32_e32 v69, v8
	v_mov_b32_e32 v70, v8
	v_mov_b32_e32 v71, v8
	v_mov_b32_e32 v72, v8
	v_mov_b32_e32 v73, v8
	v_mov_b32_e32 v74, v8
	v_mov_b32_e32 v75, v8
	v_mov_b32_e32 v76, v8
	v_mov_b32_e32 v77, v8
	v_mov_b32_e32 v78, v8
	v_mov_b32_e32 v79, v8
	v_mov_b32_e32 v80, v8
	v_mov_b32_e32 v81, v8
	v_mov_b32_e32 v82, v8
	v_mov_b32_e32 v83, v8
	v_mov_b32_e32 v84, v8
	v_mov_b32_e32 v85, v8
	v_mov_b32_e32 v86, v8
	v_mov_b32_e32 v87, v8
	v_mov_b32_e32 v88, v8
	v_mov_b32_e32 v89, v8
	v_mov_b32_e32 v90, v8
	v_mov_b32_e32 v91, v8
	v_mov_b32_e32 v92, v8
	v_mov_b32_e32 v93, v8
	v_mov_b32_e32 v94, v8
	v_mov_b32_e32 v95, v8
	v_mov_b32_e32 v96, v8
	v_mov_b32_e32 v97, v8
	v_mov_b32_e32 v98, v8
	v_mov_b32_e32 v99, v8
	v_mov_b32_e32 v100, v8
	v_mov_b32_e32 v101, v8
	v_mov_b32_e32 v102, v8
	v_mov_b32_e32 v103, v8
	v_mov_b32_e32 v104, v8
	v_mov_b32_e32 v105, v8
	v_mov_b32_e32 v106, v8
	v_mov_b32_e32 v107, v8
	v_mov_b32_e32 v108, v8
	v_mov_b32_e32 v109, v8
	v_mov_b32_e32 v110, v8
	v_mov_b32_e32 v111, v8
	v_mov_b32_e32 v112, v8
	v_mov_b32_e32 v113, v8
	v_mov_b32_e32 v114, v8
	v_mov_b32_e32 v115, v8
	v_mov_b32_e32 v116, v8
	v_mov_b32_e32 v117, v8
	v_mov_b32_e32 v118, v8
	v_mov_b32_e32 v119, v8
	v_mov_b32_e32 v120, v8
	v_mov_b32_e32 v121, v8
	v_mov_b32_e32 v122, v8
	v_mov_b32_e32 v123, v8
	v_mov_b32_e32 v124, v8
	v_mov_b32_e32 v125, v8
	v_mov_b32_e32 v126, v8
	v_mov_b32_e32 v127, v8
	s_waitcnt vmcnt(0) lgkmcnt(0)
	s_barrier
	v_readfirstlane_b32 s100, v151
	s_mov_b64 s[98:99], 0x80
	s_and_b32 s0, s29, 0x10000
	s_xor_b32 s53, s0, 0x10000
	s_add_i32 s0, s0, 0
	v_add3_u32 v130, s0, v152, v153
	v_add3_u32 v163, s0, v152, v154
	v_add3_u32 v196, s0, v156, v155
	v_add3_u32 v197, s0, v156, v157
	v_add3_u32 v198, s0, v156, v158
	v_add3_u32 v199, s0, v156, v159
	v_add3_u32 v200, s0, v156, v160
	v_add3_u32 v201, s0, v156, v161
	v_add3_u32 v202, s0, v156, v162
	ds_read_b128 v[180:183], v130 offset:32768
	ds_read_b128 v[164:167], v163
	ds_read_b128 v[168:171], v196
	ds_read_b128 v[172:175], v197
	ds_read_b128 v[176:179], v198
	ds_read_b128 v[184:187], v130 offset:34816
	ds_read_b128 v[188:191], v130 offset:36864
	ds_read_b128 v[192:195], v130 offset:38912
	s_add_i32 s101, s100, s53
	s_mov_b32 m0, s101
	s_nop 0
	global_load_lds_dwordx4 v[148:149], off
	s_add_i32 m0, s101, 0x8000
	s_nop 0
	global_load_lds_dwordx4 v[140:141], off
	s_add_i32 m0, s101, 0x2000
	s_nop 0
	global_load_lds_dwordx4 v[146:147], off
	s_add_i32 m0, s101, 0xa000
	s_nop 0
	global_load_lds_dwordx4 v[138:139], off
	s_add_i32 m0, s101, 0x4000
	s_nop 0
	global_load_lds_dwordx4 v[144:145], off
	s_add_i32 m0, s101, 0xc000
	s_nop 0
	global_load_lds_dwordx4 v[136:137], off
	s_add_i32 m0, s101, 0x6000
	s_nop 0
	global_load_lds_dwordx4 v[142:143], off
	s_add_i32 m0, s101, 0xe000
	s_nop 0
	global_load_lds_dwordx4 v[134:135], off
.LBB0_795:
	s_and_b32 s0, s29, 0x10000
	s_xor_b32 s53, s0, 0x10000
	s_add_i32 s0, s0, 0
	s_add_i32 s101, s100, s53
	s_cmpk_eq_i32 s42, 0
	s_cbranch_scc1 .Lg1n_795
	s_waitcnt lgkmcnt(3)
	v_mfma_f32_16x16x32_bf16 v[124:127], v[180:183], v[164:167], v[124:127]
	v_mfma_f32_16x16x32_bf16 v[108:111], v[180:183], v[168:171], v[108:111]
	v_mfma_f32_16x16x32_bf16 v[92:95], v[180:183], v[172:175], v[92:95]
	v_mfma_f32_16x16x32_bf16 v[76:79], v[180:183], v[176:179], v[76:79]
	ds_read_b128 v[240:243], v199
	ds_read_b128 v[244:247], v200
	s_add_i32 m0, s101, 0x4000
	v_lshl_add_u64 v[144:145], v[144:145], 0, s[98:99]
	global_load_lds_dwordx4 v[144:145], off
	s_waitcnt lgkmcnt(4)
	v_mfma_f32_16x16x32_bf16 v[120:123], v[184:187], v[164:167], v[120:123]
	v_mfma_f32_16x16x32_bf16 v[104:107], v[184:187], v[168:171], v[104:107]
	v_mfma_f32_16x16x32_bf16 v[88:91], v[184:187], v[172:175], v[88:91]
	v_mfma_f32_16x16x32_bf16 v[72:75], v[184:187], v[176:179], v[72:75]
	ds_read_b128 v[248:251], v201
	ds_read_b128 v[252:255], v202
	s_add_i32 m0, s101, 0xc000
	v_lshl_add_u64 v[136:137], v[136:137], 0, s[98:99]
	global_load_lds_dwordx4 v[136:137], off
	s_waitcnt lgkmcnt(5)
	v_mfma_f32_16x16x32_bf16 v[116:119], v[188:191], v[164:167], v[116:119]
	v_mfma_f32_16x16x32_bf16 v[100:103], v[188:191], v[168:171], v[100:103]
	v_mfma_f32_16x16x32_bf16 v[84:87], v[188:191], v[172:175], v[84:87]
	v_mfma_f32_16x16x32_bf16 v[68:71], v[188:191], v[176:179], v[68:71]
	s_add_i32 m0, s101, 0x6000
	v_lshl_add_u64 v[142:143], v[142:143], 0, s[98:99]
	global_load_lds_dwordx4 v[142:143], off
	s_waitcnt lgkmcnt(4)
	v_mfma_f32_16x16x32_bf16 v[112:115], v[192:195], v[164:167], v[112:115]
	v_mfma_f32_16x16x32_bf16 v[96:99], v[192:195], v[168:171], v[96:99]
	v_mfma_f32_16x16x32_bf16 v[80:83], v[192:195], v[172:175], v[80:83]
	v_mfma_f32_16x16x32_bf16 v[64:67], v[192:195], v[176:179], v[64:67]
	s_add_i32 m0, s101, 0xe000
	v_lshl_add_u64 v[134:135], v[134:135], 0, s[98:99]
	global_load_lds_dwordx4 v[134:135], off
.Lg2_795:
	ds_read_b128 v[164:167], v163 offset:1024
	ds_read_b128 v[168:171], v196 offset:1024
	ds_read_b128 v[172:175], v197 offset:1024
	ds_read_b128 v[176:179], v198 offset:1024
	s_waitcnt lgkmcnt(4)
	v_mfma_f32_16x16x32_bf16 v[60:63], v[180:183], v[240:243], v[60:63]
	v_mfma_f32_16x16x32_bf16 v[44:47], v[180:183], v[244:247], v[44:47]
	v_mfma_f32_16x16x32_bf16 v[16:19], v[180:183], v[248:251], v[16:19]
	v_mfma_f32_16x16x32_bf16 v[36:39], v[180:183], v[252:255], v[36:39]
	ds_read_b128 v[180:183], v130 offset:33792
	v_mfma_f32_16x16x32_bf16 v[56:59], v[184:187], v[240:243], v[56:59]
	v_mfma_f32_16x16x32_bf16 v[40:43], v[184:187], v[244:247], v[40:43]
	v_mfma_f32_16x16x32_bf16 v[12:15], v[184:187], v[248:251], v[12:15]
	v_mfma_f32_16x16x32_bf16 v[28:31], v[184:187], v[252:255], v[28:31]
	ds_read_b128 v[184:187], v130 offset:35840
	v_mfma_f32_16x16x32_bf16 v[52:55], v[188:191], v[240:243], v[52:55]
	v_mfma_f32_16x16x32_bf16 v[32:35], v[188:191], v[244:247], v[32:35]
	v_mfma_f32_16x16x32_bf16 v[4:7], v[188:191], v[248:251], v[4:7]
	v_mfma_f32_16x16x32_bf16 v[20:23], v[188:191], v[252:255], v[20:23]
	ds_read_b128 v[188:191], v130 offset:37888
	v_mfma_f32_16x16x32_bf16 v[48:51], v[192:195], v[240:243], v[48:51]
	v_mfma_f32_16x16x32_bf16 v[24:27], v[192:195], v[244:247], v[24:27]
	v_mfma_f32_16x16x32_bf16 v[0:3], v[192:195], v[248:251], v[0:3]
	v_mfma_f32_16x16x32_bf16 v[8:11], v[192:195], v[252:255], v[8:11]
	ds_read_b128 v[192:195], v130 offset:39936
	s_waitcnt lgkmcnt(3)
	v_mfma_f32_16x16x32_bf16 v[124:127], v[180:183], v[164:167], v[124:127]
	v_mfma_f32_16x16x32_bf16 v[108:111], v[180:183], v[168:171], v[108:111]
	v_mfma_f32_16x16x32_bf16 v[92:95], v[180:183], v[172:175], v[92:95]
	v_mfma_f32_16x16x32_bf16 v[76:79], v[180:183], v[176:179], v[76:79]
	ds_read_b128 v[240:243], v199 offset:1024
	ds_read_b128 v[244:247], v200 offset:1024
	s_waitcnt lgkmcnt(4)
	v_mfma_f32_16x16x32_bf16 v[120:123], v[184:187], v[164:167], v[120:123]
	v_mfma_f32_16x16x32_bf16 v[104:107], v[184:187], v[168:171], v[104:107]
	v_mfma_f32_16x16x32_bf16 v[88:91], v[184:187], v[172:175], v[88:91]
	v_mfma_f32_16x16x32_bf16 v[72:75], v[184:187], v[176:179], v[72:75]
	ds_read_b128 v[248:251], v201 offset:1024
	ds_read_b128 v[252:255], v202 offset:1024
	s_waitcnt lgkmcnt(5)
	v_mfma_f32_16x16x32_bf16 v[116:119], v[188:191], v[164:167], v[116:119]
	v_mfma_f32_16x16x32_bf16 v[100:103], v[188:191], v[168:171], v[100:103]
	v_mfma_f32_16x16x32_bf16 v[84:87], v[188:191], v[172:175], v[84:87]
	v_mfma_f32_16x16x32_bf16 v[68:71], v[188:191], v[176:179], v[68:71]
	s_waitcnt lgkmcnt(4)
	v_mfma_f32_16x16x32_bf16 v[112:115], v[192:195], v[164:167], v[112:115]
	v_mfma_f32_16x16x32_bf16 v[96:99], v[192:195], v[168:171], v[96:99]
	v_mfma_f32_16x16x32_bf16 v[80:83], v[192:195], v[172:175], v[80:83]
	v_mfma_f32_16x16x32_bf16 v[64:67], v[192:195], v[176:179], v[64:67]
	s_waitcnt vmcnt(0) lgkmcnt(0)
	s_barrier
	s_add_i32 s101, s100, s0
	s_cmpk_eq_i32 s42, 0x700
	s_cbranch_scc1 .Lg4n_795
	v_mfma_f32_16x16x32_bf16 v[60:63], v[180:183], v[240:243], v[60:63]
	v_mfma_f32_16x16x32_bf16 v[44:47], v[180:183], v[244:247], v[44:47]
	v_mfma_f32_16x16x32_bf16 v[16:19], v[180:183], v[248:251], v[16:19]
	v_mfma_f32_16x16x32_bf16 v[36:39], v[180:183], v[252:255], v[36:39]
	v_add3_u32 v130, s53, v152, v153
	ds_read_b128 v[180:183], v130 offset:32768
	v_add3_u32 v163, s53, v152, v154
	v_add3_u32 v196, s53, v156, v155
	v_add3_u32 v197, s53, v156, v157
	v_add3_u32 v198, s53, v156, v158
	ds_read_b128 v[164:167], v163
	ds_read_b128 v[168:171], v196
	ds_read_b128 v[172:175], v197
	ds_read_b128 v[176:179], v198
	s_mov_b32 m0, s101
	v_lshl_add_u64 v[148:149], v[148:149], 0, s[98:99]
	global_load_lds_dwordx4 v[148:149], off
	v_mfma_f32_16x16x32_bf16 v[56:59], v[184:187], v[240:243], v[56:59]
	v_mfma_f32_16x16x32_bf16 v[40:43], v[184:187], v[244:247], v[40:43]
	v_mfma_f32_16x16x32_bf16 v[12:15], v[184:187], v[248:251], v[12:15]
	v_mfma_f32_16x16x32_bf16 v[28:31], v[184:187], v[252:255], v[28:31]
	ds_read_b128 v[184:187], v130 offset:34816
	v_add3_u32 v199, s53, v156, v159
	v_add3_u32 v200, s53, v156, v160
	v_add3_u32 v201, s53, v156, v161
	v_add3_u32 v202, s53, v156, v162
	s_add_i32 m0, s101, 0x8000
	v_lshl_add_u64 v[140:141], v[140:141], 0, s[98:99]
	global_load_lds_dwordx4 v[140:141], off
	v_mfma_f32_16x16x32_bf16 v[52:55], v[188:191], v[240:243], v[52:55]
	v_mfma_f32_16x16x32_bf16 v[32:35], v[188:191], v[244:247], v[32:35]
	v_mfma_f32_16x16x32_bf16 v[4:7], v[188:191], v[248:251], v[4:7]
	v_mfma_f32_16x16x32_bf16 v[20:23], v[188:191], v[252:255], v[20:23]
	ds_read_b128 v[188:191], v130 offset:36864
	s_add_i32 m0, s101, 0x2000
	v_lshl_add_u64 v[146:147], v[146:147], 0, s[98:99]
	global_load_lds_dwordx4 v[146:147], off
	v_mfma_f32_16x16x32_bf16 v[48:51], v[192:195], v[240:243], v[48:51]
	v_mfma_f32_16x16x32_bf16 v[24:27], v[192:195], v[244:247], v[24:27]
	v_mfma_f32_16x16x32_bf16 v[0:3], v[192:195], v[248:251], v[0:3]
	v_mfma_f32_16x16x32_bf16 v[8:11], v[192:195], v[252:255], v[8:11]
	ds_read_b128 v[192:195], v130 offset:38912
	s_add_i32 m0, s101, 0xa000
	v_lshl_add_u64 v[138:139], v[138:139], 0, s[98:99]
	global_load_lds_dwordx4 v[138:139], off
.Ltl_795:
	s_add_i32 s29, s29, 0x10000
	s_add_u32 s42, s42, 0x80
	s_addc_u32 s43, s43, 0
	s_cmpk_lg_i32 s42, 0x780
	s_cbranch_scc1 .LBB0_795
	s_branch .Lex_795
.Lg1n_795:
	s_waitcnt lgkmcnt(3)
	v_mfma_f32_16x16x32_bf16 v[124:127], v[180:183], v[164:167], v[124:127]
	v_mfma_f32_16x16x32_bf16 v[108:111], v[180:183], v[168:171], v[108:111]
	v_mfma_f32_16x16x32_bf16 v[92:95], v[180:183], v[172:175], v[92:95]
	v_mfma_f32_16x16x32_bf16 v[76:79], v[180:183], v[176:179], v[76:79]
	ds_read_b128 v[240:243], v199
	ds_read_b128 v[244:247], v200
	s_waitcnt lgkmcnt(4)
	v_mfma_f32_16x16x32_bf16 v[120:123], v[184:187], v[164:167], v[120:123]
	v_mfma_f32_16x16x32_bf16 v[104:107], v[184:187], v[168:171], v[104:107]
	v_mfma_f32_16x16x32_bf16 v[88:91], v[184:187], v[172:175], v[88:91]
	v_mfma_f32_16x16x32_bf16 v[72:75], v[184:187], v[176:179], v[72:75]
	ds_read_b128 v[248:251], v201
	ds_read_b128 v[252:255], v202
	s_waitcnt lgkmcnt(5)
	v_mfma_f32_16x16x32_bf16 v[116:119], v[188:191], v[164:167], v[116:119]
	v_mfma_f32_16x16x32_bf16 v[100:103], v[188:191], v[168:171], v[100:103]
	v_mfma_f32_16x16x32_bf16 v[84:87], v[188:191], v[172:175], v[84:87]
	v_mfma_f32_16x16x32_bf16 v[68:71], v[188:191], v[176:179], v[68:71]
	s_waitcnt lgkmcnt(4)
	v_mfma_f32_16x16x32_bf16 v[112:115], v[192:195], v[164:167], v[112:115]
	v_mfma_f32_16x16x32_bf16 v[96:99], v[192:195], v[168:171], v[96:99]
	v_mfma_f32_16x16x32_bf16 v[80:83], v[192:195], v[172:175], v[80:83]
	v_mfma_f32_16x16x32_bf16 v[64:67], v[192:195], v[176:179], v[64:67]
	s_branch .Lg2_795
.Lg4n_795:
	v_mfma_f32_16x16x32_bf16 v[60:63], v[180:183], v[240:243], v[60:63]
	v_mfma_f32_16x16x32_bf16 v[44:47], v[180:183], v[244:247], v[44:47]
	v_mfma_f32_16x16x32_bf16 v[16:19], v[180:183], v[248:251], v[16:19]
	v_mfma_f32_16x16x32_bf16 v[36:39], v[180:183], v[252:255], v[36:39]
	v_add3_u32 v130, s53, v152, v153
	ds_read_b128 v[180:183], v130 offset:32768
	v_add3_u32 v163, s53, v152, v154
	v_add3_u32 v196, s53, v156, v155
	v_add3_u32 v197, s53, v156, v157
	v_add3_u32 v198, s53, v156, v158
	ds_read_b128 v[164:167], v163
	ds_read_b128 v[168:171], v196
	ds_read_b128 v[172:175], v197
	ds_read_b128 v[176:179], v198
	v_mfma_f32_16x16x32_bf16 v[56:59], v[184:187], v[240:243], v[56:59]
	v_mfma_f32_16x16x32_bf16 v[40:43], v[184:187], v[244:247], v[40:43]
	v_mfma_f32_16x16x32_bf16 v[12:15], v[184:187], v[248:251], v[12:15]
	v_mfma_f32_16x16x32_bf16 v[28:31], v[184:187], v[252:255], v[28:31]
	ds_read_b128 v[184:187], v130 offset:34816
	v_add3_u32 v199, s53, v156, v159
	v_add3_u32 v200, s53, v156, v160
	v_add3_u32 v201, s53, v156, v161
	v_add3_u32 v202, s53, v156, v162
	v_mfma_f32_16x16x32_bf16 v[52:55], v[188:191], v[240:243], v[52:55]
	v_mfma_f32_16x16x32_bf16 v[32:35], v[188:191], v[244:247], v[32:35]
	v_mfma_f32_16x16x32_bf16 v[4:7], v[188:191], v[248:251], v[4:7]
	v_mfma_f32_16x16x32_bf16 v[20:23], v[188:191], v[252:255], v[20:23]
	ds_read_b128 v[188:191], v130 offset:36864
	v_mfma_f32_16x16x32_bf16 v[48:51], v[192:195], v[240:243], v[48:51]
	v_mfma_f32_16x16x32_bf16 v[24:27], v[192:195], v[244:247], v[24:27]
	v_mfma_f32_16x16x32_bf16 v[0:3], v[192:195], v[248:251], v[0:3]
	v_mfma_f32_16x16x32_bf16 v[8:11], v[192:195], v[252:255], v[8:11]
	ds_read_b128 v[192:195], v130 offset:38912
	s_branch .Ltl_795
.Lex_795:
	s_waitcnt lgkmcnt(0)
	v_add3_u32 v130, s46, v156, v162
	v_add3_u32 v151, s46, v156, v161
	v_add3_u32 v206, s46, v156, v160
	v_add3_u32 v198, s46, v156, v159
	v_add3_u32 v186, s46, v156, v158
	v_add3_u32 v187, s46, v156, v157
	v_add3_u32 v188, s46, v156, v155
	v_add3_u32 v189, s46, v152, v154
	v_add3_u32 v190, s47, v152, v153
	ds_read_b128 v[134:137], v130
	ds_read_b128 v[138:141], v151
	ds_read_b128 v[142:145], v206
	ds_read_b128 v[146:149], v198
	ds_read_b128 v[158:161], v186
	ds_read_b128 v[162:165], v187
	ds_read_b128 v[166:169], v188
	ds_read_b128 v[154:157], v189
	ds_read_b128 v[170:173], v190
	s_waitcnt lgkmcnt(0)
	v_mfma_f32_16x16x32_bf16 v[16:19], v[170:173], v[138:141], v[16:19]
	v_mfma_f32_16x16x32_bf16 v[174:177], v[170:173], v[134:137], v[36:39]
	s_nop 2
	ds_read_b128 v[36:39], v190 offset:2048
	s_waitcnt lgkmcnt(0)
	v_mfma_f32_16x16x32_bf16 v[12:15], v[36:39], v[138:141], v[12:15]
	v_mfma_f32_16x16x32_bf16 v[60:63], v[170:173], v[146:149], v[60:63]
	v_mfma_f32_16x16x32_bf16 v[28:31], v[36:39], v[134:137], v[28:31]
	v_mfma_f32_16x16x32_bf16 v[56:59], v[36:39], v[146:149], v[56:59]
	ds_read_b128 v[178:181], v190 offset:4096
	s_waitcnt lgkmcnt(0)
	v_mfma_f32_16x16x32_bf16 v[182:185], v[178:181], v[134:137], v[20:23]
	v_mfma_f32_16x16x32_bf16 v[52:55], v[178:181], v[146:149], v[52:55]
	s_nop 1
	ds_read_b128 v[20:23], v190 offset:6144
	s_waitcnt lgkmcnt(0)
	v_mfma_f32_16x16x32_bf16 v[134:137], v[20:23], v[134:137], v[8:11]
	v_mfma_f32_16x16x32_bf16 v[8:11], v[20:23], v[154:157], v[112:115]
	v_mfma_f32_16x16x32_bf16 v[112:115], v[20:23], v[158:161], v[64:67]
	v_mfma_f32_16x16x32_bf16 v[64:67], v[178:181], v[154:157], v[116:119]
	v_mfma_f32_16x16x32_bf16 v[116:119], v[178:181], v[158:161], v[68:71]
	v_mfma_f32_16x16x32_bf16 v[68:71], v[36:39], v[154:157], v[120:123]
	v_mfma_f32_16x16x32_bf16 v[120:123], v[36:39], v[158:161], v[72:75]
	v_mfma_f32_16x16x32_bf16 v[72:75], v[170:173], v[154:157], v[124:127]
	v_mfma_f32_16x16x32_bf16 v[124:127], v[170:173], v[158:161], v[76:79]
	v_mfma_f32_16x16x32_bf16 v[48:51], v[20:23], v[146:149], v[48:51]
	v_mfma_f32_16x16x32_bf16 v[146:149], v[170:173], v[142:145], v[44:47]
	v_mfma_f32_16x16x32_bf16 v[152:155], v[36:39], v[142:145], v[40:43]
	v_mfma_f32_16x16x32_bf16 v[156:159], v[178:181], v[142:145], v[32:35]
	v_mfma_f32_16x16x32_bf16 v[24:27], v[20:23], v[142:145], v[24:27]
	v_mfma_f32_16x16x32_bf16 v[142:145], v[178:181], v[138:141], v[4:7]
	v_mfma_f32_16x16x32_bf16 v[108:111], v[170:173], v[166:169], v[108:111]
	v_mfma_f32_16x16x32_bf16 v[92:95], v[170:173], v[162:165], v[92:95]
	v_mfma_f32_16x16x32_bf16 v[104:107], v[36:39], v[166:169], v[104:107]
	v_mfma_f32_16x16x32_bf16 v[88:91], v[36:39], v[162:165], v[88:91]
	v_mfma_f32_16x16x32_bf16 v[100:103], v[178:181], v[166:169], v[100:103]
	v_mfma_f32_16x16x32_bf16 v[84:87], v[178:181], v[162:165], v[84:87]
	v_mfma_f32_16x16x32_bf16 v[96:99], v[20:23], v[166:169], v[96:99]
	v_mfma_f32_16x16x32_bf16 v[80:83], v[20:23], v[162:165], v[80:83]
	v_mfma_f32_16x16x32_bf16 v[20:23], v[20:23], v[138:141], v[0:3]
	ds_read_b128 v[138:141], v190 offset:1024
	ds_read_b128 v[160:163], v190 offset:3072
	ds_read_b128 v[164:167], v190 offset:5120
	ds_read_b128 v[168:171], v190 offset:7168
	ds_read_b128 v[0:3], v189 offset:1024
	ds_read_b128 v[4:7], v188 offset:1024
	ds_read_b128 v[32:35], v187 offset:1024
	ds_read_b128 v[36:39], v186 offset:1024
	s_waitcnt lgkmcnt(3)
	v_mfma_f32_16x16x32_bf16 v[178:181], v[138:141], v[0:3], v[72:75]
	v_mfma_f32_16x16x32_bf16 v[186:189], v[160:163], v[0:3], v[68:71]
	v_mfma_f32_16x16x32_bf16 v[190:193], v[164:167], v[0:3], v[64:67]
	v_mfma_f32_16x16x32_bf16 v[194:197], v[168:171], v[0:3], v[8:11]
	ds_read_b128 v[0:3], v198 offset:1024
	s_waitcnt lgkmcnt(3)
	v_mfma_f32_16x16x32_bf16 v[108:111], v[138:141], v[4:7], v[108:111]
	v_mfma_f32_16x16x32_bf16 v[104:107], v[160:163], v[4:7], v[104:107]
	v_mfma_f32_16x16x32_bf16 v[198:201], v[164:167], v[4:7], v[100:103]
	v_mfma_f32_16x16x32_bf16 v[202:205], v[168:171], v[4:7], v[96:99]
	ds_read_b128 v[4:7], v206 offset:1024
	s_waitcnt lgkmcnt(3)
	v_mfma_f32_16x16x32_bf16 v[64:67], v[138:141], v[32:35], v[92:95]
	v_mfma_f32_16x16x32_bf16 v[68:71], v[160:163], v[32:35], v[88:91]
	v_mfma_f32_16x16x32_bf16 v[72:75], v[164:167], v[32:35], v[84:87]
	v_mfma_f32_16x16x32_bf16 v[76:79], v[168:171], v[32:35], v[80:83]
	ds_read_b128 v[96:99], v151 offset:1024
	s_waitcnt lgkmcnt(3)
	v_mfma_f32_16x16x32_bf16 v[80:83], v[138:141], v[36:39], v[124:127]
	v_mfma_f32_16x16x32_bf16 v[84:87], v[160:163], v[36:39], v[120:123]
	v_mfma_f32_16x16x32_bf16 v[88:91], v[164:167], v[36:39], v[116:119]
	v_mfma_f32_16x16x32_bf16 v[92:95], v[168:171], v[36:39], v[112:115]
	ds_read_b128 v[100:103], v130 offset:1024
	s_waitcnt lgkmcnt(3)
	v_mfma_f32_16x16x32_bf16 v[32:35], v[138:141], v[0:3], v[60:63]
	v_mfma_f32_16x16x32_bf16 v[36:39], v[160:163], v[0:3], v[56:59]
	v_mfma_f32_16x16x32_bf16 v[40:43], v[164:167], v[0:3], v[52:55]
	v_mfma_f32_16x16x32_bf16 v[44:47], v[168:171], v[0:3], v[48:51]
	s_waitcnt lgkmcnt(2)
	v_mfma_f32_16x16x32_bf16 v[48:51], v[138:141], v[4:7], v[146:149]
	v_mfma_f32_16x16x32_bf16 v[52:55], v[160:163], v[4:7], v[152:155]
	v_mfma_f32_16x16x32_bf16 v[56:59], v[164:167], v[4:7], v[156:159]
	v_mfma_f32_16x16x32_bf16 v[60:63], v[168:171], v[4:7], v[24:27]
	s_waitcnt lgkmcnt(1)
	v_mfma_f32_16x16x32_bf16 v[0:3], v[138:141], v[96:99], v[16:19]
	v_mfma_f32_16x16x32_bf16 v[4:7], v[160:163], v[96:99], v[12:15]
	v_mfma_f32_16x16x32_bf16 v[8:11], v[164:167], v[96:99], v[142:145]
	v_mfma_f32_16x16x32_bf16 v[12:15], v[168:171], v[96:99], v[20:23]
	s_waitcnt lgkmcnt(0)
	v_mfma_f32_16x16x32_bf16 v[16:19], v[138:141], v[100:103], v[174:177]
	v_mfma_f32_16x16x32_bf16 v[20:23], v[160:163], v[100:103], v[28:31]
	v_mfma_f32_16x16x32_bf16 v[24:27], v[164:167], v[100:103], v[182:185]
	v_mfma_f32_16x16x32_bf16 v[28:31], v[168:171], v[100:103], v[134:137]
	v_lshrrev_b32_e32 v96, 6, v150
	v_lshlrev_b32_e32 v98, 2, v150
	v_and_b32_e32 v97, 15, v150
	v_mul_lo_u32 v96, v96, s48
	v_and_b32_e32 v112, 60, v98
	v_bfe_u32 v99, v150, 4, 2
	v_add_u32_e32 v96, s46, v96
	v_and_b32_e32 v100, 48, v150
	v_lshlrev_b32_e32 v98, 2, v112
	v_mul_u32_u24_e32 v101, 0x110, v99
	v_mul_u32_u24_e32 v97, 0x110, v97
	v_add3_u32 v98, v96, v98, v101
	v_add3_u32 v101, v96, v100, v97
	s_waitcnt vmcnt(0)
	s_barrier
	ds_write_b128 v101, v[178:181]
	ds_write_b128 v101, v[186:189] offset:64
	ds_write_b128 v101, v[190:193] offset:128
	ds_write_b128 v101, v[194:197] offset:192
	ds_write_b128 v101, v[108:111] offset:4352
	ds_write_b128 v101, v[104:107] offset:4416
	ds_write_b128 v101, v[198:201] offset:4480
	ds_write_b128 v101, v[202:205] offset:4544
	ds_read_b128 v[102:105], v98
	v_ashrrev_i32_e32 v113, 1, v150
	v_and_b32_e32 v96, 0xffffff80, v113
	v_and_or_b32 v106, v150, s49, v112
	v_add_u32_e32 v100, s28, v96
	s_waitcnt lgkmcnt(0)
	v_mul_f32_e32 v102, 0xbfb8aa3b, v102
	v_mul_f32_e32 v103, 0xbfb8aa3b, v103
	v_mul_f32_e32 v104, 0xbfb8aa3b, v104
	v_mul_f32_e32 v105, 0xbfb8aa3b, v105
	v_exp_f32_e32 v102, v102
	v_exp_f32_e32 v103, v103
	v_exp_f32_e32 v104, v104
	v_exp_f32_e32 v105, v105
	v_add_f32_e32 v102, 1.0, v102
	v_add_f32_e32 v103, 1.0, v103
	v_add_f32_e32 v104, 1.0, v104
	v_add_f32_e32 v105, 1.0, v105
	v_rcp_f32_e32 v102, v102
	v_rcp_f32_e32 v103, v103
	v_rcp_f32_e32 v104, v104
	v_rcp_f32_e32 v105, v105
	v_lshl_add_u64 v[96:97], v[128:129], 0, s[38:39]
	v_lshlrev_b32_e32 v130, 1, v106
	v_cvt_pk_bf16_f32 v102, v102, v103
	v_cvt_pk_bf16_f32 v103, v104, v105
	v_or_b32_e32 v104, v100, v99
	v_lshl_add_u64 v[96:97], v[96:97], 0, v[130:131]
	v_ashrrev_i32_e32 v105, 31, v104
	v_lshl_add_u64 v[96:97], v[96:97], 0, s[26:27]
	v_lshlrev_b64 v[104:105], 11, v[104:105]
	v_lshl_add_u64 v[104:105], v[96:97], 0, v[104:105]
	flat_store_dwordx2 v[104:105], v[102:103]
	ds_read_b128 v[102:105], v98 offset:1088
	v_mov_b32_e32 v150, v132
	s_waitcnt lgkmcnt(0)
	v_mul_f32_e32 v102, 0xbfb8aa3b, v102
	v_exp_f32_e32 v102, v102
	v_mul_f32_e32 v103, 0xbfb8aa3b, v103
	v_exp_f32_e32 v103, v103
	v_add_f32_e32 v102, 1.0, v102
	v_rcp_f32_e32 v106, v102
	v_add_f32_e32 v102, 1.0, v103
	v_mul_f32_e32 v103, 0xbfb8aa3b, v104
	v_exp_f32_e32 v103, v103
	v_mul_f32_e32 v104, 0xbfb8aa3b, v105
	v_exp_f32_e32 v104, v104
	v_rcp_f32_e32 v105, v102
	v_add_f32_e32 v102, 1.0, v103
	v_rcp_f32_e32 v103, v102
	v_add_f32_e32 v102, 1.0, v104
	v_rcp_f32_e32 v107, v102
	v_or_b32_e32 v102, 4, v99
	v_cvt_pk_bf16_f32 v104, v106, v105
	v_or_b32_e32 v106, v100, v102
	v_cvt_pk_bf16_f32 v105, v103, v107
	v_ashrrev_i32_e32 v107, 31, v106
	v_lshlrev_b64 v[106:107], 11, v[106:107]
	v_lshl_add_u64 v[106:107], v[96:97], 0, v[106:107]
	flat_store_dwordx2 v[106:107], v[104:105]
	ds_read_b128 v[104:107], v98 offset:2176
	s_waitcnt lgkmcnt(0)
	v_mul_f32_e32 v103, 0xbfb8aa3b, v104
	v_exp_f32_e32 v103, v103
	v_mul_f32_e32 v104, 0xbfb8aa3b, v105
	v_exp_f32_e32 v104, v104
	v_add_f32_e32 v103, 1.0, v103
	v_rcp_f32_e32 v105, v103
	v_add_f32_e32 v103, 1.0, v104
	v_mul_f32_e32 v104, 0xbfb8aa3b, v106
	v_exp_f32_e32 v104, v104
	v_mul_f32_e32 v106, 0xbfb8aa3b, v107
	v_exp_f32_e32 v106, v106
	v_rcp_f32_e32 v107, v103
	v_add_f32_e32 v103, 1.0, v104
	v_rcp_f32_e32 v108, v103
	v_add_f32_e32 v103, 1.0, v106
	v_rcp_f32_e32 v106, v103
	v_or_b32_e32 v103, 8, v99
	v_cvt_pk_bf16_f32 v104, v105, v107
	v_cvt_pk_bf16_f32 v105, v108, v106
	v_or_b32_e32 v106, v100, v103
	v_ashrrev_i32_e32 v107, 31, v106
	v_lshlrev_b64 v[106:107], 11, v[106:107]
	v_lshl_add_u64 v[106:107], v[96:97], 0, v[106:107]
	flat_store_dwordx2 v[106:107], v[104:105]
	ds_read_b128 v[104:107], v98 offset:3264
	s_waitcnt lgkmcnt(0)
	v_mul_f32_e32 v104, 0xbfb8aa3b, v104
	v_exp_f32_e32 v104, v104
	v_mul_f32_e32 v105, 0xbfb8aa3b, v105
	v_exp_f32_e32 v105, v105
	v_add_f32_e32 v104, 1.0, v104
	v_rcp_f32_e32 v108, v104
	v_add_f32_e32 v104, 1.0, v105
	v_mul_f32_e32 v105, 0xbfb8aa3b, v106
	v_exp_f32_e32 v105, v105
	v_mul_f32_e32 v106, 0xbfb8aa3b, v107
	v_exp_f32_e32 v106, v106
	v_rcp_f32_e32 v107, v104
	v_add_f32_e32 v104, 1.0, v105
	v_rcp_f32_e32 v105, v104
	v_add_f32_e32 v104, 1.0, v106
	v_rcp_f32_e32 v109, v104
	v_or_b32_e32 v104, 12, v99
	v_cvt_pk_bf16_f32 v106, v108, v107
	v_or_b32_e32 v108, v100, v104
	v_cvt_pk_bf16_f32 v107, v105, v109
	v_ashrrev_i32_e32 v109, 31, v108
	v_lshlrev_b64 v[108:109], 11, v[108:109]
	v_lshl_add_u64 v[108:109], v[96:97], 0, v[108:109]
	flat_store_dwordx2 v[108:109], v[106:107]
	ds_read_b128 v[106:109], v98 offset:4352
	s_waitcnt lgkmcnt(0)
	v_mul_f32_e32 v105, 0xbfb8aa3b, v106
	v_exp_f32_e32 v105, v105
	v_mul_f32_e32 v106, 0xbfb8aa3b, v107
	v_exp_f32_e32 v106, v106
	v_add_f32_e32 v105, 1.0, v105
	v_rcp_f32_e32 v107, v105
	v_add_f32_e32 v105, 1.0, v106
	v_mul_f32_e32 v106, 0xbfb8aa3b, v108
	v_exp_f32_e32 v106, v106
	v_mul_f32_e32 v108, 0xbfb8aa3b, v109
	v_exp_f32_e32 v108, v108
	v_rcp_f32_e32 v109, v105
	v_add_f32_e32 v105, 1.0, v106
	v_rcp_f32_e32 v110, v105
	v_add_f32_e32 v105, 1.0, v108
	v_rcp_f32_e32 v108, v105
	v_or_b32_e32 v105, 16, v99
	v_cvt_pk_bf16_f32 v106, v107, v109
	v_cvt_pk_bf16_f32 v107, v110, v108
	v_or_b32_e32 v108, v100, v105
	v_ashrrev_i32_e32 v109, 31, v108
	v_lshlrev_b64 v[108:109], 11, v[108:109]
	v_lshl_add_u64 v[108:109], v[96:97], 0, v[108:109]
	flat_store_dwordx2 v[108:109], v[106:107]
	ds_read_b128 v[106:109], v98 offset:5440
	s_waitcnt lgkmcnt(0)
	v_mul_f32_e32 v106, 0xbfb8aa3b, v106
	v_exp_f32_e32 v106, v106
	v_mul_f32_e32 v107, 0xbfb8aa3b, v107
	v_exp_f32_e32 v107, v107
	v_add_f32_e32 v106, 1.0, v106
	v_rcp_f32_e32 v110, v106
	v_add_f32_e32 v106, 1.0, v107
	v_mul_f32_e32 v107, 0xbfb8aa3b, v108
	v_exp_f32_e32 v107, v107
	v_mul_f32_e32 v108, 0xbfb8aa3b, v109
	v_exp_f32_e32 v108, v108
	v_rcp_f32_e32 v109, v106
	v_add_f32_e32 v106, 1.0, v107
	v_rcp_f32_e32 v107, v106
	v_add_f32_e32 v106, 1.0, v108
	v_rcp_f32_e32 v111, v106
	v_or_b32_e32 v106, 20, v99
	v_cvt_pk_bf16_f32 v108, v110, v109
	v_or_b32_e32 v110, v100, v106
	v_cvt_pk_bf16_f32 v109, v107, v111
	v_ashrrev_i32_e32 v111, 31, v110
	v_lshlrev_b64 v[110:111], 11, v[110:111]
	v_lshl_add_u64 v[110:111], v[96:97], 0, v[110:111]
	flat_store_dwordx2 v[110:111], v[108:109]
	ds_read_b128 v[108:111], v98 offset:6528
	s_waitcnt lgkmcnt(0)
	v_mul_f32_e32 v107, 0xbfb8aa3b, v108
	v_exp_f32_e32 v107, v107
	v_mul_f32_e32 v108, 0xbfb8aa3b, v109
	v_exp_f32_e32 v108, v108
	v_add_f32_e32 v107, 1.0, v107
	v_rcp_f32_e32 v109, v107
	v_add_f32_e32 v107, 1.0, v108
	v_mul_f32_e32 v108, 0xbfb8aa3b, v110
	v_exp_f32_e32 v108, v108
	v_mul_f32_e32 v110, 0xbfb8aa3b, v111
	v_exp_f32_e32 v110, v110
	v_rcp_f32_e32 v111, v107
	v_add_f32_e32 v107, 1.0, v108
	v_rcp_f32_e32 v112, v107
	v_add_f32_e32 v107, 1.0, v110
	v_rcp_f32_e32 v110, v107
	v_or_b32_e32 v107, 24, v99
	v_cvt_pk_bf16_f32 v108, v109, v111
	v_cvt_pk_bf16_f32 v109, v112, v110
	v_or_b32_e32 v110, v100, v107
	v_ashrrev_i32_e32 v111, 31, v110
	v_lshlrev_b64 v[110:111], 11, v[110:111]
	v_lshl_add_u64 v[110:111], v[96:97], 0, v[110:111]
	flat_store_dwordx2 v[110:111], v[108:109]
	ds_read_b128 v[108:111], v98 offset:7616
	s_waitcnt lgkmcnt(0)
	v_mul_f32_e32 v108, 0xbfb8aa3b, v108
	v_exp_f32_e32 v108, v108
	v_mul_f32_e32 v109, 0xbfb8aa3b, v109
	v_exp_f32_e32 v109, v109
	v_add_f32_e32 v108, 1.0, v108
	v_rcp_f32_e32 v112, v108
	v_add_f32_e32 v108, 1.0, v109
	v_mul_f32_e32 v109, 0xbfb8aa3b, v110
	v_exp_f32_e32 v109, v109
	v_mul_f32_e32 v110, 0xbfb8aa3b, v111
	v_exp_f32_e32 v110, v110
	v_rcp_f32_e32 v111, v108
	v_add_f32_e32 v108, 1.0, v109
	v_rcp_f32_e32 v109, v108
	v_add_f32_e32 v108, 1.0, v110
	v_rcp_f32_e32 v113, v108
	v_or_b32_e32 v108, 28, v99
	v_cvt_pk_bf16_f32 v110, v112, v111
	v_or_b32_e32 v112, v100, v108
	v_cvt_pk_bf16_f32 v111, v109, v113
	v_ashrrev_i32_e32 v113, 31, v112
	v_lshlrev_b64 v[112:113], 11, v[112:113]
	v_lshl_add_u64 v[112:113], v[96:97], 0, v[112:113]
	flat_store_dwordx2 v[112:113], v[110:111]
	ds_write_b128 v101, v[64:67]
	ds_write_b128 v101, v[68:71] offset:64
	ds_write_b128 v101, v[72:75] offset:128
	ds_write_b128 v101, v[76:79] offset:192
	ds_write_b128 v101, v[80:83] offset:4352
	ds_write_b128 v101, v[84:87] offset:4416
	ds_write_b128 v101, v[88:91] offset:4480
	ds_write_b128 v101, v[92:95] offset:4544
	ds_read_b128 v[64:67], v98
	v_or_b32_e32 v68, 32, v100
	s_waitcnt lgkmcnt(0)
	v_mul_f32_e32 v64, 0xbfb8aa3b, v64
	v_mul_f32_e32 v65, 0xbfb8aa3b, v65
	v_mul_f32_e32 v66, 0xbfb8aa3b, v66
	v_mul_f32_e32 v67, 0xbfb8aa3b, v67
	v_exp_f32_e32 v64, v64
	v_exp_f32_e32 v65, v65
	v_exp_f32_e32 v66, v66
	v_exp_f32_e32 v67, v67
	v_add_f32_e32 v64, 1.0, v64
	v_add_f32_e32 v65, 1.0, v65
	v_add_f32_e32 v66, 1.0, v66
	v_add_f32_e32 v67, 1.0, v67
	v_rcp_f32_e32 v64, v64
	v_rcp_f32_e32 v65, v65
	v_rcp_f32_e32 v66, v66
	v_rcp_f32_e32 v67, v67
	v_cvt_pk_bf16_f32 v64, v64, v65
	v_cvt_pk_bf16_f32 v65, v66, v67
	v_or_b32_e32 v66, v68, v99
	v_ashrrev_i32_e32 v67, 31, v66
	v_lshlrev_b64 v[66:67], 11, v[66:67]
	v_lshl_add_u64 v[66:67], v[96:97], 0, v[66:67]
	flat_store_dwordx2 v[66:67], v[64:65]
	ds_read_b128 v[64:67], v98 offset:1088
	s_waitcnt lgkmcnt(0)
	v_mul_f32_e32 v64, 0xbfb8aa3b, v64
	v_mul_f32_e32 v65, 0xbfb8aa3b, v65
	v_mul_f32_e32 v66, 0xbfb8aa3b, v66
	v_mul_f32_e32 v67, 0xbfb8aa3b, v67
	v_exp_f32_e32 v64, v64
	v_exp_f32_e32 v65, v65
	v_exp_f32_e32 v66, v66
	v_exp_f32_e32 v67, v67
	v_add_f32_e32 v64, 1.0, v64
	v_add_f32_e32 v65, 1.0, v65
	v_add_f32_e32 v66, 1.0, v66
	v_add_f32_e32 v67, 1.0, v67
	v_rcp_f32_e32 v64, v64
	v_rcp_f32_e32 v65, v65
	v_rcp_f32_e32 v66, v66
	v_rcp_f32_e32 v67, v67
	v_cvt_pk_bf16_f32 v64, v64, v65
	v_cvt_pk_bf16_f32 v65, v66, v67
	v_or_b32_e32 v66, v68, v102
	v_ashrrev_i32_e32 v67, 31, v66
	v_lshlrev_b64 v[66:67], 11, v[66:67]
	v_lshl_add_u64 v[66:67], v[96:97], 0, v[66:67]
	flat_store_dwordx2 v[66:67], v[64:65]
	ds_read_b128 v[64:67], v98 offset:2176
	s_waitcnt lgkmcnt(0)
	v_mul_f32_e32 v64, 0xbfb8aa3b, v64
	v_mul_f32_e32 v65, 0xbfb8aa3b, v65
	v_mul_f32_e32 v66, 0xbfb8aa3b, v66
	v_mul_f32_e32 v67, 0xbfb8aa3b, v67
	v_exp_f32_e32 v64, v64
	v_exp_f32_e32 v65, v65
	v_exp_f32_e32 v66, v66
	v_exp_f32_e32 v67, v67
	v_add_f32_e32 v64, 1.0, v64
	v_add_f32_e32 v65, 1.0, v65
	v_add_f32_e32 v66, 1.0, v66
	v_add_f32_e32 v67, 1.0, v67
	v_rcp_f32_e32 v64, v64
	v_rcp_f32_e32 v65, v65
	v_rcp_f32_e32 v66, v66
	v_rcp_f32_e32 v67, v67
	v_cvt_pk_bf16_f32 v64, v64, v65
	v_cvt_pk_bf16_f32 v65, v66, v67
	v_or_b32_e32 v66, v68, v103
	v_ashrrev_i32_e32 v67, 31, v66
	v_lshlrev_b64 v[66:67], 11, v[66:67]
	v_lshl_add_u64 v[66:67], v[96:97], 0, v[66:67]
	flat_store_dwordx2 v[66:67], v[64:65]
	ds_read_b128 v[64:67], v98 offset:3264
	s_waitcnt lgkmcnt(0)
	v_mul_f32_e32 v64, 0xbfb8aa3b, v64
	v_mul_f32_e32 v65, 0xbfb8aa3b, v65
	v_mul_f32_e32 v66, 0xbfb8aa3b, v66
	v_mul_f32_e32 v67, 0xbfb8aa3b, v67
	v_exp_f32_e32 v64, v64
	v_exp_f32_e32 v65, v65
	v_exp_f32_e32 v66, v66
	v_exp_f32_e32 v67, v67
	v_add_f32_e32 v64, 1.0, v64
	v_add_f32_e32 v65, 1.0, v65
	v_add_f32_e32 v66, 1.0, v66
	v_add_f32_e32 v67, 1.0, v67
	v_rcp_f32_e32 v64, v64
	v_rcp_f32_e32 v65, v65
	v_rcp_f32_e32 v66, v66
	v_rcp_f32_e32 v67, v67
	v_cvt_pk_bf16_f32 v64, v64, v65
	v_cvt_pk_bf16_f32 v65, v66, v67
	v_or_b32_e32 v66, v68, v104
	v_ashrrev_i32_e32 v67, 31, v66
	v_lshlrev_b64 v[66:67], 11, v[66:67]
	v_lshl_add_u64 v[66:67], v[96:97], 0, v[66:67]
	flat_store_dwordx2 v[66:67], v[64:65]
	ds_read_b128 v[64:67], v98 offset:4352
	s_waitcnt lgkmcnt(0)
	v_mul_f32_e32 v64, 0xbfb8aa3b, v64
	v_mul_f32_e32 v65, 0xbfb8aa3b, v65
	v_mul_f32_e32 v66, 0xbfb8aa3b, v66
	v_mul_f32_e32 v67, 0xbfb8aa3b, v67
	v_exp_f32_e32 v64, v64
	v_exp_f32_e32 v65, v65
	v_exp_f32_e32 v66, v66
	v_exp_f32_e32 v67, v67
	v_add_f32_e32 v64, 1.0, v64
	v_add_f32_e32 v65, 1.0, v65
	v_add_f32_e32 v66, 1.0, v66
	v_add_f32_e32 v67, 1.0, v67
	v_rcp_f32_e32 v64, v64
	v_rcp_f32_e32 v65, v65
	v_rcp_f32_e32 v66, v66
	v_rcp_f32_e32 v67, v67
	v_cvt_pk_bf16_f32 v64, v64, v65
	v_cvt_pk_bf16_f32 v65, v66, v67
	v_or_b32_e32 v66, v68, v105
	v_ashrrev_i32_e32 v67, 31, v66
	v_lshlrev_b64 v[66:67], 11, v[66:67]
	v_lshl_add_u64 v[66:67], v[96:97], 0, v[66:67]
	flat_store_dwordx2 v[66:67], v[64:65]
	ds_read_b128 v[64:67], v98 offset:5440
	s_waitcnt lgkmcnt(0)
	v_mul_f32_e32 v64, 0xbfb8aa3b, v64
	v_mul_f32_e32 v65, 0xbfb8aa3b, v65
	v_mul_f32_e32 v66, 0xbfb8aa3b, v66
	v_mul_f32_e32 v67, 0xbfb8aa3b, v67
	v_exp_f32_e32 v64, v64
	v_exp_f32_e32 v65, v65
	v_exp_f32_e32 v66, v66
	v_exp_f32_e32 v67, v67
	v_add_f32_e32 v64, 1.0, v64
	v_add_f32_e32 v65, 1.0, v65
	v_add_f32_e32 v66, 1.0, v66
	v_add_f32_e32 v67, 1.0, v67
	v_rcp_f32_e32 v64, v64
	v_rcp_f32_e32 v65, v65
	v_rcp_f32_e32 v66, v66
	v_rcp_f32_e32 v67, v67
	v_cvt_pk_bf16_f32 v64, v64, v65
	v_cvt_pk_bf16_f32 v65, v66, v67
	v_or_b32_e32 v66, v68, v106
	v_ashrrev_i32_e32 v67, 31, v66
	v_lshlrev_b64 v[66:67], 11, v[66:67]
	v_lshl_add_u64 v[66:67], v[96:97], 0, v[66:67]
	flat_store_dwordx2 v[66:67], v[64:65]
	ds_read_b128 v[64:67], v98 offset:6528
	s_waitcnt lgkmcnt(0)
	v_mul_f32_e32 v64, 0xbfb8aa3b, v64
	v_mul_f32_e32 v65, 0xbfb8aa3b, v65
	v_mul_f32_e32 v66, 0xbfb8aa3b, v66
	v_mul_f32_e32 v67, 0xbfb8aa3b, v67
	v_exp_f32_e32 v64, v64
	v_exp_f32_e32 v65, v65
	v_exp_f32_e32 v66, v66
	v_exp_f32_e32 v67, v67
	v_add_f32_e32 v64, 1.0, v64
	v_add_f32_e32 v65, 1.0, v65
	v_add_f32_e32 v66, 1.0, v66
	v_add_f32_e32 v67, 1.0, v67
	v_rcp_f32_e32 v64, v64
	v_rcp_f32_e32 v65, v65
	v_rcp_f32_e32 v66, v66
	v_rcp_f32_e32 v67, v67
	v_cvt_pk_bf16_f32 v64, v64, v65
	v_cvt_pk_bf16_f32 v65, v66, v67
	v_or_b32_e32 v66, v68, v107
	v_ashrrev_i32_e32 v67, 31, v66
	v_lshlrev_b64 v[66:67], 11, v[66:67]
	v_lshl_add_u64 v[66:67], v[96:97], 0, v[66:67]
	flat_store_dwordx2 v[66:67], v[64:65]
	ds_read_b128 v[64:67], v98 offset:7616
	s_waitcnt lgkmcnt(0)
	v_mul_f32_e32 v64, 0xbfb8aa3b, v64
	v_mul_f32_e32 v65, 0xbfb8aa3b, v65
	v_mul_f32_e32 v66, 0xbfb8aa3b, v66
	v_mul_f32_e32 v67, 0xbfb8aa3b, v67
	v_exp_f32_e32 v64, v64
	v_exp_f32_e32 v65, v65
	v_exp_f32_e32 v66, v66
	v_exp_f32_e32 v67, v67
	v_add_f32_e32 v64, 1.0, v64
	v_add_f32_e32 v65, 1.0, v65
	v_add_f32_e32 v66, 1.0, v66
	v_add_f32_e32 v67, 1.0, v67
	v_rcp_f32_e32 v64, v64
	v_rcp_f32_e32 v65, v65
	v_rcp_f32_e32 v66, v66
	v_rcp_f32_e32 v67, v67
	v_cvt_pk_bf16_f32 v64, v64, v65
	v_cvt_pk_bf16_f32 v65, v66, v67
	v_or_b32_e32 v66, v68, v108
	v_ashrrev_i32_e32 v67, 31, v66
	v_lshlrev_b64 v[66:67], 11, v[66:67]
	v_lshl_add_u64 v[66:67], v[96:97], 0, v[66:67]
	flat_store_dwordx2 v[66:67], v[64:65]
	ds_write_b128 v101, v[32:35]
	ds_write_b128 v101, v[36:39] offset:64
	ds_write_b128 v101, v[40:43] offset:128
	ds_write_b128 v101, v[44:47] offset:192
	ds_write_b128 v101, v[48:51] offset:4352
	ds_write_b128 v101, v[52:55] offset:4416
	ds_write_b128 v101, v[56:59] offset:4480
	ds_write_b128 v101, v[60:63] offset:4544
	ds_read_b128 v[32:35], v98
	v_or_b32_e32 v36, 64, v100
	s_waitcnt lgkmcnt(0)
	v_mul_f32_e32 v32, 0xbfb8aa3b, v32
	v_mul_f32_e32 v33, 0xbfb8aa3b, v33
	v_mul_f32_e32 v34, 0xbfb8aa3b, v34
	v_mul_f32_e32 v35, 0xbfb8aa3b, v35
	v_exp_f32_e32 v32, v32
	v_exp_f32_e32 v33, v33
	v_exp_f32_e32 v34, v34
	v_exp_f32_e32 v35, v35
	v_add_f32_e32 v32, 1.0, v32
	v_add_f32_e32 v33, 1.0, v33
	v_add_f32_e32 v34, 1.0, v34
	v_add_f32_e32 v35, 1.0, v35
	v_rcp_f32_e32 v32, v32
	v_rcp_f32_e32 v33, v33
	v_rcp_f32_e32 v34, v34
	v_rcp_f32_e32 v35, v35
	v_cvt_pk_bf16_f32 v32, v32, v33
	v_cvt_pk_bf16_f32 v33, v34, v35
	v_or_b32_e32 v34, v36, v99
	v_ashrrev_i32_e32 v35, 31, v34
	v_lshlrev_b64 v[34:35], 11, v[34:35]
	v_lshl_add_u64 v[34:35], v[96:97], 0, v[34:35]
	flat_store_dwordx2 v[34:35], v[32:33]
	ds_read_b128 v[32:35], v98 offset:1088
	s_waitcnt lgkmcnt(0)
	v_mul_f32_e32 v32, 0xbfb8aa3b, v32
	v_mul_f32_e32 v33, 0xbfb8aa3b, v33
	v_mul_f32_e32 v34, 0xbfb8aa3b, v34
	v_mul_f32_e32 v35, 0xbfb8aa3b, v35
	v_exp_f32_e32 v32, v32
	v_exp_f32_e32 v33, v33
	v_exp_f32_e32 v34, v34
	v_exp_f32_e32 v35, v35
	v_add_f32_e32 v32, 1.0, v32
	v_add_f32_e32 v33, 1.0, v33
	v_add_f32_e32 v34, 1.0, v34
	v_add_f32_e32 v35, 1.0, v35
	v_rcp_f32_e32 v32, v32
	v_rcp_f32_e32 v33, v33
	v_rcp_f32_e32 v34, v34
	v_rcp_f32_e32 v35, v35
	v_cvt_pk_bf16_f32 v32, v32, v33
	v_cvt_pk_bf16_f32 v33, v34, v35
	v_or_b32_e32 v34, v36, v102
	v_ashrrev_i32_e32 v35, 31, v34
	v_lshlrev_b64 v[34:35], 11, v[34:35]
	v_lshl_add_u64 v[34:35], v[96:97], 0, v[34:35]
	flat_store_dwordx2 v[34:35], v[32:33]
	ds_read_b128 v[32:35], v98 offset:2176
	s_waitcnt lgkmcnt(0)
	v_mul_f32_e32 v32, 0xbfb8aa3b, v32
	v_mul_f32_e32 v33, 0xbfb8aa3b, v33
	v_mul_f32_e32 v34, 0xbfb8aa3b, v34
	v_mul_f32_e32 v35, 0xbfb8aa3b, v35
	v_exp_f32_e32 v32, v32
	v_exp_f32_e32 v33, v33
	v_exp_f32_e32 v34, v34
	v_exp_f32_e32 v35, v35
	v_add_f32_e32 v32, 1.0, v32
	v_add_f32_e32 v33, 1.0, v33
	v_add_f32_e32 v34, 1.0, v34
	v_add_f32_e32 v35, 1.0, v35
	v_rcp_f32_e32 v32, v32
	v_rcp_f32_e32 v33, v33
	v_rcp_f32_e32 v34, v34
	v_rcp_f32_e32 v35, v35
	v_cvt_pk_bf16_f32 v32, v32, v33
	v_cvt_pk_bf16_f32 v33, v34, v35
	v_or_b32_e32 v34, v36, v103
	v_ashrrev_i32_e32 v35, 31, v34
	v_lshlrev_b64 v[34:35], 11, v[34:35]
	v_lshl_add_u64 v[34:35], v[96:97], 0, v[34:35]
	flat_store_dwordx2 v[34:35], v[32:33]
	ds_read_b128 v[32:35], v98 offset:3264
	s_waitcnt lgkmcnt(0)
	v_mul_f32_e32 v32, 0xbfb8aa3b, v32
	v_mul_f32_e32 v33, 0xbfb8aa3b, v33
	v_mul_f32_e32 v34, 0xbfb8aa3b, v34
	v_mul_f32_e32 v35, 0xbfb8aa3b, v35
	v_exp_f32_e32 v32, v32
	v_exp_f32_e32 v33, v33
	v_exp_f32_e32 v34, v34
	v_exp_f32_e32 v35, v35
	v_add_f32_e32 v32, 1.0, v32
	v_add_f32_e32 v33, 1.0, v33
	v_add_f32_e32 v34, 1.0, v34
	v_add_f32_e32 v35, 1.0, v35
	v_rcp_f32_e32 v32, v32
	v_rcp_f32_e32 v33, v33
	v_rcp_f32_e32 v34, v34
	v_rcp_f32_e32 v35, v35
	v_cvt_pk_bf16_f32 v32, v32, v33
	v_cvt_pk_bf16_f32 v33, v34, v35
	v_or_b32_e32 v34, v36, v104
	v_ashrrev_i32_e32 v35, 31, v34
	v_lshlrev_b64 v[34:35], 11, v[34:35]
	v_lshl_add_u64 v[34:35], v[96:97], 0, v[34:35]
	flat_store_dwordx2 v[34:35], v[32:33]
	ds_read_b128 v[32:35], v98 offset:4352
	s_waitcnt lgkmcnt(0)
	v_mul_f32_e32 v32, 0xbfb8aa3b, v32
	v_mul_f32_e32 v33, 0xbfb8aa3b, v33
	v_mul_f32_e32 v34, 0xbfb8aa3b, v34
	v_mul_f32_e32 v35, 0xbfb8aa3b, v35
	v_exp_f32_e32 v32, v32
	v_exp_f32_e32 v33, v33
	v_exp_f32_e32 v34, v34
	v_exp_f32_e32 v35, v35
	v_add_f32_e32 v32, 1.0, v32
	v_add_f32_e32 v33, 1.0, v33
	v_add_f32_e32 v34, 1.0, v34
	v_add_f32_e32 v35, 1.0, v35
	v_rcp_f32_e32 v32, v32
	v_rcp_f32_e32 v33, v33
	v_rcp_f32_e32 v34, v34
	v_rcp_f32_e32 v35, v35
	v_cvt_pk_bf16_f32 v32, v32, v33
	v_cvt_pk_bf16_f32 v33, v34, v35
	v_or_b32_e32 v34, v36, v105
	v_ashrrev_i32_e32 v35, 31, v34
	v_lshlrev_b64 v[34:35], 11, v[34:35]
	v_lshl_add_u64 v[34:35], v[96:97], 0, v[34:35]
	flat_store_dwordx2 v[34:35], v[32:33]
	ds_read_b128 v[32:35], v98 offset:5440
	s_waitcnt lgkmcnt(0)
	v_mul_f32_e32 v32, 0xbfb8aa3b, v32
	v_mul_f32_e32 v33, 0xbfb8aa3b, v33
	v_mul_f32_e32 v34, 0xbfb8aa3b, v34
	v_mul_f32_e32 v35, 0xbfb8aa3b, v35
	v_exp_f32_e32 v32, v32
	v_exp_f32_e32 v33, v33
	v_exp_f32_e32 v34, v34
	v_exp_f32_e32 v35, v35
	v_add_f32_e32 v32, 1.0, v32
	v_add_f32_e32 v33, 1.0, v33
	v_add_f32_e32 v34, 1.0, v34
	v_add_f32_e32 v35, 1.0, v35
	v_rcp_f32_e32 v32, v32
	v_rcp_f32_e32 v33, v33
	v_rcp_f32_e32 v34, v34
	v_rcp_f32_e32 v35, v35
	v_cvt_pk_bf16_f32 v32, v32, v33
	v_cvt_pk_bf16_f32 v33, v34, v35
	v_or_b32_e32 v34, v36, v106
	v_ashrrev_i32_e32 v35, 31, v34
	v_lshlrev_b64 v[34:35], 11, v[34:35]
	v_lshl_add_u64 v[34:35], v[96:97], 0, v[34:35]
	flat_store_dwordx2 v[34:35], v[32:33]
	ds_read_b128 v[32:35], v98 offset:6528
	s_waitcnt lgkmcnt(0)
	v_mul_f32_e32 v32, 0xbfb8aa3b, v32
	v_mul_f32_e32 v33, 0xbfb8aa3b, v33
	v_mul_f32_e32 v34, 0xbfb8aa3b, v34
	v_mul_f32_e32 v35, 0xbfb8aa3b, v35
	v_exp_f32_e32 v32, v32
	v_exp_f32_e32 v33, v33
	v_exp_f32_e32 v34, v34
	v_exp_f32_e32 v35, v35
	v_add_f32_e32 v32, 1.0, v32
	v_add_f32_e32 v33, 1.0, v33
	v_add_f32_e32 v34, 1.0, v34
	v_add_f32_e32 v35, 1.0, v35
	v_rcp_f32_e32 v32, v32
	v_rcp_f32_e32 v33, v33
	v_rcp_f32_e32 v34, v34
	v_rcp_f32_e32 v35, v35
	v_cvt_pk_bf16_f32 v32, v32, v33
	v_cvt_pk_bf16_f32 v33, v34, v35
	v_or_b32_e32 v34, v36, v107
	v_ashrrev_i32_e32 v35, 31, v34
	v_lshlrev_b64 v[34:35], 11, v[34:35]
	v_lshl_add_u64 v[34:35], v[96:97], 0, v[34:35]
	flat_store_dwordx2 v[34:35], v[32:33]
	ds_read_b128 v[32:35], v98 offset:7616
	s_waitcnt lgkmcnt(0)
	v_mul_f32_e32 v32, 0xbfb8aa3b, v32
	v_mul_f32_e32 v33, 0xbfb8aa3b, v33
	v_mul_f32_e32 v34, 0xbfb8aa3b, v34
	v_mul_f32_e32 v35, 0xbfb8aa3b, v35
	v_exp_f32_e32 v32, v32
	v_exp_f32_e32 v33, v33
	v_exp_f32_e32 v34, v34
	v_exp_f32_e32 v35, v35
	v_add_f32_e32 v32, 1.0, v32
	v_add_f32_e32 v33, 1.0, v33
	v_add_f32_e32 v34, 1.0, v34
	v_add_f32_e32 v35, 1.0, v35
	v_rcp_f32_e32 v32, v32
	v_rcp_f32_e32 v33, v33
	v_rcp_f32_e32 v34, v34
	v_rcp_f32_e32 v35, v35
	v_cvt_pk_bf16_f32 v32, v32, v33
	v_cvt_pk_bf16_f32 v33, v34, v35
	v_or_b32_e32 v34, v36, v108
	v_ashrrev_i32_e32 v35, 31, v34
	v_lshlrev_b64 v[34:35], 11, v[34:35]
	v_lshl_add_u64 v[34:35], v[96:97], 0, v[34:35]
	flat_store_dwordx2 v[34:35], v[32:33]
	ds_write_b128 v101, v[0:3]
	ds_write_b128 v101, v[4:7] offset:64
	ds_write_b128 v101, v[8:11] offset:128
	ds_write_b128 v101, v[12:15] offset:192
	ds_write_b128 v101, v[16:19] offset:4352
	ds_write_b128 v101, v[20:23] offset:4416
	ds_write_b128 v101, v[24:27] offset:4480
	ds_write_b128 v101, v[28:31] offset:4544
	ds_read_b128 v[0:3], v98
	v_or_b32_e32 v4, 0x60, v100
	v_mov_b32_e32 v12, v132
	s_waitcnt lgkmcnt(0)
	v_mul_f32_e32 v0, 0xbfb8aa3b, v0
	v_mul_f32_e32 v1, 0xbfb8aa3b, v1
	v_mul_f32_e32 v2, 0xbfb8aa3b, v2
	v_mul_f32_e32 v3, 0xbfb8aa3b, v3
	v_exp_f32_e32 v0, v0
	v_exp_f32_e32 v1, v1
	v_exp_f32_e32 v2, v2
	v_exp_f32_e32 v3, v3
	v_add_f32_e32 v0, 1.0, v0
	v_add_f32_e32 v1, 1.0, v1
	v_add_f32_e32 v2, 1.0, v2
	v_add_f32_e32 v3, 1.0, v3
	v_rcp_f32_e32 v0, v0
	v_rcp_f32_e32 v1, v1
	v_rcp_f32_e32 v2, v2
	v_rcp_f32_e32 v3, v3
	v_cvt_pk_bf16_f32 v0, v0, v1
	v_cvt_pk_bf16_f32 v1, v2, v3
	v_or_b32_e32 v2, v4, v99
	v_ashrrev_i32_e32 v3, 31, v2
	v_lshlrev_b64 v[2:3], 11, v[2:3]
	v_lshl_add_u64 v[2:3], v[96:97], 0, v[2:3]
	flat_store_dwordx2 v[2:3], v[0:1]
	ds_read_b128 v[0:3], v98 offset:1088
	s_waitcnt lgkmcnt(0)
	v_mul_f32_e32 v0, 0xbfb8aa3b, v0
	v_mul_f32_e32 v1, 0xbfb8aa3b, v1
	v_mul_f32_e32 v2, 0xbfb8aa3b, v2
	v_mul_f32_e32 v3, 0xbfb8aa3b, v3
	v_exp_f32_e32 v0, v0
	v_exp_f32_e32 v1, v1
	v_exp_f32_e32 v2, v2
	v_exp_f32_e32 v3, v3
	v_add_f32_e32 v0, 1.0, v0
	v_add_f32_e32 v1, 1.0, v1
	v_add_f32_e32 v2, 1.0, v2
	v_add_f32_e32 v3, 1.0, v3
	v_rcp_f32_e32 v0, v0
	v_rcp_f32_e32 v1, v1
	v_rcp_f32_e32 v2, v2
	v_rcp_f32_e32 v3, v3
	v_cvt_pk_bf16_f32 v0, v0, v1
	v_cvt_pk_bf16_f32 v1, v2, v3
	v_or_b32_e32 v2, v4, v102
	v_ashrrev_i32_e32 v3, 31, v2
	v_lshlrev_b64 v[2:3], 11, v[2:3]
	v_lshl_add_u64 v[2:3], v[96:97], 0, v[2:3]
	flat_store_dwordx2 v[2:3], v[0:1]
	ds_read_b128 v[0:3], v98 offset:2176
	s_waitcnt lgkmcnt(0)
	v_mul_f32_e32 v0, 0xbfb8aa3b, v0
	v_mul_f32_e32 v1, 0xbfb8aa3b, v1
	v_mul_f32_e32 v2, 0xbfb8aa3b, v2
	v_mul_f32_e32 v3, 0xbfb8aa3b, v3
	v_exp_f32_e32 v0, v0
	v_exp_f32_e32 v1, v1
	v_exp_f32_e32 v2, v2
	v_exp_f32_e32 v3, v3
	v_add_f32_e32 v0, 1.0, v0
	v_add_f32_e32 v1, 1.0, v1
	v_add_f32_e32 v2, 1.0, v2
	v_add_f32_e32 v3, 1.0, v3
	v_rcp_f32_e32 v0, v0
	v_rcp_f32_e32 v1, v1
	v_rcp_f32_e32 v2, v2
	v_rcp_f32_e32 v3, v3
	v_cvt_pk_bf16_f32 v0, v0, v1
	v_cvt_pk_bf16_f32 v1, v2, v3
	v_or_b32_e32 v2, v4, v103
	v_ashrrev_i32_e32 v3, 31, v2
	v_lshlrev_b64 v[2:3], 11, v[2:3]
	v_lshl_add_u64 v[2:3], v[96:97], 0, v[2:3]
	flat_store_dwordx2 v[2:3], v[0:1]
	ds_read_b128 v[0:3], v98 offset:3264
	s_waitcnt lgkmcnt(0)
	v_mul_f32_e32 v0, 0xbfb8aa3b, v0
	v_mul_f32_e32 v1, 0xbfb8aa3b, v1
	v_mul_f32_e32 v2, 0xbfb8aa3b, v2
	v_mul_f32_e32 v3, 0xbfb8aa3b, v3
	v_exp_f32_e32 v0, v0
	v_exp_f32_e32 v1, v1
	v_exp_f32_e32 v2, v2
	v_exp_f32_e32 v3, v3
	v_add_f32_e32 v0, 1.0, v0
	v_add_f32_e32 v1, 1.0, v1
	v_add_f32_e32 v2, 1.0, v2
	v_add_f32_e32 v3, 1.0, v3
	v_rcp_f32_e32 v0, v0
	v_rcp_f32_e32 v1, v1
	v_rcp_f32_e32 v2, v2
	v_rcp_f32_e32 v3, v3
	v_cvt_pk_bf16_f32 v0, v0, v1
	v_cvt_pk_bf16_f32 v1, v2, v3
	v_or_b32_e32 v2, v4, v104
	v_ashrrev_i32_e32 v3, 31, v2
	v_lshlrev_b64 v[2:3], 11, v[2:3]
	v_lshl_add_u64 v[2:3], v[96:97], 0, v[2:3]
	flat_store_dwordx2 v[2:3], v[0:1]
	ds_read_b128 v[0:3], v98 offset:4352
	s_waitcnt lgkmcnt(0)
	v_mul_f32_e32 v0, 0xbfb8aa3b, v0
	v_mul_f32_e32 v1, 0xbfb8aa3b, v1
	v_mul_f32_e32 v2, 0xbfb8aa3b, v2
	v_mul_f32_e32 v3, 0xbfb8aa3b, v3
	v_exp_f32_e32 v0, v0
	v_exp_f32_e32 v1, v1
	v_exp_f32_e32 v2, v2
	v_exp_f32_e32 v3, v3
	v_add_f32_e32 v0, 1.0, v0
	v_add_f32_e32 v1, 1.0, v1
	v_add_f32_e32 v2, 1.0, v2
	v_add_f32_e32 v3, 1.0, v3
	v_rcp_f32_e32 v0, v0
	v_rcp_f32_e32 v1, v1
	v_rcp_f32_e32 v2, v2
	v_rcp_f32_e32 v3, v3
	v_cvt_pk_bf16_f32 v0, v0, v1
	v_cvt_pk_bf16_f32 v1, v2, v3
	v_or_b32_e32 v2, v4, v105
	v_ashrrev_i32_e32 v3, 31, v2
	v_lshlrev_b64 v[2:3], 11, v[2:3]
	v_lshl_add_u64 v[2:3], v[96:97], 0, v[2:3]
	flat_store_dwordx2 v[2:3], v[0:1]
	ds_read_b128 v[0:3], v98 offset:5440
	s_waitcnt lgkmcnt(0)
	v_mul_f32_e32 v0, 0xbfb8aa3b, v0
	v_mul_f32_e32 v1, 0xbfb8aa3b, v1
	v_mul_f32_e32 v2, 0xbfb8aa3b, v2
	v_mul_f32_e32 v3, 0xbfb8aa3b, v3
	v_exp_f32_e32 v0, v0
	v_exp_f32_e32 v1, v1
	v_exp_f32_e32 v2, v2
	v_exp_f32_e32 v3, v3
	v_add_f32_e32 v0, 1.0, v0
	v_add_f32_e32 v1, 1.0, v1
	v_add_f32_e32 v2, 1.0, v2
	v_add_f32_e32 v3, 1.0, v3
	v_rcp_f32_e32 v0, v0
	v_rcp_f32_e32 v1, v1
	v_rcp_f32_e32 v2, v2
	v_rcp_f32_e32 v3, v3
	v_cvt_pk_bf16_f32 v0, v0, v1
	v_cvt_pk_bf16_f32 v1, v2, v3
	v_or_b32_e32 v2, v4, v106
	v_ashrrev_i32_e32 v3, 31, v2
	v_lshlrev_b64 v[2:3], 11, v[2:3]
	v_lshl_add_u64 v[2:3], v[96:97], 0, v[2:3]
	flat_store_dwordx2 v[2:3], v[0:1]
	ds_read_b128 v[0:3], v98 offset:6528
	s_waitcnt lgkmcnt(0)
	v_mul_f32_e32 v0, 0xbfb8aa3b, v0
	v_mul_f32_e32 v1, 0xbfb8aa3b, v1
	v_mul_f32_e32 v2, 0xbfb8aa3b, v2
	v_mul_f32_e32 v3, 0xbfb8aa3b, v3
	v_exp_f32_e32 v0, v0
	v_exp_f32_e32 v1, v1
	v_exp_f32_e32 v2, v2
	v_exp_f32_e32 v3, v3
	v_add_f32_e32 v0, 1.0, v0
	v_add_f32_e32 v1, 1.0, v1
	v_add_f32_e32 v2, 1.0, v2
	v_add_f32_e32 v3, 1.0, v3
	v_rcp_f32_e32 v0, v0
	v_rcp_f32_e32 v1, v1
	v_rcp_f32_e32 v2, v2
	v_rcp_f32_e32 v3, v3
	v_cvt_pk_bf16_f32 v0, v0, v1
	v_cvt_pk_bf16_f32 v1, v2, v3
	v_or_b32_e32 v2, v4, v107
	v_ashrrev_i32_e32 v3, 31, v2
	v_lshlrev_b64 v[2:3], 11, v[2:3]
	v_lshl_add_u64 v[2:3], v[96:97], 0, v[2:3]
	flat_store_dwordx2 v[2:3], v[0:1]
	ds_read_b128 v[0:3], v98 offset:7616
	s_waitcnt lgkmcnt(0)
	v_mul_f32_e32 v0, 0xbfb8aa3b, v0
	v_mul_f32_e32 v1, 0xbfb8aa3b, v1
	v_mul_f32_e32 v2, 0xbfb8aa3b, v2
	v_mul_f32_e32 v3, 0xbfb8aa3b, v3
	v_exp_f32_e32 v0, v0
	v_exp_f32_e32 v1, v1
	v_exp_f32_e32 v2, v2
	v_exp_f32_e32 v3, v3
	v_add_f32_e32 v0, 1.0, v0
	v_add_f32_e32 v1, 1.0, v1
	v_add_f32_e32 v2, 1.0, v2
	v_add_f32_e32 v3, 1.0, v3
	v_rcp_f32_e32 v0, v0
	v_rcp_f32_e32 v1, v1
	v_rcp_f32_e32 v2, v2
	v_rcp_f32_e32 v3, v3
	v_cvt_pk_bf16_f32 v0, v0, v1
	v_cvt_pk_bf16_f32 v1, v2, v3
	v_or_b32_e32 v2, v4, v108
	v_ashrrev_i32_e32 v3, 31, v2
	v_lshlrev_b64 v[2:3], 11, v[2:3]
	v_lshl_add_u64 v[2:3], v[96:97], 0, v[2:3]
	flat_store_dwordx2 v[2:3], v[0:1]
	v_mov_b32_e32 v0, s3
	ds_read_b128 v[0:3], v0
	s_waitcnt lgkmcnt(0)
	v_readfirstlane_b32 s0, v3
	v_readfirstlane_b32 s29, v2
	v_lshlrev_b32_e32 v3, 4, v12
	v_and_b32_e32 v2, 32, v12
	s_add_u32 s42, s29, s36
	v_lshrrev_b32_e32 v4, 1, v12
	v_bitop3_b32 v2, v3, v2, 48 bitop3:0x6c
	s_addc_u32 s43, s0, s37
	v_bfe_u32 v13, v12, 2, 4
	v_and_b32_e32 v14, 32, v4
	v_lshrrev_b32_e32 v15, 1, v2
	v_ashrrev_i32_e32 v16, 3, v12
	s_add_u32 s36, s42, 0x18800000
	v_or_b32_e32 v6, v15, v14
	v_and_or_b32 v2, v16, s44, v13
	s_addc_u32 s37, s43, 0
	s_lshl_b64 s[38:39], s[30:31], 11
	v_and_b32_e32 v5, 0xfffffc00, v3
	v_lshl_or_b32 v130, v2, 10, v6
	v_add_u32_e32 v2, 0x2000, v3
	v_add_u32_e32 v4, 0x4000, v3
	v_add_u32_e32 v3, 0x6000, v3
	s_add_u32 s53, s29, s38
	v_ashrrev_i32_e32 v17, 7, v2
	v_ashrrev_i32_e32 v18, 7, v4
	v_ashrrev_i32_e32 v19, 7, v3
	s_addc_u32 s54, s0, s39
	v_and_or_b32 v2, v17, s44, v13
	v_and_or_b32 v4, v18, s44, v13
	v_and_or_b32 v3, v19, s44, v13
	v_add_u32_e32 v151, 0, v5
	s_add_u32 s38, s53, 0xe00000
	v_lshl_or_b32 v2, v2, 10, v6
	v_lshl_or_b32 v4, v4, 10, v6
	v_lshl_or_b32 v6, v3, 10, v6
	v_add_u32_e32 v3, 0x8000, v151
	v_lshlrev_b64 v[8:9], 1, v[130:131]
	v_readfirstlane_b32 s55, v151
	s_addc_u32 s39, s54, 0
	v_lshl_add_u64 v[10:11], s[36:37], 0, v[8:9]
	s_mov_b32 m0, s55
	v_readfirstlane_b32 s55, v3
	v_mov_b32_e32 v3, v131
	v_add_u32_e32 v5, 0x2000, v151
	global_load_lds_dwordx4 v[10:11], off
	v_lshl_add_u64 v[8:9], s[38:39], 0, v[8:9]
	s_mov_b32 m0, s55
	v_lshlrev_b64 v[2:3], 1, v[2:3]
	v_readfirstlane_b32 s55, v5
	v_add_u32_e32 v5, 0xa000, v151
	global_load_lds_dwordx4 v[8:9], off
	v_lshl_add_u64 v[8:9], s[36:37], 0, v[2:3]
	s_mov_b32 m0, s55
	v_readfirstlane_b32 s55, v5
	global_load_lds_dwordx4 v[8:9], off
	v_lshl_add_u64 v[2:3], s[38:39], 0, v[2:3]
	s_mov_b32 m0, s55
	v_mov_b32_e32 v5, v131
	v_add_u32_e32 v7, 0x4000, v151
	global_load_lds_dwordx4 v[2:3], off
	v_lshlrev_b64 v[2:3], 1, v[4:5]
	v_readfirstlane_b32 s55, v7
	v_lshl_add_u64 v[4:5], s[36:37], 0, v[2:3]
	s_mov_b32 m0, s55
	v_lshl_add_u64 v[2:3], s[38:39], 0, v[2:3]
	global_load_lds_dwordx4 v[4:5], off
	v_add_u32_e32 v4, 0xc000, v151
	v_mov_b32_e32 v7, v131
	v_readfirstlane_b32 s55, v4
	s_mov_b32 m0, s55
	v_and_b32_e32 v20, 15, v12
	global_load_lds_dwordx4 v[2:3], off
	v_lshlrev_b64 v[2:3], 1, v[6:7]
	v_add_u32_e32 v6, 0x6000, v151
	v_lshl_add_u64 v[4:5], s[36:37], 0, v[2:3]
	v_readfirstlane_b32 s36, v6
	s_mov_b32 m0, s36
	v_lshl_add_u64 v[2:3], s[38:39], 0, v[2:3]
	global_load_lds_dwordx4 v[4:5], off
	v_add_u32_e32 v4, 0xe000, v151
	v_lshlrev_b32_e32 v8, 10, v13
	v_readfirstlane_b32 s36, v4
	s_mov_b32 m0, s36
	v_lshlrev_b32_e32 v4, 2, v12
	global_load_lds_dwordx4 v[2:3], off
	v_and_b32_e32 v2, 48, v12
	v_lshlrev_b32_e32 v3, 6, v20
	v_and_b32_e32 v4, 32, v4
	v_bitop3_b32 v152, v3, v4, v2 bitop3:0x36
	v_lshlrev_b32_e32 v3, 7, v12
	v_and_b32_e32 v153, 0x6000, v3
	v_lshlrev_b32_e32 v3, 6, v12
	v_and_b32_e32 v154, 0xffffc000, v3
	v_and_b32_e32 v3, 0x3c0, v3
	v_bitop3_b32 v156, v3, v4, v2 bitop3:0x36
	v_lshlrev_b32_e32 v2, 10, v19
	v_and_or_b32 v2, v2, s45, v15
	v_lshlrev_b32_e32 v4, 10, v18
	v_or3_b32 v130, v2, v8, v14
	v_and_or_b32 v4, v4, s45, v15
	v_lshlrev_b32_e32 v6, 10, v17
	v_lshlrev_b64 v[2:3], 1, v[130:131]
	v_or3_b32 v130, v4, v8, v14
	v_and_or_b32 v6, v6, s45, v15
	v_lshlrev_b32_e32 v9, 10, v16
	v_lshlrev_b64 v[4:5], 1, v[130:131]
	v_or3_b32 v130, v6, v8, v14
	v_and_or_b32 v9, v9, s45, v15
	s_add_u32 s36, s53, 0xe00080
	v_lshlrev_b64 v[6:7], 1, v[130:131]
	v_or3_b32 v130, v9, v8, v14
	s_addc_u32 s37, s54, 0
	v_lshlrev_b64 v[8:9], 1, v[130:131]
	s_waitcnt vmcnt(0)
	v_lshl_add_u64 v[134:135], s[36:37], 0, v[2:3]
	v_lshl_add_u64 v[136:137], s[36:37], 0, v[4:5]
	v_lshl_add_u64 v[138:139], s[36:37], 0, v[6:7]
	v_lshl_add_u64 v[140:141], s[36:37], 0, v[8:9]
	s_add_u32 s36, s42, 0x18800080
	s_addc_u32 s37, s43, 0
	v_mov_b32_e32 v10, 0
	v_or_b32_e32 v155, 0x800, v154
	v_or_b32_e32 v157, 0x1000, v154
	v_or_b32_e32 v158, 0x1800, v154
	v_or_b32_e32 v159, 0x2000, v154
	v_or_b32_e32 v160, 0x2800, v154
	v_or_b32_e32 v161, 0x3000, v154
	v_or_b32_e32 v162, 0x3800, v154
	v_lshl_add_u64 v[142:143], s[36:37], 0, v[2:3]
	v_lshl_add_u64 v[144:145], s[36:37], 0, v[4:5]
	v_lshl_add_u64 v[146:147], s[36:37], 0, v[6:7]
	v_lshl_add_u64 v[148:149], s[36:37], 0, v[8:9]
	s_mov_b32 s38, 0
	s_mov_b64 s[36:37], 0
	v_mov_b32_e32 v11, v10
	v_mov_b32_e32 v12, v10
	v_mov_b32_e32 v13, v10
	v_mov_b32_e32 v22, v10
	v_mov_b32_e32 v23, v10
	v_mov_b32_e32 v24, v10
	v_mov_b32_e32 v25, v10
	v_mov_b32_e32 v30, v10
	v_mov_b32_e32 v31, v10
	v_mov_b32_e32 v32, v10
	v_mov_b32_e32 v33, v10
	v_mov_b32_e32 v38, v10
	v_mov_b32_e32 v39, v10
	v_mov_b32_e32 v40, v10
	v_mov_b32_e32 v41, v10
	v_mov_b32_e32 v2, v10
	v_mov_b32_e32 v3, v10
	v_mov_b32_e32 v4, v10
	v_mov_b32_e32 v5, v10
	v_mov_b32_e32 v6, v10
	v_mov_b32_e32 v7, v10
	v_mov_b32_e32 v8, v10
	v_mov_b32_e32 v9, v10
	v_mov_b32_e32 v14, v10
	v_mov_b32_e32 v15, v10
	v_mov_b32_e32 v16, v10
	v_mov_b32_e32 v17, v10
	v_mov_b32_e32 v18, v10
	v_mov_b32_e32 v19, v10
	v_mov_b32_e32 v20, v10
	v_mov_b32_e32 v21, v10
	v_mov_b32_e32 v26, v10
	v_mov_b32_e32 v27, v10
	v_mov_b32_e32 v28, v10
	v_mov_b32_e32 v29, v10
	v_mov_b32_e32 v34, v10
	v_mov_b32_e32 v35, v10
	v_mov_b32_e32 v36, v10
	v_mov_b32_e32 v37, v10
	v_mov_b32_e32 v42, v10
	v_mov_b32_e32 v43, v10
	v_mov_b32_e32 v44, v10
	v_mov_b32_e32 v45, v10
	v_mov_b32_e32 v46, v10
	v_mov_b32_e32 v47, v10
	v_mov_b32_e32 v48, v10
	v_mov_b32_e32 v49, v10
	v_mov_b32_e32 v50, v10
	v_mov_b32_e32 v51, v10
	v_mov_b32_e32 v52, v10
	v_mov_b32_e32 v53, v10
	v_mov_b32_e32 v54, v10
	v_mov_b32_e32 v55, v10
	v_mov_b32_e32 v56, v10
	v_mov_b32_e32 v57, v10
	v_mov_b32_e32 v58, v10
	v_mov_b32_e32 v59, v10
	v_mov_b32_e32 v60, v10
	v_mov_b32_e32 v61, v10
	v_mov_b32_e32 v62, v10
	v_mov_b32_e32 v63, v10
	v_mov_b32_e32 v64, v10
	v_mov_b32_e32 v65, v10
	v_mov_b32_e32 v66, v10
	v_mov_b32_e32 v67, v10
	v_mov_b32_e32 v68, v10
	v_mov_b32_e32 v69, v10
	v_mov_b32_e32 v70, v10
	v_mov_b32_e32 v71, v10
	v_mov_b32_e32 v72, v10
	v_mov_b32_e32 v73, v10
	v_mov_b32_e32 v74, v10
	v_mov_b32_e32 v75, v10
	v_mov_b32_e32 v76, v10
	v_mov_b32_e32 v77, v10
	v_mov_b32_e32 v78, v10
	v_mov_b32_e32 v79, v10
	v_mov_b32_e32 v80, v10
	v_mov_b32_e32 v81, v10
	v_mov_b32_e32 v82, v10
	v_mov_b32_e32 v83, v10
	v_mov_b32_e32 v84, v10
	v_mov_b32_e32 v85, v10
	v_mov_b32_e32 v86, v10
	v_mov_b32_e32 v87, v10
	v_mov_b32_e32 v88, v10
	v_mov_b32_e32 v89, v10
	v_mov_b32_e32 v90, v10
	v_mov_b32_e32 v91, v10
	v_mov_b32_e32 v92, v10
	v_mov_b32_e32 v93, v10
	v_mov_b32_e32 v94, v10
	v_mov_b32_e32 v95, v10
	v_mov_b32_e32 v96, v10
	v_mov_b32_e32 v97, v10
	v_mov_b32_e32 v98, v10
	v_mov_b32_e32 v99, v10
	v_mov_b32_e32 v100, v10
	v_mov_b32_e32 v101, v10
	v_mov_b32_e32 v102, v10
	v_mov_b32_e32 v103, v10
	v_mov_b32_e32 v104, v10
	v_mov_b32_e32 v105, v10
	v_mov_b32_e32 v106, v10
	v_mov_b32_e32 v107, v10
	v_mov_b32_e32 v108, v10
	v_mov_b32_e32 v109, v10
	v_mov_b32_e32 v110, v10
	v_mov_b32_e32 v111, v10
	v_mov_b32_e32 v112, v10
	v_mov_b32_e32 v113, v10
	v_mov_b32_e32 v114, v10
	v_mov_b32_e32 v115, v10
	v_mov_b32_e32 v116, v10
	v_mov_b32_e32 v117, v10
	v_mov_b32_e32 v118, v10
	v_mov_b32_e32 v119, v10
	v_mov_b32_e32 v120, v10
	v_mov_b32_e32 v121, v10
	v_mov_b32_e32 v122, v10
	v_mov_b32_e32 v123, v10
	v_mov_b32_e32 v124, v10
	v_mov_b32_e32 v125, v10
	v_mov_b32_e32 v126, v10
	v_mov_b32_e32 v127, v10
	v_mov_b32_e32 v128, v10
	v_mov_b32_e32 v129, v10
	s_waitcnt vmcnt(0) lgkmcnt(0)
	s_barrier
	v_readfirstlane_b32 s100, v151
	s_mov_b64 s[98:99], 0x80
	s_and_b32 s39, s38, 0x10000
	s_xor_b32 s42, s39, 0x10000
	s_add_i32 s39, s39, 0
	v_add3_u32 v130, s39, v152, v153
	v_add3_u32 v163, s39, v152, v154
	v_add3_u32 v196, s39, v156, v155
	v_add3_u32 v197, s39, v156, v157
	v_add3_u32 v198, s39, v156, v158
	v_add3_u32 v199, s39, v156, v159
	v_add3_u32 v200, s39, v156, v160
	v_add3_u32 v201, s39, v156, v161
	v_add3_u32 v202, s39, v156, v162
	ds_read_b128 v[180:183], v130 offset:32768
	ds_read_b128 v[164:167], v163
	ds_read_b128 v[168:171], v196
	ds_read_b128 v[172:175], v197
	ds_read_b128 v[176:179], v198
	ds_read_b128 v[184:187], v130 offset:34816
	ds_read_b128 v[188:191], v130 offset:36864
	ds_read_b128 v[192:195], v130 offset:38912
	s_add_i32 s101, s100, s42
	s_mov_b32 m0, s101
	s_nop 0
	global_load_lds_dwordx4 v[148:149], off
	s_add_i32 m0, s101, 0x8000
	s_nop 0
	global_load_lds_dwordx4 v[140:141], off
	s_add_i32 m0, s101, 0x2000
	s_nop 0
	global_load_lds_dwordx4 v[146:147], off
	s_add_i32 m0, s101, 0xa000
	s_nop 0
	global_load_lds_dwordx4 v[138:139], off
	s_add_i32 m0, s101, 0x4000
	s_nop 0
	global_load_lds_dwordx4 v[144:145], off
	s_add_i32 m0, s101, 0xc000
	s_nop 0
	global_load_lds_dwordx4 v[136:137], off
	s_add_i32 m0, s101, 0x6000
	s_nop 0
	global_load_lds_dwordx4 v[142:143], off
	s_add_i32 m0, s101, 0xe000
	s_nop 0
	global_load_lds_dwordx4 v[134:135], off
.LBB0_797:
	s_and_b32 s39, s38, 0x10000
	s_xor_b32 s42, s39, 0x10000
	s_add_i32 s39, s39, 0
	s_add_i32 s101, s100, s42
	s_cmpk_eq_i32 s36, 0
	s_cbranch_scc1 .Lg1n_797
	s_waitcnt lgkmcnt(3)
	v_mfma_f32_16x16x32_bf16 v[126:129], v[180:183], v[164:167], v[126:129]
	v_mfma_f32_16x16x32_bf16 v[110:113], v[180:183], v[168:171], v[110:113]
	v_mfma_f32_16x16x32_bf16 v[94:97], v[180:183], v[172:175], v[94:97]
	v_mfma_f32_16x16x32_bf16 v[78:81], v[180:183], v[176:179], v[78:81]
	ds_read_b128 v[240:243], v199
	ds_read_b128 v[244:247], v200
	s_add_i32 m0, s101, 0x4000
	v_lshl_add_u64 v[144:145], v[144:145], 0, s[98:99]
	global_load_lds_dwordx4 v[144:145], off
	s_waitcnt lgkmcnt(4)
	v_mfma_f32_16x16x32_bf16 v[122:125], v[184:187], v[164:167], v[122:125]
	v_mfma_f32_16x16x32_bf16 v[106:109], v[184:187], v[168:171], v[106:109]
	v_mfma_f32_16x16x32_bf16 v[90:93], v[184:187], v[172:175], v[90:93]
	v_mfma_f32_16x16x32_bf16 v[74:77], v[184:187], v[176:179], v[74:77]
	ds_read_b128 v[248:251], v201
	ds_read_b128 v[252:255], v202
	s_add_i32 m0, s101, 0xc000
	v_lshl_add_u64 v[136:137], v[136:137], 0, s[98:99]
	global_load_lds_dwordx4 v[136:137], off
	s_waitcnt lgkmcnt(5)
	v_mfma_f32_16x16x32_bf16 v[118:121], v[188:191], v[164:167], v[118:121]
	v_mfma_f32_16x16x32_bf16 v[102:105], v[188:191], v[168:171], v[102:105]
	v_mfma_f32_16x16x32_bf16 v[86:89], v[188:191], v[172:175], v[86:89]
	v_mfma_f32_16x16x32_bf16 v[70:73], v[188:191], v[176:179], v[70:73]
	s_add_i32 m0, s101, 0x6000
	v_lshl_add_u64 v[142:143], v[142:143], 0, s[98:99]
	global_load_lds_dwordx4 v[142:143], off
	s_waitcnt lgkmcnt(4)
	v_mfma_f32_16x16x32_bf16 v[114:117], v[192:195], v[164:167], v[114:117]
	v_mfma_f32_16x16x32_bf16 v[98:101], v[192:195], v[168:171], v[98:101]
	v_mfma_f32_16x16x32_bf16 v[82:85], v[192:195], v[172:175], v[82:85]
	v_mfma_f32_16x16x32_bf16 v[66:69], v[192:195], v[176:179], v[66:69]
	s_add_i32 m0, s101, 0xe000
	v_lshl_add_u64 v[134:135], v[134:135], 0, s[98:99]
	global_load_lds_dwordx4 v[134:135], off
.Lg2_797:
	ds_read_b128 v[164:167], v163 offset:1024
	ds_read_b128 v[168:171], v196 offset:1024
	ds_read_b128 v[172:175], v197 offset:1024
	ds_read_b128 v[176:179], v198 offset:1024
	s_waitcnt lgkmcnt(4)
	v_mfma_f32_16x16x32_bf16 v[62:65], v[180:183], v[240:243], v[62:65]
	v_mfma_f32_16x16x32_bf16 v[46:49], v[180:183], v[244:247], v[46:49]
	v_mfma_f32_16x16x32_bf16 v[18:21], v[180:183], v[248:251], v[18:21]
	v_mfma_f32_16x16x32_bf16 v[38:41], v[180:183], v[252:255], v[38:41]
	ds_read_b128 v[180:183], v130 offset:33792
	v_mfma_f32_16x16x32_bf16 v[58:61], v[184:187], v[240:243], v[58:61]
	v_mfma_f32_16x16x32_bf16 v[42:45], v[184:187], v[244:247], v[42:45]
	v_mfma_f32_16x16x32_bf16 v[14:17], v[184:187], v[248:251], v[14:17]
	v_mfma_f32_16x16x32_bf16 v[30:33], v[184:187], v[252:255], v[30:33]
	ds_read_b128 v[184:187], v130 offset:35840
	v_mfma_f32_16x16x32_bf16 v[54:57], v[188:191], v[240:243], v[54:57]
	v_mfma_f32_16x16x32_bf16 v[34:37], v[188:191], v[244:247], v[34:37]
	v_mfma_f32_16x16x32_bf16 v[6:9], v[188:191], v[248:251], v[6:9]
	v_mfma_f32_16x16x32_bf16 v[22:25], v[188:191], v[252:255], v[22:25]
	ds_read_b128 v[188:191], v130 offset:37888
	v_mfma_f32_16x16x32_bf16 v[50:53], v[192:195], v[240:243], v[50:53]
	v_mfma_f32_16x16x32_bf16 v[26:29], v[192:195], v[244:247], v[26:29]
	v_mfma_f32_16x16x32_bf16 v[2:5], v[192:195], v[248:251], v[2:5]
	v_mfma_f32_16x16x32_bf16 v[10:13], v[192:195], v[252:255], v[10:13]
	ds_read_b128 v[192:195], v130 offset:39936
	s_waitcnt lgkmcnt(3)
	v_mfma_f32_16x16x32_bf16 v[126:129], v[180:183], v[164:167], v[126:129]
	v_mfma_f32_16x16x32_bf16 v[110:113], v[180:183], v[168:171], v[110:113]
	v_mfma_f32_16x16x32_bf16 v[94:97], v[180:183], v[172:175], v[94:97]
	v_mfma_f32_16x16x32_bf16 v[78:81], v[180:183], v[176:179], v[78:81]
	ds_read_b128 v[240:243], v199 offset:1024
	ds_read_b128 v[244:247], v200 offset:1024
	s_waitcnt lgkmcnt(4)
	v_mfma_f32_16x16x32_bf16 v[122:125], v[184:187], v[164:167], v[122:125]
	v_mfma_f32_16x16x32_bf16 v[106:109], v[184:187], v[168:171], v[106:109]
	v_mfma_f32_16x16x32_bf16 v[90:93], v[184:187], v[172:175], v[90:93]
	v_mfma_f32_16x16x32_bf16 v[74:77], v[184:187], v[176:179], v[74:77]
	ds_read_b128 v[248:251], v201 offset:1024
	ds_read_b128 v[252:255], v202 offset:1024
	s_waitcnt lgkmcnt(5)
	v_mfma_f32_16x16x32_bf16 v[118:121], v[188:191], v[164:167], v[118:121]
	v_mfma_f32_16x16x32_bf16 v[102:105], v[188:191], v[168:171], v[102:105]
	v_mfma_f32_16x16x32_bf16 v[86:89], v[188:191], v[172:175], v[86:89]
	v_mfma_f32_16x16x32_bf16 v[70:73], v[188:191], v[176:179], v[70:73]
	s_waitcnt lgkmcnt(4)
	v_mfma_f32_16x16x32_bf16 v[114:117], v[192:195], v[164:167], v[114:117]
	v_mfma_f32_16x16x32_bf16 v[98:101], v[192:195], v[168:171], v[98:101]
	v_mfma_f32_16x16x32_bf16 v[82:85], v[192:195], v[172:175], v[82:85]
	v_mfma_f32_16x16x32_bf16 v[66:69], v[192:195], v[176:179], v[66:69]
	s_waitcnt vmcnt(0) lgkmcnt(0)
	s_barrier
	s_add_i32 s101, s100, s39
	s_cmpk_eq_i32 s36, 0x700
	s_cbranch_scc1 .Lg4n_797
	v_mfma_f32_16x16x32_bf16 v[62:65], v[180:183], v[240:243], v[62:65]
	v_mfma_f32_16x16x32_bf16 v[46:49], v[180:183], v[244:247], v[46:49]
	v_mfma_f32_16x16x32_bf16 v[18:21], v[180:183], v[248:251], v[18:21]
	v_mfma_f32_16x16x32_bf16 v[38:41], v[180:183], v[252:255], v[38:41]
	v_add3_u32 v130, s42, v152, v153
	ds_read_b128 v[180:183], v130 offset:32768
	v_add3_u32 v163, s42, v152, v154
	v_add3_u32 v196, s42, v156, v155
	v_add3_u32 v197, s42, v156, v157
	v_add3_u32 v198, s42, v156, v158
	ds_read_b128 v[164:167], v163
	ds_read_b128 v[168:171], v196
	ds_read_b128 v[172:175], v197
	ds_read_b128 v[176:179], v198
	s_mov_b32 m0, s101
	v_lshl_add_u64 v[148:149], v[148:149], 0, s[98:99]
	global_load_lds_dwordx4 v[148:149], off
	v_mfma_f32_16x16x32_bf16 v[58:61], v[184:187], v[240:243], v[58:61]
	v_mfma_f32_16x16x32_bf16 v[42:45], v[184:187], v[244:247], v[42:45]
	v_mfma_f32_16x16x32_bf16 v[14:17], v[184:187], v[248:251], v[14:17]
	v_mfma_f32_16x16x32_bf16 v[30:33], v[184:187], v[252:255], v[30:33]
	ds_read_b128 v[184:187], v130 offset:34816
	v_add3_u32 v199, s42, v156, v159
	v_add3_u32 v200, s42, v156, v160
	v_add3_u32 v201, s42, v156, v161
	v_add3_u32 v202, s42, v156, v162
	s_add_i32 m0, s101, 0x8000
	v_lshl_add_u64 v[140:141], v[140:141], 0, s[98:99]
	global_load_lds_dwordx4 v[140:141], off
	v_mfma_f32_16x16x32_bf16 v[54:57], v[188:191], v[240:243], v[54:57]
	v_mfma_f32_16x16x32_bf16 v[34:37], v[188:191], v[244:247], v[34:37]
	v_mfma_f32_16x16x32_bf16 v[6:9], v[188:191], v[248:251], v[6:9]
	v_mfma_f32_16x16x32_bf16 v[22:25], v[188:191], v[252:255], v[22:25]
	ds_read_b128 v[188:191], v130 offset:36864
	s_add_i32 m0, s101, 0x2000
	v_lshl_add_u64 v[146:147], v[146:147], 0, s[98:99]
	global_load_lds_dwordx4 v[146:147], off
	v_mfma_f32_16x16x32_bf16 v[50:53], v[192:195], v[240:243], v[50:53]
	v_mfma_f32_16x16x32_bf16 v[26:29], v[192:195], v[244:247], v[26:29]
	v_mfma_f32_16x16x32_bf16 v[2:5], v[192:195], v[248:251], v[2:5]
	v_mfma_f32_16x16x32_bf16 v[10:13], v[192:195], v[252:255], v[10:13]
	ds_read_b128 v[192:195], v130 offset:38912
	s_add_i32 m0, s101, 0xa000
	v_lshl_add_u64 v[138:139], v[138:139], 0, s[98:99]
	global_load_lds_dwordx4 v[138:139], off
.Ltl_797:
	s_add_i32 s38, s38, 0x10000
	s_add_u32 s36, s36, 0x80
	s_addc_u32 s37, s37, 0
	s_cmpk_lg_i32 s36, 0x780
	s_cbranch_scc1 .LBB0_797
	s_branch .Lex_797

.Lg4n_797:
	v_mfma_f32_16x16x32_bf16 v[62:65], v[180:183], v[240:243], v[62:65]
	v_mfma_f32_16x16x32_bf16 v[46:49], v[180:183], v[244:247], v[46:49]
	v_mfma_f32_16x16x32_bf16 v[18:21], v[180:183], v[248:251], v[18:21]
	v_mfma_f32_16x16x32_bf16 v[38:41], v[180:183], v[252:255], v[38:41]
	v_add3_u32 v130, s42, v152, v153
	ds_read_b128 v[180:183], v130 offset:32768
	v_add3_u32 v163, s42, v152, v154
	v_add3_u32 v196, s42, v156, v155
	v_add3_u32 v197, s42, v156, v157
	v_add3_u32 v198, s42, v156, v158
	ds_read_b128 v[164:167], v163
	ds_read_b128 v[168:171], v196
	ds_read_b128 v[172:175], v197
	ds_read_b128 v[176:179], v198
	v_mfma_f32_16x16x32_bf16 v[58:61], v[184:187], v[240:243], v[58:61]
	v_mfma_f32_16x16x32_bf16 v[42:45], v[184:187], v[244:247], v[42:45]
	v_mfma_f32_16x16x32_bf16 v[14:17], v[184:187], v[248:251], v[14:17]
	v_mfma_f32_16x16x32_bf16 v[30:33], v[184:187], v[252:255], v[30:33]
	ds_read_b128 v[184:187], v130 offset:34816
	v_add3_u32 v199, s42, v156, v159
	v_add3_u32 v200, s42, v156, v160
	v_add3_u32 v201, s42, v156, v161
	v_add3_u32 v202, s42, v156, v162
	v_mfma_f32_16x16x32_bf16 v[54:57], v[188:191], v[240:243], v[54:57]
	v_mfma_f32_16x16x32_bf16 v[34:37], v[188:191], v[244:247], v[34:37]
	v_mfma_f32_16x16x32_bf16 v[6:9], v[188:191], v[248:251], v[6:9]
	v_mfma_f32_16x16x32_bf16 v[22:25], v[188:191], v[252:255], v[22:25]
	ds_read_b128 v[188:191], v130 offset:36864
	v_mfma_f32_16x16x32_bf16 v[50:53], v[192:195], v[240:243], v[50:53]
	v_mfma_f32_16x16x32_bf16 v[26:29], v[192:195], v[244:247], v[26:29]
	v_mfma_f32_16x16x32_bf16 v[2:5], v[192:195], v[248:251], v[2:5]
	v_mfma_f32_16x16x32_bf16 v[10:13], v[192:195], v[252:255], v[10:13]
	ds_read_b128 v[192:195], v130 offset:38912
	s_branch .Ltl_797
.Lex_797:
	s_waitcnt lgkmcnt(0)
	v_add3_u32 v130, s46, v156, v162
	v_add3_u32 v151, s46, v156, v161
	v_add3_u32 v210, s46, v156, v160
	v_add3_u32 v198, s46, v156, v159
	v_add3_u32 v186, s46, v156, v158
	v_add3_u32 v187, s46, v156, v157
	v_add3_u32 v188, s46, v156, v155
	v_add3_u32 v189, s46, v152, v154
	v_add3_u32 v190, s47, v152, v153
	ds_read_b128 v[134:137], v130
	ds_read_b128 v[138:141], v151
	ds_read_b128 v[142:145], v210
	ds_read_b128 v[146:149], v198
	ds_read_b128 v[158:161], v186
	ds_read_b128 v[162:165], v187
	ds_read_b128 v[166:169], v188
	ds_read_b128 v[154:157], v189
	ds_read_b128 v[170:173], v190
	s_waitcnt lgkmcnt(0)
	v_mfma_f32_16x16x32_bf16 v[18:21], v[170:173], v[138:141], v[18:21]
	s_add_u32 s36, s29, 0xc800000
	s_addc_u32 s37, s0, 0
	v_mfma_f32_16x16x32_bf16 v[174:177], v[170:173], v[134:137], v[38:41]
	s_nop 2
	ds_read_b128 v[38:41], v190 offset:2048
	s_waitcnt lgkmcnt(0)
	v_mfma_f32_16x16x32_bf16 v[14:17], v[38:41], v[138:141], v[14:17]
	v_mfma_f32_16x16x32_bf16 v[62:65], v[170:173], v[146:149], v[62:65]
	v_mfma_f32_16x16x32_bf16 v[30:33], v[38:41], v[134:137], v[30:33]
	v_mfma_f32_16x16x32_bf16 v[58:61], v[38:41], v[146:149], v[58:61]
	ds_read_b128 v[178:181], v190 offset:4096
	s_waitcnt lgkmcnt(0)
	v_mfma_f32_16x16x32_bf16 v[182:185], v[178:181], v[134:137], v[22:25]
	v_mfma_f32_16x16x32_bf16 v[54:57], v[178:181], v[146:149], v[54:57]
	s_nop 1
	ds_read_b128 v[22:25], v190 offset:6144
	s_waitcnt lgkmcnt(0)
	v_mfma_f32_16x16x32_bf16 v[134:137], v[22:25], v[134:137], v[10:13]
	v_mfma_f32_16x16x32_bf16 v[10:13], v[22:25], v[154:157], v[114:117]
	v_mfma_f32_16x16x32_bf16 v[114:117], v[22:25], v[158:161], v[66:69]
	v_mfma_f32_16x16x32_bf16 v[66:69], v[178:181], v[154:157], v[118:121]
	v_mfma_f32_16x16x32_bf16 v[118:121], v[178:181], v[158:161], v[70:73]
	v_mfma_f32_16x16x32_bf16 v[70:73], v[38:41], v[154:157], v[122:125]
	v_mfma_f32_16x16x32_bf16 v[122:125], v[38:41], v[158:161], v[74:77]
	v_mfma_f32_16x16x32_bf16 v[74:77], v[170:173], v[154:157], v[126:129]
	v_mfma_f32_16x16x32_bf16 v[126:129], v[170:173], v[158:161], v[78:81]
	v_mfma_f32_16x16x32_bf16 v[50:53], v[22:25], v[146:149], v[50:53]
	v_mfma_f32_16x16x32_bf16 v[146:149], v[170:173], v[142:145], v[46:49]
	v_mfma_f32_16x16x32_bf16 v[152:155], v[38:41], v[142:145], v[42:45]
	v_mfma_f32_16x16x32_bf16 v[156:159], v[178:181], v[142:145], v[34:37]
	v_mfma_f32_16x16x32_bf16 v[26:29], v[22:25], v[142:145], v[26:29]
	v_mfma_f32_16x16x32_bf16 v[142:145], v[178:181], v[138:141], v[6:9]
	v_mfma_f32_16x16x32_bf16 v[110:113], v[170:173], v[166:169], v[110:113]
	v_mfma_f32_16x16x32_bf16 v[94:97], v[170:173], v[162:165], v[94:97]
	v_mfma_f32_16x16x32_bf16 v[106:109], v[38:41], v[166:169], v[106:109]
	v_mfma_f32_16x16x32_bf16 v[90:93], v[38:41], v[162:165], v[90:93]
	v_mfma_f32_16x16x32_bf16 v[102:105], v[178:181], v[166:169], v[102:105]
	v_mfma_f32_16x16x32_bf16 v[86:89], v[178:181], v[162:165], v[86:89]
	v_mfma_f32_16x16x32_bf16 v[98:101], v[22:25], v[166:169], v[98:101]
	v_mfma_f32_16x16x32_bf16 v[82:85], v[22:25], v[162:165], v[82:85]
	v_mfma_f32_16x16x32_bf16 v[22:25], v[22:25], v[138:141], v[2:5]
	ds_read_b128 v[138:141], v190 offset:1024
	ds_read_b128 v[160:163], v190 offset:3072
	ds_read_b128 v[164:167], v190 offset:5120
	ds_read_b128 v[168:171], v190 offset:7168
	ds_read_b128 v[2:5], v189 offset:1024
	ds_read_b128 v[6:9], v188 offset:1024
	ds_read_b128 v[34:37], v187 offset:1024
	ds_read_b128 v[38:41], v186 offset:1024
	s_waitcnt lgkmcnt(3)
	v_mfma_f32_16x16x32_bf16 v[178:181], v[138:141], v[2:5], v[74:77]
	v_mfma_f32_16x16x32_bf16 v[186:189], v[160:163], v[2:5], v[70:73]
	v_mfma_f32_16x16x32_bf16 v[190:193], v[164:167], v[2:5], v[66:69]
	v_mfma_f32_16x16x32_bf16 v[194:197], v[168:171], v[2:5], v[10:13]
	ds_read_b128 v[2:5], v198 offset:1024
	s_waitcnt lgkmcnt(3)
	v_mfma_f32_16x16x32_bf16 v[110:113], v[138:141], v[6:9], v[110:113]
	v_mfma_f32_16x16x32_bf16 v[198:201], v[160:163], v[6:9], v[106:109]
	v_mfma_f32_16x16x32_bf16 v[202:205], v[164:167], v[6:9], v[102:105]
	v_mfma_f32_16x16x32_bf16 v[206:209], v[168:171], v[6:9], v[98:101]
	ds_read_b128 v[6:9], v210 offset:1024
	s_waitcnt lgkmcnt(3)
	v_mfma_f32_16x16x32_bf16 v[66:69], v[138:141], v[34:37], v[94:97]
	v_mfma_f32_16x16x32_bf16 v[70:73], v[160:163], v[34:37], v[90:93]
	v_mfma_f32_16x16x32_bf16 v[74:77], v[164:167], v[34:37], v[86:89]
	v_mfma_f32_16x16x32_bf16 v[78:81], v[168:171], v[34:37], v[82:85]
	ds_read_b128 v[98:101], v151 offset:1024
	s_waitcnt lgkmcnt(3)
	v_mfma_f32_16x16x32_bf16 v[82:85], v[138:141], v[38:41], v[126:129]
	v_mfma_f32_16x16x32_bf16 v[86:89], v[160:163], v[38:41], v[122:125]
	v_mfma_f32_16x16x32_bf16 v[90:93], v[164:167], v[38:41], v[118:121]
	v_mfma_f32_16x16x32_bf16 v[94:97], v[168:171], v[38:41], v[114:117]
	ds_read_b128 v[102:105], v130 offset:1024
	s_waitcnt lgkmcnt(3)
	v_mfma_f32_16x16x32_bf16 v[34:37], v[138:141], v[2:5], v[62:65]
	v_mfma_f32_16x16x32_bf16 v[38:41], v[160:163], v[2:5], v[58:61]
	v_mfma_f32_16x16x32_bf16 v[42:45], v[164:167], v[2:5], v[54:57]
	v_mfma_f32_16x16x32_bf16 v[46:49], v[168:171], v[2:5], v[50:53]
	s_waitcnt lgkmcnt(2)
	v_mfma_f32_16x16x32_bf16 v[50:53], v[138:141], v[6:9], v[146:149]
	v_mfma_f32_16x16x32_bf16 v[54:57], v[160:163], v[6:9], v[152:155]
	v_mfma_f32_16x16x32_bf16 v[58:61], v[164:167], v[6:9], v[156:159]
	v_mfma_f32_16x16x32_bf16 v[62:65], v[168:171], v[6:9], v[26:29]
	s_waitcnt lgkmcnt(1)
	v_mfma_f32_16x16x32_bf16 v[2:5], v[138:141], v[98:101], v[18:21]
	v_mfma_f32_16x16x32_bf16 v[6:9], v[160:163], v[98:101], v[14:17]
	v_mfma_f32_16x16x32_bf16 v[10:13], v[164:167], v[98:101], v[142:145]
	v_mfma_f32_16x16x32_bf16 v[14:17], v[168:171], v[98:101], v[22:25]
	s_waitcnt lgkmcnt(0)
	v_mfma_f32_16x16x32_bf16 v[18:21], v[138:141], v[102:105], v[174:177]
	v_mfma_f32_16x16x32_bf16 v[22:25], v[160:163], v[102:105], v[30:33]
	v_mfma_f32_16x16x32_bf16 v[26:29], v[164:167], v[102:105], v[182:185]
	v_mfma_f32_16x16x32_bf16 v[30:33], v[168:171], v[102:105], v[134:137]
	v_lshrrev_b32_e32 v98, 6, v150
	v_mul_lo_u32 v98, v98, s48
	v_add_u32_e32 v105, s46, v98
	v_lshlrev_b32_e32 v98, 2, v150
	v_and_b32_e32 v109, 60, v98
	v_ashrrev_i32_e32 v98, 1, v150
	v_and_b32_e32 v98, 0xffffff80, v98
	v_add_u32_e32 v104, s28, v98
	v_bfe_u32 v108, v150, 4, 2
	v_or_b32_e32 v102, v104, v108
	v_and_b32_e32 v99, 0xc0, v150
	v_ashrrev_i32_e32 v103, 31, v102
	v_and_b32_e32 v100, 15, v150
	v_or3_b32 v98, v109, v99, s30
	v_mov_b32_e32 v99, s31
	v_lshlrev_b64 v[102:103], 10, v[102:103]
	v_and_b32_e32 v101, 48, v150
	v_mul_u32_u24_e32 v100, 0x110, v100
	v_lshl_add_u64 v[102:103], v[102:103], 0, v[98:99]
	v_add3_u32 v101, v105, v101, v100
	v_lshlrev_b64 v[106:107], 1, v[102:103]
	s_waitcnt vmcnt(0)
	s_barrier
	ds_write_b128 v101, v[178:181]
	ds_write_b128 v101, v[186:189] offset:64
	ds_write_b128 v101, v[190:193] offset:128
	ds_write_b128 v101, v[194:197] offset:192
	ds_write_b128 v101, v[110:113] offset:4352
	ds_write_b128 v101, v[198:201] offset:4416
	ds_write_b128 v101, v[202:205] offset:4480
	ds_write_b128 v101, v[206:209] offset:4544
	v_lshl_add_u64 v[102:103], v[0:1], 0, v[106:107]
	flat_load_dwordx2 v[114:115], v[102:103]
	v_lshl_add_u64 v[102:103], s[36:37], 0, v[106:107]
	flat_load_dwordx2 v[116:117], v[102:103]
	v_mul_u32_u24_e32 v100, 0x110, v108
	v_lshlrev_b32_e32 v103, 2, v109
	v_add3_u32 v100, v105, v103, v100
	ds_read_b128 v[110:113], v100
	v_or_b32_e32 v102, 4, v108
	v_or_b32_e32 v118, v104, v102
	v_ashrrev_i32_e32 v119, 31, v118
	s_add_u32 s28, s29, 0x14800000
	v_lshlrev_b64 v[118:119], 10, v[118:119]
	s_addc_u32 s29, s0, 0
	v_lshl_add_u64 v[118:119], v[118:119], 0, v[98:99]
	v_lshlrev_b64 v[118:119], 1, v[118:119]
	v_lshl_add_u64 v[106:107], s[28:29], 0, v[106:107]
	v_lshl_add_u64 v[120:121], v[0:1], 0, v[118:119]
	v_or_b32_e32 v103, 8, v108
	v_or_b32_e32 v105, 12, v108
	v_or_b32_e32 v109, 24, v108
	s_add_i32 s52, s52, s40
	s_cmpk_gt_i32 s52, 0x1ff
	s_waitcnt vmcnt(0) lgkmcnt(0)
	v_and_b32_e32 v123, 0xffff0000, v114
	v_lshlrev_b32_e32 v122, 16, v114
	v_and_b32_e32 v125, 0xffff0000, v116
	v_lshlrev_b32_e32 v124, 16, v116
	v_and_b32_e32 v127, 0xffff0000, v115
	v_lshlrev_b32_e32 v126, 16, v115
	v_and_b32_e32 v115, 0xffff0000, v117
	v_lshlrev_b32_e32 v114, 16, v117
	v_pk_fma_f32 v[110:111], v[110:111], v[124:125], v[122:123]
	v_pk_fma_f32 v[112:113], v[112:113], v[114:115], v[126:127]
	v_cvt_pk_bf16_f32 v110, v110, v111
	v_cvt_pk_bf16_f32 v111, v112, v113
	flat_store_dwordx2 v[106:107], v[110:111]
	v_lshl_add_u64 v[110:111], s[36:37], 0, v[118:119]
	flat_load_dwordx2 v[106:107], v[120:121]
	flat_load_dwordx2 v[114:115], v[110:111]
	v_or_b32_e32 v110, v104, v103
	v_ashrrev_i32_e32 v111, 31, v110
	v_lshlrev_b64 v[110:111], 10, v[110:111]
	v_lshl_add_u64 v[110:111], v[110:111], 0, v[98:99]
	v_lshlrev_b64 v[116:117], 1, v[110:111]
	ds_read_b128 v[110:113], v100 offset:1088
	v_lshl_add_u64 v[118:119], s[28:29], 0, v[118:119]
	v_lshl_add_u64 v[120:121], v[0:1], 0, v[116:117]
	s_waitcnt vmcnt(0) lgkmcnt(0)
	v_and_b32_e32 v123, 0xffff0000, v106
	v_lshlrev_b32_e32 v122, 16, v106
	v_and_b32_e32 v125, 0xffff0000, v114
	v_lshlrev_b32_e32 v124, 16, v114
	v_and_b32_e32 v127, 0xffff0000, v107
	v_lshlrev_b32_e32 v126, 16, v107
	v_and_b32_e32 v107, 0xffff0000, v115
	v_lshlrev_b32_e32 v106, 16, v115
	v_pk_fma_f32 v[110:111], v[110:111], v[124:125], v[122:123]
	v_pk_fma_f32 v[106:107], v[112:113], v[106:107], v[126:127]
	v_cvt_pk_bf16_f32 v110, v110, v111
	v_cvt_pk_bf16_f32 v111, v106, v107
	flat_store_dwordx2 v[118:119], v[110:111]
	v_lshl_add_u64 v[110:111], s[36:37], 0, v[116:117]
	flat_load_dwordx2 v[106:107], v[120:121]
	flat_load_dwordx2 v[114:115], v[110:111]
	v_or_b32_e32 v110, v104, v105
	v_ashrrev_i32_e32 v111, 31, v110
	v_lshlrev_b64 v[110:111], 10, v[110:111]
	v_lshl_add_u64 v[110:111], v[110:111], 0, v[98:99]
	v_lshlrev_b64 v[118:119], 1, v[110:111]
	ds_read_b128 v[110:113], v100 offset:2176
	v_lshl_add_u64 v[116:117], s[28:29], 0, v[116:117]
	v_lshl_add_u64 v[120:121], v[0:1], 0, v[118:119]
	s_waitcnt vmcnt(0) lgkmcnt(0)
	v_and_b32_e32 v123, 0xffff0000, v106
	v_lshlrev_b32_e32 v122, 16, v106
	v_and_b32_e32 v125, 0xffff0000, v114
	v_lshlrev_b32_e32 v124, 16, v114
	v_and_b32_e32 v127, 0xffff0000, v107
	v_lshlrev_b32_e32 v126, 16, v107
	v_and_b32_e32 v107, 0xffff0000, v115
	v_lshlrev_b32_e32 v106, 16, v115
	v_pk_fma_f32 v[110:111], v[110:111], v[124:125], v[122:123]
	v_pk_fma_f32 v[106:107], v[112:113], v[106:107], v[126:127]
	v_cvt_pk_bf16_f32 v110, v110, v111
	v_cvt_pk_bf16_f32 v111, v106, v107
	flat_store_dwordx2 v[116:117], v[110:111]
	v_lshl_add_u64 v[106:107], s[36:37], 0, v[118:119]
	flat_load_dwordx2 v[114:115], v[120:121]
	flat_load_dwordx2 v[116:117], v[106:107]
	v_or_b32_e32 v106, 16, v108
	v_or_b32_e32 v110, v104, v106
	v_ashrrev_i32_e32 v111, 31, v110
	v_lshlrev_b64 v[110:111], 10, v[110:111]
	v_lshl_add_u64 v[110:111], v[110:111], 0, v[98:99]
	v_lshlrev_b64 v[120:121], 1, v[110:111]
	ds_read_b128 v[110:113], v100 offset:3264
	v_lshl_add_u64 v[118:119], s[28:29], 0, v[118:119]
	v_lshl_add_u64 v[122:123], v[0:1], 0, v[120:121]
	v_or_b32_e32 v107, 20, v108
	s_waitcnt vmcnt(0) lgkmcnt(0)
	v_and_b32_e32 v125, 0xffff0000, v114
	v_lshlrev_b32_e32 v124, 16, v114
	v_and_b32_e32 v127, 0xffff0000, v116
	v_lshlrev_b32_e32 v126, 16, v116
	v_and_b32_e32 v129, 0xffff0000, v115
	v_lshlrev_b32_e32 v128, 16, v115
	v_and_b32_e32 v115, 0xffff0000, v117
	v_lshlrev_b32_e32 v114, 16, v117
	v_pk_fma_f32 v[110:111], v[110:111], v[126:127], v[124:125]
	v_pk_fma_f32 v[112:113], v[112:113], v[114:115], v[128:129]
	v_cvt_pk_bf16_f32 v110, v110, v111
	v_cvt_pk_bf16_f32 v111, v112, v113
	flat_store_dwordx2 v[118:119], v[110:111]
	v_lshl_add_u64 v[110:111], s[36:37], 0, v[120:121]
	flat_load_dwordx2 v[114:115], v[122:123]
	flat_load_dwordx2 v[116:117], v[110:111]
	v_or_b32_e32 v110, v104, v107
	v_ashrrev_i32_e32 v111, 31, v110
	v_lshlrev_b64 v[110:111], 10, v[110:111]
	v_lshl_add_u64 v[110:111], v[110:111], 0, v[98:99]
	v_lshlrev_b64 v[118:119], 1, v[110:111]
	ds_read_b128 v[110:113], v100 offset:4352
	v_lshl_add_u64 v[120:121], s[28:29], 0, v[120:121]
	v_lshl_add_u64 v[122:123], v[0:1], 0, v[118:119]
	s_waitcnt vmcnt(0) lgkmcnt(0)
	v_and_b32_e32 v125, 0xffff0000, v114
	v_lshlrev_b32_e32 v124, 16, v114
	v_and_b32_e32 v127, 0xffff0000, v116
	v_lshlrev_b32_e32 v126, 16, v116
	v_and_b32_e32 v129, 0xffff0000, v115
	v_lshlrev_b32_e32 v128, 16, v115
	v_and_b32_e32 v115, 0xffff0000, v117
	v_lshlrev_b32_e32 v114, 16, v117
	v_pk_fma_f32 v[110:111], v[110:111], v[126:127], v[124:125]
	v_pk_fma_f32 v[112:113], v[112:113], v[114:115], v[128:129]
	v_cvt_pk_bf16_f32 v110, v110, v111
	v_cvt_pk_bf16_f32 v111, v112, v113
	flat_store_dwordx2 v[120:121], v[110:111]
	v_lshl_add_u64 v[110:111], s[36:37], 0, v[118:119]
	flat_load_dwordx2 v[114:115], v[122:123]
	flat_load_dwordx2 v[116:117], v[110:111]
	v_or_b32_e32 v110, v104, v109
	v_ashrrev_i32_e32 v111, 31, v110
	v_lshlrev_b64 v[110:111], 10, v[110:111]
	v_lshl_add_u64 v[110:111], v[110:111], 0, v[98:99]
	v_lshlrev_b64 v[120:121], 1, v[110:111]
	ds_read_b128 v[110:113], v100 offset:5440
	v_lshl_add_u64 v[118:119], s[28:29], 0, v[118:119]
	v_lshl_add_u64 v[122:123], v[0:1], 0, v[120:121]
	s_waitcnt vmcnt(0) lgkmcnt(0)
	v_and_b32_e32 v125, 0xffff0000, v114
	v_lshlrev_b32_e32 v124, 16, v114
	v_and_b32_e32 v127, 0xffff0000, v116
	v_lshlrev_b32_e32 v126, 16, v116
	v_and_b32_e32 v129, 0xffff0000, v115
	v_lshlrev_b32_e32 v128, 16, v115
	v_and_b32_e32 v115, 0xffff0000, v117
	v_lshlrev_b32_e32 v114, 16, v117
	v_pk_fma_f32 v[110:111], v[110:111], v[126:127], v[124:125]
	v_pk_fma_f32 v[112:113], v[112:113], v[114:115], v[128:129]
	v_cvt_pk_bf16_f32 v110, v110, v111
	v_cvt_pk_bf16_f32 v111, v112, v113
	flat_store_dwordx2 v[118:119], v[110:111]
	v_lshl_add_u64 v[110:111], s[36:37], 0, v[120:121]
	flat_load_dwordx2 v[116:117], v[122:123]
	flat_load_dwordx2 v[118:119], v[110:111]
	v_or_b32_e32 v110, 28, v108
	v_or_b32_e32 v112, v104, v110
	v_ashrrev_i32_e32 v113, 31, v112
	v_lshlrev_b64 v[112:113], 10, v[112:113]
	v_lshl_add_u64 v[112:113], v[112:113], 0, v[98:99]
	v_lshlrev_b64 v[122:123], 1, v[112:113]
	ds_read_b128 v[112:115], v100 offset:6528
	v_lshl_add_u64 v[120:121], s[28:29], 0, v[120:121]
	v_lshl_add_u64 v[124:125], v[0:1], 0, v[122:123]
	v_or_b32_e32 v111, 32, v104
	s_waitcnt vmcnt(0) lgkmcnt(0)
	v_and_b32_e32 v127, 0xffff0000, v116
	v_lshlrev_b32_e32 v126, 16, v116
	v_and_b32_e32 v129, 0xffff0000, v118
	v_lshlrev_b32_e32 v128, 16, v118
	v_and_b32_e32 v135, 0xffff0000, v117
	v_lshlrev_b32_e32 v134, 16, v117
	v_and_b32_e32 v117, 0xffff0000, v119
	v_lshlrev_b32_e32 v116, 16, v119
	v_pk_fma_f32 v[112:113], v[112:113], v[128:129], v[126:127]
	v_pk_fma_f32 v[114:115], v[114:115], v[116:117], v[134:135]
	v_cvt_pk_bf16_f32 v112, v112, v113
	v_cvt_pk_bf16_f32 v113, v114, v115
	flat_store_dwordx2 v[120:121], v[112:113]
	v_lshl_add_u64 v[112:113], s[36:37], 0, v[122:123]
	flat_load_dwordx2 v[116:117], v[124:125]
	flat_load_dwordx2 v[118:119], v[112:113]
	v_or_b32_e32 v112, v111, v108
	v_ashrrev_i32_e32 v113, 31, v112
	v_lshlrev_b64 v[112:113], 10, v[112:113]
	v_lshl_add_u64 v[112:113], v[112:113], 0, v[98:99]
	v_lshl_add_u64 v[120:121], s[28:29], 0, v[122:123]
	v_lshlrev_b64 v[122:123], 1, v[112:113]
	ds_read_b128 v[112:115], v100 offset:7616
	v_lshl_add_u64 v[124:125], v[0:1], 0, v[122:123]
	s_waitcnt vmcnt(0) lgkmcnt(0)
	v_and_b32_e32 v127, 0xffff0000, v116
	v_lshlrev_b32_e32 v126, 16, v116
	v_and_b32_e32 v129, 0xffff0000, v118
	v_lshlrev_b32_e32 v128, 16, v118
	v_and_b32_e32 v135, 0xffff0000, v117
	v_lshlrev_b32_e32 v134, 16, v117
	v_and_b32_e32 v117, 0xffff0000, v119
	v_lshlrev_b32_e32 v116, 16, v119
	v_pk_fma_f32 v[112:113], v[112:113], v[128:129], v[126:127]
	v_pk_fma_f32 v[114:115], v[114:115], v[116:117], v[134:135]
	v_cvt_pk_bf16_f32 v112, v112, v113
	v_cvt_pk_bf16_f32 v113, v114, v115
	flat_store_dwordx2 v[120:121], v[112:113]
	ds_write_b128 v101, v[66:69]
	ds_write_b128 v101, v[70:73] offset:64
	ds_write_b128 v101, v[74:77] offset:128
	ds_write_b128 v101, v[78:81] offset:192
	ds_write_b128 v101, v[82:85] offset:4352
	ds_write_b128 v101, v[86:89] offset:4416
	ds_write_b128 v101, v[90:93] offset:4480
	ds_write_b128 v101, v[94:97] offset:4544
	v_lshl_add_u64 v[66:67], s[36:37], 0, v[122:123]
	flat_load_dwordx2 v[70:71], v[124:125]
	flat_load_dwordx2 v[72:73], v[66:67]
	v_or_b32_e32 v66, v111, v102
	v_ashrrev_i32_e32 v67, 31, v66
	v_lshlrev_b64 v[66:67], 10, v[66:67]
	v_lshl_add_u64 v[66:67], v[66:67], 0, v[98:99]
	v_lshlrev_b64 v[74:75], 1, v[66:67]
	ds_read_b128 v[66:69], v100
	v_lshl_add_u64 v[76:77], s[28:29], 0, v[122:123]
	v_lshl_add_u64 v[78:79], v[0:1], 0, v[74:75]
	v_or_b32_e32 v86, 64, v104
	s_waitcnt vmcnt(0) lgkmcnt(0)
	v_and_b32_e32 v81, 0xffff0000, v70
	v_lshlrev_b32_e32 v80, 16, v70
	v_and_b32_e32 v83, 0xffff0000, v72
	v_lshlrev_b32_e32 v82, 16, v72
	v_and_b32_e32 v85, 0xffff0000, v71
	v_lshlrev_b32_e32 v84, 16, v71
	v_and_b32_e32 v71, 0xffff0000, v73
	v_lshlrev_b32_e32 v70, 16, v73
	v_pk_fma_f32 v[66:67], v[66:67], v[82:83], v[80:81]
	v_pk_fma_f32 v[68:69], v[68:69], v[70:71], v[84:85]
	v_cvt_pk_bf16_f32 v66, v66, v67
	v_cvt_pk_bf16_f32 v67, v68, v69
	flat_store_dwordx2 v[76:77], v[66:67]
	v_lshl_add_u64 v[66:67], s[36:37], 0, v[74:75]
	flat_load_dwordx2 v[70:71], v[78:79]
	flat_load_dwordx2 v[72:73], v[66:67]
	v_or_b32_e32 v66, v111, v103
	v_ashrrev_i32_e32 v67, 31, v66
	v_lshlrev_b64 v[66:67], 10, v[66:67]
	v_lshl_add_u64 v[66:67], v[66:67], 0, v[98:99]
	v_lshlrev_b64 v[76:77], 1, v[66:67]
	ds_read_b128 v[66:69], v100 offset:1088
	v_lshl_add_u64 v[74:75], s[28:29], 0, v[74:75]
	v_lshl_add_u64 v[78:79], v[0:1], 0, v[76:77]
	s_waitcnt vmcnt(0) lgkmcnt(0)
	v_and_b32_e32 v81, 0xffff0000, v70
	v_lshlrev_b32_e32 v80, 16, v70
	v_and_b32_e32 v83, 0xffff0000, v72
	v_lshlrev_b32_e32 v82, 16, v72
	v_and_b32_e32 v85, 0xffff0000, v71
	v_lshlrev_b32_e32 v84, 16, v71
	v_and_b32_e32 v71, 0xffff0000, v73
	v_lshlrev_b32_e32 v70, 16, v73
	v_pk_fma_f32 v[66:67], v[66:67], v[82:83], v[80:81]
	v_pk_fma_f32 v[68:69], v[68:69], v[70:71], v[84:85]
	v_cvt_pk_bf16_f32 v66, v66, v67
	v_cvt_pk_bf16_f32 v67, v68, v69
	flat_store_dwordx2 v[74:75], v[66:67]
	v_lshl_add_u64 v[66:67], s[36:37], 0, v[76:77]
	flat_load_dwordx2 v[70:71], v[78:79]
	flat_load_dwordx2 v[72:73], v[66:67]
	v_or_b32_e32 v66, v111, v105
	v_ashrrev_i32_e32 v67, 31, v66
	v_lshlrev_b64 v[66:67], 10, v[66:67]
	v_lshl_add_u64 v[66:67], v[66:67], 0, v[98:99]
	v_lshlrev_b64 v[74:75], 1, v[66:67]
	ds_read_b128 v[66:69], v100 offset:2176
	v_lshl_add_u64 v[76:77], s[28:29], 0, v[76:77]
	v_lshl_add_u64 v[78:79], v[0:1], 0, v[74:75]
	s_waitcnt vmcnt(0) lgkmcnt(0)
	v_and_b32_e32 v81, 0xffff0000, v70
	v_lshlrev_b32_e32 v80, 16, v70
	v_and_b32_e32 v83, 0xffff0000, v72
	v_lshlrev_b32_e32 v82, 16, v72
	v_and_b32_e32 v85, 0xffff0000, v71
	v_lshlrev_b32_e32 v84, 16, v71
	v_and_b32_e32 v71, 0xffff0000, v73
	v_lshlrev_b32_e32 v70, 16, v73
	v_pk_fma_f32 v[66:67], v[66:67], v[82:83], v[80:81]
	v_pk_fma_f32 v[68:69], v[68:69], v[70:71], v[84:85]
	v_cvt_pk_bf16_f32 v66, v66, v67
	v_cvt_pk_bf16_f32 v67, v68, v69
	flat_store_dwordx2 v[76:77], v[66:67]
	v_lshl_add_u64 v[66:67], s[36:37], 0, v[74:75]
	flat_load_dwordx2 v[70:71], v[78:79]
	flat_load_dwordx2 v[72:73], v[66:67]
	v_or_b32_e32 v66, v111, v106
	v_ashrrev_i32_e32 v67, 31, v66
	v_lshlrev_b64 v[66:67], 10, v[66:67]
	v_lshl_add_u64 v[66:67], v[66:67], 0, v[98:99]
	v_lshlrev_b64 v[76:77], 1, v[66:67]
	ds_read_b128 v[66:69], v100 offset:3264
	v_lshl_add_u64 v[74:75], s[28:29], 0, v[74:75]
	v_lshl_add_u64 v[78:79], v[0:1], 0, v[76:77]
	s_waitcnt vmcnt(0) lgkmcnt(0)
	v_and_b32_e32 v81, 0xffff0000, v70
	v_lshlrev_b32_e32 v80, 16, v70
	v_and_b32_e32 v83, 0xffff0000, v72
	v_lshlrev_b32_e32 v82, 16, v72
	v_and_b32_e32 v85, 0xffff0000, v71
	v_lshlrev_b32_e32 v84, 16, v71
	v_and_b32_e32 v71, 0xffff0000, v73
	v_lshlrev_b32_e32 v70, 16, v73
	v_pk_fma_f32 v[66:67], v[66:67], v[82:83], v[80:81]
	v_pk_fma_f32 v[68:69], v[68:69], v[70:71], v[84:85]
	v_cvt_pk_bf16_f32 v66, v66, v67
	v_cvt_pk_bf16_f32 v67, v68, v69
	flat_store_dwordx2 v[74:75], v[66:67]
	v_lshl_add_u64 v[66:67], s[36:37], 0, v[76:77]
	flat_load_dwordx2 v[70:71], v[78:79]
	flat_load_dwordx2 v[72:73], v[66:67]
	v_or_b32_e32 v66, v111, v107
	v_ashrrev_i32_e32 v67, 31, v66
	v_lshlrev_b64 v[66:67], 10, v[66:67]
	v_lshl_add_u64 v[66:67], v[66:67], 0, v[98:99]
	v_lshlrev_b64 v[74:75], 1, v[66:67]
	ds_read_b128 v[66:69], v100 offset:4352
	v_lshl_add_u64 v[76:77], s[28:29], 0, v[76:77]
	v_lshl_add_u64 v[78:79], v[0:1], 0, v[74:75]
	s_waitcnt vmcnt(0) lgkmcnt(0)
	v_and_b32_e32 v81, 0xffff0000, v70
	v_lshlrev_b32_e32 v80, 16, v70
	v_and_b32_e32 v83, 0xffff0000, v72
	v_lshlrev_b32_e32 v82, 16, v72
	v_and_b32_e32 v85, 0xffff0000, v71
	v_lshlrev_b32_e32 v84, 16, v71
	v_and_b32_e32 v71, 0xffff0000, v73
	v_lshlrev_b32_e32 v70, 16, v73
	v_pk_fma_f32 v[66:67], v[66:67], v[82:83], v[80:81]
	v_pk_fma_f32 v[68:69], v[68:69], v[70:71], v[84:85]
	v_cvt_pk_bf16_f32 v66, v66, v67
	v_cvt_pk_bf16_f32 v67, v68, v69
	flat_store_dwordx2 v[76:77], v[66:67]
	v_lshl_add_u64 v[66:67], s[36:37], 0, v[74:75]
	flat_load_dwordx2 v[70:71], v[78:79]
	flat_load_dwordx2 v[72:73], v[66:67]
	v_or_b32_e32 v66, v111, v109
	v_ashrrev_i32_e32 v67, 31, v66
	v_lshlrev_b64 v[66:67], 10, v[66:67]
	v_lshl_add_u64 v[66:67], v[66:67], 0, v[98:99]
	v_lshlrev_b64 v[76:77], 1, v[66:67]
	ds_read_b128 v[66:69], v100 offset:5440
	v_lshl_add_u64 v[74:75], s[28:29], 0, v[74:75]
	v_lshl_add_u64 v[78:79], v[0:1], 0, v[76:77]
	s_waitcnt vmcnt(0) lgkmcnt(0)
	v_and_b32_e32 v81, 0xffff0000, v70
	v_lshlrev_b32_e32 v80, 16, v70
	v_and_b32_e32 v83, 0xffff0000, v72
	v_lshlrev_b32_e32 v82, 16, v72
	v_and_b32_e32 v85, 0xffff0000, v71
	v_lshlrev_b32_e32 v84, 16, v71
	v_and_b32_e32 v71, 0xffff0000, v73
	v_lshlrev_b32_e32 v70, 16, v73
	v_pk_fma_f32 v[66:67], v[66:67], v[82:83], v[80:81]
	v_pk_fma_f32 v[68:69], v[68:69], v[70:71], v[84:85]
	v_cvt_pk_bf16_f32 v66, v66, v67
	v_cvt_pk_bf16_f32 v67, v68, v69
	flat_store_dwordx2 v[74:75], v[66:67]
	v_lshl_add_u64 v[66:67], s[36:37], 0, v[76:77]
	flat_load_dwordx2 v[70:71], v[78:79]
	flat_load_dwordx2 v[72:73], v[66:67]
	v_or_b32_e32 v66, v111, v110
	v_ashrrev_i32_e32 v67, 31, v66
	v_lshlrev_b64 v[66:67], 10, v[66:67]
	v_lshl_add_u64 v[66:67], v[66:67], 0, v[98:99]
	v_lshlrev_b64 v[74:75], 1, v[66:67]
	ds_read_b128 v[66:69], v100 offset:6528
	v_lshl_add_u64 v[76:77], s[28:29], 0, v[76:77]
	v_lshl_add_u64 v[78:79], v[0:1], 0, v[74:75]
	s_waitcnt vmcnt(0) lgkmcnt(0)
	v_and_b32_e32 v81, 0xffff0000, v70
	v_lshlrev_b32_e32 v80, 16, v70
	v_and_b32_e32 v83, 0xffff0000, v72
	v_lshlrev_b32_e32 v82, 16, v72
	v_and_b32_e32 v85, 0xffff0000, v71
	v_lshlrev_b32_e32 v84, 16, v71
	v_and_b32_e32 v71, 0xffff0000, v73
	v_lshlrev_b32_e32 v70, 16, v73
	v_pk_fma_f32 v[66:67], v[66:67], v[82:83], v[80:81]
	v_pk_fma_f32 v[68:69], v[68:69], v[70:71], v[84:85]
	v_cvt_pk_bf16_f32 v66, v66, v67
	v_cvt_pk_bf16_f32 v67, v68, v69
	flat_store_dwordx2 v[76:77], v[66:67]
	v_lshl_add_u64 v[66:67], s[36:37], 0, v[74:75]
	flat_load_dwordx2 v[70:71], v[78:79]
	flat_load_dwordx2 v[72:73], v[66:67]
	v_or_b32_e32 v66, v86, v108
	v_ashrrev_i32_e32 v67, 31, v66
	v_lshlrev_b64 v[66:67], 10, v[66:67]
	v_lshl_add_u64 v[66:67], v[66:67], 0, v[98:99]
	v_lshlrev_b64 v[76:77], 1, v[66:67]
	ds_read_b128 v[66:69], v100 offset:7616
	v_lshl_add_u64 v[74:75], s[28:29], 0, v[74:75]
	v_lshl_add_u64 v[78:79], v[0:1], 0, v[76:77]
	s_waitcnt vmcnt(0) lgkmcnt(0)
	v_and_b32_e32 v81, 0xffff0000, v70
	v_lshlrev_b32_e32 v80, 16, v70
	v_and_b32_e32 v83, 0xffff0000, v72
	v_lshlrev_b32_e32 v82, 16, v72
	v_and_b32_e32 v85, 0xffff0000, v71
	v_lshlrev_b32_e32 v84, 16, v71
	v_and_b32_e32 v71, 0xffff0000, v73
	v_lshlrev_b32_e32 v70, 16, v73
	v_pk_fma_f32 v[66:67], v[66:67], v[82:83], v[80:81]
	v_pk_fma_f32 v[68:69], v[68:69], v[70:71], v[84:85]
	v_cvt_pk_bf16_f32 v66, v66, v67
	v_cvt_pk_bf16_f32 v67, v68, v69
	flat_store_dwordx2 v[74:75], v[66:67]
	ds_write_b128 v101, v[34:37]
	ds_write_b128 v101, v[38:41] offset:64
	ds_write_b128 v101, v[42:45] offset:128
	ds_write_b128 v101, v[46:49] offset:192
	ds_write_b128 v101, v[50:53] offset:4352
	ds_write_b128 v101, v[54:57] offset:4416
	ds_write_b128 v101, v[58:61] offset:4480
	ds_write_b128 v101, v[62:65] offset:4544
	v_lshl_add_u64 v[34:35], s[36:37], 0, v[76:77]
	flat_load_dwordx2 v[38:39], v[78:79]
	flat_load_dwordx2 v[40:41], v[34:35]
	v_or_b32_e32 v34, v86, v102
	v_ashrrev_i32_e32 v35, 31, v34
	v_lshlrev_b64 v[34:35], 10, v[34:35]
	v_lshl_add_u64 v[34:35], v[34:35], 0, v[98:99]
	v_lshlrev_b64 v[42:43], 1, v[34:35]
	ds_read_b128 v[34:37], v100
	v_lshl_add_u64 v[44:45], s[28:29], 0, v[76:77]
	v_lshl_add_u64 v[46:47], v[0:1], 0, v[42:43]
	v_or_b32_e32 v54, 0x60, v104
	s_waitcnt vmcnt(0) lgkmcnt(0)
	v_and_b32_e32 v49, 0xffff0000, v38
	v_lshlrev_b32_e32 v48, 16, v38
	v_and_b32_e32 v51, 0xffff0000, v40
	v_lshlrev_b32_e32 v50, 16, v40
	v_and_b32_e32 v53, 0xffff0000, v39
	v_lshlrev_b32_e32 v52, 16, v39
	v_and_b32_e32 v39, 0xffff0000, v41
	v_lshlrev_b32_e32 v38, 16, v41
	v_pk_fma_f32 v[34:35], v[34:35], v[50:51], v[48:49]
	v_pk_fma_f32 v[36:37], v[36:37], v[38:39], v[52:53]
	v_cvt_pk_bf16_f32 v34, v34, v35
	v_cvt_pk_bf16_f32 v35, v36, v37
	flat_store_dwordx2 v[44:45], v[34:35]
	v_lshl_add_u64 v[34:35], s[36:37], 0, v[42:43]
	flat_load_dwordx2 v[38:39], v[46:47]
	flat_load_dwordx2 v[40:41], v[34:35]
	v_or_b32_e32 v34, v86, v103
	v_ashrrev_i32_e32 v35, 31, v34
	v_lshlrev_b64 v[34:35], 10, v[34:35]
	v_lshl_add_u64 v[34:35], v[34:35], 0, v[98:99]
	v_lshlrev_b64 v[44:45], 1, v[34:35]
	ds_read_b128 v[34:37], v100 offset:1088
	v_lshl_add_u64 v[42:43], s[28:29], 0, v[42:43]
	v_lshl_add_u64 v[46:47], v[0:1], 0, v[44:45]
	s_waitcnt vmcnt(0) lgkmcnt(0)
	v_and_b32_e32 v49, 0xffff0000, v38
	v_lshlrev_b32_e32 v48, 16, v38
	v_and_b32_e32 v51, 0xffff0000, v40
	v_lshlrev_b32_e32 v50, 16, v40
	v_and_b32_e32 v53, 0xffff0000, v39
	v_lshlrev_b32_e32 v52, 16, v39
	v_and_b32_e32 v39, 0xffff0000, v41
	v_lshlrev_b32_e32 v38, 16, v41
	v_pk_fma_f32 v[34:35], v[34:35], v[50:51], v[48:49]
	v_pk_fma_f32 v[36:37], v[36:37], v[38:39], v[52:53]
	v_cvt_pk_bf16_f32 v34, v34, v35
	v_cvt_pk_bf16_f32 v35, v36, v37
	flat_store_dwordx2 v[42:43], v[34:35]
	v_lshl_add_u64 v[34:35], s[36:37], 0, v[44:45]
	flat_load_dwordx2 v[38:39], v[46:47]
	flat_load_dwordx2 v[40:41], v[34:35]
	v_or_b32_e32 v34, v86, v105
	v_ashrrev_i32_e32 v35, 31, v34
	v_lshlrev_b64 v[34:35], 10, v[34:35]
	v_lshl_add_u64 v[34:35], v[34:35], 0, v[98:99]
	v_lshlrev_b64 v[42:43], 1, v[34:35]
	ds_read_b128 v[34:37], v100 offset:2176
	v_lshl_add_u64 v[44:45], s[28:29], 0, v[44:45]
	v_lshl_add_u64 v[46:47], v[0:1], 0, v[42:43]
	s_waitcnt vmcnt(0) lgkmcnt(0)
	v_and_b32_e32 v49, 0xffff0000, v38
	v_lshlrev_b32_e32 v48, 16, v38
	v_and_b32_e32 v51, 0xffff0000, v40
	v_lshlrev_b32_e32 v50, 16, v40
	v_and_b32_e32 v53, 0xffff0000, v39
	v_lshlrev_b32_e32 v52, 16, v39
	v_and_b32_e32 v39, 0xffff0000, v41
	v_lshlrev_b32_e32 v38, 16, v41
	v_pk_fma_f32 v[34:35], v[34:35], v[50:51], v[48:49]
	v_pk_fma_f32 v[36:37], v[36:37], v[38:39], v[52:53]
	v_cvt_pk_bf16_f32 v34, v34, v35
	v_cvt_pk_bf16_f32 v35, v36, v37
	flat_store_dwordx2 v[44:45], v[34:35]
	v_lshl_add_u64 v[34:35], s[36:37], 0, v[42:43]
	flat_load_dwordx2 v[38:39], v[46:47]
	flat_load_dwordx2 v[40:41], v[34:35]
	v_or_b32_e32 v34, v86, v106
	v_ashrrev_i32_e32 v35, 31, v34
	v_lshlrev_b64 v[34:35], 10, v[34:35]
	v_lshl_add_u64 v[34:35], v[34:35], 0, v[98:99]
	v_lshlrev_b64 v[44:45], 1, v[34:35]
	ds_read_b128 v[34:37], v100 offset:3264
	v_lshl_add_u64 v[42:43], s[28:29], 0, v[42:43]
	v_lshl_add_u64 v[46:47], v[0:1], 0, v[44:45]
	s_waitcnt vmcnt(0) lgkmcnt(0)
	v_and_b32_e32 v49, 0xffff0000, v38
	v_lshlrev_b32_e32 v48, 16, v38
	v_and_b32_e32 v51, 0xffff0000, v40
	v_lshlrev_b32_e32 v50, 16, v40
	v_and_b32_e32 v53, 0xffff0000, v39
	v_lshlrev_b32_e32 v52, 16, v39
	v_and_b32_e32 v39, 0xffff0000, v41
	v_lshlrev_b32_e32 v38, 16, v41
	v_pk_fma_f32 v[34:35], v[34:35], v[50:51], v[48:49]
	v_pk_fma_f32 v[36:37], v[36:37], v[38:39], v[52:53]
	v_cvt_pk_bf16_f32 v34, v34, v35
	v_cvt_pk_bf16_f32 v35, v36, v37
	flat_store_dwordx2 v[42:43], v[34:35]
	v_lshl_add_u64 v[34:35], s[36:37], 0, v[44:45]
	flat_load_dwordx2 v[38:39], v[46:47]
	flat_load_dwordx2 v[40:41], v[34:35]
	v_or_b32_e32 v34, v86, v107
	v_ashrrev_i32_e32 v35, 31, v34
	v_lshlrev_b64 v[34:35], 10, v[34:35]
	v_lshl_add_u64 v[34:35], v[34:35], 0, v[98:99]
	v_lshlrev_b64 v[42:43], 1, v[34:35]
	ds_read_b128 v[34:37], v100 offset:4352
	v_lshl_add_u64 v[44:45], s[28:29], 0, v[44:45]
	v_lshl_add_u64 v[46:47], v[0:1], 0, v[42:43]
	s_waitcnt vmcnt(0) lgkmcnt(0)
	v_and_b32_e32 v49, 0xffff0000, v38
	v_lshlrev_b32_e32 v48, 16, v38
	v_and_b32_e32 v51, 0xffff0000, v40
	v_lshlrev_b32_e32 v50, 16, v40
	v_and_b32_e32 v53, 0xffff0000, v39
	v_lshlrev_b32_e32 v52, 16, v39
	v_and_b32_e32 v39, 0xffff0000, v41
	v_lshlrev_b32_e32 v38, 16, v41
	v_pk_fma_f32 v[34:35], v[34:35], v[50:51], v[48:49]
	v_pk_fma_f32 v[36:37], v[36:37], v[38:39], v[52:53]
	v_cvt_pk_bf16_f32 v34, v34, v35
	v_cvt_pk_bf16_f32 v35, v36, v37
	flat_store_dwordx2 v[44:45], v[34:35]
	v_lshl_add_u64 v[34:35], s[36:37], 0, v[42:43]
	flat_load_dwordx2 v[38:39], v[46:47]
	flat_load_dwordx2 v[40:41], v[34:35]
	v_or_b32_e32 v34, v86, v109
	v_ashrrev_i32_e32 v35, 31, v34
	v_lshlrev_b64 v[34:35], 10, v[34:35]
	v_lshl_add_u64 v[34:35], v[34:35], 0, v[98:99]
	v_lshlrev_b64 v[44:45], 1, v[34:35]
	ds_read_b128 v[34:37], v100 offset:5440
	v_lshl_add_u64 v[42:43], s[28:29], 0, v[42:43]
	v_lshl_add_u64 v[46:47], v[0:1], 0, v[44:45]
	s_waitcnt vmcnt(0) lgkmcnt(0)
	v_and_b32_e32 v49, 0xffff0000, v38
	v_lshlrev_b32_e32 v48, 16, v38
	v_and_b32_e32 v51, 0xffff0000, v40
	v_lshlrev_b32_e32 v50, 16, v40
	v_and_b32_e32 v53, 0xffff0000, v39
	v_lshlrev_b32_e32 v52, 16, v39
	v_and_b32_e32 v39, 0xffff0000, v41
	v_lshlrev_b32_e32 v38, 16, v41
	v_pk_fma_f32 v[34:35], v[34:35], v[50:51], v[48:49]
	v_pk_fma_f32 v[36:37], v[36:37], v[38:39], v[52:53]
	v_cvt_pk_bf16_f32 v34, v34, v35
	v_cvt_pk_bf16_f32 v35, v36, v37
	flat_store_dwordx2 v[42:43], v[34:35]
	v_lshl_add_u64 v[34:35], s[36:37], 0, v[44:45]
	flat_load_dwordx2 v[38:39], v[46:47]
	flat_load_dwordx2 v[40:41], v[34:35]
	v_or_b32_e32 v34, v86, v110
	v_ashrrev_i32_e32 v35, 31, v34
	v_lshlrev_b64 v[34:35], 10, v[34:35]
	v_lshl_add_u64 v[34:35], v[34:35], 0, v[98:99]
	v_lshlrev_b64 v[42:43], 1, v[34:35]
	ds_read_b128 v[34:37], v100 offset:6528
	v_lshl_add_u64 v[44:45], s[28:29], 0, v[44:45]
	v_lshl_add_u64 v[46:47], v[0:1], 0, v[42:43]
	s_waitcnt vmcnt(0) lgkmcnt(0)
	v_and_b32_e32 v49, 0xffff0000, v38
	v_lshlrev_b32_e32 v48, 16, v38
	v_and_b32_e32 v51, 0xffff0000, v40
	v_lshlrev_b32_e32 v50, 16, v40
	v_and_b32_e32 v53, 0xffff0000, v39
	v_lshlrev_b32_e32 v52, 16, v39
	v_and_b32_e32 v39, 0xffff0000, v41
	v_lshlrev_b32_e32 v38, 16, v41
	v_pk_fma_f32 v[34:35], v[34:35], v[50:51], v[48:49]
	v_pk_fma_f32 v[36:37], v[36:37], v[38:39], v[52:53]
	v_cvt_pk_bf16_f32 v34, v34, v35
	v_cvt_pk_bf16_f32 v35, v36, v37
	flat_store_dwordx2 v[44:45], v[34:35]
	v_lshl_add_u64 v[34:35], s[36:37], 0, v[42:43]
	flat_load_dwordx2 v[38:39], v[46:47]
	flat_load_dwordx2 v[40:41], v[34:35]
	v_or_b32_e32 v34, v54, v108
	v_ashrrev_i32_e32 v35, 31, v34
	v_lshlrev_b64 v[34:35], 10, v[34:35]
	v_lshl_add_u64 v[34:35], v[34:35], 0, v[98:99]
	v_lshlrev_b64 v[44:45], 1, v[34:35]
	ds_read_b128 v[34:37], v100 offset:7616
	v_lshl_add_u64 v[42:43], s[28:29], 0, v[42:43]
	v_lshl_add_u64 v[46:47], v[0:1], 0, v[44:45]
	s_waitcnt vmcnt(0) lgkmcnt(0)
	v_and_b32_e32 v49, 0xffff0000, v38
	v_lshlrev_b32_e32 v48, 16, v38
	v_and_b32_e32 v51, 0xffff0000, v40
	v_lshlrev_b32_e32 v50, 16, v40
	v_and_b32_e32 v53, 0xffff0000, v39
	v_lshlrev_b32_e32 v52, 16, v39
	v_and_b32_e32 v39, 0xffff0000, v41
	v_lshlrev_b32_e32 v38, 16, v41
	v_pk_fma_f32 v[34:35], v[34:35], v[50:51], v[48:49]
	v_pk_fma_f32 v[36:37], v[36:37], v[38:39], v[52:53]
	v_cvt_pk_bf16_f32 v34, v34, v35
	v_cvt_pk_bf16_f32 v35, v36, v37
	flat_store_dwordx2 v[42:43], v[34:35]
	ds_write_b128 v101, v[2:5]
	ds_write_b128 v101, v[6:9] offset:64
	ds_write_b128 v101, v[10:13] offset:128
	ds_write_b128 v101, v[14:17] offset:192
	ds_write_b128 v101, v[18:21] offset:4352
	ds_write_b128 v101, v[22:25] offset:4416
	ds_write_b128 v101, v[26:29] offset:4480
	ds_write_b128 v101, v[30:33] offset:4544
	v_lshl_add_u64 v[2:3], s[36:37], 0, v[44:45]
	flat_load_dwordx2 v[6:7], v[46:47]
	flat_load_dwordx2 v[8:9], v[2:3]
	v_or_b32_e32 v2, v54, v102
	v_ashrrev_i32_e32 v3, 31, v2
	v_lshlrev_b64 v[2:3], 10, v[2:3]
	v_lshl_add_u64 v[2:3], v[2:3], 0, v[98:99]
	v_lshlrev_b64 v[10:11], 1, v[2:3]
	ds_read_b128 v[2:5], v100
	v_lshl_add_u64 v[12:13], s[28:29], 0, v[44:45]
	v_lshl_add_u64 v[14:15], v[0:1], 0, v[10:11]
	s_waitcnt vmcnt(0) lgkmcnt(0)
	v_and_b32_e32 v17, 0xffff0000, v6
	v_lshlrev_b32_e32 v16, 16, v6
	v_and_b32_e32 v19, 0xffff0000, v8
	v_lshlrev_b32_e32 v18, 16, v8
	v_and_b32_e32 v21, 0xffff0000, v7
	v_lshlrev_b32_e32 v20, 16, v7
	v_and_b32_e32 v7, 0xffff0000, v9
	v_lshlrev_b32_e32 v6, 16, v9
	v_pk_fma_f32 v[2:3], v[2:3], v[18:19], v[16:17]
	v_pk_fma_f32 v[4:5], v[4:5], v[6:7], v[20:21]
	v_cvt_pk_bf16_f32 v2, v2, v3
	v_cvt_pk_bf16_f32 v3, v4, v5
	flat_store_dwordx2 v[12:13], v[2:3]
	v_lshl_add_u64 v[2:3], s[36:37], 0, v[10:11]
	flat_load_dwordx2 v[6:7], v[14:15]
	flat_load_dwordx2 v[8:9], v[2:3]
	v_or_b32_e32 v2, v54, v103
	v_ashrrev_i32_e32 v3, 31, v2
	v_lshlrev_b64 v[2:3], 10, v[2:3]
	v_lshl_add_u64 v[2:3], v[2:3], 0, v[98:99]
	v_lshlrev_b64 v[12:13], 1, v[2:3]
	ds_read_b128 v[2:5], v100 offset:1088
	v_lshl_add_u64 v[10:11], s[28:29], 0, v[10:11]
	v_lshl_add_u64 v[14:15], v[0:1], 0, v[12:13]
	s_waitcnt vmcnt(0) lgkmcnt(0)
	v_and_b32_e32 v17, 0xffff0000, v6
	v_lshlrev_b32_e32 v16, 16, v6
	v_and_b32_e32 v19, 0xffff0000, v8
	v_lshlrev_b32_e32 v18, 16, v8
	v_and_b32_e32 v21, 0xffff0000, v7
	v_lshlrev_b32_e32 v20, 16, v7
	v_and_b32_e32 v7, 0xffff0000, v9
	v_lshlrev_b32_e32 v6, 16, v9
	v_pk_fma_f32 v[2:3], v[2:3], v[18:19], v[16:17]
	v_pk_fma_f32 v[4:5], v[4:5], v[6:7], v[20:21]
	v_cvt_pk_bf16_f32 v2, v2, v3
	v_cvt_pk_bf16_f32 v3, v4, v5
	flat_store_dwordx2 v[10:11], v[2:3]
	v_lshl_add_u64 v[2:3], s[36:37], 0, v[12:13]
	flat_load_dwordx2 v[6:7], v[14:15]
	flat_load_dwordx2 v[8:9], v[2:3]
	v_or_b32_e32 v2, v54, v105
	v_ashrrev_i32_e32 v3, 31, v2
	v_lshlrev_b64 v[2:3], 10, v[2:3]
	v_lshl_add_u64 v[2:3], v[2:3], 0, v[98:99]
	v_lshlrev_b64 v[10:11], 1, v[2:3]
	ds_read_b128 v[2:5], v100 offset:2176
	v_lshl_add_u64 v[12:13], s[28:29], 0, v[12:13]
	v_lshl_add_u64 v[14:15], v[0:1], 0, v[10:11]
	s_waitcnt vmcnt(0) lgkmcnt(0)
	v_and_b32_e32 v17, 0xffff0000, v6
	v_lshlrev_b32_e32 v16, 16, v6
	v_and_b32_e32 v19, 0xffff0000, v8
	v_lshlrev_b32_e32 v18, 16, v8
	v_and_b32_e32 v21, 0xffff0000, v7
	v_lshlrev_b32_e32 v20, 16, v7
	v_and_b32_e32 v7, 0xffff0000, v9
	v_lshlrev_b32_e32 v6, 16, v9
	v_pk_fma_f32 v[2:3], v[2:3], v[18:19], v[16:17]
	v_pk_fma_f32 v[4:5], v[4:5], v[6:7], v[20:21]
	v_cvt_pk_bf16_f32 v2, v2, v3
	v_cvt_pk_bf16_f32 v3, v4, v5
	flat_store_dwordx2 v[12:13], v[2:3]
	v_lshl_add_u64 v[2:3], s[36:37], 0, v[10:11]
	flat_load_dwordx2 v[6:7], v[14:15]
	flat_load_dwordx2 v[8:9], v[2:3]
	v_or_b32_e32 v2, v54, v106
	v_ashrrev_i32_e32 v3, 31, v2
	v_lshlrev_b64 v[2:3], 10, v[2:3]
	v_lshl_add_u64 v[2:3], v[2:3], 0, v[98:99]
	v_lshlrev_b64 v[12:13], 1, v[2:3]
	ds_read_b128 v[2:5], v100 offset:3264
	v_lshl_add_u64 v[10:11], s[28:29], 0, v[10:11]
	v_lshl_add_u64 v[14:15], v[0:1], 0, v[12:13]
	s_waitcnt vmcnt(0) lgkmcnt(0)
	v_and_b32_e32 v17, 0xffff0000, v6
	v_lshlrev_b32_e32 v16, 16, v6
	v_and_b32_e32 v19, 0xffff0000, v8
	v_lshlrev_b32_e32 v18, 16, v8
	v_and_b32_e32 v21, 0xffff0000, v7
	v_lshlrev_b32_e32 v20, 16, v7
	v_and_b32_e32 v7, 0xffff0000, v9
	v_lshlrev_b32_e32 v6, 16, v9
	v_pk_fma_f32 v[2:3], v[2:3], v[18:19], v[16:17]
	v_pk_fma_f32 v[4:5], v[4:5], v[6:7], v[20:21]
	v_cvt_pk_bf16_f32 v2, v2, v3
	v_cvt_pk_bf16_f32 v3, v4, v5
	flat_store_dwordx2 v[10:11], v[2:3]
	v_lshl_add_u64 v[2:3], s[36:37], 0, v[12:13]
	flat_load_dwordx2 v[6:7], v[14:15]
	flat_load_dwordx2 v[8:9], v[2:3]
	v_or_b32_e32 v2, v54, v107
	v_ashrrev_i32_e32 v3, 31, v2
	v_lshlrev_b64 v[2:3], 10, v[2:3]
	v_lshl_add_u64 v[2:3], v[2:3], 0, v[98:99]
	v_lshlrev_b64 v[10:11], 1, v[2:3]
	ds_read_b128 v[2:5], v100 offset:4352
	v_lshl_add_u64 v[12:13], s[28:29], 0, v[12:13]
	v_lshl_add_u64 v[14:15], v[0:1], 0, v[10:11]
	s_waitcnt vmcnt(0) lgkmcnt(0)
	v_and_b32_e32 v17, 0xffff0000, v6
	v_lshlrev_b32_e32 v16, 16, v6
	v_and_b32_e32 v19, 0xffff0000, v8
	v_lshlrev_b32_e32 v18, 16, v8
	v_and_b32_e32 v21, 0xffff0000, v7
	v_lshlrev_b32_e32 v20, 16, v7
	v_and_b32_e32 v7, 0xffff0000, v9
	v_lshlrev_b32_e32 v6, 16, v9
	v_pk_fma_f32 v[2:3], v[2:3], v[18:19], v[16:17]
	v_pk_fma_f32 v[4:5], v[4:5], v[6:7], v[20:21]
	v_cvt_pk_bf16_f32 v2, v2, v3
	v_cvt_pk_bf16_f32 v3, v4, v5
	flat_store_dwordx2 v[12:13], v[2:3]
	v_lshl_add_u64 v[2:3], s[36:37], 0, v[10:11]
	flat_load_dwordx2 v[6:7], v[14:15]
	flat_load_dwordx2 v[8:9], v[2:3]
	v_or_b32_e32 v2, v54, v109
	v_ashrrev_i32_e32 v3, 31, v2
	v_lshlrev_b64 v[2:3], 10, v[2:3]
	v_lshl_add_u64 v[2:3], v[2:3], 0, v[98:99]
	v_lshlrev_b64 v[12:13], 1, v[2:3]
	ds_read_b128 v[2:5], v100 offset:5440
	v_lshl_add_u64 v[10:11], s[28:29], 0, v[10:11]
	v_lshl_add_u64 v[14:15], v[0:1], 0, v[12:13]
	s_waitcnt vmcnt(0) lgkmcnt(0)
	v_and_b32_e32 v17, 0xffff0000, v6
	v_lshlrev_b32_e32 v16, 16, v6
	v_and_b32_e32 v19, 0xffff0000, v8
	v_lshlrev_b32_e32 v18, 16, v8
	v_and_b32_e32 v21, 0xffff0000, v7
	v_lshlrev_b32_e32 v20, 16, v7
	v_and_b32_e32 v7, 0xffff0000, v9
	v_lshlrev_b32_e32 v6, 16, v9
	v_pk_fma_f32 v[2:3], v[2:3], v[18:19], v[16:17]
	v_pk_fma_f32 v[4:5], v[4:5], v[6:7], v[20:21]
	v_cvt_pk_bf16_f32 v2, v2, v3
	v_cvt_pk_bf16_f32 v3, v4, v5
	flat_store_dwordx2 v[10:11], v[2:3]
	v_lshl_add_u64 v[2:3], s[36:37], 0, v[12:13]
	flat_load_dwordx2 v[4:5], v[14:15]
	flat_load_dwordx2 v[6:7], v[2:3]
	v_or_b32_e32 v2, v54, v110
	v_ashrrev_i32_e32 v3, 31, v2
	v_lshlrev_b64 v[2:3], 10, v[2:3]
	v_lshl_add_u64 v[2:3], v[2:3], 0, v[98:99]
	v_lshlrev_b64 v[8:9], 1, v[2:3]
	v_lshl_add_u64 v[10:11], s[28:29], 0, v[12:13]
	v_lshl_add_u64 v[12:13], v[0:1], 0, v[8:9]
	ds_read_b128 v[0:3], v100 offset:6528
	s_waitcnt vmcnt(0) lgkmcnt(0)
	v_and_b32_e32 v15, 0xffff0000, v4
	v_lshlrev_b32_e32 v14, 16, v4
	v_and_b32_e32 v17, 0xffff0000, v6
	v_lshlrev_b32_e32 v16, 16, v6
	v_and_b32_e32 v19, 0xffff0000, v5
	v_lshlrev_b32_e32 v18, 16, v5
	v_and_b32_e32 v5, 0xffff0000, v7
	v_lshlrev_b32_e32 v4, 16, v7
	v_pk_fma_f32 v[0:1], v[0:1], v[16:17], v[14:15]
	v_pk_fma_f32 v[2:3], v[2:3], v[4:5], v[18:19]
	v_cvt_pk_bf16_f32 v0, v0, v1
	v_cvt_pk_bf16_f32 v1, v2, v3
	flat_store_dwordx2 v[10:11], v[0:1]
	v_lshl_add_u64 v[0:1], s[36:37], 0, v[8:9]
	flat_load_dwordx2 v[4:5], v[12:13]
	flat_load_dwordx2 v[6:7], v[0:1]
	ds_read_b128 v[0:3], v100 offset:7616
	v_lshl_add_u64 v[8:9], s[28:29], 0, v[8:9]
	s_waitcnt vmcnt(0) lgkmcnt(0)
	v_and_b32_e32 v11, 0xffff0000, v4
	v_lshlrev_b32_e32 v10, 16, v4
	v_and_b32_e32 v13, 0xffff0000, v6
	v_lshlrev_b32_e32 v12, 16, v6
	v_and_b32_e32 v15, 0xffff0000, v5
	v_lshlrev_b32_e32 v14, 16, v5
	v_and_b32_e32 v5, 0xffff0000, v7
	v_lshlrev_b32_e32 v4, 16, v7
	v_pk_fma_f32 v[0:1], v[0:1], v[12:13], v[10:11]
	v_pk_fma_f32 v[2:3], v[2:3], v[4:5], v[14:15]
	v_cvt_pk_bf16_f32 v0, v0, v1
	v_cvt_pk_bf16_f32 v1, v2, v3
	flat_store_dwordx2 v[8:9], v[0:1]
	s_cbranch_scc0 .LBB0_792

.LBB0_846:
	s_and_b32 s29, s15, 0x10000
	s_xor_b32 s30, s29, 0x10000
	s_add_i32 s29, s29, 0
	s_add_i32 s101, s100, s30
	s_cmpk_eq_i32 s16, 0
	s_cbranch_scc1 .Lg1n_846
	s_waitcnt lgkmcnt(3)
	v_mfma_f32_16x16x32_bf16 v[124:127], v[178:181], v[162:165], v[124:127]
	v_mfma_f32_16x16x32_bf16 v[108:111], v[178:181], v[166:169], v[108:111]
	v_mfma_f32_16x16x32_bf16 v[92:95], v[178:181], v[170:173], v[92:95]
	v_mfma_f32_16x16x32_bf16 v[76:79], v[178:181], v[174:177], v[76:79]
	ds_read_b128 v[240:243], v197
	ds_read_b128 v[244:247], v198
	s_add_i32 m0, s101, 0x4000
	v_lshl_add_u64 v[142:143], v[142:143], 0, s[98:99]
	global_load_lds_dwordx4 v[142:143], off
	s_waitcnt lgkmcnt(4)
	v_mfma_f32_16x16x32_bf16 v[120:123], v[182:185], v[162:165], v[120:123]
	v_mfma_f32_16x16x32_bf16 v[104:107], v[182:185], v[166:169], v[104:107]
	v_mfma_f32_16x16x32_bf16 v[88:91], v[182:185], v[170:173], v[88:91]
	v_mfma_f32_16x16x32_bf16 v[72:75], v[182:185], v[174:177], v[72:75]
	ds_read_b128 v[248:251], v199
	ds_read_b128 v[252:255], v200
	s_add_i32 m0, s101, 0xc000
	v_lshl_add_u64 v[134:135], v[134:135], 0, s[98:99]
	global_load_lds_dwordx4 v[134:135], off
	s_waitcnt lgkmcnt(5)
	v_mfma_f32_16x16x32_bf16 v[116:119], v[186:189], v[162:165], v[116:119]
	v_mfma_f32_16x16x32_bf16 v[100:103], v[186:189], v[166:169], v[100:103]
	v_mfma_f32_16x16x32_bf16 v[84:87], v[186:189], v[170:173], v[84:87]
	v_mfma_f32_16x16x32_bf16 v[68:71], v[186:189], v[174:177], v[68:71]
	s_add_i32 m0, s101, 0x6000
	v_lshl_add_u64 v[140:141], v[140:141], 0, s[98:99]
	global_load_lds_dwordx4 v[140:141], off
	s_waitcnt lgkmcnt(4)
	v_mfma_f32_16x16x32_bf16 v[112:115], v[190:193], v[162:165], v[112:115]
	v_mfma_f32_16x16x32_bf16 v[96:99], v[190:193], v[166:169], v[96:99]
	v_mfma_f32_16x16x32_bf16 v[80:83], v[190:193], v[170:173], v[80:83]
	v_mfma_f32_16x16x32_bf16 v[64:67], v[190:193], v[174:177], v[64:67]
	s_add_i32 m0, s101, 0xe000
	v_lshl_add_u64 v[130:131], v[130:131], 0, s[98:99]
	global_load_lds_dwordx4 v[130:131], off
.Lg2_846:
	ds_read_b128 v[162:165], v161 offset:1024
	ds_read_b128 v[166:169], v194 offset:1024
	ds_read_b128 v[170:173], v195 offset:1024
	ds_read_b128 v[174:177], v196 offset:1024
	s_waitcnt lgkmcnt(4)
	v_mfma_f32_16x16x32_bf16 v[60:63], v[178:181], v[240:243], v[60:63]
	v_mfma_f32_16x16x32_bf16 v[44:47], v[178:181], v[244:247], v[44:47]
	v_mfma_f32_16x16x32_bf16 v[16:19], v[178:181], v[248:251], v[16:19]
	v_mfma_f32_16x16x32_bf16 v[36:39], v[178:181], v[252:255], v[36:39]
	ds_read_b128 v[178:181], v128 offset:33792
	v_mfma_f32_16x16x32_bf16 v[56:59], v[182:185], v[240:243], v[56:59]
	v_mfma_f32_16x16x32_bf16 v[40:43], v[182:185], v[244:247], v[40:43]
	v_mfma_f32_16x16x32_bf16 v[8:11], v[182:185], v[248:251], v[8:11]
	v_mfma_f32_16x16x32_bf16 v[28:31], v[182:185], v[252:255], v[28:31]
	ds_read_b128 v[182:185], v128 offset:35840
	v_mfma_f32_16x16x32_bf16 v[52:55], v[186:189], v[240:243], v[52:55]
	v_mfma_f32_16x16x32_bf16 v[32:35], v[186:189], v[244:247], v[32:35]
	v_mfma_f32_16x16x32_bf16 v[4:7], v[186:189], v[248:251], v[4:7]
	v_mfma_f32_16x16x32_bf16 v[20:23], v[186:189], v[252:255], v[20:23]
	ds_read_b128 v[186:189], v128 offset:37888
	v_mfma_f32_16x16x32_bf16 v[48:51], v[190:193], v[240:243], v[48:51]
	v_mfma_f32_16x16x32_bf16 v[24:27], v[190:193], v[244:247], v[24:27]
	v_mfma_f32_16x16x32_bf16 v[0:3], v[190:193], v[248:251], v[0:3]
	v_mfma_f32_16x16x32_bf16 v[12:15], v[190:193], v[252:255], v[12:15]
	ds_read_b128 v[190:193], v128 offset:39936
	s_waitcnt lgkmcnt(3)
	v_mfma_f32_16x16x32_bf16 v[124:127], v[178:181], v[162:165], v[124:127]
	v_mfma_f32_16x16x32_bf16 v[108:111], v[178:181], v[166:169], v[108:111]
	v_mfma_f32_16x16x32_bf16 v[92:95], v[178:181], v[170:173], v[92:95]
	v_mfma_f32_16x16x32_bf16 v[76:79], v[178:181], v[174:177], v[76:79]
	ds_read_b128 v[240:243], v197 offset:1024
	ds_read_b128 v[244:247], v198 offset:1024
	s_waitcnt lgkmcnt(4)
	v_mfma_f32_16x16x32_bf16 v[120:123], v[182:185], v[162:165], v[120:123]
	v_mfma_f32_16x16x32_bf16 v[104:107], v[182:185], v[166:169], v[104:107]
	v_mfma_f32_16x16x32_bf16 v[88:91], v[182:185], v[170:173], v[88:91]
	v_mfma_f32_16x16x32_bf16 v[72:75], v[182:185], v[174:177], v[72:75]
	ds_read_b128 v[248:251], v199 offset:1024
	ds_read_b128 v[252:255], v200 offset:1024
	s_waitcnt lgkmcnt(5)
	v_mfma_f32_16x16x32_bf16 v[116:119], v[186:189], v[162:165], v[116:119]
	v_mfma_f32_16x16x32_bf16 v[100:103], v[186:189], v[166:169], v[100:103]
	v_mfma_f32_16x16x32_bf16 v[84:87], v[186:189], v[170:173], v[84:87]
	v_mfma_f32_16x16x32_bf16 v[68:71], v[186:189], v[174:177], v[68:71]
	s_waitcnt lgkmcnt(4)
	v_mfma_f32_16x16x32_bf16 v[112:115], v[190:193], v[162:165], v[112:115]
	v_mfma_f32_16x16x32_bf16 v[96:99], v[190:193], v[166:169], v[96:99]
	v_mfma_f32_16x16x32_bf16 v[80:83], v[190:193], v[170:173], v[80:83]
	v_mfma_f32_16x16x32_bf16 v[64:67], v[190:193], v[174:177], v[64:67]
	s_waitcnt vmcnt(0) lgkmcnt(0)
	s_barrier
	s_add_i32 s101, s100, s29
	s_cmpk_eq_i32 s16, 0x700
	s_cbranch_scc1 .Lg4n_846
	v_mfma_f32_16x16x32_bf16 v[60:63], v[178:181], v[240:243], v[60:63]
	v_mfma_f32_16x16x32_bf16 v[44:47], v[178:181], v[244:247], v[44:47]
	v_mfma_f32_16x16x32_bf16 v[16:19], v[178:181], v[248:251], v[16:19]
	v_mfma_f32_16x16x32_bf16 v[36:39], v[178:181], v[252:255], v[36:39]
	v_add3_u32 v128, s30, v150, v151
	ds_read_b128 v[178:181], v128 offset:32768
	v_add3_u32 v161, s30, v150, v152
	v_add3_u32 v194, s30, v154, v153
	v_add3_u32 v195, s30, v154, v155
	v_add3_u32 v196, s30, v154, v156
	ds_read_b128 v[162:165], v161
	ds_read_b128 v[166:169], v194
	ds_read_b128 v[170:173], v195
	ds_read_b128 v[174:177], v196
	s_mov_b32 m0, s101
	v_lshl_add_u64 v[146:147], v[146:147], 0, s[98:99]
	global_load_lds_dwordx4 v[146:147], off
	v_mfma_f32_16x16x32_bf16 v[56:59], v[182:185], v[240:243], v[56:59]
	v_mfma_f32_16x16x32_bf16 v[40:43], v[182:185], v[244:247], v[40:43]
	v_mfma_f32_16x16x32_bf16 v[8:11], v[182:185], v[248:251], v[8:11]
	v_mfma_f32_16x16x32_bf16 v[28:31], v[182:185], v[252:255], v[28:31]
	ds_read_b128 v[182:185], v128 offset:34816
	v_add3_u32 v197, s30, v154, v157
	v_add3_u32 v198, s30, v154, v158
	v_add3_u32 v199, s30, v154, v159
	v_add3_u32 v200, s30, v154, v160
	s_add_i32 m0, s101, 0x8000
	v_lshl_add_u64 v[138:139], v[138:139], 0, s[98:99]
	global_load_lds_dwordx4 v[138:139], off
	v_mfma_f32_16x16x32_bf16 v[52:55], v[186:189], v[240:243], v[52:55]
	v_mfma_f32_16x16x32_bf16 v[32:35], v[186:189], v[244:247], v[32:35]
	v_mfma_f32_16x16x32_bf16 v[4:7], v[186:189], v[248:251], v[4:7]
	v_mfma_f32_16x16x32_bf16 v[20:23], v[186:189], v[252:255], v[20:23]
	ds_read_b128 v[186:189], v128 offset:36864
	s_add_i32 m0, s101, 0x2000
	v_lshl_add_u64 v[144:145], v[144:145], 0, s[98:99]
	global_load_lds_dwordx4 v[144:145], off
	v_mfma_f32_16x16x32_bf16 v[48:51], v[190:193], v[240:243], v[48:51]
	v_mfma_f32_16x16x32_bf16 v[24:27], v[190:193], v[244:247], v[24:27]
	v_mfma_f32_16x16x32_bf16 v[0:3], v[190:193], v[248:251], v[0:3]
	v_mfma_f32_16x16x32_bf16 v[12:15], v[190:193], v[252:255], v[12:15]
	ds_read_b128 v[190:193], v128 offset:38912
	s_add_i32 m0, s101, 0xa000
	v_lshl_add_u64 v[136:137], v[136:137], 0, s[98:99]
	global_load_lds_dwordx4 v[136:137], off
.Ltl_846:
	s_add_i32 s15, s15, 0x10000
	s_add_u32 s16, s16, 0x80
	s_addc_u32 s17, s17, 0
	s_cmpk_lg_i32 s16, 0x780
	s_cbranch_scc1 .LBB0_846
	s_branch .Lex_846
.Lg1n_846:
	s_waitcnt lgkmcnt(3)
	v_mfma_f32_16x16x32_bf16 v[124:127], v[178:181], v[162:165], v[124:127]
	v_mfma_f32_16x16x32_bf16 v[108:111], v[178:181], v[166:169], v[108:111]
	v_mfma_f32_16x16x32_bf16 v[92:95], v[178:181], v[170:173], v[92:95]
	v_mfma_f32_16x16x32_bf16 v[76:79], v[178:181], v[174:177], v[76:79]
	ds_read_b128 v[240:243], v197
	ds_read_b128 v[244:247], v198
	s_waitcnt lgkmcnt(4)
	v_mfma_f32_16x16x32_bf16 v[120:123], v[182:185], v[162:165], v[120:123]
	v_mfma_f32_16x16x32_bf16 v[104:107], v[182:185], v[166:169], v[104:107]
	v_mfma_f32_16x16x32_bf16 v[88:91], v[182:185], v[170:173], v[88:91]
	v_mfma_f32_16x16x32_bf16 v[72:75], v[182:185], v[174:177], v[72:75]
	ds_read_b128 v[248:251], v199
	ds_read_b128 v[252:255], v200
	s_waitcnt lgkmcnt(5)
	v_mfma_f32_16x16x32_bf16 v[116:119], v[186:189], v[162:165], v[116:119]
	v_mfma_f32_16x16x32_bf16 v[100:103], v[186:189], v[166:169], v[100:103]
	v_mfma_f32_16x16x32_bf16 v[84:87], v[186:189], v[170:173], v[84:87]
	v_mfma_f32_16x16x32_bf16 v[68:71], v[186:189], v[174:177], v[68:71]
	s_waitcnt lgkmcnt(4)
	v_mfma_f32_16x16x32_bf16 v[112:115], v[190:193], v[162:165], v[112:115]
	v_mfma_f32_16x16x32_bf16 v[96:99], v[190:193], v[166:169], v[96:99]
	v_mfma_f32_16x16x32_bf16 v[80:83], v[190:193], v[170:173], v[80:83]
	v_mfma_f32_16x16x32_bf16 v[64:67], v[190:193], v[174:177], v[64:67]
	s_branch .Lg2_846
.Lg4n_846:
	v_mfma_f32_16x16x32_bf16 v[60:63], v[178:181], v[240:243], v[60:63]
	v_mfma_f32_16x16x32_bf16 v[44:47], v[178:181], v[244:247], v[44:47]
	v_mfma_f32_16x16x32_bf16 v[16:19], v[178:181], v[248:251], v[16:19]
	v_mfma_f32_16x16x32_bf16 v[36:39], v[178:181], v[252:255], v[36:39]
	v_add3_u32 v128, s30, v150, v151
	ds_read_b128 v[178:181], v128 offset:32768
	v_add3_u32 v161, s30, v150, v152
	v_add3_u32 v194, s30, v154, v153
	v_add3_u32 v195, s30, v154, v155
	v_add3_u32 v196, s30, v154, v156
	ds_read_b128 v[162:165], v161
	ds_read_b128 v[166:169], v194
	ds_read_b128 v[170:173], v195
	ds_read_b128 v[174:177], v196
	v_mfma_f32_16x16x32_bf16 v[56:59], v[182:185], v[240:243], v[56:59]
	v_mfma_f32_16x16x32_bf16 v[40:43], v[182:185], v[244:247], v[40:43]
	v_mfma_f32_16x16x32_bf16 v[8:11], v[182:185], v[248:251], v[8:11]
	v_mfma_f32_16x16x32_bf16 v[28:31], v[182:185], v[252:255], v[28:31]
	ds_read_b128 v[182:185], v128 offset:34816
	v_add3_u32 v197, s30, v154, v157
	v_add3_u32 v198, s30, v154, v158
	v_add3_u32 v199, s30, v154, v159
	v_add3_u32 v200, s30, v154, v160
	v_mfma_f32_16x16x32_bf16 v[52:55], v[186:189], v[240:243], v[52:55]
	v_mfma_f32_16x16x32_bf16 v[32:35], v[186:189], v[244:247], v[32:35]
	v_mfma_f32_16x16x32_bf16 v[4:7], v[186:189], v[248:251], v[4:7]
	v_mfma_f32_16x16x32_bf16 v[20:23], v[186:189], v[252:255], v[20:23]
	ds_read_b128 v[186:189], v128 offset:36864
	v_mfma_f32_16x16x32_bf16 v[48:51], v[190:193], v[240:243], v[48:51]
	v_mfma_f32_16x16x32_bf16 v[24:27], v[190:193], v[244:247], v[24:27]
	v_mfma_f32_16x16x32_bf16 v[0:3], v[190:193], v[248:251], v[0:3]
	v_mfma_f32_16x16x32_bf16 v[12:15], v[190:193], v[252:255], v[12:15]
	ds_read_b128 v[190:193], v128 offset:38912
	s_branch .Ltl_846
.Lex_846:
	s_waitcnt lgkmcnt(0)
	v_add3_u32 v128, s20, v154, v160
	v_add3_u32 v130, s20, v154, v159
	v_add3_u32 v131, s20, v154, v158
	v_add3_u32 v146, s20, v154, v157
	v_add3_u32 v147, s20, v154, v156
	v_add3_u32 v149, s20, v154, v155
	v_add3_u32 v186, s20, v154, v153
	v_add3_u32 v187, s20, v150, v152
	v_add3_u32 v188, s21, v150, v151
	ds_read_b128 v[134:137], v128
	ds_read_b128 v[138:141], v130
	ds_read_b128 v[142:145], v131
	ds_read_b128 v[158:161], v146
	ds_read_b128 v[162:165], v147
	ds_read_b128 v[166:169], v149
	ds_read_b128 v[154:157], v186
	ds_read_b128 v[170:173], v187
	ds_read_b128 v[150:153], v188
	s_waitcnt lgkmcnt(0)
	v_mfma_f32_16x16x32_bf16 v[16:19], v[150:153], v[138:141], v[16:19]
	v_mfma_f32_16x16x32_bf16 v[174:177], v[150:153], v[134:137], v[36:39]
	s_nop 2
	ds_read_b128 v[36:39], v188 offset:2048
	s_waitcnt lgkmcnt(0)
	v_mfma_f32_16x16x32_bf16 v[8:11], v[36:39], v[138:141], v[8:11]
	v_mfma_f32_16x16x32_bf16 v[108:111], v[150:153], v[154:157], v[108:111]
	v_mfma_f32_16x16x32_bf16 v[60:63], v[150:153], v[158:161], v[60:63]
	v_mfma_f32_16x16x32_bf16 v[28:31], v[36:39], v[134:137], v[28:31]
	v_mfma_f32_16x16x32_bf16 v[104:107], v[36:39], v[154:157], v[104:107]
	v_mfma_f32_16x16x32_bf16 v[56:59], v[36:39], v[158:161], v[56:59]
	ds_read_b128 v[178:181], v188 offset:4096
	s_waitcnt lgkmcnt(0)
	v_mfma_f32_16x16x32_bf16 v[182:185], v[178:181], v[134:137], v[20:23]
	v_mfma_f32_16x16x32_bf16 v[100:103], v[178:181], v[154:157], v[100:103]
	v_mfma_f32_16x16x32_bf16 v[52:55], v[178:181], v[158:161], v[52:55]
	s_nop 0
	ds_read_b128 v[20:23], v188 offset:6144
	s_waitcnt lgkmcnt(0)
	v_mfma_f32_16x16x32_bf16 v[134:137], v[20:23], v[134:137], v[12:15]
	v_mfma_f32_16x16x32_bf16 v[12:15], v[20:23], v[170:173], v[112:115]
	v_mfma_f32_16x16x32_bf16 v[96:99], v[20:23], v[154:157], v[96:99]
	v_mfma_f32_16x16x32_bf16 v[112:115], v[20:23], v[162:165], v[64:67]
	v_mfma_f32_16x16x32_bf16 v[64:67], v[178:181], v[170:173], v[116:119]
	v_mfma_f32_16x16x32_bf16 v[116:119], v[178:181], v[162:165], v[68:71]
	v_mfma_f32_16x16x32_bf16 v[68:71], v[36:39], v[170:173], v[120:123]
	v_mfma_f32_16x16x32_bf16 v[120:123], v[36:39], v[162:165], v[72:75]
	v_mfma_f32_16x16x32_bf16 v[72:75], v[150:153], v[170:173], v[124:127]
	v_mfma_f32_16x16x32_bf16 v[124:127], v[150:153], v[162:165], v[76:79]
	v_mfma_f32_16x16x32_bf16 v[48:51], v[20:23], v[158:161], v[48:51]
	v_mfma_f32_16x16x32_bf16 v[154:157], v[150:153], v[142:145], v[44:47]
	v_mfma_f32_16x16x32_bf16 v[158:161], v[36:39], v[142:145], v[40:43]
	v_mfma_f32_16x16x32_bf16 v[162:165], v[178:181], v[142:145], v[32:35]
	v_mfma_f32_16x16x32_bf16 v[24:27], v[20:23], v[142:145], v[24:27]
	v_mfma_f32_16x16x32_bf16 v[142:145], v[178:181], v[138:141], v[4:7]
	v_mfma_f32_16x16x32_bf16 v[92:95], v[150:153], v[166:169], v[92:95]
	v_mfma_f32_16x16x32_bf16 v[88:91], v[36:39], v[166:169], v[88:91]
	v_mfma_f32_16x16x32_bf16 v[84:87], v[178:181], v[166:169], v[84:87]
	v_mfma_f32_16x16x32_bf16 v[80:83], v[20:23], v[166:169], v[80:83]
	v_mfma_f32_16x16x32_bf16 v[20:23], v[20:23], v[138:141], v[0:3]
	ds_read_b128 v[138:141], v188 offset:1024
	ds_read_b128 v[150:153], v188 offset:3072
	ds_read_b128 v[166:169], v188 offset:5120
	ds_read_b128 v[170:173], v188 offset:7168
	ds_read_b128 v[0:3], v187 offset:1024
	ds_read_b128 v[4:7], v186 offset:1024
	ds_read_b128 v[32:35], v149 offset:1024
	ds_read_b128 v[36:39], v147 offset:1024
	s_waitcnt lgkmcnt(3)
	v_mfma_f32_16x16x32_bf16 v[178:181], v[138:141], v[0:3], v[72:75]
	v_mfma_f32_16x16x32_bf16 v[186:189], v[150:153], v[0:3], v[68:71]
	v_mfma_f32_16x16x32_bf16 v[190:193], v[166:169], v[0:3], v[64:67]
	v_mfma_f32_16x16x32_bf16 v[194:197], v[170:173], v[0:3], v[12:15]
	ds_read_b128 v[0:3], v146 offset:1024
	s_waitcnt lgkmcnt(3)
	v_mfma_f32_16x16x32_bf16 v[108:111], v[138:141], v[4:7], v[108:111]
	v_mfma_f32_16x16x32_bf16 v[198:201], v[150:153], v[4:7], v[104:107]
	v_mfma_f32_16x16x32_bf16 v[202:205], v[166:169], v[4:7], v[100:103]
	v_mfma_f32_16x16x32_bf16 v[98:101], v[170:173], v[4:7], v[96:99]
	ds_read_b128 v[4:7], v131 offset:1024
	s_waitcnt lgkmcnt(3)
	v_mfma_f32_16x16x32_bf16 v[64:67], v[138:141], v[32:35], v[92:95]
	v_mfma_f32_16x16x32_bf16 v[68:71], v[150:153], v[32:35], v[88:91]
	v_mfma_f32_16x16x32_bf16 v[72:75], v[166:169], v[32:35], v[84:87]
	v_mfma_f32_16x16x32_bf16 v[76:79], v[170:173], v[32:35], v[80:83]
	ds_read_b128 v[12:15], v130 offset:1024
	s_waitcnt lgkmcnt(3)
	v_mfma_f32_16x16x32_bf16 v[80:83], v[138:141], v[36:39], v[124:127]
	v_mfma_f32_16x16x32_bf16 v[84:87], v[150:153], v[36:39], v[120:123]
	v_mfma_f32_16x16x32_bf16 v[88:91], v[166:169], v[36:39], v[116:119]
	v_mfma_f32_16x16x32_bf16 v[92:95], v[170:173], v[36:39], v[112:115]
	ds_read_b128 v[102:105], v128 offset:1024
	s_waitcnt lgkmcnt(3)
	v_mfma_f32_16x16x32_bf16 v[32:35], v[138:141], v[0:3], v[60:63]
	v_mfma_f32_16x16x32_bf16 v[36:39], v[150:153], v[0:3], v[56:59]
	v_mfma_f32_16x16x32_bf16 v[40:43], v[166:169], v[0:3], v[52:55]
	v_mfma_f32_16x16x32_bf16 v[44:47], v[170:173], v[0:3], v[48:51]
	s_waitcnt lgkmcnt(2)
	v_mfma_f32_16x16x32_bf16 v[48:51], v[138:141], v[4:7], v[154:157]
	v_mfma_f32_16x16x32_bf16 v[52:55], v[150:153], v[4:7], v[158:161]
	v_mfma_f32_16x16x32_bf16 v[56:59], v[166:169], v[4:7], v[162:165]
	v_mfma_f32_16x16x32_bf16 v[60:63], v[170:173], v[4:7], v[24:27]
	s_waitcnt lgkmcnt(1)
	v_mfma_f32_16x16x32_bf16 v[0:3], v[138:141], v[12:15], v[16:19]
	v_mfma_f32_16x16x32_bf16 v[4:7], v[150:153], v[12:15], v[8:11]
	v_mfma_f32_16x16x32_bf16 v[8:11], v[166:169], v[12:15], v[142:145]
	v_mfma_f32_16x16x32_bf16 v[12:15], v[170:173], v[12:15], v[20:23]
	s_waitcnt lgkmcnt(0)
	v_mfma_f32_16x16x32_bf16 v[16:19], v[138:141], v[102:105], v[174:177]
	v_mfma_f32_16x16x32_bf16 v[20:23], v[150:153], v[102:105], v[28:31]
	v_mfma_f32_16x16x32_bf16 v[24:27], v[166:169], v[102:105], v[182:185]
	v_mfma_f32_16x16x32_bf16 v[28:31], v[170:173], v[102:105], v[134:137]
	v_lshrrev_b32_e32 v96, 6, v148
	v_mul_lo_u32 v96, v96, s22
	v_mov_b32_e32 v97, s3
	v_add_u32_e32 v118, s20, v96
	v_lshlrev_b32_e32 v96, 2, v148
	s_waitcnt vmcnt(0)
	s_barrier
	v_and_b32_e32 v102, 63, v132
	v_lshrrev_b32_e32 v103, 6, v132
	v_and_b32_e32 v104, 15, v102
	v_lshrrev_b32_e32 v105, 4, v102
	v_mul_u32_u24_e32 v112, 0x2400, v103
	v_add_u32_e32 v112, 0x10000, v112
	v_mul_u32_u24_e32 v128, 0x110, v104
	v_lshl_add_u32 v128, v105, 4, v128
	v_add_u32_e32 v128, v128, v112
	v_mul_u32_u24_e32 v134, 0x110, v105
	v_lshl_add_u32 v134, v104, 4, v134
	v_add_u32_e32 v134, v134, v112
	v_lshrrev_b32_e32 v113, 2, v103
	v_lshl_add_u32 v113, v113, 7, v105
	v_add_u32_e32 v113, s14, v113
	v_and_b32_e32 v114, 3, v103
	v_lshlrev_b32_e32 v114, 6, v114
	v_lshl_add_u32 v114, v104, 2, v114
	v_add_u32_e32 v114, s12, v114
	v_mov_b32_e32 v130, 0x24000
	ds_read_b64 v[96:97], v130
	v_mov_b32_e32 v130, 0x240a0
	ds_read_b64 v[106:107], v130
	v_mov_b32_e32 v130, 0x240a8
	ds_read_b64 v[124:125], v130
	s_lshr_b32 s100, s14, 12
	s_mul_i32 s100, s100, 0x6000
	s_add_i32 s100, s100, 0x2282000
	s_mov_b64 s[98:99], 0x4000
	v_lshlrev_b32_e32 v130, 12, v113
	v_lshl_add_u32 v130, v114, 2, v130
	v_mov_b32_e32 v131, 0
	s_waitcnt lgkmcnt(0)
	v_lshl_add_u64 v[96:97], v[96:97], 0, v[130:131]
	v_lshl_add_u64 v[106:107], v[106:107], 0, v[130:131]
	v_lshl_add_u32 v130, v114, 2, s100
	v_lshl_add_u64 v[124:125], v[124:125], 0, v[130:131]
	global_load_dwordx4 v[124:127], v[124:125], off
	ds_write_b128 v128, v[178:181]
	ds_write_b128 v128, v[186:189] offset:64
	ds_write_b128 v128, v[190:193] offset:128
	ds_write_b128 v128, v[194:197] offset:192
	ds_write_b128 v128, v[108:111] offset:4352
	ds_write_b128 v128, v[198:201] offset:4416
	ds_write_b128 v128, v[202:205] offset:4480
	ds_write_b128 v128, v[98:101] offset:4544
	s_waitcnt lgkmcnt(0)
	global_load_dwordx4 v[102:105], v[96:97], off nt
	v_lshl_add_u64 v[96:97], v[96:97], 0, s[98:99]
	global_load_dwordx4 v[112:115], v[96:97], off nt
	v_lshl_add_u64 v[96:97], v[96:97], 0, s[98:99]
	global_load_dwordx4 v[116:119], v[96:97], off nt
	v_lshl_add_u64 v[96:97], v[96:97], 0, s[98:99]
	global_load_dwordx4 v[120:123], v[96:97], off nt
	v_lshl_add_u64 v[96:97], v[96:97], 0, s[98:99]
	global_load_dwordx4 v[178:181], v[96:97], off nt
	v_lshl_add_u64 v[96:97], v[96:97], 0, s[98:99]
	global_load_dwordx4 v[186:189], v[96:97], off nt
	v_lshl_add_u64 v[96:97], v[96:97], 0, s[98:99]
	global_load_dwordx4 v[190:193], v[96:97], off nt
	v_lshl_add_u64 v[96:97], v[96:97], 0, s[98:99]
	global_load_dwordx4 v[194:197], v[96:97], off nt
	v_lshl_add_u64 v[96:97], v[96:97], 0, s[98:99]
	ds_read_b128 v[240:243], v134
	s_waitcnt vmcnt(7) lgkmcnt(0)
	v_pk_fma_f32 v[104:105], v[242:243], v[126:127], v[104:105]
	v_pk_fma_f32 v[102:103], v[240:241], v[124:125], v[102:103]
	global_store_dwordx4 v[106:107], v[102:105], off nt
	v_lshl_add_u64 v[106:107], v[106:107], 0, s[98:99]
	ds_read_b128 v[240:243], v134 offset:1088
	s_waitcnt vmcnt(7) lgkmcnt(0)
	v_pk_fma_f32 v[114:115], v[242:243], v[126:127], v[114:115]
	v_pk_fma_f32 v[112:113], v[240:241], v[124:125], v[112:113]
	global_store_dwordx4 v[106:107], v[112:115], off nt
	v_lshl_add_u64 v[106:107], v[106:107], 0, s[98:99]
	ds_read_b128 v[240:243], v134 offset:2176
	s_waitcnt vmcnt(7) lgkmcnt(0)
	v_pk_fma_f32 v[118:119], v[242:243], v[126:127], v[118:119]
	v_pk_fma_f32 v[116:117], v[240:241], v[124:125], v[116:117]
	global_store_dwordx4 v[106:107], v[116:119], off nt
	v_lshl_add_u64 v[106:107], v[106:107], 0, s[98:99]
	ds_read_b128 v[240:243], v134 offset:3264
	s_waitcnt vmcnt(7) lgkmcnt(0)
	v_pk_fma_f32 v[122:123], v[242:243], v[126:127], v[122:123]
	v_pk_fma_f32 v[120:121], v[240:241], v[124:125], v[120:121]
	global_store_dwordx4 v[106:107], v[120:123], off nt
	v_lshl_add_u64 v[106:107], v[106:107], 0, s[98:99]
	global_load_dwordx4 v[102:105], v[96:97], off nt
	v_lshl_add_u64 v[96:97], v[96:97], 0, s[98:99]
	global_load_dwordx4 v[112:115], v[96:97], off nt
	v_lshl_add_u64 v[96:97], v[96:97], 0, s[98:99]
	global_load_dwordx4 v[116:119], v[96:97], off nt
	v_lshl_add_u64 v[96:97], v[96:97], 0, s[98:99]
	global_load_dwordx4 v[120:123], v[96:97], off nt
	v_lshl_add_u64 v[96:97], v[96:97], 0, s[98:99]
	ds_read_b128 v[240:243], v134 offset:4352
	s_waitcnt vmcnt(11) lgkmcnt(0)
	v_pk_fma_f32 v[180:181], v[242:243], v[126:127], v[180:181]
	v_pk_fma_f32 v[178:179], v[240:241], v[124:125], v[178:179]
	global_store_dwordx4 v[106:107], v[178:181], off nt
	v_lshl_add_u64 v[106:107], v[106:107], 0, s[98:99]
	ds_read_b128 v[240:243], v134 offset:5440
	s_waitcnt vmcnt(11) lgkmcnt(0)
	v_pk_fma_f32 v[188:189], v[242:243], v[126:127], v[188:189]
	v_pk_fma_f32 v[186:187], v[240:241], v[124:125], v[186:187]
	global_store_dwordx4 v[106:107], v[186:189], off nt
	v_lshl_add_u64 v[106:107], v[106:107], 0, s[98:99]
	ds_read_b128 v[240:243], v134 offset:6528
	s_waitcnt vmcnt(11) lgkmcnt(0)
	v_pk_fma_f32 v[192:193], v[242:243], v[126:127], v[192:193]
	v_pk_fma_f32 v[190:191], v[240:241], v[124:125], v[190:191]
	global_store_dwordx4 v[106:107], v[190:193], off nt
	v_lshl_add_u64 v[106:107], v[106:107], 0, s[98:99]
	ds_read_b128 v[240:243], v134 offset:7616
	s_waitcnt vmcnt(11) lgkmcnt(0)
	v_pk_fma_f32 v[196:197], v[242:243], v[126:127], v[196:197]
	v_pk_fma_f32 v[194:195], v[240:241], v[124:125], v[194:195]
	global_store_dwordx4 v[106:107], v[194:197], off nt
	v_lshl_add_u64 v[106:107], v[106:107], 0, s[98:99]
	ds_write_b128 v128, v[64:67]
	ds_write_b128 v128, v[68:71] offset:64
	ds_write_b128 v128, v[72:75] offset:128
	ds_write_b128 v128, v[76:79] offset:192
	ds_write_b128 v128, v[80:83] offset:4352
	ds_write_b128 v128, v[84:87] offset:4416
	ds_write_b128 v128, v[88:91] offset:4480
	ds_write_b128 v128, v[92:95] offset:4544
	global_load_dwordx4 v[178:181], v[96:97], off nt
	v_lshl_add_u64 v[96:97], v[96:97], 0, s[98:99]
	global_load_dwordx4 v[186:189], v[96:97], off nt
	v_lshl_add_u64 v[96:97], v[96:97], 0, s[98:99]
	global_load_dwordx4 v[190:193], v[96:97], off nt
	v_lshl_add_u64 v[96:97], v[96:97], 0, s[98:99]
	global_load_dwordx4 v[194:197], v[96:97], off nt
	v_lshl_add_u64 v[96:97], v[96:97], 0, s[98:99]
	ds_read_b128 v[240:243], v134
	s_waitcnt vmcnt(11) lgkmcnt(0)
	v_pk_fma_f32 v[104:105], v[242:243], v[126:127], v[104:105]
	v_pk_fma_f32 v[102:103], v[240:241], v[124:125], v[102:103]
	global_store_dwordx4 v[106:107], v[102:105], off nt
	v_lshl_add_u64 v[106:107], v[106:107], 0, s[98:99]
	ds_read_b128 v[240:243], v134 offset:1088
	s_waitcnt vmcnt(11) lgkmcnt(0)
	v_pk_fma_f32 v[114:115], v[242:243], v[126:127], v[114:115]
	v_pk_fma_f32 v[112:113], v[240:241], v[124:125], v[112:113]
	global_store_dwordx4 v[106:107], v[112:115], off nt
	v_lshl_add_u64 v[106:107], v[106:107], 0, s[98:99]
	ds_read_b128 v[240:243], v134 offset:2176
	s_waitcnt vmcnt(11) lgkmcnt(0)
	v_pk_fma_f32 v[118:119], v[242:243], v[126:127], v[118:119]
	v_pk_fma_f32 v[116:117], v[240:241], v[124:125], v[116:117]
	global_store_dwordx4 v[106:107], v[116:119], off nt
	v_lshl_add_u64 v[106:107], v[106:107], 0, s[98:99]
	ds_read_b128 v[240:243], v134 offset:3264
	s_waitcnt vmcnt(11) lgkmcnt(0)
	v_pk_fma_f32 v[122:123], v[242:243], v[126:127], v[122:123]
	v_pk_fma_f32 v[120:121], v[240:241], v[124:125], v[120:121]
	global_store_dwordx4 v[106:107], v[120:123], off nt
	v_lshl_add_u64 v[106:107], v[106:107], 0, s[98:99]
	global_load_dwordx4 v[102:105], v[96:97], off nt
	v_lshl_add_u64 v[96:97], v[96:97], 0, s[98:99]
	global_load_dwordx4 v[112:115], v[96:97], off nt
	v_lshl_add_u64 v[96:97], v[96:97], 0, s[98:99]
	global_load_dwordx4 v[116:119], v[96:97], off nt
	v_lshl_add_u64 v[96:97], v[96:97], 0, s[98:99]
	global_load_dwordx4 v[120:123], v[96:97], off nt
	v_lshl_add_u64 v[96:97], v[96:97], 0, s[98:99]
	ds_read_b128 v[240:243], v134 offset:4352
	s_waitcnt vmcnt(11) lgkmcnt(0)
	v_pk_fma_f32 v[180:181], v[242:243], v[126:127], v[180:181]
	v_pk_fma_f32 v[178:179], v[240:241], v[124:125], v[178:179]
	global_store_dwordx4 v[106:107], v[178:181], off nt
	v_lshl_add_u64 v[106:107], v[106:107], 0, s[98:99]
	ds_read_b128 v[240:243], v134 offset:5440
	s_waitcnt vmcnt(11) lgkmcnt(0)
	v_pk_fma_f32 v[188:189], v[242:243], v[126:127], v[188:189]
	v_pk_fma_f32 v[186:187], v[240:241], v[124:125], v[186:187]
	global_store_dwordx4 v[106:107], v[186:189], off nt
	v_lshl_add_u64 v[106:107], v[106:107], 0, s[98:99]
	ds_read_b128 v[240:243], v134 offset:6528
	s_waitcnt vmcnt(11) lgkmcnt(0)
	v_pk_fma_f32 v[192:193], v[242:243], v[126:127], v[192:193]
	v_pk_fma_f32 v[190:191], v[240:241], v[124:125], v[190:191]
	global_store_dwordx4 v[106:107], v[190:193], off nt
	v_lshl_add_u64 v[106:107], v[106:107], 0, s[98:99]
	ds_read_b128 v[240:243], v134 offset:7616
	s_waitcnt vmcnt(11) lgkmcnt(0)
	v_pk_fma_f32 v[196:197], v[242:243], v[126:127], v[196:197]
	v_pk_fma_f32 v[194:195], v[240:241], v[124:125], v[194:195]
	global_store_dwordx4 v[106:107], v[194:197], off nt
	v_lshl_add_u64 v[106:107], v[106:107], 0, s[98:99]
	ds_write_b128 v128, v[32:35]
	ds_write_b128 v128, v[36:39] offset:64
	ds_write_b128 v128, v[40:43] offset:128
	ds_write_b128 v128, v[44:47] offset:192
	ds_write_b128 v128, v[48:51] offset:4352
	ds_write_b128 v128, v[52:55] offset:4416
	ds_write_b128 v128, v[56:59] offset:4480
	ds_write_b128 v128, v[60:63] offset:4544
	global_load_dwordx4 v[178:181], v[96:97], off nt
	v_lshl_add_u64 v[96:97], v[96:97], 0, s[98:99]
	global_load_dwordx4 v[186:189], v[96:97], off nt
	v_lshl_add_u64 v[96:97], v[96:97], 0, s[98:99]
	global_load_dwordx4 v[190:193], v[96:97], off nt
	v_lshl_add_u64 v[96:97], v[96:97], 0, s[98:99]
	global_load_dwordx4 v[194:197], v[96:97], off nt
	v_lshl_add_u64 v[96:97], v[96:97], 0, s[98:99]
	ds_read_b128 v[240:243], v134
	s_waitcnt vmcnt(11) lgkmcnt(0)
	v_pk_fma_f32 v[104:105], v[242:243], v[126:127], v[104:105]
	v_pk_fma_f32 v[102:103], v[240:241], v[124:125], v[102:103]
	global_store_dwordx4 v[106:107], v[102:105], off nt
	v_lshl_add_u64 v[106:107], v[106:107], 0, s[98:99]
	ds_read_b128 v[240:243], v134 offset:1088
	s_waitcnt vmcnt(11) lgkmcnt(0)
	v_pk_fma_f32 v[114:115], v[242:243], v[126:127], v[114:115]
	v_pk_fma_f32 v[112:113], v[240:241], v[124:125], v[112:113]
	global_store_dwordx4 v[106:107], v[112:115], off nt
	v_lshl_add_u64 v[106:107], v[106:107], 0, s[98:99]
	ds_read_b128 v[240:243], v134 offset:2176
	s_waitcnt vmcnt(11) lgkmcnt(0)
	v_pk_fma_f32 v[118:119], v[242:243], v[126:127], v[118:119]
	v_pk_fma_f32 v[116:117], v[240:241], v[124:125], v[116:117]
	global_store_dwordx4 v[106:107], v[116:119], off nt
	v_lshl_add_u64 v[106:107], v[106:107], 0, s[98:99]
	ds_read_b128 v[240:243], v134 offset:3264
	s_waitcnt vmcnt(11) lgkmcnt(0)
	v_pk_fma_f32 v[122:123], v[242:243], v[126:127], v[122:123]
	v_pk_fma_f32 v[120:121], v[240:241], v[124:125], v[120:121]
	global_store_dwordx4 v[106:107], v[120:123], off nt
	v_lshl_add_u64 v[106:107], v[106:107], 0, s[98:99]
	global_load_dwordx4 v[102:105], v[96:97], off nt
	v_lshl_add_u64 v[96:97], v[96:97], 0, s[98:99]
	global_load_dwordx4 v[112:115], v[96:97], off nt
	v_lshl_add_u64 v[96:97], v[96:97], 0, s[98:99]
	global_load_dwordx4 v[116:119], v[96:97], off nt
	v_lshl_add_u64 v[96:97], v[96:97], 0, s[98:99]
	global_load_dwordx4 v[120:123], v[96:97], off nt
	v_lshl_add_u64 v[96:97], v[96:97], 0, s[98:99]
	ds_read_b128 v[240:243], v134 offset:4352
	s_waitcnt vmcnt(11) lgkmcnt(0)
	v_pk_fma_f32 v[180:181], v[242:243], v[126:127], v[180:181]
	v_pk_fma_f32 v[178:179], v[240:241], v[124:125], v[178:179]
	global_store_dwordx4 v[106:107], v[178:181], off nt
	v_lshl_add_u64 v[106:107], v[106:107], 0, s[98:99]
	ds_read_b128 v[240:243], v134 offset:5440
	s_waitcnt vmcnt(11) lgkmcnt(0)
	v_pk_fma_f32 v[188:189], v[242:243], v[126:127], v[188:189]
	v_pk_fma_f32 v[186:187], v[240:241], v[124:125], v[186:187]
	global_store_dwordx4 v[106:107], v[186:189], off nt
	v_lshl_add_u64 v[106:107], v[106:107], 0, s[98:99]
	ds_read_b128 v[240:243], v134 offset:6528
	s_waitcnt vmcnt(11) lgkmcnt(0)
	v_pk_fma_f32 v[192:193], v[242:243], v[126:127], v[192:193]
	v_pk_fma_f32 v[190:191], v[240:241], v[124:125], v[190:191]
	global_store_dwordx4 v[106:107], v[190:193], off nt
	v_lshl_add_u64 v[106:107], v[106:107], 0, s[98:99]
	ds_read_b128 v[240:243], v134 offset:7616
	s_waitcnt vmcnt(11) lgkmcnt(0)
	v_pk_fma_f32 v[196:197], v[242:243], v[126:127], v[196:197]
	v_pk_fma_f32 v[194:195], v[240:241], v[124:125], v[194:195]
	global_store_dwordx4 v[106:107], v[194:197], off nt
	v_lshl_add_u64 v[106:107], v[106:107], 0, s[98:99]
	ds_write_b128 v128, v[0:3]
	ds_write_b128 v128, v[4:7] offset:64
	ds_write_b128 v128, v[8:11] offset:128
	ds_write_b128 v128, v[12:15] offset:192
	ds_write_b128 v128, v[16:19] offset:4352
	ds_write_b128 v128, v[20:23] offset:4416
	ds_write_b128 v128, v[24:27] offset:4480
	ds_write_b128 v128, v[28:31] offset:4544
	global_load_dwordx4 v[178:181], v[96:97], off nt
	v_lshl_add_u64 v[96:97], v[96:97], 0, s[98:99]
	global_load_dwordx4 v[186:189], v[96:97], off nt
	v_lshl_add_u64 v[96:97], v[96:97], 0, s[98:99]
	global_load_dwordx4 v[190:193], v[96:97], off nt
	v_lshl_add_u64 v[96:97], v[96:97], 0, s[98:99]
	global_load_dwordx4 v[194:197], v[96:97], off nt
	v_lshl_add_u64 v[96:97], v[96:97], 0, s[98:99]
	ds_read_b128 v[240:243], v134
	s_waitcnt vmcnt(11) lgkmcnt(0)
	v_pk_fma_f32 v[104:105], v[242:243], v[126:127], v[104:105]
	v_pk_fma_f32 v[102:103], v[240:241], v[124:125], v[102:103]
	global_store_dwordx4 v[106:107], v[102:105], off nt
	v_lshl_add_u64 v[106:107], v[106:107], 0, s[98:99]
	ds_read_b128 v[240:243], v134 offset:1088
	s_waitcnt vmcnt(11) lgkmcnt(0)
	v_pk_fma_f32 v[114:115], v[242:243], v[126:127], v[114:115]
	v_pk_fma_f32 v[112:113], v[240:241], v[124:125], v[112:113]
	global_store_dwordx4 v[106:107], v[112:115], off nt
	v_lshl_add_u64 v[106:107], v[106:107], 0, s[98:99]
	ds_read_b128 v[240:243], v134 offset:2176
	s_waitcnt vmcnt(11) lgkmcnt(0)
	v_pk_fma_f32 v[118:119], v[242:243], v[126:127], v[118:119]
	v_pk_fma_f32 v[116:117], v[240:241], v[124:125], v[116:117]
	global_store_dwordx4 v[106:107], v[116:119], off nt
	v_lshl_add_u64 v[106:107], v[106:107], 0, s[98:99]
	ds_read_b128 v[240:243], v134 offset:3264
	s_waitcnt vmcnt(11) lgkmcnt(0)
	v_pk_fma_f32 v[122:123], v[242:243], v[126:127], v[122:123]
	v_pk_fma_f32 v[120:121], v[240:241], v[124:125], v[120:121]
	global_store_dwordx4 v[106:107], v[120:123], off nt
	v_lshl_add_u64 v[106:107], v[106:107], 0, s[98:99]
	ds_read_b128 v[240:243], v134 offset:4352
	s_waitcnt vmcnt(7) lgkmcnt(0)
	v_pk_fma_f32 v[180:181], v[242:243], v[126:127], v[180:181]
	v_pk_fma_f32 v[178:179], v[240:241], v[124:125], v[178:179]
	global_store_dwordx4 v[106:107], v[178:181], off nt
	v_lshl_add_u64 v[106:107], v[106:107], 0, s[98:99]
	ds_read_b128 v[240:243], v134 offset:5440
	s_waitcnt vmcnt(7) lgkmcnt(0)
	v_pk_fma_f32 v[188:189], v[242:243], v[126:127], v[188:189]
	v_pk_fma_f32 v[186:187], v[240:241], v[124:125], v[186:187]
	global_store_dwordx4 v[106:107], v[186:189], off nt
	v_lshl_add_u64 v[106:107], v[106:107], 0, s[98:99]
	ds_read_b128 v[240:243], v134 offset:6528
	s_waitcnt vmcnt(7) lgkmcnt(0)
	v_pk_fma_f32 v[192:193], v[242:243], v[126:127], v[192:193]
	v_pk_fma_f32 v[190:191], v[240:241], v[124:125], v[190:191]
	global_store_dwordx4 v[106:107], v[190:193], off nt
	v_lshl_add_u64 v[106:107], v[106:107], 0, s[98:99]
	ds_read_b128 v[240:243], v134 offset:7616
	s_waitcnt vmcnt(7) lgkmcnt(0)
	v_pk_fma_f32 v[196:197], v[242:243], v[126:127], v[196:197]
	v_pk_fma_f32 v[194:195], v[240:241], v[124:125], v[194:195]
	global_store_dwordx4 v[106:107], v[194:197], off nt
	v_lshl_add_u64 v[106:107], v[106:107], 0, s[98:99]
	s_add_i32 s27, s27, s40
	s_cmpk_gt_i32 s27, 0x1ff
	s_cbranch_scc0 .LBB0_845

.LBB0_942:
	s_and_b32 s17, s15, 0x10000
	s_xor_b32 s42, s17, 0x10000
	s_add_i32 s17, s17, 0
	s_add_i32 s101, s100, s42
	s_cmpk_eq_i32 s18, 0
	s_cbranch_scc1 .Lg1n_942
	s_waitcnt lgkmcnt(3)
	v_mfma_f32_16x16x32_bf16 v[108:111], v[178:181], v[162:165], v[108:111]
	v_mfma_f32_16x16x32_bf16 v[92:95], v[178:181], v[166:169], v[92:95]
	v_mfma_f32_16x16x32_bf16 v[76:79], v[178:181], v[170:173], v[76:79]
	v_mfma_f32_16x16x32_bf16 v[60:63], v[178:181], v[174:177], v[60:63]
	ds_read_b128 v[240:243], v197
	ds_read_b128 v[244:247], v198
	s_add_i32 m0, s101, 0x4000
	v_lshl_add_u64 v[142:143], v[142:143], 0, s[98:99]
	global_load_lds_dwordx4 v[142:143], off
	s_waitcnt lgkmcnt(4)
	v_mfma_f32_16x16x32_bf16 v[104:107], v[182:185], v[162:165], v[104:107]
	v_mfma_f32_16x16x32_bf16 v[88:91], v[182:185], v[166:169], v[88:91]
	v_mfma_f32_16x16x32_bf16 v[72:75], v[182:185], v[170:173], v[72:75]
	v_mfma_f32_16x16x32_bf16 v[56:59], v[182:185], v[174:177], v[56:59]
	ds_read_b128 v[248:251], v199
	ds_read_b128 v[252:255], v200
	s_add_i32 m0, s101, 0xc000
	v_lshl_add_u64 v[134:135], v[134:135], 0, s[98:99]
	global_load_lds_dwordx4 v[134:135], off
	s_waitcnt lgkmcnt(5)
	v_mfma_f32_16x16x32_bf16 v[100:103], v[186:189], v[162:165], v[100:103]
	v_mfma_f32_16x16x32_bf16 v[84:87], v[186:189], v[166:169], v[84:87]
	v_mfma_f32_16x16x32_bf16 v[68:71], v[186:189], v[170:173], v[68:71]
	v_mfma_f32_16x16x32_bf16 v[52:55], v[186:189], v[174:177], v[52:55]
	s_add_i32 m0, s101, 0x6000
	v_lshl_add_u64 v[140:141], v[140:141], 0, s[98:99]
	global_load_lds_dwordx4 v[140:141], off
	s_waitcnt lgkmcnt(4)
	v_mfma_f32_16x16x32_bf16 v[96:99], v[190:193], v[162:165], v[96:99]
	v_mfma_f32_16x16x32_bf16 v[80:83], v[190:193], v[166:169], v[80:83]
	v_mfma_f32_16x16x32_bf16 v[64:67], v[190:193], v[170:173], v[64:67]
	v_mfma_f32_16x16x32_bf16 v[48:51], v[190:193], v[174:177], v[48:51]
	s_add_i32 m0, s101, 0xe000
	v_lshl_add_u64 v[130:131], v[130:131], 0, s[98:99]
	global_load_lds_dwordx4 v[130:131], off
.Lg2_942:
	ds_read_b128 v[162:165], v161 offset:1024
	ds_read_b128 v[166:169], v194 offset:1024
	ds_read_b128 v[170:173], v195 offset:1024
	ds_read_b128 v[174:177], v196 offset:1024
	s_waitcnt lgkmcnt(4)
	v_mfma_f32_16x16x32_bf16 v[44:47], v[178:181], v[240:243], v[44:47]
	v_mfma_f32_16x16x32_bf16 v[28:31], v[178:181], v[244:247], v[28:31]
	v_mfma_f32_16x16x32_bf16 v[12:15], v[178:181], v[248:251], v[12:15]
	v_mfma_f32_16x16x32_bf16 v[112:115], v[178:181], v[252:255], v[112:115]
	ds_read_b128 v[178:181], v128 offset:33792
	v_mfma_f32_16x16x32_bf16 v[40:43], v[182:185], v[240:243], v[40:43]
	v_mfma_f32_16x16x32_bf16 v[24:27], v[182:185], v[244:247], v[24:27]
	v_mfma_f32_16x16x32_bf16 v[8:11], v[182:185], v[248:251], v[8:11]
	v_mfma_f32_16x16x32_bf16 v[116:119], v[182:185], v[252:255], v[116:119]
	ds_read_b128 v[182:185], v128 offset:35840
	v_mfma_f32_16x16x32_bf16 v[36:39], v[186:189], v[240:243], v[36:39]
	v_mfma_f32_16x16x32_bf16 v[20:23], v[186:189], v[244:247], v[20:23]
	v_mfma_f32_16x16x32_bf16 v[4:7], v[186:189], v[248:251], v[4:7]
	v_mfma_f32_16x16x32_bf16 v[120:123], v[186:189], v[252:255], v[120:123]
	ds_read_b128 v[186:189], v128 offset:37888
	v_mfma_f32_16x16x32_bf16 v[32:35], v[190:193], v[240:243], v[32:35]
	v_mfma_f32_16x16x32_bf16 v[16:19], v[190:193], v[244:247], v[16:19]
	v_mfma_f32_16x16x32_bf16 v[0:3], v[190:193], v[248:251], v[0:3]
	v_mfma_f32_16x16x32_bf16 v[124:127], v[190:193], v[252:255], v[124:127]
	ds_read_b128 v[190:193], v128 offset:39936
	s_waitcnt lgkmcnt(3)
	v_mfma_f32_16x16x32_bf16 v[108:111], v[178:181], v[162:165], v[108:111]
	v_mfma_f32_16x16x32_bf16 v[92:95], v[178:181], v[166:169], v[92:95]
	v_mfma_f32_16x16x32_bf16 v[76:79], v[178:181], v[170:173], v[76:79]
	v_mfma_f32_16x16x32_bf16 v[60:63], v[178:181], v[174:177], v[60:63]
	ds_read_b128 v[240:243], v197 offset:1024
	ds_read_b128 v[244:247], v198 offset:1024
	s_waitcnt lgkmcnt(4)
	v_mfma_f32_16x16x32_bf16 v[104:107], v[182:185], v[162:165], v[104:107]
	v_mfma_f32_16x16x32_bf16 v[88:91], v[182:185], v[166:169], v[88:91]
	v_mfma_f32_16x16x32_bf16 v[72:75], v[182:185], v[170:173], v[72:75]
	v_mfma_f32_16x16x32_bf16 v[56:59], v[182:185], v[174:177], v[56:59]
	ds_read_b128 v[248:251], v199 offset:1024
	ds_read_b128 v[252:255], v200 offset:1024
	s_waitcnt lgkmcnt(5)
	v_mfma_f32_16x16x32_bf16 v[100:103], v[186:189], v[162:165], v[100:103]
	v_mfma_f32_16x16x32_bf16 v[84:87], v[186:189], v[166:169], v[84:87]
	v_mfma_f32_16x16x32_bf16 v[68:71], v[186:189], v[170:173], v[68:71]
	v_mfma_f32_16x16x32_bf16 v[52:55], v[186:189], v[174:177], v[52:55]
	s_waitcnt lgkmcnt(4)
	v_mfma_f32_16x16x32_bf16 v[96:99], v[190:193], v[162:165], v[96:99]
	v_mfma_f32_16x16x32_bf16 v[80:83], v[190:193], v[166:169], v[80:83]
	v_mfma_f32_16x16x32_bf16 v[64:67], v[190:193], v[170:173], v[64:67]
	v_mfma_f32_16x16x32_bf16 v[48:51], v[190:193], v[174:177], v[48:51]
	s_waitcnt vmcnt(0) lgkmcnt(0)
	s_barrier
	s_add_i32 s101, s100, s17
	s_cmpk_eq_i32 s18, 0x700
	s_cbranch_scc1 .Lg4n_942
	v_mfma_f32_16x16x32_bf16 v[44:47], v[178:181], v[240:243], v[44:47]
	v_mfma_f32_16x16x32_bf16 v[28:31], v[178:181], v[244:247], v[28:31]
	v_mfma_f32_16x16x32_bf16 v[12:15], v[178:181], v[248:251], v[12:15]
	v_mfma_f32_16x16x32_bf16 v[112:115], v[178:181], v[252:255], v[112:115]
	v_add3_u32 v128, s42, v150, v151
	ds_read_b128 v[178:181], v128 offset:32768
	v_add3_u32 v161, s42, v150, v152
	v_add3_u32 v194, s42, v154, v153
	v_add3_u32 v195, s42, v154, v155
	v_add3_u32 v196, s42, v154, v156
	ds_read_b128 v[162:165], v161
	ds_read_b128 v[166:169], v194
	ds_read_b128 v[170:173], v195
	ds_read_b128 v[174:177], v196
	s_mov_b32 m0, s101
	v_lshl_add_u64 v[146:147], v[146:147], 0, s[98:99]
	global_load_lds_dwordx4 v[146:147], off
	v_mfma_f32_16x16x32_bf16 v[40:43], v[182:185], v[240:243], v[40:43]
	v_mfma_f32_16x16x32_bf16 v[24:27], v[182:185], v[244:247], v[24:27]
	v_mfma_f32_16x16x32_bf16 v[8:11], v[182:185], v[248:251], v[8:11]
	v_mfma_f32_16x16x32_bf16 v[116:119], v[182:185], v[252:255], v[116:119]
	ds_read_b128 v[182:185], v128 offset:34816
	v_add3_u32 v197, s42, v154, v157
	v_add3_u32 v198, s42, v154, v158
	v_add3_u32 v199, s42, v154, v159
	v_add3_u32 v200, s42, v154, v160
	s_add_i32 m0, s101, 0x8000
	v_lshl_add_u64 v[138:139], v[138:139], 0, s[98:99]
	global_load_lds_dwordx4 v[138:139], off
	v_mfma_f32_16x16x32_bf16 v[36:39], v[186:189], v[240:243], v[36:39]
	v_mfma_f32_16x16x32_bf16 v[20:23], v[186:189], v[244:247], v[20:23]
	v_mfma_f32_16x16x32_bf16 v[4:7], v[186:189], v[248:251], v[4:7]
	v_mfma_f32_16x16x32_bf16 v[120:123], v[186:189], v[252:255], v[120:123]
	ds_read_b128 v[186:189], v128 offset:36864
	s_add_i32 m0, s101, 0x2000
	v_lshl_add_u64 v[144:145], v[144:145], 0, s[98:99]
	global_load_lds_dwordx4 v[144:145], off
	v_mfma_f32_16x16x32_bf16 v[32:35], v[190:193], v[240:243], v[32:35]
	v_mfma_f32_16x16x32_bf16 v[16:19], v[190:193], v[244:247], v[16:19]
	v_mfma_f32_16x16x32_bf16 v[0:3], v[190:193], v[248:251], v[0:3]
	v_mfma_f32_16x16x32_bf16 v[124:127], v[190:193], v[252:255], v[124:127]
	ds_read_b128 v[190:193], v128 offset:38912
	s_add_i32 m0, s101, 0xa000
	v_lshl_add_u64 v[136:137], v[136:137], 0, s[98:99]
	global_load_lds_dwordx4 v[136:137], off
.Ltl_942:
	s_add_i32 s15, s15, 0x10000
	s_add_u32 s18, s18, 0x80
	s_addc_u32 s19, s19, 0
	s_cmpk_lg_i32 s18, 0x780
	s_cbranch_scc1 .LBB0_942
	s_branch .Lex_942
.Lg1n_942:
	s_waitcnt lgkmcnt(3)
	v_mfma_f32_16x16x32_bf16 v[108:111], v[178:181], v[162:165], v[108:111]
	v_mfma_f32_16x16x32_bf16 v[92:95], v[178:181], v[166:169], v[92:95]
	v_mfma_f32_16x16x32_bf16 v[76:79], v[178:181], v[170:173], v[76:79]
	v_mfma_f32_16x16x32_bf16 v[60:63], v[178:181], v[174:177], v[60:63]
	ds_read_b128 v[240:243], v197
	ds_read_b128 v[244:247], v198
	s_waitcnt lgkmcnt(4)
	v_mfma_f32_16x16x32_bf16 v[104:107], v[182:185], v[162:165], v[104:107]
	v_mfma_f32_16x16x32_bf16 v[88:91], v[182:185], v[166:169], v[88:91]
	v_mfma_f32_16x16x32_bf16 v[72:75], v[182:185], v[170:173], v[72:75]
	v_mfma_f32_16x16x32_bf16 v[56:59], v[182:185], v[174:177], v[56:59]
	ds_read_b128 v[248:251], v199
	ds_read_b128 v[252:255], v200
	s_waitcnt lgkmcnt(5)
	v_mfma_f32_16x16x32_bf16 v[100:103], v[186:189], v[162:165], v[100:103]
	v_mfma_f32_16x16x32_bf16 v[84:87], v[186:189], v[166:169], v[84:87]
	v_mfma_f32_16x16x32_bf16 v[68:71], v[186:189], v[170:173], v[68:71]
	v_mfma_f32_16x16x32_bf16 v[52:55], v[186:189], v[174:177], v[52:55]
	s_waitcnt lgkmcnt(4)
	v_mfma_f32_16x16x32_bf16 v[96:99], v[190:193], v[162:165], v[96:99]
	v_mfma_f32_16x16x32_bf16 v[80:83], v[190:193], v[166:169], v[80:83]
	v_mfma_f32_16x16x32_bf16 v[64:67], v[190:193], v[170:173], v[64:67]
	v_mfma_f32_16x16x32_bf16 v[48:51], v[190:193], v[174:177], v[48:51]
	s_branch .Lg2_942
.Lg4n_942:
	v_mfma_f32_16x16x32_bf16 v[44:47], v[178:181], v[240:243], v[44:47]
	v_mfma_f32_16x16x32_bf16 v[28:31], v[178:181], v[244:247], v[28:31]
	v_mfma_f32_16x16x32_bf16 v[12:15], v[178:181], v[248:251], v[12:15]
	v_mfma_f32_16x16x32_bf16 v[112:115], v[178:181], v[252:255], v[112:115]
	v_add3_u32 v128, s42, v150, v151
	ds_read_b128 v[178:181], v128 offset:32768
	v_add3_u32 v161, s42, v150, v152
	v_add3_u32 v194, s42, v154, v153
	v_add3_u32 v195, s42, v154, v155
	v_add3_u32 v196, s42, v154, v156
	ds_read_b128 v[162:165], v161
	ds_read_b128 v[166:169], v194
	ds_read_b128 v[170:173], v195
	ds_read_b128 v[174:177], v196
	v_mfma_f32_16x16x32_bf16 v[40:43], v[182:185], v[240:243], v[40:43]
	v_mfma_f32_16x16x32_bf16 v[24:27], v[182:185], v[244:247], v[24:27]
	v_mfma_f32_16x16x32_bf16 v[8:11], v[182:185], v[248:251], v[8:11]
	v_mfma_f32_16x16x32_bf16 v[116:119], v[182:185], v[252:255], v[116:119]
	ds_read_b128 v[182:185], v128 offset:34816
	v_add3_u32 v197, s42, v154, v157
	v_add3_u32 v198, s42, v154, v158
	v_add3_u32 v199, s42, v154, v159
	v_add3_u32 v200, s42, v154, v160
	v_mfma_f32_16x16x32_bf16 v[36:39], v[186:189], v[240:243], v[36:39]
	v_mfma_f32_16x16x32_bf16 v[20:23], v[186:189], v[244:247], v[20:23]
	v_mfma_f32_16x16x32_bf16 v[4:7], v[186:189], v[248:251], v[4:7]
	v_mfma_f32_16x16x32_bf16 v[120:123], v[186:189], v[252:255], v[120:123]
	ds_read_b128 v[186:189], v128 offset:36864
	v_mfma_f32_16x16x32_bf16 v[32:35], v[190:193], v[240:243], v[32:35]
	v_mfma_f32_16x16x32_bf16 v[16:19], v[190:193], v[244:247], v[16:19]
	v_mfma_f32_16x16x32_bf16 v[0:3], v[190:193], v[248:251], v[0:3]
	v_mfma_f32_16x16x32_bf16 v[124:127], v[190:193], v[252:255], v[124:127]
	ds_read_b128 v[190:193], v128 offset:38912
	s_branch .Ltl_942
.Lex_942:
	s_waitcnt lgkmcnt(0)
	v_add3_u32 v128, s24, v154, v160
	v_add3_u32 v130, s24, v154, v159
	v_add3_u32 v131, s24, v154, v158
	v_add3_u32 v146, s24, v154, v157
	v_add3_u32 v147, s24, v154, v156
	v_add3_u32 v149, s24, v154, v155
	v_add3_u32 v186, s24, v154, v153
	v_add3_u32 v187, s24, v150, v152
	v_add3_u32 v188, s26, v150, v151
	ds_read_b128 v[134:137], v128
	ds_read_b128 v[138:141], v130
	ds_read_b128 v[142:145], v131
	ds_read_b128 v[158:161], v146
	ds_read_b128 v[162:165], v147
	ds_read_b128 v[166:169], v149
	ds_read_b128 v[154:157], v186
	ds_read_b128 v[170:173], v187
	ds_read_b128 v[178:181], v188 offset:4096
	s_waitcnt lgkmcnt(0)
	v_mfma_f32_16x16x32_bf16 v[4:7], v[178:181], v[138:141], v[4:7]
	ds_read_b128 v[174:177], v188 offset:2048
	s_waitcnt lgkmcnt(0)
	v_mfma_f32_16x16x32_bf16 v[8:11], v[174:177], v[138:141], v[8:11]
	ds_read_b128 v[150:153], v188
	s_waitcnt lgkmcnt(0)
	v_mfma_f32_16x16x32_bf16 v[12:15], v[150:153], v[138:141], v[12:15]
	v_mfma_f32_16x16x32_bf16 v[112:115], v[150:153], v[134:137], v[112:115]
	v_mfma_f32_16x16x32_bf16 v[108:111], v[150:153], v[170:173], v[108:111]
	v_mfma_f32_16x16x32_bf16 v[92:95], v[150:153], v[154:157], v[92:95]
	v_mfma_f32_16x16x32_bf16 v[76:79], v[150:153], v[166:169], v[76:79]
	v_mfma_f32_16x16x32_bf16 v[116:119], v[174:177], v[134:137], v[116:119]
	v_mfma_f32_16x16x32_bf16 v[104:107], v[174:177], v[170:173], v[104:107]
	v_mfma_f32_16x16x32_bf16 v[88:91], v[174:177], v[154:157], v[88:91]
	v_mfma_f32_16x16x32_bf16 v[72:75], v[174:177], v[166:169], v[72:75]
	v_mfma_f32_16x16x32_bf16 v[120:123], v[178:181], v[134:137], v[120:123]
	v_mfma_f32_16x16x32_bf16 v[100:103], v[178:181], v[170:173], v[100:103]
	v_mfma_f32_16x16x32_bf16 v[84:87], v[178:181], v[154:157], v[84:87]
	v_mfma_f32_16x16x32_bf16 v[68:71], v[178:181], v[166:169], v[68:71]
	ds_read_b128 v[182:185], v188 offset:6144
	s_waitcnt lgkmcnt(0)
	v_mfma_f32_16x16x32_bf16 v[124:127], v[182:185], v[134:137], v[124:127]
	v_mfma_f32_16x16x32_bf16 v[96:99], v[182:185], v[170:173], v[96:99]
	v_mfma_f32_16x16x32_bf16 v[80:83], v[182:185], v[154:157], v[80:83]
	v_mfma_f32_16x16x32_bf16 v[64:67], v[182:185], v[166:169], v[64:67]
	v_mfma_f32_16x16x32_bf16 v[48:51], v[182:185], v[162:165], v[48:51]
	v_mfma_f32_16x16x32_bf16 v[52:55], v[178:181], v[162:165], v[52:55]
	v_mfma_f32_16x16x32_bf16 v[56:59], v[174:177], v[162:165], v[56:59]
	v_mfma_f32_16x16x32_bf16 v[60:63], v[150:153], v[162:165], v[60:63]
	v_mfma_f32_16x16x32_bf16 v[44:47], v[150:153], v[158:161], v[44:47]
	v_mfma_f32_16x16x32_bf16 v[40:43], v[174:177], v[158:161], v[40:43]
	v_mfma_f32_16x16x32_bf16 v[36:39], v[178:181], v[158:161], v[36:39]
	v_mfma_f32_16x16x32_bf16 v[32:35], v[182:185], v[158:161], v[32:35]
	v_mfma_f32_16x16x32_bf16 v[28:31], v[150:153], v[142:145], v[28:31]
	v_mfma_f32_16x16x32_bf16 v[24:27], v[174:177], v[142:145], v[24:27]
	v_mfma_f32_16x16x32_bf16 v[20:23], v[178:181], v[142:145], v[20:23]
	v_mfma_f32_16x16x32_bf16 v[16:19], v[182:185], v[142:145], v[16:19]
	v_mfma_f32_16x16x32_bf16 v[0:3], v[182:185], v[138:141], v[0:3]
	ds_read_b128 v[134:137], v188 offset:1024
	ds_read_b128 v[138:141], v188 offset:3072
	ds_read_b128 v[142:145], v188 offset:5120
	ds_read_b128 v[154:157], v188 offset:7168
	ds_read_b128 v[150:153], v187 offset:1024
	ds_read_b128 v[158:161], v186 offset:1024
	ds_read_b128 v[162:165], v149 offset:1024
	ds_read_b128 v[166:169], v147 offset:1024
	s_waitcnt lgkmcnt(3)
	v_mfma_f32_16x16x32_bf16 v[108:111], v[134:137], v[150:153], v[108:111]
	v_mfma_f32_16x16x32_bf16 v[104:107], v[138:141], v[150:153], v[104:107]
	v_mfma_f32_16x16x32_bf16 v[100:103], v[142:145], v[150:153], v[100:103]
	v_mfma_f32_16x16x32_bf16 v[96:99], v[154:157], v[150:153], v[96:99]
	ds_read_b128 v[150:153], v146 offset:1024
	s_waitcnt lgkmcnt(3)
	v_mfma_f32_16x16x32_bf16 v[92:95], v[134:137], v[158:161], v[92:95]
	v_mfma_f32_16x16x32_bf16 v[88:91], v[138:141], v[158:161], v[88:91]
	v_mfma_f32_16x16x32_bf16 v[84:87], v[142:145], v[158:161], v[84:87]
	v_mfma_f32_16x16x32_bf16 v[80:83], v[154:157], v[158:161], v[80:83]
	ds_read_b128 v[158:161], v131 offset:1024
	s_waitcnt lgkmcnt(3)
	v_mfma_f32_16x16x32_bf16 v[76:79], v[134:137], v[162:165], v[76:79]
	v_mfma_f32_16x16x32_bf16 v[72:75], v[138:141], v[162:165], v[72:75]
	v_mfma_f32_16x16x32_bf16 v[68:71], v[142:145], v[162:165], v[68:71]
	v_mfma_f32_16x16x32_bf16 v[64:67], v[154:157], v[162:165], v[64:67]
	ds_read_b128 v[162:165], v130 offset:1024
	s_waitcnt lgkmcnt(3)
	v_mfma_f32_16x16x32_bf16 v[60:63], v[134:137], v[166:169], v[60:63]
	v_mfma_f32_16x16x32_bf16 v[56:59], v[138:141], v[166:169], v[56:59]
	v_mfma_f32_16x16x32_bf16 v[52:55], v[142:145], v[166:169], v[52:55]
	v_mfma_f32_16x16x32_bf16 v[48:51], v[154:157], v[166:169], v[48:51]
	ds_read_b128 v[166:169], v128 offset:1024
	s_waitcnt lgkmcnt(3)
	v_mfma_f32_16x16x32_bf16 v[44:47], v[134:137], v[150:153], v[44:47]
	v_mfma_f32_16x16x32_bf16 v[40:43], v[138:141], v[150:153], v[40:43]
	v_mfma_f32_16x16x32_bf16 v[36:39], v[142:145], v[150:153], v[36:39]
	v_mfma_f32_16x16x32_bf16 v[32:35], v[154:157], v[150:153], v[32:35]
	s_waitcnt lgkmcnt(2)
	v_mfma_f32_16x16x32_bf16 v[28:31], v[134:137], v[158:161], v[28:31]
	v_mfma_f32_16x16x32_bf16 v[24:27], v[138:141], v[158:161], v[24:27]
	v_mfma_f32_16x16x32_bf16 v[20:23], v[142:145], v[158:161], v[20:23]
	v_mfma_f32_16x16x32_bf16 v[16:19], v[154:157], v[158:161], v[16:19]
	s_waitcnt lgkmcnt(1)
	v_mfma_f32_16x16x32_bf16 v[12:15], v[134:137], v[162:165], v[12:15]
	v_mfma_f32_16x16x32_bf16 v[8:11], v[138:141], v[162:165], v[8:11]
	v_mfma_f32_16x16x32_bf16 v[4:7], v[142:145], v[162:165], v[4:7]
	v_mfma_f32_16x16x32_bf16 v[0:3], v[154:157], v[162:165], v[0:3]
	s_waitcnt lgkmcnt(0)
	v_mfma_f32_16x16x32_bf16 v[112:115], v[134:137], v[166:169], v[112:115]
	v_mfma_f32_16x16x32_bf16 v[116:119], v[138:141], v[166:169], v[116:119]
	v_mfma_f32_16x16x32_bf16 v[120:123], v[142:145], v[166:169], v[120:123]
	v_mfma_f32_16x16x32_bf16 v[124:127], v[154:157], v[166:169], v[124:127]
	v_mov_b32_e32 v128, s3
	s_waitcnt vmcnt(0)
	s_barrier
	ds_read_b64 v[130:131], v128
	v_ashrrev_i32_e32 v128, 1, v148
	v_and_b32_e32 v128, 0xffffff80, v128
	v_add_u32_e32 v128, s16, v128
	s_ashr_i32 s15, s14, 31
	s_waitcnt lgkmcnt(0)
	v_mad_i64_i32 v[130:131], s[16:17], v128, s23, v[130:131]
	v_and_b32_e32 v128, 0xc0, v148
	v_lshrrev_b32_e32 v135, 6, v148
	v_lshl_add_u64 v[130:131], s[14:15], 1, v[130:131]
	v_lshlrev_b32_e32 v128, 1, v128
	v_lshl_add_u64 v[130:131], v[130:131], 0, v[128:129]
	v_mul_lo_u32 v128, v135, s27
	v_add_u32_e32 v135, s24, v128
	v_lshrrev_b32_e32 v128, 1, v148
	v_and_b32_e32 v136, 24, v128
	v_lshlrev_b32_e32 v128, 4, v148
	v_bfe_u32 v137, v148, 3, 3
	v_and_b32_e32 v134, 15, v148
	v_and_b32_e32 v128, 0x70, v128
	v_mul_u32_u24_e32 v138, 0x90, v137
	v_lshl_add_u64 v[130:131], v[130:131], 0, v[128:129]
	v_add3_u32 v138, v135, v128, v138
	v_mul_u32_u24_e32 v128, 0x90, v134
	v_add3_u32 v134, v135, v136, v128
	v_cvt_pk_bf16_f32 v108, v108, v109
	v_cvt_pk_bf16_f32 v109, v110, v111
	v_cvt_pk_bf16_f32 v104, v104, v105
	v_cvt_pk_bf16_f32 v105, v106, v107
	v_cvt_pk_bf16_f32 v100, v100, v101
	v_cvt_pk_bf16_f32 v101, v102, v103
	v_cvt_pk_bf16_f32 v96, v96, v97
	v_cvt_pk_bf16_f32 v97, v98, v99
	v_cvt_pk_bf16_f32 v92, v92, v93
	v_cvt_pk_bf16_f32 v93, v94, v95
	v_cvt_pk_bf16_f32 v88, v88, v89
	v_cvt_pk_bf16_f32 v89, v90, v91
	v_cvt_pk_bf16_f32 v84, v84, v85
	v_cvt_pk_bf16_f32 v85, v86, v87
	v_cvt_pk_bf16_f32 v80, v80, v81
	v_cvt_pk_bf16_f32 v81, v82, v83
	v_cvt_pk_bf16_f32 v76, v76, v77
	v_cvt_pk_bf16_f32 v77, v78, v79
	v_cvt_pk_bf16_f32 v72, v72, v73
	v_cvt_pk_bf16_f32 v73, v74, v75
	v_cvt_pk_bf16_f32 v68, v68, v69
	v_cvt_pk_bf16_f32 v69, v70, v71
	v_cvt_pk_bf16_f32 v64, v64, v65
	v_cvt_pk_bf16_f32 v65, v66, v67
	v_cvt_pk_bf16_f32 v60, v60, v61
	v_cvt_pk_bf16_f32 v61, v62, v63
	v_cvt_pk_bf16_f32 v56, v56, v57
	v_cvt_pk_bf16_f32 v57, v58, v59
	v_cvt_pk_bf16_f32 v52, v52, v53
	v_cvt_pk_bf16_f32 v53, v54, v55
	v_cvt_pk_bf16_f32 v48, v48, v49
	v_cvt_pk_bf16_f32 v49, v50, v51
	ds_write_b64 v134, v[108:109]
	ds_write_b64 v134, v[104:105] offset:32
	ds_write_b64 v134, v[100:101] offset:64
	ds_write_b64 v134, v[96:97] offset:96
	ds_write_b64 v134, v[92:93] offset:2304
	ds_write_b64 v134, v[88:89] offset:2336
	ds_write_b64 v134, v[84:85] offset:2368
	ds_write_b64 v134, v[80:81] offset:2400
	ds_write_b64 v134, v[76:77] offset:4608
	ds_write_b64 v134, v[72:73] offset:4640
	ds_write_b64 v134, v[68:69] offset:4672
	ds_write_b64 v134, v[64:65] offset:4704
	ds_write_b64 v134, v[60:61] offset:6912
	ds_write_b64 v134, v[56:57] offset:6944
	ds_write_b64 v134, v[52:53] offset:6976
	ds_write_b64 v134, v[48:49] offset:7008
	ds_read_b128 v[48:51], v138
	v_mul_u32_u24_e32 v54, 0xc00, v137
	v_lshl_add_u64 v[52:53], v[130:131], 0, s[12:13]
	v_lshlrev_b32_e32 v128, 1, v54
	v_lshl_add_u64 v[54:55], v[52:53], 0, v[128:129]
	s_waitcnt lgkmcnt(0)
	flat_store_dwordx4 v[54:55], v[48:51] nt
	ds_read_b128 v[48:51], v138 offset:1152
	v_add_co_u32_e32 v56, vcc, s21, v54
	v_cvt_pk_bf16_f32 v0, v0, v1
	s_nop 0
	v_addc_co_u32_e32 v57, vcc, 0, v55, vcc
	s_waitcnt lgkmcnt(0)
	flat_store_dwordx4 v[56:57], v[48:51] nt
	ds_read_b128 v[48:51], v138 offset:2304
	v_add_co_u32_e32 v56, vcc, s25, v54
	v_cvt_pk_bf16_f32 v1, v2, v3
	s_nop 0
	v_addc_co_u32_e32 v57, vcc, 0, v55, vcc
	s_waitcnt lgkmcnt(0)
	flat_store_dwordx4 v[56:57], v[48:51] nt
	ds_read_b128 v[48:51], v138 offset:3456
	v_add_co_u32_e32 v56, vcc, s28, v54
	v_cvt_pk_bf16_f32 v44, v44, v45
	s_nop 0
	v_addc_co_u32_e32 v57, vcc, 0, v55, vcc
	s_waitcnt lgkmcnt(0)
	flat_store_dwordx4 v[56:57], v[48:51] nt
	ds_read_b128 v[48:51], v138 offset:4608
	v_or_b32_e32 v56, 0x30000, v128
	v_mov_b32_e32 v57, v129
	v_lshl_add_u64 v[56:57], v[52:53], 0, v[56:57]
	v_cvt_pk_bf16_f32 v45, v46, v47
	s_waitcnt lgkmcnt(0)
	flat_store_dwordx4 v[56:57], v[48:51] nt
	ds_read_b128 v[48:51], v138 offset:5760
	v_add_u32_e32 v56, 0x3c000, v128
	v_mov_b32_e32 v57, v129
	v_lshl_add_u64 v[56:57], v[52:53], 0, v[56:57]
	v_cvt_pk_bf16_f32 v40, v40, v41
	s_waitcnt lgkmcnt(0)
	flat_store_dwordx4 v[56:57], v[48:51] nt
	ds_read_b128 v[48:51], v138 offset:6912
	v_add_u32_e32 v56, 0x48000, v128
	v_mov_b32_e32 v57, v129
	v_lshl_add_u64 v[56:57], v[52:53], 0, v[56:57]
	v_add_u32_e32 v128, 0x54000, v128
	s_waitcnt lgkmcnt(0)
	flat_store_dwordx4 v[56:57], v[48:51] nt
	ds_read_b128 v[48:51], v138 offset:8064
	v_lshl_add_u64 v[52:53], v[52:53], 0, v[128:129]
	v_cvt_pk_bf16_f32 v41, v42, v43
	v_cvt_pk_bf16_f32 v36, v36, v37
	v_cvt_pk_bf16_f32 v37, v38, v39
	s_waitcnt lgkmcnt(0)
	flat_store_dwordx4 v[52:53], v[48:51] nt
	ds_write_b64 v134, v[0:1] offset:4704
	v_cvt_pk_bf16_f32 v0, v112, v113
	v_cvt_pk_bf16_f32 v1, v114, v115
	ds_write_b64 v134, v[0:1] offset:6912
	v_cvt_pk_bf16_f32 v0, v116, v117
	v_cvt_pk_bf16_f32 v1, v118, v119
	ds_write_b64 v134, v[0:1] offset:6944
	v_cvt_pk_bf16_f32 v0, v120, v121
	v_cvt_pk_bf16_f32 v1, v122, v123
	v_cvt_pk_bf16_f32 v32, v32, v33
	v_cvt_pk_bf16_f32 v33, v34, v35
	v_cvt_pk_bf16_f32 v28, v28, v29
	v_cvt_pk_bf16_f32 v29, v30, v31
	v_cvt_pk_bf16_f32 v24, v24, v25
	v_cvt_pk_bf16_f32 v25, v26, v27
	v_cvt_pk_bf16_f32 v20, v20, v21
	v_cvt_pk_bf16_f32 v21, v22, v23
	v_cvt_pk_bf16_f32 v16, v16, v17
	v_cvt_pk_bf16_f32 v17, v18, v19
	v_cvt_pk_bf16_f32 v12, v12, v13
	v_cvt_pk_bf16_f32 v13, v14, v15
	v_cvt_pk_bf16_f32 v8, v8, v9
	v_cvt_pk_bf16_f32 v9, v10, v11
	v_cvt_pk_bf16_f32 v4, v4, v5
	v_cvt_pk_bf16_f32 v5, v6, v7
	ds_write_b64 v134, v[0:1] offset:6976
	v_cvt_pk_bf16_f32 v0, v124, v125
	v_cvt_pk_bf16_f32 v1, v126, v127
	ds_write_b64 v134, v[44:45]
	ds_write_b64 v134, v[40:41] offset:32
	ds_write_b64 v134, v[36:37] offset:64
	ds_write_b64 v134, v[32:33] offset:96
	ds_write_b64 v134, v[28:29] offset:2304
	ds_write_b64 v134, v[24:25] offset:2336
	ds_write_b64 v134, v[20:21] offset:2368
	ds_write_b64 v134, v[16:17] offset:2400
	ds_write_b64 v134, v[12:13] offset:4608
	ds_write_b64 v134, v[8:9] offset:4640
	ds_write_b64 v134, v[4:5] offset:4672
	ds_write_b64 v134, v[0:1] offset:7008
	ds_read_b128 v[0:3], v138
	v_add_co_u32_e32 v4, vcc, s29, v54
	s_add_i32 s39, s39, s40
	s_nop 0
	v_addc_co_u32_e32 v5, vcc, 0, v55, vcc
	s_waitcnt lgkmcnt(0)
	flat_store_dwordx4 v[4:5], v[0:3] nt
	ds_read_b128 v[0:3], v138 offset:1152
	v_add_co_u32_e32 v4, vcc, s30, v54
	s_cmpk_gt_i32 s39, 0x5ff
	s_nop 0
	v_addc_co_u32_e32 v5, vcc, 0, v55, vcc
	s_waitcnt lgkmcnt(0)
	flat_store_dwordx4 v[4:5], v[0:3] nt
	ds_read_b128 v[0:3], v138 offset:2304
	v_add_co_u32_e32 v4, vcc, s31, v54
	s_nop 1
	v_addc_co_u32_e32 v5, vcc, 0, v55, vcc
	s_waitcnt lgkmcnt(0)
	flat_store_dwordx4 v[4:5], v[0:3] nt
	ds_read_b128 v[0:3], v138 offset:3456
	v_add_co_u32_e32 v4, vcc, s34, v54
	s_nop 1
	v_addc_co_u32_e32 v5, vcc, 0, v55, vcc
	s_waitcnt lgkmcnt(0)
	flat_store_dwordx4 v[4:5], v[0:3] nt
	ds_read_b128 v[0:3], v138 offset:4608
	v_add_co_u32_e32 v4, vcc, s35, v54
	s_nop 1
	v_addc_co_u32_e32 v5, vcc, 0, v55, vcc
	s_waitcnt lgkmcnt(0)
	flat_store_dwordx4 v[4:5], v[0:3] nt
	ds_read_b128 v[0:3], v138 offset:5760
	v_add_co_u32_e32 v4, vcc, s38, v54
	s_nop 1
	v_addc_co_u32_e32 v5, vcc, 0, v55, vcc
	s_waitcnt lgkmcnt(0)
	flat_store_dwordx4 v[4:5], v[0:3] nt
	ds_read_b128 v[0:3], v138 offset:6912
	v_add_co_u32_e32 v4, vcc, 0xa8000, v54
	s_nop 1
	v_addc_co_u32_e32 v5, vcc, 0, v55, vcc
	s_waitcnt lgkmcnt(0)
	flat_store_dwordx4 v[4:5], v[0:3] nt
	ds_read_b128 v[0:3], v138 offset:8064
	v_add_co_u32_e32 v4, vcc, 0xb4000, v54
	s_nop 1
	v_addc_co_u32_e32 v5, vcc, 0, v55, vcc
	s_waitcnt lgkmcnt(0)
	flat_store_dwordx4 v[4:5], v[0:3] nt
	s_cbranch_scc0 .LBB0_941

.LBB0_1040:
	s_and_b32 s17, s15, 0x10000
	s_xor_b32 s43, s17, 0x10000
	s_add_i32 s17, s17, 0
	s_add_i32 s101, s100, s43
	s_cmpk_eq_i32 s18, 0
	s_cbranch_scc1 .Lg1n_1040
	s_waitcnt lgkmcnt(3)
	v_mfma_f32_16x16x32_bf16 v[108:111], v[178:181], v[162:165], v[108:111]
	v_mfma_f32_16x16x32_bf16 v[92:95], v[178:181], v[166:169], v[92:95]
	v_mfma_f32_16x16x32_bf16 v[76:79], v[178:181], v[170:173], v[76:79]
	v_mfma_f32_16x16x32_bf16 v[60:63], v[178:181], v[174:177], v[60:63]
	ds_read_b128 v[240:243], v197
	ds_read_b128 v[244:247], v198
	s_add_i32 m0, s101, 0x4000
	v_lshl_add_u64 v[142:143], v[142:143], 0, s[98:99]
	global_load_lds_dwordx4 v[142:143], off
	s_waitcnt lgkmcnt(4)
	v_mfma_f32_16x16x32_bf16 v[104:107], v[182:185], v[162:165], v[104:107]
	v_mfma_f32_16x16x32_bf16 v[88:91], v[182:185], v[166:169], v[88:91]
	v_mfma_f32_16x16x32_bf16 v[72:75], v[182:185], v[170:173], v[72:75]
	v_mfma_f32_16x16x32_bf16 v[56:59], v[182:185], v[174:177], v[56:59]
	ds_read_b128 v[248:251], v199
	ds_read_b128 v[252:255], v200
	s_add_i32 m0, s101, 0xc000
	v_lshl_add_u64 v[134:135], v[134:135], 0, s[98:99]
	global_load_lds_dwordx4 v[134:135], off
	s_waitcnt lgkmcnt(5)
	v_mfma_f32_16x16x32_bf16 v[100:103], v[186:189], v[162:165], v[100:103]
	v_mfma_f32_16x16x32_bf16 v[84:87], v[186:189], v[166:169], v[84:87]
	v_mfma_f32_16x16x32_bf16 v[68:71], v[186:189], v[170:173], v[68:71]
	v_mfma_f32_16x16x32_bf16 v[52:55], v[186:189], v[174:177], v[52:55]
	s_add_i32 m0, s101, 0x6000
	v_lshl_add_u64 v[140:141], v[140:141], 0, s[98:99]
	global_load_lds_dwordx4 v[140:141], off
	s_waitcnt lgkmcnt(4)
	v_mfma_f32_16x16x32_bf16 v[96:99], v[190:193], v[162:165], v[96:99]
	v_mfma_f32_16x16x32_bf16 v[80:83], v[190:193], v[166:169], v[80:83]
	v_mfma_f32_16x16x32_bf16 v[64:67], v[190:193], v[170:173], v[64:67]
	v_mfma_f32_16x16x32_bf16 v[48:51], v[190:193], v[174:177], v[48:51]
	s_add_i32 m0, s101, 0xe000
	v_lshl_add_u64 v[130:131], v[130:131], 0, s[98:99]
	global_load_lds_dwordx4 v[130:131], off
.Lg2_1040:
	ds_read_b128 v[162:165], v161 offset:1024
	ds_read_b128 v[166:169], v194 offset:1024
	ds_read_b128 v[170:173], v195 offset:1024
	ds_read_b128 v[174:177], v196 offset:1024
	s_waitcnt lgkmcnt(4)
	v_mfma_f32_16x16x32_bf16 v[44:47], v[178:181], v[240:243], v[44:47]
	v_mfma_f32_16x16x32_bf16 v[28:31], v[178:181], v[244:247], v[28:31]
	v_mfma_f32_16x16x32_bf16 v[12:15], v[178:181], v[248:251], v[12:15]
	v_mfma_f32_16x16x32_bf16 v[112:115], v[178:181], v[252:255], v[112:115]
	ds_read_b128 v[178:181], v128 offset:33792
	v_mfma_f32_16x16x32_bf16 v[40:43], v[182:185], v[240:243], v[40:43]
	v_mfma_f32_16x16x32_bf16 v[24:27], v[182:185], v[244:247], v[24:27]
	v_mfma_f32_16x16x32_bf16 v[8:11], v[182:185], v[248:251], v[8:11]
	v_mfma_f32_16x16x32_bf16 v[116:119], v[182:185], v[252:255], v[116:119]
	ds_read_b128 v[182:185], v128 offset:35840
	v_mfma_f32_16x16x32_bf16 v[36:39], v[186:189], v[240:243], v[36:39]
	v_mfma_f32_16x16x32_bf16 v[20:23], v[186:189], v[244:247], v[20:23]
	v_mfma_f32_16x16x32_bf16 v[4:7], v[186:189], v[248:251], v[4:7]
	v_mfma_f32_16x16x32_bf16 v[120:123], v[186:189], v[252:255], v[120:123]
	ds_read_b128 v[186:189], v128 offset:37888
	v_mfma_f32_16x16x32_bf16 v[32:35], v[190:193], v[240:243], v[32:35]
	v_mfma_f32_16x16x32_bf16 v[16:19], v[190:193], v[244:247], v[16:19]
	v_mfma_f32_16x16x32_bf16 v[0:3], v[190:193], v[248:251], v[0:3]
	v_mfma_f32_16x16x32_bf16 v[124:127], v[190:193], v[252:255], v[124:127]
	ds_read_b128 v[190:193], v128 offset:39936
	s_waitcnt lgkmcnt(3)
	v_mfma_f32_16x16x32_bf16 v[108:111], v[178:181], v[162:165], v[108:111]
	v_mfma_f32_16x16x32_bf16 v[92:95], v[178:181], v[166:169], v[92:95]
	v_mfma_f32_16x16x32_bf16 v[76:79], v[178:181], v[170:173], v[76:79]
	v_mfma_f32_16x16x32_bf16 v[60:63], v[178:181], v[174:177], v[60:63]
	ds_read_b128 v[240:243], v197 offset:1024
	ds_read_b128 v[244:247], v198 offset:1024
	s_waitcnt lgkmcnt(4)
	v_mfma_f32_16x16x32_bf16 v[104:107], v[182:185], v[162:165], v[104:107]
	v_mfma_f32_16x16x32_bf16 v[88:91], v[182:185], v[166:169], v[88:91]
	v_mfma_f32_16x16x32_bf16 v[72:75], v[182:185], v[170:173], v[72:75]
	v_mfma_f32_16x16x32_bf16 v[56:59], v[182:185], v[174:177], v[56:59]
	ds_read_b128 v[248:251], v199 offset:1024
	ds_read_b128 v[252:255], v200 offset:1024
	s_waitcnt lgkmcnt(5)
	v_mfma_f32_16x16x32_bf16 v[100:103], v[186:189], v[162:165], v[100:103]
	v_mfma_f32_16x16x32_bf16 v[84:87], v[186:189], v[166:169], v[84:87]
	v_mfma_f32_16x16x32_bf16 v[68:71], v[186:189], v[170:173], v[68:71]
	v_mfma_f32_16x16x32_bf16 v[52:55], v[186:189], v[174:177], v[52:55]
	s_waitcnt lgkmcnt(4)
	v_mfma_f32_16x16x32_bf16 v[96:99], v[190:193], v[162:165], v[96:99]
	v_mfma_f32_16x16x32_bf16 v[80:83], v[190:193], v[166:169], v[80:83]
	v_mfma_f32_16x16x32_bf16 v[64:67], v[190:193], v[170:173], v[64:67]
	v_mfma_f32_16x16x32_bf16 v[48:51], v[190:193], v[174:177], v[48:51]
	s_waitcnt vmcnt(0) lgkmcnt(0)
	s_barrier
	s_add_i32 s101, s100, s17
	s_cmpk_eq_i32 s18, 0x700
	s_cbranch_scc1 .Lg4n_1040
	v_mfma_f32_16x16x32_bf16 v[44:47], v[178:181], v[240:243], v[44:47]
	v_mfma_f32_16x16x32_bf16 v[28:31], v[178:181], v[244:247], v[28:31]
	v_mfma_f32_16x16x32_bf16 v[12:15], v[178:181], v[248:251], v[12:15]
	v_mfma_f32_16x16x32_bf16 v[112:115], v[178:181], v[252:255], v[112:115]
	v_add3_u32 v128, s43, v150, v151
	ds_read_b128 v[178:181], v128 offset:32768
	v_add3_u32 v161, s43, v150, v152
	v_add3_u32 v194, s43, v154, v153
	v_add3_u32 v195, s43, v154, v155
	v_add3_u32 v196, s43, v154, v156
	ds_read_b128 v[162:165], v161
	ds_read_b128 v[166:169], v194
	ds_read_b128 v[170:173], v195
	ds_read_b128 v[174:177], v196
	s_mov_b32 m0, s101
	v_lshl_add_u64 v[146:147], v[146:147], 0, s[98:99]
	global_load_lds_dwordx4 v[146:147], off
	v_mfma_f32_16x16x32_bf16 v[40:43], v[182:185], v[240:243], v[40:43]
	v_mfma_f32_16x16x32_bf16 v[24:27], v[182:185], v[244:247], v[24:27]
	v_mfma_f32_16x16x32_bf16 v[8:11], v[182:185], v[248:251], v[8:11]
	v_mfma_f32_16x16x32_bf16 v[116:119], v[182:185], v[252:255], v[116:119]
	ds_read_b128 v[182:185], v128 offset:34816
	v_add3_u32 v197, s43, v154, v157
	v_add3_u32 v198, s43, v154, v158
	v_add3_u32 v199, s43, v154, v159
	v_add3_u32 v200, s43, v154, v160
	s_add_i32 m0, s101, 0x8000
	v_lshl_add_u64 v[138:139], v[138:139], 0, s[98:99]
	global_load_lds_dwordx4 v[138:139], off
	v_mfma_f32_16x16x32_bf16 v[36:39], v[186:189], v[240:243], v[36:39]
	v_mfma_f32_16x16x32_bf16 v[20:23], v[186:189], v[244:247], v[20:23]
	v_mfma_f32_16x16x32_bf16 v[4:7], v[186:189], v[248:251], v[4:7]
	v_mfma_f32_16x16x32_bf16 v[120:123], v[186:189], v[252:255], v[120:123]
	ds_read_b128 v[186:189], v128 offset:36864
	s_add_i32 m0, s101, 0x2000
	v_lshl_add_u64 v[144:145], v[144:145], 0, s[98:99]
	global_load_lds_dwordx4 v[144:145], off
	v_mfma_f32_16x16x32_bf16 v[32:35], v[190:193], v[240:243], v[32:35]
	v_mfma_f32_16x16x32_bf16 v[16:19], v[190:193], v[244:247], v[16:19]
	v_mfma_f32_16x16x32_bf16 v[0:3], v[190:193], v[248:251], v[0:3]
	v_mfma_f32_16x16x32_bf16 v[124:127], v[190:193], v[252:255], v[124:127]
	ds_read_b128 v[190:193], v128 offset:38912
	s_add_i32 m0, s101, 0xa000
	v_lshl_add_u64 v[136:137], v[136:137], 0, s[98:99]
	global_load_lds_dwordx4 v[136:137], off

.Lg4n_1040:
	v_mfma_f32_16x16x32_bf16 v[44:47], v[178:181], v[240:243], v[44:47]
	v_mfma_f32_16x16x32_bf16 v[28:31], v[178:181], v[244:247], v[28:31]
	v_mfma_f32_16x16x32_bf16 v[12:15], v[178:181], v[248:251], v[12:15]
	v_mfma_f32_16x16x32_bf16 v[112:115], v[178:181], v[252:255], v[112:115]
	v_add3_u32 v128, s43, v150, v151
	ds_read_b128 v[178:181], v128 offset:32768
	v_add3_u32 v161, s43, v150, v152
	v_add3_u32 v194, s43, v154, v153
	v_add3_u32 v195, s43, v154, v155
	v_add3_u32 v196, s43, v154, v156
	ds_read_b128 v[162:165], v161
	ds_read_b128 v[166:169], v194
	ds_read_b128 v[170:173], v195
	ds_read_b128 v[174:177], v196
	v_mfma_f32_16x16x32_bf16 v[40:43], v[182:185], v[240:243], v[40:43]
	v_mfma_f32_16x16x32_bf16 v[24:27], v[182:185], v[244:247], v[24:27]
	v_mfma_f32_16x16x32_bf16 v[8:11], v[182:185], v[248:251], v[8:11]
	v_mfma_f32_16x16x32_bf16 v[116:119], v[182:185], v[252:255], v[116:119]
	ds_read_b128 v[182:185], v128 offset:34816
	v_add3_u32 v197, s43, v154, v157
	v_add3_u32 v198, s43, v154, v158
	v_add3_u32 v199, s43, v154, v159
	v_add3_u32 v200, s43, v154, v160
	v_mfma_f32_16x16x32_bf16 v[36:39], v[186:189], v[240:243], v[36:39]
	v_mfma_f32_16x16x32_bf16 v[20:23], v[186:189], v[244:247], v[20:23]
	v_mfma_f32_16x16x32_bf16 v[4:7], v[186:189], v[248:251], v[4:7]
	v_mfma_f32_16x16x32_bf16 v[120:123], v[186:189], v[252:255], v[120:123]
	ds_read_b128 v[186:189], v128 offset:36864
	v_mfma_f32_16x16x32_bf16 v[32:35], v[190:193], v[240:243], v[32:35]
	v_mfma_f32_16x16x32_bf16 v[16:19], v[190:193], v[244:247], v[16:19]
	v_mfma_f32_16x16x32_bf16 v[0:3], v[190:193], v[248:251], v[0:3]
	v_mfma_f32_16x16x32_bf16 v[124:127], v[190:193], v[252:255], v[124:127]
	ds_read_b128 v[190:193], v128 offset:38912
	s_branch .Ltl_1040
.Lex_1040:
	s_waitcnt lgkmcnt(0)
	v_add3_u32 v128, s24, v154, v160
	v_add3_u32 v130, s24, v154, v159
	v_add3_u32 v131, s24, v154, v158
	v_add3_u32 v146, s24, v154, v157
	v_add3_u32 v147, s24, v154, v156
	v_add3_u32 v149, s24, v154, v155
	v_add3_u32 v186, s24, v154, v153
	v_add3_u32 v187, s24, v150, v152
	v_add3_u32 v188, s25, v150, v151
	ds_read_b128 v[134:137], v128
	ds_read_b128 v[138:141], v130
	ds_read_b128 v[142:145], v131
	ds_read_b128 v[158:161], v146
	ds_read_b128 v[162:165], v147
	ds_read_b128 v[166:169], v149
	ds_read_b128 v[154:157], v186
	ds_read_b128 v[170:173], v187
	ds_read_b128 v[178:181], v188 offset:4096
	s_waitcnt lgkmcnt(0)
	v_mfma_f32_16x16x32_bf16 v[4:7], v[178:181], v[138:141], v[4:7]
	ds_read_b128 v[174:177], v188 offset:2048
	s_waitcnt lgkmcnt(0)
	v_mfma_f32_16x16x32_bf16 v[8:11], v[174:177], v[138:141], v[8:11]
	ds_read_b128 v[150:153], v188
	s_waitcnt lgkmcnt(0)
	v_mfma_f32_16x16x32_bf16 v[12:15], v[150:153], v[138:141], v[12:15]
	v_mfma_f32_16x16x32_bf16 v[112:115], v[150:153], v[134:137], v[112:115]
	v_mfma_f32_16x16x32_bf16 v[108:111], v[150:153], v[170:173], v[108:111]
	v_mfma_f32_16x16x32_bf16 v[92:95], v[150:153], v[154:157], v[92:95]
	v_mfma_f32_16x16x32_bf16 v[76:79], v[150:153], v[166:169], v[76:79]
	v_mfma_f32_16x16x32_bf16 v[116:119], v[174:177], v[134:137], v[116:119]
	v_mfma_f32_16x16x32_bf16 v[104:107], v[174:177], v[170:173], v[104:107]
	v_mfma_f32_16x16x32_bf16 v[88:91], v[174:177], v[154:157], v[88:91]
	v_mfma_f32_16x16x32_bf16 v[72:75], v[174:177], v[166:169], v[72:75]
	v_mfma_f32_16x16x32_bf16 v[120:123], v[178:181], v[134:137], v[120:123]
	v_mfma_f32_16x16x32_bf16 v[100:103], v[178:181], v[170:173], v[100:103]
	v_mfma_f32_16x16x32_bf16 v[84:87], v[178:181], v[154:157], v[84:87]
	v_mfma_f32_16x16x32_bf16 v[68:71], v[178:181], v[166:169], v[68:71]
	ds_read_b128 v[182:185], v188 offset:6144
	s_waitcnt lgkmcnt(0)
	v_mfma_f32_16x16x32_bf16 v[124:127], v[182:185], v[134:137], v[124:127]
	v_mfma_f32_16x16x32_bf16 v[96:99], v[182:185], v[170:173], v[96:99]
	v_mfma_f32_16x16x32_bf16 v[80:83], v[182:185], v[154:157], v[80:83]
	v_mfma_f32_16x16x32_bf16 v[64:67], v[182:185], v[166:169], v[64:67]
	v_mfma_f32_16x16x32_bf16 v[48:51], v[182:185], v[162:165], v[48:51]
	v_mfma_f32_16x16x32_bf16 v[52:55], v[178:181], v[162:165], v[52:55]
	v_mfma_f32_16x16x32_bf16 v[56:59], v[174:177], v[162:165], v[56:59]
	v_mfma_f32_16x16x32_bf16 v[60:63], v[150:153], v[162:165], v[60:63]
	v_mfma_f32_16x16x32_bf16 v[44:47], v[150:153], v[158:161], v[44:47]
	v_mfma_f32_16x16x32_bf16 v[40:43], v[174:177], v[158:161], v[40:43]
	v_mfma_f32_16x16x32_bf16 v[36:39], v[178:181], v[158:161], v[36:39]
	v_mfma_f32_16x16x32_bf16 v[32:35], v[182:185], v[158:161], v[32:35]
	v_mfma_f32_16x16x32_bf16 v[28:31], v[150:153], v[142:145], v[28:31]
	v_mfma_f32_16x16x32_bf16 v[24:27], v[174:177], v[142:145], v[24:27]
	v_mfma_f32_16x16x32_bf16 v[20:23], v[178:181], v[142:145], v[20:23]
	v_mfma_f32_16x16x32_bf16 v[16:19], v[182:185], v[142:145], v[16:19]
	v_mfma_f32_16x16x32_bf16 v[0:3], v[182:185], v[138:141], v[0:3]
	ds_read_b128 v[134:137], v188 offset:1024
	ds_read_b128 v[138:141], v188 offset:3072
	ds_read_b128 v[142:145], v188 offset:5120
	ds_read_b128 v[154:157], v188 offset:7168
	ds_read_b128 v[150:153], v187 offset:1024
	ds_read_b128 v[158:161], v186 offset:1024
	ds_read_b128 v[162:165], v149 offset:1024
	ds_read_b128 v[166:169], v147 offset:1024
	s_waitcnt lgkmcnt(3)
	v_mfma_f32_16x16x32_bf16 v[108:111], v[134:137], v[150:153], v[108:111]
	v_mfma_f32_16x16x32_bf16 v[104:107], v[138:141], v[150:153], v[104:107]
	v_mfma_f32_16x16x32_bf16 v[100:103], v[142:145], v[150:153], v[100:103]
	v_mfma_f32_16x16x32_bf16 v[96:99], v[154:157], v[150:153], v[96:99]
	ds_read_b128 v[150:153], v146 offset:1024
	s_waitcnt lgkmcnt(3)
	v_mfma_f32_16x16x32_bf16 v[92:95], v[134:137], v[158:161], v[92:95]
	v_mfma_f32_16x16x32_bf16 v[88:91], v[138:141], v[158:161], v[88:91]
	v_mfma_f32_16x16x32_bf16 v[84:87], v[142:145], v[158:161], v[84:87]
	v_mfma_f32_16x16x32_bf16 v[80:83], v[154:157], v[158:161], v[80:83]
	ds_read_b128 v[158:161], v131 offset:1024
	s_waitcnt lgkmcnt(3)
	v_mfma_f32_16x16x32_bf16 v[76:79], v[134:137], v[162:165], v[76:79]
	v_mfma_f32_16x16x32_bf16 v[72:75], v[138:141], v[162:165], v[72:75]
	v_mfma_f32_16x16x32_bf16 v[68:71], v[142:145], v[162:165], v[68:71]
	v_mfma_f32_16x16x32_bf16 v[64:67], v[154:157], v[162:165], v[64:67]
	ds_read_b128 v[162:165], v130 offset:1024
	s_waitcnt lgkmcnt(3)
	v_mfma_f32_16x16x32_bf16 v[60:63], v[134:137], v[166:169], v[60:63]
	v_mfma_f32_16x16x32_bf16 v[56:59], v[138:141], v[166:169], v[56:59]
	v_mfma_f32_16x16x32_bf16 v[52:55], v[142:145], v[166:169], v[52:55]
	v_mfma_f32_16x16x32_bf16 v[48:51], v[154:157], v[166:169], v[48:51]
	ds_read_b128 v[166:169], v128 offset:1024
	s_waitcnt lgkmcnt(3)
	v_mfma_f32_16x16x32_bf16 v[44:47], v[134:137], v[150:153], v[44:47]
	v_mfma_f32_16x16x32_bf16 v[40:43], v[138:141], v[150:153], v[40:43]
	v_mfma_f32_16x16x32_bf16 v[36:39], v[142:145], v[150:153], v[36:39]
	v_mfma_f32_16x16x32_bf16 v[32:35], v[154:157], v[150:153], v[32:35]
	s_waitcnt lgkmcnt(2)
	v_mfma_f32_16x16x32_bf16 v[28:31], v[134:137], v[158:161], v[28:31]
	v_mfma_f32_16x16x32_bf16 v[24:27], v[138:141], v[158:161], v[24:27]
	v_mfma_f32_16x16x32_bf16 v[20:23], v[142:145], v[158:161], v[20:23]
	v_mfma_f32_16x16x32_bf16 v[16:19], v[154:157], v[158:161], v[16:19]
	s_waitcnt lgkmcnt(1)
	v_mfma_f32_16x16x32_bf16 v[12:15], v[134:137], v[162:165], v[12:15]
	v_mfma_f32_16x16x32_bf16 v[8:11], v[138:141], v[162:165], v[8:11]
	v_mfma_f32_16x16x32_bf16 v[4:7], v[142:145], v[162:165], v[4:7]
	v_mfma_f32_16x16x32_bf16 v[0:3], v[154:157], v[162:165], v[0:3]
	s_waitcnt lgkmcnt(0)
	v_mfma_f32_16x16x32_bf16 v[112:115], v[134:137], v[166:169], v[112:115]
	v_mfma_f32_16x16x32_bf16 v[116:119], v[138:141], v[166:169], v[116:119]
	v_mfma_f32_16x16x32_bf16 v[120:123], v[142:145], v[166:169], v[120:123]
	v_mfma_f32_16x16x32_bf16 v[124:127], v[154:157], v[166:169], v[124:127]
	v_mov_b32_e32 v128, s20
	s_waitcnt vmcnt(0)
	s_barrier
	ds_read_b64 v[130:131], v128
	v_ashrrev_i32_e32 v128, 1, v148
	v_and_b32_e32 v128, 0xffffff80, v128
	v_add_u32_e32 v128, s16, v128
	s_ashr_i32 s15, s14, 31
	s_waitcnt lgkmcnt(0)
	v_mad_i64_i32 v[130:131], s[16:17], v128, s26, v[130:131]
	v_and_b32_e32 v128, 0xc0, v148
	v_lshrrev_b32_e32 v135, 6, v148
	v_lshl_add_u64 v[130:131], s[14:15], 1, v[130:131]
	v_lshlrev_b32_e32 v128, 1, v128
	v_lshl_add_u64 v[130:131], v[130:131], 0, v[128:129]
	v_mul_lo_u32 v128, v135, s27
	v_add_u32_e32 v135, s24, v128
	v_lshrrev_b32_e32 v128, 1, v148
	v_and_b32_e32 v136, 24, v128
	v_lshlrev_b32_e32 v128, 4, v148
	v_bfe_u32 v137, v148, 3, 3
	v_and_b32_e32 v134, 15, v148
	v_and_b32_e32 v128, 0x70, v128
	v_mul_u32_u24_e32 v138, 0x90, v137
	v_lshl_add_u64 v[130:131], v[130:131], 0, v[128:129]
	v_add3_u32 v138, v135, v128, v138
	v_mul_u32_u24_e32 v128, 0x90, v134
	v_add3_u32 v134, v135, v136, v128
	v_cvt_pk_bf16_f32 v108, v108, v109
	v_cvt_pk_bf16_f32 v109, v110, v111
	v_cvt_pk_bf16_f32 v104, v104, v105
	v_cvt_pk_bf16_f32 v105, v106, v107
	v_cvt_pk_bf16_f32 v100, v100, v101
	v_cvt_pk_bf16_f32 v101, v102, v103
	v_cvt_pk_bf16_f32 v96, v96, v97
	v_cvt_pk_bf16_f32 v97, v98, v99
	v_cvt_pk_bf16_f32 v92, v92, v93
	v_cvt_pk_bf16_f32 v93, v94, v95
	v_cvt_pk_bf16_f32 v88, v88, v89
	v_cvt_pk_bf16_f32 v89, v90, v91
	v_cvt_pk_bf16_f32 v84, v84, v85
	v_cvt_pk_bf16_f32 v85, v86, v87
	v_cvt_pk_bf16_f32 v80, v80, v81
	v_cvt_pk_bf16_f32 v81, v82, v83
	v_cvt_pk_bf16_f32 v76, v76, v77
	v_cvt_pk_bf16_f32 v77, v78, v79
	v_cvt_pk_bf16_f32 v72, v72, v73
	v_cvt_pk_bf16_f32 v73, v74, v75
	v_cvt_pk_bf16_f32 v68, v68, v69
	v_cvt_pk_bf16_f32 v69, v70, v71
	v_cvt_pk_bf16_f32 v64, v64, v65
	v_cvt_pk_bf16_f32 v65, v66, v67
	v_cvt_pk_bf16_f32 v60, v60, v61
	v_cvt_pk_bf16_f32 v61, v62, v63
	v_cvt_pk_bf16_f32 v56, v56, v57
	v_cvt_pk_bf16_f32 v57, v58, v59
	v_cvt_pk_bf16_f32 v52, v52, v53
	v_cvt_pk_bf16_f32 v53, v54, v55
	v_cvt_pk_bf16_f32 v48, v48, v49
	v_cvt_pk_bf16_f32 v49, v50, v51
	ds_write_b64 v134, v[108:109]
	ds_write_b64 v134, v[104:105] offset:32
	ds_write_b64 v134, v[100:101] offset:64
	ds_write_b64 v134, v[96:97] offset:96
	ds_write_b64 v134, v[92:93] offset:2304
	ds_write_b64 v134, v[88:89] offset:2336
	ds_write_b64 v134, v[84:85] offset:2368
	ds_write_b64 v134, v[80:81] offset:2400
	ds_write_b64 v134, v[76:77] offset:4608
	ds_write_b64 v134, v[72:73] offset:4640
	ds_write_b64 v134, v[68:69] offset:4672
	ds_write_b64 v134, v[64:65] offset:4704
	ds_write_b64 v134, v[60:61] offset:6912
	ds_write_b64 v134, v[56:57] offset:6944
	ds_write_b64 v134, v[52:53] offset:6976
	ds_write_b64 v134, v[48:49] offset:7008
	ds_read_b128 v[48:51], v138
	v_mul_u32_u24_e32 v54, 0xa00, v137
	v_lshl_add_u64 v[52:53], v[130:131], 0, s[12:13]
	v_lshlrev_b32_e32 v128, 1, v54
	v_lshl_add_u64 v[54:55], v[52:53], 0, v[128:129]
	s_waitcnt lgkmcnt(0)
	flat_store_dwordx4 v[54:55], v[48:51] nt
	ds_read_b128 v[48:51], v138 offset:1152
	v_add_co_u32_e32 v56, vcc, s22, v54
	v_cvt_pk_bf16_f32 v0, v0, v1
	s_nop 0
	v_addc_co_u32_e32 v57, vcc, 0, v55, vcc
	s_waitcnt lgkmcnt(0)
	flat_store_dwordx4 v[56:57], v[48:51] nt
	ds_read_b128 v[48:51], v138 offset:2304
	v_add_co_u32_e32 v56, vcc, s28, v54
	v_cvt_pk_bf16_f32 v1, v2, v3
	s_nop 0
	v_addc_co_u32_e32 v57, vcc, 0, v55, vcc
	s_waitcnt lgkmcnt(0)
	flat_store_dwordx4 v[56:57], v[48:51] nt
	ds_read_b128 v[48:51], v138 offset:3456
	v_add_co_u32_e32 v56, vcc, s29, v54
	v_cvt_pk_bf16_f32 v44, v44, v45
	s_nop 0
	v_addc_co_u32_e32 v57, vcc, 0, v55, vcc
	s_waitcnt lgkmcnt(0)
	flat_store_dwordx4 v[56:57], v[48:51] nt
	ds_read_b128 v[48:51], v138 offset:4608
	v_add_u32_e32 v56, 0x28000, v128
	v_mov_b32_e32 v57, v129
	v_lshl_add_u64 v[56:57], v[52:53], 0, v[56:57]
	v_cvt_pk_bf16_f32 v45, v46, v47
	s_waitcnt lgkmcnt(0)
	flat_store_dwordx4 v[56:57], v[48:51] nt
	ds_read_b128 v[48:51], v138 offset:5760
	v_add_u32_e32 v56, 0x32000, v128
	v_mov_b32_e32 v57, v129
	v_lshl_add_u64 v[56:57], v[52:53], 0, v[56:57]
	v_cvt_pk_bf16_f32 v40, v40, v41
	s_waitcnt lgkmcnt(0)
	flat_store_dwordx4 v[56:57], v[48:51] nt
	ds_read_b128 v[48:51], v138 offset:6912
	v_add_u32_e32 v56, 0x3c000, v128
	v_mov_b32_e32 v57, v129
	v_lshl_add_u64 v[56:57], v[52:53], 0, v[56:57]
	v_add_u32_e32 v128, 0x46000, v128
	s_waitcnt lgkmcnt(0)
	flat_store_dwordx4 v[56:57], v[48:51] nt
	ds_read_b128 v[48:51], v138 offset:8064
	v_lshl_add_u64 v[52:53], v[52:53], 0, v[128:129]
	v_cvt_pk_bf16_f32 v41, v42, v43
	v_cvt_pk_bf16_f32 v36, v36, v37
	v_cvt_pk_bf16_f32 v37, v38, v39
	s_waitcnt lgkmcnt(0)
	flat_store_dwordx4 v[52:53], v[48:51] nt
	ds_write_b64 v134, v[0:1] offset:4704
	v_cvt_pk_bf16_f32 v0, v112, v113
	v_cvt_pk_bf16_f32 v1, v114, v115
	ds_write_b64 v134, v[0:1] offset:6912
	v_cvt_pk_bf16_f32 v0, v116, v117
	v_cvt_pk_bf16_f32 v1, v118, v119
	ds_write_b64 v134, v[0:1] offset:6944
	v_cvt_pk_bf16_f32 v0, v120, v121
	v_cvt_pk_bf16_f32 v1, v122, v123
	v_cvt_pk_bf16_f32 v32, v32, v33
	v_cvt_pk_bf16_f32 v33, v34, v35
	v_cvt_pk_bf16_f32 v28, v28, v29
	v_cvt_pk_bf16_f32 v29, v30, v31
	v_cvt_pk_bf16_f32 v24, v24, v25
	v_cvt_pk_bf16_f32 v25, v26, v27
	v_cvt_pk_bf16_f32 v20, v20, v21
	v_cvt_pk_bf16_f32 v21, v22, v23
	v_cvt_pk_bf16_f32 v16, v16, v17
	v_cvt_pk_bf16_f32 v17, v18, v19
	v_cvt_pk_bf16_f32 v12, v12, v13
	v_cvt_pk_bf16_f32 v13, v14, v15
	v_cvt_pk_bf16_f32 v8, v8, v9
	v_cvt_pk_bf16_f32 v9, v10, v11
	v_cvt_pk_bf16_f32 v4, v4, v5
	v_cvt_pk_bf16_f32 v5, v6, v7
	ds_write_b64 v134, v[0:1] offset:6976
	v_cvt_pk_bf16_f32 v0, v124, v125
	v_cvt_pk_bf16_f32 v1, v126, v127
	ds_write_b64 v134, v[44:45]
	ds_write_b64 v134, v[40:41] offset:32
	ds_write_b64 v134, v[36:37] offset:64
	ds_write_b64 v134, v[32:33] offset:96
	ds_write_b64 v134, v[28:29] offset:2304
	ds_write_b64 v134, v[24:25] offset:2336
	ds_write_b64 v134, v[20:21] offset:2368
	ds_write_b64 v134, v[16:17] offset:2400
	ds_write_b64 v134, v[12:13] offset:4608
	ds_write_b64 v134, v[8:9] offset:4640
	ds_write_b64 v134, v[4:5] offset:4672
	ds_write_b64 v134, v[0:1] offset:7008
	ds_read_b128 v[0:3], v138
	v_add_co_u32_e32 v4, vcc, s30, v54
	s_add_i32 s42, s42, s40
	s_nop 0
	v_addc_co_u32_e32 v5, vcc, 0, v55, vcc
	s_waitcnt lgkmcnt(0)
	flat_store_dwordx4 v[4:5], v[0:3] nt
	ds_read_b128 v[0:3], v138 offset:1152
	v_add_co_u32_e32 v4, vcc, s31, v54
	s_cmpk_gt_i32 s42, 0x4ff
	s_nop 0
	v_addc_co_u32_e32 v5, vcc, 0, v55, vcc
	s_waitcnt lgkmcnt(0)
	flat_store_dwordx4 v[4:5], v[0:3] nt
	ds_read_b128 v[0:3], v138 offset:2304
	v_add_co_u32_e32 v4, vcc, s34, v54
	s_nop 1
	v_addc_co_u32_e32 v5, vcc, 0, v55, vcc
	s_waitcnt lgkmcnt(0)
	flat_store_dwordx4 v[4:5], v[0:3] nt
	ds_read_b128 v[0:3], v138 offset:3456
	v_add_co_u32_e32 v4, vcc, s35, v54
	s_nop 1
	v_addc_co_u32_e32 v5, vcc, 0, v55, vcc
	s_waitcnt lgkmcnt(0)
	flat_store_dwordx4 v[4:5], v[0:3] nt
	ds_read_b128 v[0:3], v138 offset:4608
	v_add_co_u32_e32 v4, vcc, s38, v54
	s_nop 1
	v_addc_co_u32_e32 v5, vcc, 0, v55, vcc
	s_waitcnt lgkmcnt(0)
	flat_store_dwordx4 v[4:5], v[0:3] nt
	ds_read_b128 v[0:3], v138 offset:5760
	v_add_co_u32_e32 v4, vcc, s39, v54
	s_nop 1
	v_addc_co_u32_e32 v5, vcc, 0, v55, vcc
	s_waitcnt lgkmcnt(0)
	flat_store_dwordx4 v[4:5], v[0:3] nt
	ds_read_b128 v[0:3], v138 offset:6912
	v_add_co_u32_e32 v4, vcc, 0x8c000, v54
	s_nop 1
	v_addc_co_u32_e32 v5, vcc, 0, v55, vcc
	s_waitcnt lgkmcnt(0)
	flat_store_dwordx4 v[4:5], v[0:3] nt
	ds_read_b128 v[0:3], v138 offset:8064
	v_add_co_u32_e32 v4, vcc, 0x96000, v54
	s_nop 1
	v_addc_co_u32_e32 v5, vcc, 0, v55, vcc
	s_waitcnt lgkmcnt(0)
	flat_store_dwordx4 v[4:5], v[0:3] nt
	s_cbranch_scc0 .LBB0_1039

.LBB0_1138:
	s_and_b32 s27, s26, 0x10000
	s_xor_b32 s28, s27, 0x10000
	s_add_i32 s27, s27, 0
	s_add_i32 s101, s100, s28
	s_cmpk_eq_i32 s12, 0
	s_cbranch_scc1 .Lg1n_1138
	s_waitcnt lgkmcnt(3)
	v_mfma_f32_16x16x32_bf16 v[124:127], v[178:181], v[162:165], v[124:127]
	v_mfma_f32_16x16x32_bf16 v[108:111], v[178:181], v[166:169], v[108:111]
	v_mfma_f32_16x16x32_bf16 v[92:95], v[178:181], v[170:173], v[92:95]
	v_mfma_f32_16x16x32_bf16 v[76:79], v[178:181], v[174:177], v[76:79]
	ds_read_b128 v[240:243], v197
	ds_read_b128 v[244:247], v198
	s_add_i32 m0, s101, 0x4000
	v_lshl_add_u64 v[142:143], v[142:143], 0, s[98:99]
	global_load_lds_dwordx4 v[142:143], off
	s_waitcnt lgkmcnt(4)
	v_mfma_f32_16x16x32_bf16 v[120:123], v[182:185], v[162:165], v[120:123]
	v_mfma_f32_16x16x32_bf16 v[104:107], v[182:185], v[166:169], v[104:107]
	v_mfma_f32_16x16x32_bf16 v[88:91], v[182:185], v[170:173], v[88:91]
	v_mfma_f32_16x16x32_bf16 v[72:75], v[182:185], v[174:177], v[72:75]
	ds_read_b128 v[248:251], v199
	ds_read_b128 v[252:255], v200
	s_add_i32 m0, s101, 0xc000
	v_lshl_add_u64 v[134:135], v[134:135], 0, s[98:99]
	global_load_lds_dwordx4 v[134:135], off
	s_waitcnt lgkmcnt(5)
	v_mfma_f32_16x16x32_bf16 v[116:119], v[186:189], v[162:165], v[116:119]
	v_mfma_f32_16x16x32_bf16 v[100:103], v[186:189], v[166:169], v[100:103]
	v_mfma_f32_16x16x32_bf16 v[84:87], v[186:189], v[170:173], v[84:87]
	v_mfma_f32_16x16x32_bf16 v[68:71], v[186:189], v[174:177], v[68:71]
	s_add_i32 m0, s101, 0x6000
	v_lshl_add_u64 v[140:141], v[140:141], 0, s[98:99]
	global_load_lds_dwordx4 v[140:141], off
	s_waitcnt lgkmcnt(4)
	v_mfma_f32_16x16x32_bf16 v[112:115], v[190:193], v[162:165], v[112:115]
	v_mfma_f32_16x16x32_bf16 v[96:99], v[190:193], v[166:169], v[96:99]
	v_mfma_f32_16x16x32_bf16 v[80:83], v[190:193], v[170:173], v[80:83]
	v_mfma_f32_16x16x32_bf16 v[64:67], v[190:193], v[174:177], v[64:67]
	s_add_i32 m0, s101, 0xe000
	v_lshl_add_u64 v[130:131], v[130:131], 0, s[98:99]
	global_load_lds_dwordx4 v[130:131], off
.Lg2_1138:
	ds_read_b128 v[162:165], v161 offset:1024
	ds_read_b128 v[166:169], v194 offset:1024
	ds_read_b128 v[170:173], v195 offset:1024
	ds_read_b128 v[174:177], v196 offset:1024
	s_waitcnt lgkmcnt(4)
	v_mfma_f32_16x16x32_bf16 v[60:63], v[178:181], v[240:243], v[60:63]
	v_mfma_f32_16x16x32_bf16 v[44:47], v[178:181], v[244:247], v[44:47]
	v_mfma_f32_16x16x32_bf16 v[16:19], v[178:181], v[248:251], v[16:19]
	v_mfma_f32_16x16x32_bf16 v[36:39], v[178:181], v[252:255], v[36:39]
	ds_read_b128 v[178:181], v128 offset:33792
	v_mfma_f32_16x16x32_bf16 v[56:59], v[182:185], v[240:243], v[56:59]
	v_mfma_f32_16x16x32_bf16 v[40:43], v[182:185], v[244:247], v[40:43]
	v_mfma_f32_16x16x32_bf16 v[8:11], v[182:185], v[248:251], v[8:11]
	v_mfma_f32_16x16x32_bf16 v[28:31], v[182:185], v[252:255], v[28:31]
	ds_read_b128 v[182:185], v128 offset:35840
	v_mfma_f32_16x16x32_bf16 v[52:55], v[186:189], v[240:243], v[52:55]
	v_mfma_f32_16x16x32_bf16 v[32:35], v[186:189], v[244:247], v[32:35]
	v_mfma_f32_16x16x32_bf16 v[4:7], v[186:189], v[248:251], v[4:7]
	v_mfma_f32_16x16x32_bf16 v[20:23], v[186:189], v[252:255], v[20:23]
	ds_read_b128 v[186:189], v128 offset:37888
	v_mfma_f32_16x16x32_bf16 v[48:51], v[190:193], v[240:243], v[48:51]
	v_mfma_f32_16x16x32_bf16 v[24:27], v[190:193], v[244:247], v[24:27]
	v_mfma_f32_16x16x32_bf16 v[0:3], v[190:193], v[248:251], v[0:3]
	v_mfma_f32_16x16x32_bf16 v[12:15], v[190:193], v[252:255], v[12:15]
	ds_read_b128 v[190:193], v128 offset:39936
	s_waitcnt lgkmcnt(3)
	v_mfma_f32_16x16x32_bf16 v[124:127], v[178:181], v[162:165], v[124:127]
	v_mfma_f32_16x16x32_bf16 v[108:111], v[178:181], v[166:169], v[108:111]
	v_mfma_f32_16x16x32_bf16 v[92:95], v[178:181], v[170:173], v[92:95]
	v_mfma_f32_16x16x32_bf16 v[76:79], v[178:181], v[174:177], v[76:79]
	ds_read_b128 v[240:243], v197 offset:1024
	ds_read_b128 v[244:247], v198 offset:1024
	s_waitcnt lgkmcnt(4)
	v_mfma_f32_16x16x32_bf16 v[120:123], v[182:185], v[162:165], v[120:123]
	v_mfma_f32_16x16x32_bf16 v[104:107], v[182:185], v[166:169], v[104:107]
	v_mfma_f32_16x16x32_bf16 v[88:91], v[182:185], v[170:173], v[88:91]
	v_mfma_f32_16x16x32_bf16 v[72:75], v[182:185], v[174:177], v[72:75]
	ds_read_b128 v[248:251], v199 offset:1024
	ds_read_b128 v[252:255], v200 offset:1024
	s_waitcnt lgkmcnt(5)
	v_mfma_f32_16x16x32_bf16 v[116:119], v[186:189], v[162:165], v[116:119]
	v_mfma_f32_16x16x32_bf16 v[100:103], v[186:189], v[166:169], v[100:103]
	v_mfma_f32_16x16x32_bf16 v[84:87], v[186:189], v[170:173], v[84:87]
	v_mfma_f32_16x16x32_bf16 v[68:71], v[186:189], v[174:177], v[68:71]
	s_waitcnt lgkmcnt(4)
	v_mfma_f32_16x16x32_bf16 v[112:115], v[190:193], v[162:165], v[112:115]
	v_mfma_f32_16x16x32_bf16 v[96:99], v[190:193], v[166:169], v[96:99]
	v_mfma_f32_16x16x32_bf16 v[80:83], v[190:193], v[170:173], v[80:83]
	v_mfma_f32_16x16x32_bf16 v[64:67], v[190:193], v[174:177], v[64:67]
	s_waitcnt vmcnt(0) lgkmcnt(0)
	s_barrier
	s_add_i32 s101, s100, s27
	s_cmpk_eq_i32 s12, 0x1500
	s_cbranch_scc1 .Lg4n_1138
	v_mfma_f32_16x16x32_bf16 v[60:63], v[178:181], v[240:243], v[60:63]
	v_mfma_f32_16x16x32_bf16 v[44:47], v[178:181], v[244:247], v[44:47]
	v_mfma_f32_16x16x32_bf16 v[16:19], v[178:181], v[248:251], v[16:19]
	v_mfma_f32_16x16x32_bf16 v[36:39], v[178:181], v[252:255], v[36:39]
	v_add3_u32 v128, s28, v150, v151
	ds_read_b128 v[178:181], v128 offset:32768
	v_add3_u32 v161, s28, v150, v152
	v_add3_u32 v194, s28, v154, v153
	v_add3_u32 v195, s28, v154, v155
	v_add3_u32 v196, s28, v154, v156
	ds_read_b128 v[162:165], v161
	ds_read_b128 v[166:169], v194
	ds_read_b128 v[170:173], v195
	ds_read_b128 v[174:177], v196
	s_mov_b32 m0, s101
	v_lshl_add_u64 v[146:147], v[146:147], 0, s[98:99]
	global_load_lds_dwordx4 v[146:147], off
	v_mfma_f32_16x16x32_bf16 v[56:59], v[182:185], v[240:243], v[56:59]
	v_mfma_f32_16x16x32_bf16 v[40:43], v[182:185], v[244:247], v[40:43]
	v_mfma_f32_16x16x32_bf16 v[8:11], v[182:185], v[248:251], v[8:11]
	v_mfma_f32_16x16x32_bf16 v[28:31], v[182:185], v[252:255], v[28:31]
	ds_read_b128 v[182:185], v128 offset:34816
	v_add3_u32 v197, s28, v154, v157
	v_add3_u32 v198, s28, v154, v158
	v_add3_u32 v199, s28, v154, v159
	v_add3_u32 v200, s28, v154, v160
	s_add_i32 m0, s101, 0x8000
	v_lshl_add_u64 v[138:139], v[138:139], 0, s[98:99]
	global_load_lds_dwordx4 v[138:139], off
	v_mfma_f32_16x16x32_bf16 v[52:55], v[186:189], v[240:243], v[52:55]
	v_mfma_f32_16x16x32_bf16 v[32:35], v[186:189], v[244:247], v[32:35]
	v_mfma_f32_16x16x32_bf16 v[4:7], v[186:189], v[248:251], v[4:7]
	v_mfma_f32_16x16x32_bf16 v[20:23], v[186:189], v[252:255], v[20:23]
	ds_read_b128 v[186:189], v128 offset:36864
	s_add_i32 m0, s101, 0x2000
	v_lshl_add_u64 v[144:145], v[144:145], 0, s[98:99]
	global_load_lds_dwordx4 v[144:145], off
	v_mfma_f32_16x16x32_bf16 v[48:51], v[190:193], v[240:243], v[48:51]
	v_mfma_f32_16x16x32_bf16 v[24:27], v[190:193], v[244:247], v[24:27]
	v_mfma_f32_16x16x32_bf16 v[0:3], v[190:193], v[248:251], v[0:3]
	v_mfma_f32_16x16x32_bf16 v[12:15], v[190:193], v[252:255], v[12:15]
	ds_read_b128 v[190:193], v128 offset:38912
	s_add_i32 m0, s101, 0xa000
	v_lshl_add_u64 v[136:137], v[136:137], 0, s[98:99]
	global_load_lds_dwordx4 v[136:137], off
.Ltl_1138:
	s_add_i32 s26, s26, 0x10000
	s_add_u32 s12, s12, 0x80
	s_addc_u32 s13, s13, 0
	s_cmpk_lg_i32 s12, 0x1580
	s_cbranch_scc1 .LBB0_1138
	s_branch .Lex_1138

.Lg4n_1138:
	v_mfma_f32_16x16x32_bf16 v[60:63], v[178:181], v[240:243], v[60:63]
	v_mfma_f32_16x16x32_bf16 v[44:47], v[178:181], v[244:247], v[44:47]
	v_mfma_f32_16x16x32_bf16 v[16:19], v[178:181], v[248:251], v[16:19]
	v_mfma_f32_16x16x32_bf16 v[36:39], v[178:181], v[252:255], v[36:39]
	v_add3_u32 v128, s28, v150, v151
	ds_read_b128 v[178:181], v128 offset:32768
	v_add3_u32 v161, s28, v150, v152
	v_add3_u32 v194, s28, v154, v153
	v_add3_u32 v195, s28, v154, v155
	v_add3_u32 v196, s28, v154, v156
	ds_read_b128 v[162:165], v161
	ds_read_b128 v[166:169], v194
	ds_read_b128 v[170:173], v195
	ds_read_b128 v[174:177], v196
	v_mfma_f32_16x16x32_bf16 v[56:59], v[182:185], v[240:243], v[56:59]
	v_mfma_f32_16x16x32_bf16 v[40:43], v[182:185], v[244:247], v[40:43]
	v_mfma_f32_16x16x32_bf16 v[8:11], v[182:185], v[248:251], v[8:11]
	v_mfma_f32_16x16x32_bf16 v[28:31], v[182:185], v[252:255], v[28:31]
	ds_read_b128 v[182:185], v128 offset:34816
	v_add3_u32 v197, s28, v154, v157
	v_add3_u32 v198, s28, v154, v158
	v_add3_u32 v199, s28, v154, v159
	v_add3_u32 v200, s28, v154, v160
	v_mfma_f32_16x16x32_bf16 v[52:55], v[186:189], v[240:243], v[52:55]
	v_mfma_f32_16x16x32_bf16 v[32:35], v[186:189], v[244:247], v[32:35]
	v_mfma_f32_16x16x32_bf16 v[4:7], v[186:189], v[248:251], v[4:7]
	v_mfma_f32_16x16x32_bf16 v[20:23], v[186:189], v[252:255], v[20:23]
	ds_read_b128 v[186:189], v128 offset:36864
	v_mfma_f32_16x16x32_bf16 v[48:51], v[190:193], v[240:243], v[48:51]
	v_mfma_f32_16x16x32_bf16 v[24:27], v[190:193], v[244:247], v[24:27]
	v_mfma_f32_16x16x32_bf16 v[0:3], v[190:193], v[248:251], v[0:3]
	v_mfma_f32_16x16x32_bf16 v[12:15], v[190:193], v[252:255], v[12:15]
	ds_read_b128 v[190:193], v128 offset:38912
	s_branch .Ltl_1138
.Lex_1138:
	s_waitcnt lgkmcnt(0)
	v_add3_u32 v128, s17, v154, v160
	v_add3_u32 v130, s17, v154, v159
	v_add3_u32 v131, s17, v154, v158
	v_add3_u32 v146, s17, v154, v157
	v_add3_u32 v147, s17, v154, v156
	v_add3_u32 v149, s17, v154, v155
	v_add3_u32 v186, s17, v154, v153
	v_add3_u32 v187, s17, v150, v152
	v_add3_u32 v188, s18, v150, v151
	ds_read_b128 v[134:137], v128
	ds_read_b128 v[138:141], v130
	ds_read_b128 v[142:145], v131
	ds_read_b128 v[158:161], v146
	ds_read_b128 v[162:165], v147
	ds_read_b128 v[166:169], v149
	ds_read_b128 v[154:157], v186
	ds_read_b128 v[170:173], v187
	ds_read_b128 v[150:153], v188
	s_waitcnt lgkmcnt(0)
	v_mfma_f32_16x16x32_bf16 v[16:19], v[150:153], v[138:141], v[16:19]
	v_mfma_f32_16x16x32_bf16 v[174:177], v[150:153], v[134:137], v[36:39]
	s_nop 2
	ds_read_b128 v[36:39], v188 offset:2048
	s_waitcnt lgkmcnt(0)
	v_mfma_f32_16x16x32_bf16 v[8:11], v[36:39], v[138:141], v[8:11]
	v_mfma_f32_16x16x32_bf16 v[108:111], v[150:153], v[154:157], v[108:111]
	v_mfma_f32_16x16x32_bf16 v[60:63], v[150:153], v[158:161], v[60:63]
	v_mfma_f32_16x16x32_bf16 v[28:31], v[36:39], v[134:137], v[28:31]
	v_mfma_f32_16x16x32_bf16 v[104:107], v[36:39], v[154:157], v[104:107]
	v_mfma_f32_16x16x32_bf16 v[56:59], v[36:39], v[158:161], v[56:59]
	ds_read_b128 v[178:181], v188 offset:4096
	s_waitcnt lgkmcnt(0)
	v_mfma_f32_16x16x32_bf16 v[182:185], v[178:181], v[134:137], v[20:23]
	v_mfma_f32_16x16x32_bf16 v[100:103], v[178:181], v[154:157], v[100:103]
	v_mfma_f32_16x16x32_bf16 v[52:55], v[178:181], v[158:161], v[52:55]
	s_nop 0
	ds_read_b128 v[20:23], v188 offset:6144
	s_waitcnt lgkmcnt(0)
	v_mfma_f32_16x16x32_bf16 v[134:137], v[20:23], v[134:137], v[12:15]
	v_mfma_f32_16x16x32_bf16 v[12:15], v[20:23], v[170:173], v[112:115]
	v_mfma_f32_16x16x32_bf16 v[96:99], v[20:23], v[154:157], v[96:99]
	v_mfma_f32_16x16x32_bf16 v[112:115], v[20:23], v[162:165], v[64:67]
	v_mfma_f32_16x16x32_bf16 v[64:67], v[178:181], v[170:173], v[116:119]
	v_mfma_f32_16x16x32_bf16 v[116:119], v[178:181], v[162:165], v[68:71]
	v_mfma_f32_16x16x32_bf16 v[68:71], v[36:39], v[170:173], v[120:123]
	v_mfma_f32_16x16x32_bf16 v[120:123], v[36:39], v[162:165], v[72:75]
	v_mfma_f32_16x16x32_bf16 v[72:75], v[150:153], v[170:173], v[124:127]
	v_mfma_f32_16x16x32_bf16 v[124:127], v[150:153], v[162:165], v[76:79]
	v_mfma_f32_16x16x32_bf16 v[48:51], v[20:23], v[158:161], v[48:51]
	v_mfma_f32_16x16x32_bf16 v[154:157], v[150:153], v[142:145], v[44:47]
	v_mfma_f32_16x16x32_bf16 v[158:161], v[36:39], v[142:145], v[40:43]
	v_mfma_f32_16x16x32_bf16 v[162:165], v[178:181], v[142:145], v[32:35]
	v_mfma_f32_16x16x32_bf16 v[24:27], v[20:23], v[142:145], v[24:27]
	v_mfma_f32_16x16x32_bf16 v[142:145], v[178:181], v[138:141], v[4:7]
	v_mfma_f32_16x16x32_bf16 v[92:95], v[150:153], v[166:169], v[92:95]
	v_mfma_f32_16x16x32_bf16 v[88:91], v[36:39], v[166:169], v[88:91]
	v_mfma_f32_16x16x32_bf16 v[84:87], v[178:181], v[166:169], v[84:87]
	v_mfma_f32_16x16x32_bf16 v[80:83], v[20:23], v[166:169], v[80:83]
	v_mfma_f32_16x16x32_bf16 v[20:23], v[20:23], v[138:141], v[0:3]
	ds_read_b128 v[138:141], v188 offset:1024
	ds_read_b128 v[150:153], v188 offset:3072
	ds_read_b128 v[166:169], v188 offset:5120
	ds_read_b128 v[170:173], v188 offset:7168
	ds_read_b128 v[0:3], v187 offset:1024
	ds_read_b128 v[4:7], v186 offset:1024
	ds_read_b128 v[32:35], v149 offset:1024
	ds_read_b128 v[36:39], v147 offset:1024
	s_waitcnt lgkmcnt(3)
	v_mfma_f32_16x16x32_bf16 v[178:181], v[138:141], v[0:3], v[72:75]
	v_mfma_f32_16x16x32_bf16 v[186:189], v[150:153], v[0:3], v[68:71]
	v_mfma_f32_16x16x32_bf16 v[190:193], v[166:169], v[0:3], v[64:67]
	v_mfma_f32_16x16x32_bf16 v[194:197], v[170:173], v[0:3], v[12:15]
	ds_read_b128 v[0:3], v146 offset:1024
	s_waitcnt lgkmcnt(3)
	v_mfma_f32_16x16x32_bf16 v[108:111], v[138:141], v[4:7], v[108:111]
	v_mfma_f32_16x16x32_bf16 v[104:107], v[150:153], v[4:7], v[104:107]
	v_mfma_f32_16x16x32_bf16 v[198:201], v[166:169], v[4:7], v[100:103]
	v_mfma_f32_16x16x32_bf16 v[96:99], v[170:173], v[4:7], v[96:99]
	ds_read_b128 v[4:7], v131 offset:1024
	s_waitcnt lgkmcnt(3)
	v_mfma_f32_16x16x32_bf16 v[64:67], v[138:141], v[32:35], v[92:95]
	v_mfma_f32_16x16x32_bf16 v[68:71], v[150:153], v[32:35], v[88:91]
	v_mfma_f32_16x16x32_bf16 v[72:75], v[166:169], v[32:35], v[84:87]
	v_mfma_f32_16x16x32_bf16 v[76:79], v[170:173], v[32:35], v[80:83]
	ds_read_b128 v[12:15], v130 offset:1024
	s_waitcnt lgkmcnt(3)
	v_mfma_f32_16x16x32_bf16 v[80:83], v[138:141], v[36:39], v[124:127]
	v_mfma_f32_16x16x32_bf16 v[84:87], v[150:153], v[36:39], v[120:123]
	v_mfma_f32_16x16x32_bf16 v[88:91], v[166:169], v[36:39], v[116:119]
	v_mfma_f32_16x16x32_bf16 v[92:95], v[170:173], v[36:39], v[112:115]
	ds_read_b128 v[100:103], v128 offset:1024
	s_waitcnt lgkmcnt(3)
	v_mfma_f32_16x16x32_bf16 v[32:35], v[138:141], v[0:3], v[60:63]
	v_mfma_f32_16x16x32_bf16 v[36:39], v[150:153], v[0:3], v[56:59]
	v_mfma_f32_16x16x32_bf16 v[40:43], v[166:169], v[0:3], v[52:55]
	v_mfma_f32_16x16x32_bf16 v[44:47], v[170:173], v[0:3], v[48:51]
	s_waitcnt lgkmcnt(2)
	v_mfma_f32_16x16x32_bf16 v[48:51], v[138:141], v[4:7], v[154:157]
	v_mfma_f32_16x16x32_bf16 v[52:55], v[150:153], v[4:7], v[158:161]
	v_mfma_f32_16x16x32_bf16 v[56:59], v[166:169], v[4:7], v[162:165]
	v_mfma_f32_16x16x32_bf16 v[60:63], v[170:173], v[4:7], v[24:27]
	s_waitcnt lgkmcnt(1)
	v_mfma_f32_16x16x32_bf16 v[0:3], v[138:141], v[12:15], v[16:19]
	v_mfma_f32_16x16x32_bf16 v[4:7], v[150:153], v[12:15], v[8:11]
	v_mfma_f32_16x16x32_bf16 v[8:11], v[166:169], v[12:15], v[142:145]
	v_mfma_f32_16x16x32_bf16 v[12:15], v[170:173], v[12:15], v[20:23]
	s_waitcnt lgkmcnt(0)
	v_mfma_f32_16x16x32_bf16 v[16:19], v[138:141], v[100:103], v[174:177]
	v_mfma_f32_16x16x32_bf16 v[20:23], v[150:153], v[100:103], v[28:31]
	v_mfma_f32_16x16x32_bf16 v[24:27], v[166:169], v[100:103], v[182:185]
	v_mfma_f32_16x16x32_bf16 v[28:31], v[170:173], v[100:103], v[134:137]
	v_mov_b32_e32 v102, s3
	s_waitcnt vmcnt(0)
	s_barrier
	v_and_b32_e32 v100, 63, v132
	v_lshrrev_b32_e32 v101, 6, v132
	v_and_b32_e32 v102, 15, v100
	v_lshrrev_b32_e32 v103, 4, v100
	v_mul_u32_u24_e32 v112, 0x2400, v101
	v_add_u32_e32 v112, 0x10000, v112
	v_mul_u32_u24_e32 v124, 0x110, v102
	v_lshl_add_u32 v124, v103, 4, v124
	v_add_u32_e32 v124, v124, v112
	v_mul_u32_u24_e32 v128, 0x110, v103
	v_lshl_add_u32 v128, v102, 4, v128
	v_add_u32_e32 v128, v128, v112
	v_lshrrev_b32_e32 v113, 2, v101
	v_lshl_add_u32 v113, v113, 7, v103
	v_add_u32_e32 v113, s24, v113
	v_and_b32_e32 v114, 3, v101
	v_lshlrev_b32_e32 v114, 6, v114
	v_lshl_add_u32 v114, v102, 2, v114
	v_add_u32_e32 v114, s10, v114
	v_mov_b32_e32 v252, 0x240a0
	ds_read_b64 v[248:249], v252
	v_mov_b32_e32 v252, 0x240a0
	ds_read_b64 v[250:251], v252
	v_mov_b32_e32 v252, 0x240a8
	ds_read_b64 v[240:241], v252
	s_lshr_b32 s100, s24, 12
	s_mul_i32 s100, s100, 0x6000
	s_add_i32 s100, s100, 0x2285000
	s_mov_b64 s[98:99], 0x4000
	v_lshlrev_b32_e32 v252, 12, v113
	v_lshl_add_u32 v252, v114, 2, v252
	v_mov_b32_e32 v253, 0
	s_waitcnt lgkmcnt(0)
	v_lshl_add_u64 v[248:249], v[248:249], 0, v[252:253]
	v_lshl_add_u64 v[250:251], v[250:251], 0, v[252:253]
	v_lshl_add_u32 v252, v114, 2, s100
	v_lshl_add_u64 v[240:241], v[240:241], 0, v[252:253]
	global_load_dwordx4 v[240:243], v[240:241], off
	ds_write_b128 v124, v[178:181]
	ds_write_b128 v124, v[186:189] offset:64
	ds_write_b128 v124, v[190:193] offset:128
	ds_write_b128 v124, v[194:197] offset:192
	ds_write_b128 v124, v[108:111] offset:4352
	ds_write_b128 v124, v[104:107] offset:4416
	ds_write_b128 v124, v[198:201] offset:4480
	ds_write_b128 v124, v[96:99] offset:4544
	s_waitcnt lgkmcnt(0)
	global_load_dwordx4 v[100:103], v[248:249], off nt
	v_lshl_add_u64 v[248:249], v[248:249], 0, s[98:99]
	global_load_dwordx4 v[112:115], v[248:249], off nt
	v_lshl_add_u64 v[248:249], v[248:249], 0, s[98:99]
	global_load_dwordx4 v[116:119], v[248:249], off nt
	v_lshl_add_u64 v[248:249], v[248:249], 0, s[98:99]
	global_load_dwordx4 v[120:123], v[248:249], off nt
	v_lshl_add_u64 v[248:249], v[248:249], 0, s[98:99]
	global_load_dwordx4 v[178:181], v[248:249], off nt
	v_lshl_add_u64 v[248:249], v[248:249], 0, s[98:99]
	global_load_dwordx4 v[186:189], v[248:249], off nt
	v_lshl_add_u64 v[248:249], v[248:249], 0, s[98:99]
	global_load_dwordx4 v[190:193], v[248:249], off nt
	v_lshl_add_u64 v[248:249], v[248:249], 0, s[98:99]
	global_load_dwordx4 v[194:197], v[248:249], off nt
	v_lshl_add_u64 v[248:249], v[248:249], 0, s[98:99]
	ds_read_b128 v[244:247], v128
	s_waitcnt vmcnt(7) lgkmcnt(0)
	v_pk_fma_f32 v[102:103], v[246:247], v[242:243], v[102:103]
	v_pk_fma_f32 v[100:101], v[244:245], v[240:241], v[100:101]
	global_store_dwordx4 v[250:251], v[100:103], off nt
	v_lshl_add_u64 v[250:251], v[250:251], 0, s[98:99]
	ds_read_b128 v[244:247], v128 offset:1088
	s_waitcnt vmcnt(7) lgkmcnt(0)
	v_pk_fma_f32 v[114:115], v[246:247], v[242:243], v[114:115]
	v_pk_fma_f32 v[112:113], v[244:245], v[240:241], v[112:113]
	global_store_dwordx4 v[250:251], v[112:115], off nt
	v_lshl_add_u64 v[250:251], v[250:251], 0, s[98:99]
	ds_read_b128 v[244:247], v128 offset:2176
	s_waitcnt vmcnt(7) lgkmcnt(0)
	v_pk_fma_f32 v[118:119], v[246:247], v[242:243], v[118:119]
	v_pk_fma_f32 v[116:117], v[244:245], v[240:241], v[116:117]
	global_store_dwordx4 v[250:251], v[116:119], off nt
	v_lshl_add_u64 v[250:251], v[250:251], 0, s[98:99]
	ds_read_b128 v[244:247], v128 offset:3264
	s_waitcnt vmcnt(7) lgkmcnt(0)
	v_pk_fma_f32 v[122:123], v[246:247], v[242:243], v[122:123]
	v_pk_fma_f32 v[120:121], v[244:245], v[240:241], v[120:121]
	global_store_dwordx4 v[250:251], v[120:123], off nt
	v_lshl_add_u64 v[250:251], v[250:251], 0, s[98:99]
	global_load_dwordx4 v[100:103], v[248:249], off nt
	v_lshl_add_u64 v[248:249], v[248:249], 0, s[98:99]
	global_load_dwordx4 v[112:115], v[248:249], off nt
	v_lshl_add_u64 v[248:249], v[248:249], 0, s[98:99]
	global_load_dwordx4 v[116:119], v[248:249], off nt
	v_lshl_add_u64 v[248:249], v[248:249], 0, s[98:99]
	global_load_dwordx4 v[120:123], v[248:249], off nt
	v_lshl_add_u64 v[248:249], v[248:249], 0, s[98:99]
	ds_read_b128 v[244:247], v128 offset:4352
	s_waitcnt vmcnt(11) lgkmcnt(0)
	v_pk_fma_f32 v[180:181], v[246:247], v[242:243], v[180:181]
	v_pk_fma_f32 v[178:179], v[244:245], v[240:241], v[178:179]
	global_store_dwordx4 v[250:251], v[178:181], off nt
	v_lshl_add_u64 v[250:251], v[250:251], 0, s[98:99]
	ds_read_b128 v[244:247], v128 offset:5440
	s_waitcnt vmcnt(11) lgkmcnt(0)
	v_pk_fma_f32 v[188:189], v[246:247], v[242:243], v[188:189]
	v_pk_fma_f32 v[186:187], v[244:245], v[240:241], v[186:187]
	global_store_dwordx4 v[250:251], v[186:189], off nt
	v_lshl_add_u64 v[250:251], v[250:251], 0, s[98:99]
	ds_read_b128 v[244:247], v128 offset:6528
	s_waitcnt vmcnt(11) lgkmcnt(0)
	v_pk_fma_f32 v[192:193], v[246:247], v[242:243], v[192:193]
	v_pk_fma_f32 v[190:191], v[244:245], v[240:241], v[190:191]
	global_store_dwordx4 v[250:251], v[190:193], off nt
	v_lshl_add_u64 v[250:251], v[250:251], 0, s[98:99]
	ds_read_b128 v[244:247], v128 offset:7616
	s_waitcnt vmcnt(11) lgkmcnt(0)
	v_pk_fma_f32 v[196:197], v[246:247], v[242:243], v[196:197]
	v_pk_fma_f32 v[194:195], v[244:245], v[240:241], v[194:195]
	global_store_dwordx4 v[250:251], v[194:197], off nt
	v_lshl_add_u64 v[250:251], v[250:251], 0, s[98:99]
	ds_write_b128 v124, v[64:67]
	ds_write_b128 v124, v[68:71] offset:64
	ds_write_b128 v124, v[72:75] offset:128
	ds_write_b128 v124, v[76:79] offset:192
	ds_write_b128 v124, v[80:83] offset:4352
	ds_write_b128 v124, v[84:87] offset:4416
	ds_write_b128 v124, v[88:91] offset:4480
	ds_write_b128 v124, v[92:95] offset:4544
	global_load_dwordx4 v[178:181], v[248:249], off nt
	v_lshl_add_u64 v[248:249], v[248:249], 0, s[98:99]
	global_load_dwordx4 v[186:189], v[248:249], off nt
	v_lshl_add_u64 v[248:249], v[248:249], 0, s[98:99]
	global_load_dwordx4 v[190:193], v[248:249], off nt
	v_lshl_add_u64 v[248:249], v[248:249], 0, s[98:99]
	global_load_dwordx4 v[194:197], v[248:249], off nt
	v_lshl_add_u64 v[248:249], v[248:249], 0, s[98:99]
	ds_read_b128 v[244:247], v128
	s_waitcnt vmcnt(11) lgkmcnt(0)
	v_pk_fma_f32 v[102:103], v[246:247], v[242:243], v[102:103]
	v_pk_fma_f32 v[100:101], v[244:245], v[240:241], v[100:101]
	global_store_dwordx4 v[250:251], v[100:103], off nt
	v_lshl_add_u64 v[250:251], v[250:251], 0, s[98:99]
	ds_read_b128 v[244:247], v128 offset:1088
	s_waitcnt vmcnt(11) lgkmcnt(0)
	v_pk_fma_f32 v[114:115], v[246:247], v[242:243], v[114:115]
	v_pk_fma_f32 v[112:113], v[244:245], v[240:241], v[112:113]
	global_store_dwordx4 v[250:251], v[112:115], off nt
	v_lshl_add_u64 v[250:251], v[250:251], 0, s[98:99]
	ds_read_b128 v[244:247], v128 offset:2176
	s_waitcnt vmcnt(11) lgkmcnt(0)
	v_pk_fma_f32 v[118:119], v[246:247], v[242:243], v[118:119]
	v_pk_fma_f32 v[116:117], v[244:245], v[240:241], v[116:117]
	global_store_dwordx4 v[250:251], v[116:119], off nt
	v_lshl_add_u64 v[250:251], v[250:251], 0, s[98:99]
	ds_read_b128 v[244:247], v128 offset:3264
	s_waitcnt vmcnt(11) lgkmcnt(0)
	v_pk_fma_f32 v[122:123], v[246:247], v[242:243], v[122:123]
	v_pk_fma_f32 v[120:121], v[244:245], v[240:241], v[120:121]
	global_store_dwordx4 v[250:251], v[120:123], off nt
	v_lshl_add_u64 v[250:251], v[250:251], 0, s[98:99]
	global_load_dwordx4 v[100:103], v[248:249], off nt
	v_lshl_add_u64 v[248:249], v[248:249], 0, s[98:99]
	global_load_dwordx4 v[112:115], v[248:249], off nt
	v_lshl_add_u64 v[248:249], v[248:249], 0, s[98:99]
	global_load_dwordx4 v[116:119], v[248:249], off nt
	v_lshl_add_u64 v[248:249], v[248:249], 0, s[98:99]
	global_load_dwordx4 v[120:123], v[248:249], off nt
	v_lshl_add_u64 v[248:249], v[248:249], 0, s[98:99]
	ds_read_b128 v[244:247], v128 offset:4352
	s_waitcnt vmcnt(11) lgkmcnt(0)
	v_pk_fma_f32 v[180:181], v[246:247], v[242:243], v[180:181]
	v_pk_fma_f32 v[178:179], v[244:245], v[240:241], v[178:179]
	global_store_dwordx4 v[250:251], v[178:181], off nt
	v_lshl_add_u64 v[250:251], v[250:251], 0, s[98:99]
	ds_read_b128 v[244:247], v128 offset:5440
	s_waitcnt vmcnt(11) lgkmcnt(0)
	v_pk_fma_f32 v[188:189], v[246:247], v[242:243], v[188:189]
	v_pk_fma_f32 v[186:187], v[244:245], v[240:241], v[186:187]
	global_store_dwordx4 v[250:251], v[186:189], off nt
	v_lshl_add_u64 v[250:251], v[250:251], 0, s[98:99]
	ds_read_b128 v[244:247], v128 offset:6528
	s_waitcnt vmcnt(11) lgkmcnt(0)
	v_pk_fma_f32 v[192:193], v[246:247], v[242:243], v[192:193]
	v_pk_fma_f32 v[190:191], v[244:245], v[240:241], v[190:191]
	global_store_dwordx4 v[250:251], v[190:193], off nt
	v_lshl_add_u64 v[250:251], v[250:251], 0, s[98:99]
	ds_read_b128 v[244:247], v128 offset:7616
	s_waitcnt vmcnt(11) lgkmcnt(0)
	v_pk_fma_f32 v[196:197], v[246:247], v[242:243], v[196:197]
	v_pk_fma_f32 v[194:195], v[244:245], v[240:241], v[194:195]
	global_store_dwordx4 v[250:251], v[194:197], off nt
	v_lshl_add_u64 v[250:251], v[250:251], 0, s[98:99]
	ds_write_b128 v124, v[32:35]
	ds_write_b128 v124, v[36:39] offset:64
	ds_write_b128 v124, v[40:43] offset:128
	ds_write_b128 v124, v[44:47] offset:192
	ds_write_b128 v124, v[48:51] offset:4352
	ds_write_b128 v124, v[52:55] offset:4416
	ds_write_b128 v124, v[56:59] offset:4480
	ds_write_b128 v124, v[60:63] offset:4544
	global_load_dwordx4 v[178:181], v[248:249], off nt
	v_lshl_add_u64 v[248:249], v[248:249], 0, s[98:99]
	global_load_dwordx4 v[186:189], v[248:249], off nt
	v_lshl_add_u64 v[248:249], v[248:249], 0, s[98:99]
	global_load_dwordx4 v[190:193], v[248:249], off nt
	v_lshl_add_u64 v[248:249], v[248:249], 0, s[98:99]
	global_load_dwordx4 v[194:197], v[248:249], off nt
	v_lshl_add_u64 v[248:249], v[248:249], 0, s[98:99]
	ds_read_b128 v[244:247], v128
	s_waitcnt vmcnt(11) lgkmcnt(0)
	v_pk_fma_f32 v[102:103], v[246:247], v[242:243], v[102:103]
	v_pk_fma_f32 v[100:101], v[244:245], v[240:241], v[100:101]
	global_store_dwordx4 v[250:251], v[100:103], off nt
	v_lshl_add_u64 v[250:251], v[250:251], 0, s[98:99]
	ds_read_b128 v[244:247], v128 offset:1088
	s_waitcnt vmcnt(11) lgkmcnt(0)
	v_pk_fma_f32 v[114:115], v[246:247], v[242:243], v[114:115]
	v_pk_fma_f32 v[112:113], v[244:245], v[240:241], v[112:113]
	global_store_dwordx4 v[250:251], v[112:115], off nt
	v_lshl_add_u64 v[250:251], v[250:251], 0, s[98:99]
	ds_read_b128 v[244:247], v128 offset:2176
	s_waitcnt vmcnt(11) lgkmcnt(0)
	v_pk_fma_f32 v[118:119], v[246:247], v[242:243], v[118:119]
	v_pk_fma_f32 v[116:117], v[244:245], v[240:241], v[116:117]
	global_store_dwordx4 v[250:251], v[116:119], off nt
	v_lshl_add_u64 v[250:251], v[250:251], 0, s[98:99]
	ds_read_b128 v[244:247], v128 offset:3264
	s_waitcnt vmcnt(11) lgkmcnt(0)
	v_pk_fma_f32 v[122:123], v[246:247], v[242:243], v[122:123]
	v_pk_fma_f32 v[120:121], v[244:245], v[240:241], v[120:121]
	global_store_dwordx4 v[250:251], v[120:123], off nt
	v_lshl_add_u64 v[250:251], v[250:251], 0, s[98:99]
	global_load_dwordx4 v[100:103], v[248:249], off nt
	v_lshl_add_u64 v[248:249], v[248:249], 0, s[98:99]
	global_load_dwordx4 v[112:115], v[248:249], off nt
	v_lshl_add_u64 v[248:249], v[248:249], 0, s[98:99]
	global_load_dwordx4 v[116:119], v[248:249], off nt
	v_lshl_add_u64 v[248:249], v[248:249], 0, s[98:99]
	global_load_dwordx4 v[120:123], v[248:249], off nt
	v_lshl_add_u64 v[248:249], v[248:249], 0, s[98:99]
	ds_read_b128 v[244:247], v128 offset:4352
	s_waitcnt vmcnt(11) lgkmcnt(0)
	v_pk_fma_f32 v[180:181], v[246:247], v[242:243], v[180:181]
	v_pk_fma_f32 v[178:179], v[244:245], v[240:241], v[178:179]
	global_store_dwordx4 v[250:251], v[178:181], off nt
	v_lshl_add_u64 v[250:251], v[250:251], 0, s[98:99]
	ds_read_b128 v[244:247], v128 offset:5440
	s_waitcnt vmcnt(11) lgkmcnt(0)
	v_pk_fma_f32 v[188:189], v[246:247], v[242:243], v[188:189]
	v_pk_fma_f32 v[186:187], v[244:245], v[240:241], v[186:187]
	global_store_dwordx4 v[250:251], v[186:189], off nt
	v_lshl_add_u64 v[250:251], v[250:251], 0, s[98:99]
	ds_read_b128 v[244:247], v128 offset:6528
	s_waitcnt vmcnt(11) lgkmcnt(0)
	v_pk_fma_f32 v[192:193], v[246:247], v[242:243], v[192:193]
	v_pk_fma_f32 v[190:191], v[244:245], v[240:241], v[190:191]
	global_store_dwordx4 v[250:251], v[190:193], off nt
	v_lshl_add_u64 v[250:251], v[250:251], 0, s[98:99]
	ds_read_b128 v[244:247], v128 offset:7616
	s_waitcnt vmcnt(11) lgkmcnt(0)
	v_pk_fma_f32 v[196:197], v[246:247], v[242:243], v[196:197]
	v_pk_fma_f32 v[194:195], v[244:245], v[240:241], v[194:195]
	global_store_dwordx4 v[250:251], v[194:197], off nt
	v_lshl_add_u64 v[250:251], v[250:251], 0, s[98:99]
	ds_write_b128 v124, v[0:3]
	ds_write_b128 v124, v[4:7] offset:64
	ds_write_b128 v124, v[8:11] offset:128
	ds_write_b128 v124, v[12:15] offset:192
	ds_write_b128 v124, v[16:19] offset:4352
	ds_write_b128 v124, v[20:23] offset:4416
	ds_write_b128 v124, v[24:27] offset:4480
	ds_write_b128 v124, v[28:31] offset:4544
	global_load_dwordx4 v[178:181], v[248:249], off nt
	v_lshl_add_u64 v[248:249], v[248:249], 0, s[98:99]
	global_load_dwordx4 v[186:189], v[248:249], off nt
	v_lshl_add_u64 v[248:249], v[248:249], 0, s[98:99]
	global_load_dwordx4 v[190:193], v[248:249], off nt
	v_lshl_add_u64 v[248:249], v[248:249], 0, s[98:99]
	global_load_dwordx4 v[194:197], v[248:249], off nt
	v_lshl_add_u64 v[248:249], v[248:249], 0, s[98:99]
	ds_read_b128 v[244:247], v128
	s_waitcnt vmcnt(11) lgkmcnt(0)
	v_pk_fma_f32 v[102:103], v[246:247], v[242:243], v[102:103]
	v_pk_fma_f32 v[100:101], v[244:245], v[240:241], v[100:101]
	global_store_dwordx4 v[250:251], v[100:103], off nt
	v_lshl_add_u64 v[250:251], v[250:251], 0, s[98:99]
	ds_read_b128 v[244:247], v128 offset:1088
	s_waitcnt vmcnt(11) lgkmcnt(0)
	v_pk_fma_f32 v[114:115], v[246:247], v[242:243], v[114:115]
	v_pk_fma_f32 v[112:113], v[244:245], v[240:241], v[112:113]
	global_store_dwordx4 v[250:251], v[112:115], off nt
	v_lshl_add_u64 v[250:251], v[250:251], 0, s[98:99]
	ds_read_b128 v[244:247], v128 offset:2176
	s_waitcnt vmcnt(11) lgkmcnt(0)
	v_pk_fma_f32 v[118:119], v[246:247], v[242:243], v[118:119]
	v_pk_fma_f32 v[116:117], v[244:245], v[240:241], v[116:117]
	global_store_dwordx4 v[250:251], v[116:119], off nt
	v_lshl_add_u64 v[250:251], v[250:251], 0, s[98:99]
	ds_read_b128 v[244:247], v128 offset:3264
	s_waitcnt vmcnt(11) lgkmcnt(0)
	v_pk_fma_f32 v[122:123], v[246:247], v[242:243], v[122:123]
	v_pk_fma_f32 v[120:121], v[244:245], v[240:241], v[120:121]
	global_store_dwordx4 v[250:251], v[120:123], off nt
	v_lshl_add_u64 v[250:251], v[250:251], 0, s[98:99]
	ds_read_b128 v[244:247], v128 offset:4352
	s_waitcnt vmcnt(7) lgkmcnt(0)
	v_pk_fma_f32 v[180:181], v[246:247], v[242:243], v[180:181]
	v_pk_fma_f32 v[178:179], v[244:245], v[240:241], v[178:179]
	global_store_dwordx4 v[250:251], v[178:181], off nt
	v_lshl_add_u64 v[250:251], v[250:251], 0, s[98:99]
	ds_read_b128 v[244:247], v128 offset:5440
	s_waitcnt vmcnt(7) lgkmcnt(0)
	v_pk_fma_f32 v[188:189], v[246:247], v[242:243], v[188:189]
	v_pk_fma_f32 v[186:187], v[244:245], v[240:241], v[186:187]
	global_store_dwordx4 v[250:251], v[186:189], off nt
	v_lshl_add_u64 v[250:251], v[250:251], 0, s[98:99]
	ds_read_b128 v[244:247], v128 offset:6528
	s_waitcnt vmcnt(7) lgkmcnt(0)
	v_pk_fma_f32 v[192:193], v[246:247], v[242:243], v[192:193]
	v_pk_fma_f32 v[190:191], v[244:245], v[240:241], v[190:191]
	global_store_dwordx4 v[250:251], v[190:193], off nt
	v_lshl_add_u64 v[250:251], v[250:251], 0, s[98:99]
	ds_read_b128 v[244:247], v128 offset:7616
	s_waitcnt vmcnt(7) lgkmcnt(0)
	v_pk_fma_f32 v[196:197], v[246:247], v[242:243], v[196:197]
	v_pk_fma_f32 v[194:195], v[244:245], v[240:241], v[194:195]
	global_store_dwordx4 v[250:251], v[194:197], off nt
	v_lshl_add_u64 v[250:251], v[250:251], 0, s[98:99]
	s_add_i32 s23, s23, s40
	s_cmpk_gt_i32 s23, 0x1ff
	s_cbranch_scc0 .LBB0_1137
